# redundant wait-state pads re-derived (removed where the producer/consumer pair no longer exists) in attention, HGRN, EpiGate and EpiSwiglu epilogues
# speedup vs baseline: 1.0084x; 1.0016x over previous
; __device__ __forceinline__ void attn_fetch(const Ctx& C, int it, u32x4 (&kv)[4], u32x4 (&vv)[4], u32x4 (&qv)[2]) {
;     ...
; #pragma unroll
;     for (int k = 0; k < 4; ++k) { const int id = tid + NTHR * k, cidx = id >> 3, ch = id & 7, ik = 128 * jb - 64 + cidx;
;         kv[k] = (u32x4){0u, 0u, 0u, 0u}; vv[k] = (u32x4){0u, 0u, 0u, 0u};
;         if (ik >= 0 && ik < n) { const bf16_t* row = pd + (size_t)(b * SEQ + r + dil * ik) * 2304; kv[k] = *(const u32x4*)(row + 768 + hq * 64 + ch * 8); vv[k] = *(const u32x4*)(row + 1536 + hq * 64 + ch * 8); } }
; #pragma unroll
;     for (int k = 0; k < 2; ++k) { const int id = tid + NTHR * k, a = id >> 3, ch = id & 7;
;         qv[k] = *(const u32x4*)(pd + (size_t)(b * SEQ + r + dil * (128 * jb + a)) * 2304 + hq * 64 + ch * 8); }
; __device__ __forceinline__ void attn_item(const Ctx& C, int it, int itn, u32x4 (&kv)[4], u32x4 (&vv)[4], u32x4 (&qv)[2]) {
;     ...
;     {
; #pragma unroll
;         for (int k = 0; k < 4; ++k) { const int id = tid + NTHR * k, cidx = id >> 3, ch = id & 7;
;             *(u32x4*)(Ks + cidx * 72 + ch * 8) = kv[k];
;             *(u32x4*)(Vs + cidx * 72 + ch * 8) = vv[k]; }
; #pragma unroll
;         for (int k = 0; k < 2; ++k) { const int id = tid + NTHR * k, a = id >> 3, ch = id & 7; *(u32x4*)(Qs + a * 72 + ch * 8) = qv[k]; }
;     }
;     if (itn < 3072) attn_fetch(C, itn, kv, vv, qv);
.LBB0_349:
	s_or_b64 exec, exec, s[0:1]
	s_add_i32 s50, s50, s26
	s_cmpk_gt_i32 s50, 0xbff
	s_cselect_b64 s[44:45], -1, 0
	s_and_b64 vcc, exec, s[44:45]
	s_waitcnt vmcnt(3)
	ds_write_b128 v82, v[4:7]
	s_waitcnt vmcnt(2)
	ds_write_b128 v82, v[8:11] offset:55296
	ds_write_b128 v84, v[12:15]
	ds_write_b128 v84, v[0:3] offset:55296
	ds_write_b128 v86, v[16:19]
	ds_write_b128 v86, v[20:23] offset:55296
	ds_write_b128 v88, v[24:27]
	ds_write_b128 v88, v[28:31] offset:55296
	s_waitcnt vmcnt(0)
	ds_write_b128 v82, v[36:39] offset:36864
	ds_write_b128 v84, v[32:35] offset:36864
	s_cbranch_vccnz .LBB0_359
	s_mul_hi_i32 s0, s50, 0x2aaaaaab
	s_lshr_b32 s1, s0, 31
	s_ashr_i32 s0, s0, 6
	s_add_i32 s0, s0, s1
	s_mul_i32 s1, s0, 0xfffffe80
	s_add_i32 s1, s50, s1
	s_and_b32 s46, s1, 31
	s_ashr_i32 s1, s1, 6
	s_and_b32 s48, s1, -2
	s_lshr_b32 s1, 32, s48
	s_add_i32 s1, s1, -1
	s_and_b32 s1, s1, s46
	s_lshl_b32 s49, s1, 7
	s_sub_i32 s47, 5, s48
	s_sub_i32 s69, s49, 64
	s_lshl_b32 s1, s0, 12
	s_mulk_i32 s0, 0xfd00
	s_lshr_b32 s68, 0x1000, s48
	s_lshr_b32 s47, s46, s47
	s_add_i32 s0, s67, s0
	v_add_u32_e32 v12, s69, v92
	v_mov_b32_e32 v2, v65
	v_mov_b32_e32 v3, v65
	s_or_b32 s53, s47, s1
	s_and_b32 s46, s0, 0xffffffc0
	v_cmp_lt_i32_e64 s[0:1], -1, v12
	v_cmp_gt_i32_e32 vcc, s68, v12
	v_mov_b32_e32 v0, v65
	v_mov_b32_e32 v1, v65
	v_mov_b64_e32 v[10:11], v[2:3]
	v_mov_b64_e32 v[6:7], v[2:3]
	s_ashr_i32 s47, s46, 31
	s_and_b64 vcc, s[0:1], vcc
	v_mov_b64_e32 v[8:9], v[0:1]
	v_mov_b64_e32 v[4:5], v[0:1]
	s_and_saveexec_b64 s[0:1], vcc
	s_cbranch_execz .LBB0_352
	v_lshlrev_b32_e32 v4, s48, v12
	v_add_u32_e32 v6, s53, v4
	v_mov_b64_e32 v[4:5], s[42:43]
	v_mad_i64_i32 v[4:5], vcc, v6, s66, v[4:5]
	v_lshl_add_u64 v[4:5], s[46:47], 1, v[4:5]
	v_mov_b32_e32 v79, v65
	v_lshl_add_u64 v[8:9], v[4:5], 0, v[78:79]
	global_load_dwordx4 v[4:7], v[8:9], off offset:1536
	global_load_dwordx4 v[8:11], v[8:9], off offset:3072
.LBB0_352:
	s_or_b64 exec, exec, s[0:1]
	v_add_u32_e32 v16, s69, v93
	v_cmp_lt_i32_e32 vcc, -1, v16
	v_cmp_gt_i32_e64 s[0:1], s68, v16
	v_mov_b64_e32 v[14:15], v[2:3]
	s_and_b64 vcc, vcc, s[0:1]
	v_mov_b64_e32 v[12:13], v[0:1]
	s_and_saveexec_b64 s[0:1], vcc
	s_cbranch_execz .LBB0_354
	v_lshlrev_b32_e32 v0, s48, v16
	v_add_u32_e32 v2, s53, v0
	v_mov_b64_e32 v[0:1], s[42:43]
	v_mad_i64_i32 v[0:1], vcc, v2, s66, v[0:1]
	v_lshl_add_u64 v[0:1], s[46:47], 1, v[0:1]
	v_mov_b32_e32 v79, v65
	v_lshl_add_u64 v[0:1], v[0:1], 0, v[78:79]
	global_load_dwordx4 v[12:15], v[0:1], off offset:1536
	global_load_dwordx4 v[0:3], v[0:1], off offset:3072
.LBB0_354:
	s_or_b64 exec, exec, s[0:1]
	v_add_u32_e32 v24, s69, v94
	v_mov_b32_e32 v62, v65
	v_mov_b32_e32 v63, v65
	v_cmp_lt_i32_e32 vcc, -1, v24
	v_cmp_gt_i32_e64 s[0:1], s68, v24
	v_mov_b32_e32 v64, v65
	v_mov_b64_e32 v[20:21], v[62:63]
	v_mov_b64_e32 v[16:17], v[62:63]
	s_and_b64 vcc, vcc, s[0:1]
	v_mov_b64_e32 v[22:23], v[64:65]
	v_mov_b64_e32 v[18:19], v[64:65]
	s_and_saveexec_b64 s[0:1], vcc
	s_cbranch_execz .LBB0_356
	v_lshlrev_b32_e32 v16, s48, v24
	v_add_u32_e32 v18, s53, v16
	v_mov_b64_e32 v[16:17], s[42:43]
	v_mad_i64_i32 v[16:17], vcc, v18, s66, v[16:17]
	v_lshl_add_u64 v[16:17], s[46:47], 1, v[16:17]
	v_mov_b32_e32 v79, v65
	v_lshl_add_u64 v[20:21], v[16:17], 0, v[78:79]
	global_load_dwordx4 v[16:19], v[20:21], off offset:1536
	global_load_dwordx4 v[20:23], v[20:21], off offset:3072
.LBB0_356:
	s_or_b64 exec, exec, s[0:1]
	v_add_u32_e32 v32, s69, v95
	v_cmp_lt_i32_e32 vcc, -1, v32
	v_cmp_gt_i32_e64 s[0:1], s68, v32
	v_mov_b64_e32 v[28:29], v[62:63]
	v_mov_b64_e32 v[24:25], v[62:63]
	s_and_b64 s[68:69], vcc, s[0:1]
	v_mov_b64_e32 v[30:31], v[64:65]
	v_mov_b64_e32 v[26:27], v[64:65]
	s_and_saveexec_b64 s[0:1], s[68:69]
	s_cbranch_execz .LBB0_358
	v_lshlrev_b32_e32 v24, s48, v32
	v_add_u32_e32 v26, s53, v24
	v_mov_b64_e32 v[24:25], s[42:43]
	v_mad_i64_i32 v[24:25], s[68:69], v26, s66, v[24:25]
	v_lshl_add_u64 v[24:25], s[46:47], 1, v[24:25]
	v_mov_b32_e32 v79, v65
	v_lshl_add_u64 v[28:29], v[24:25], 0, v[78:79]
	global_load_dwordx4 v[24:27], v[28:29], off offset:1536
	global_load_dwordx4 v[28:31], v[28:29], off offset:3072
.LBB0_358:
	s_or_b64 exec, exec, s[0:1]
	v_add_u32_e32 v34, s49, v92
	v_add_u32_e32 v36, s49, v93
	v_lshlrev_b32_e32 v34, s48, v34
	v_lshlrev_b32_e32 v36, s48, v36
	v_lshl_add_u64 v[32:33], s[46:47], 1, v[80:81]
	v_add_u32_e32 v34, s53, v34
	s_movk_i32 s46, 0x1200
	v_add_u32_e32 v36, s53, v36
	v_mad_i64_i32 v[34:35], s[0:1], v34, s46, v[32:33]
	v_mad_i64_i32 v[32:33], s[0:1], v36, s46, v[32:33]
	global_load_dwordx4 v[36:39], v[34:35], off
	global_load_dwordx4 v[32:35], v[32:33], off
	s_movk_i32 s66, 0x1200
; __device__ __forceinline__ void attn_item(const Ctx& C, int it, int itn, u32x4 (&kv)[4], u32x4 (&vv)[4], u32x4 (&qv)[2]) {
;     ...
;     const int fr = lane & 15, quad = lane >> 4;
;     bf16x8 qf[2];
;     qf[0] = *(const bf16x8*)(Qs + (16 * w + fr) * 72 + 8 * quad); qf[1] = *(const bf16x8*)(Qs + (16 * w + fr) * 72 + 32 + 8 * quad);
;     f32x4 sc[9];
; #pragma unroll
;     for (int kt = 0; kt < 9; ++kt) { const bf16_t* kr = Ks + (16 * (w + kt) + fr) * 72 + 8 * quad;
;         const bf16x8 k0 = *(const bf16x8*)kr, k1 = *(const bf16x8*)(kr + 32);
;         f32x4 z4 = {0.f, 0.f, 0.f, 0.f};
;         z4 = __builtin_amdgcn_mfma_f32_16x16x32_bf16(k0, qf[0], z4, 0, 0, 0);
;         sc[kt] = __builtin_amdgcn_mfma_f32_16x16x32_bf16(k1, qf[1], z4, 0, 0, 0); }
;     const int a = 16 * w + fr;
;     float mx = -1e30f;
; #pragma unroll
;     for (int kt = 0; kt < 9; ++kt)
; #pragma unroll
;         for (int rg = 0; rg < 4; ++rg) { const int cidx = 16 * (w + kt) + 4 * quad + rg, rel = cidx - 64 - a, ik = 128 * jb - 64 + cidx;
;             const bool valid = (rel >= -64) && (rel <= 64) && (ik >= 0) && (ik < n);
;             const int bi = rel < -64 ? 0 : (rel > 64 ? 128 : rel + 64);
;             const float s = valid ? sc[kt][rg] * 0.125f + bt[bi] : -1e30f;
;             sc[kt][rg] = s; mx = fmaxf(mx, s); }
.LBB0_359:
	s_waitcnt lgkmcnt(0)
	s_barrier
	ds_read_b32 v212, v98
	ds_read_b32 v213, v100
	ds_read_b32 v214, v102
	ds_read_b32 v215, v104
	ds_read_b32 v223, v106
	ds_read_b32 v228, v108
	ds_read_b32 v229, v110
	ds_read_b32 v230, v112
	ds_read_b32 v231, v114
	ds_read_b32 v232, v116
	ds_read_b32 v233, v118
	ds_read_b32 v234, v120
	ds_read_b32 v235, v122
	ds_read_b32 v236, v124
	ds_read_b32 v237, v126
	ds_read_b32 v238, v128
	ds_read_b32 v240, v130
	ds_read_b32 v241, v132
	ds_read_b32 v242, v134
	ds_read_b32 v243, v136
	ds_read_b32 v244, v138
	ds_read_b32 v245, v140
	ds_read_b32 v246, v142
	ds_read_b32 v247, v144
	ds_read_b32 v248, v146
	ds_read_b32 v249, v148
	ds_read_b32 v250, v150
	ds_read_b128 v[40:43], v85 offset:36864
	ds_read_b128 v[194:197], v85 offset:36928
	ds_read_b128 v[44:47], v87
	ds_read_b128 v[48:51], v87 offset:64
	s_waitcnt lgkmcnt(1)
	v_mfma_f32_16x16x32_bf16 v[44:47], v[44:47], v[40:43], 0
	s_lshr_b32 s0, 32, s52
	s_and_b32 s47, s36, 31
	s_add_i32 s0, s0, -1
	s_waitcnt lgkmcnt(0)
	v_mfma_f32_16x16x32_bf16 v[74:77], v[48:51], v[194:197], v[44:47]
	s_nop 2
	ds_read_b128 v[44:47], v173
	ds_read_b128 v[48:51], v173 offset:64
	s_and_b32 s0, s0, s47
	s_lshl_b32 s46, s0, 7
	s_waitcnt lgkmcnt(1)
	v_mfma_f32_16x16x32_bf16 v[44:47], v[44:47], v[40:43], 0
	s_sub_i32 s48, s46, 64
	v_add_u32_e32 v64, s48, v89
	v_readlane_b32 s0, v255, 7
	s_waitcnt lgkmcnt(0)
	v_mfma_f32_16x16x32_bf16 v[70:73], v[48:51], v[194:197], v[44:47]
	s_nop 2
	ds_read_b128 v[44:47], v174
	ds_read_b128 v[48:51], v174 offset:64
	s_lshr_b32 s53, 0x1000, s52
	v_cmp_lt_i32_e32 vcc, -1, v64
	s_waitcnt lgkmcnt(1)
	v_mfma_f32_16x16x32_bf16 v[44:47], v[44:47], v[40:43], 0
	v_readlane_b32 s1, v255, 8
	s_and_b64 s[0:1], s[0:1], vcc
	v_cmp_gt_i32_e32 vcc, s53, v64
	s_waitcnt lgkmcnt(0)
	v_mfma_f32_16x16x32_bf16 v[66:69], v[48:51], v[194:197], v[44:47]
	s_nop 2
	ds_read_b128 v[44:47], v175
	ds_read_b128 v[48:51], v175 offset:64
	s_and_b64 s[68:69], s[0:1], vcc
	s_waitcnt lgkmcnt(1)
	v_mfma_f32_16x16x32_bf16 v[44:47], v[44:47], v[40:43], 0
	s_waitcnt lgkmcnt(0)
	v_mfma_f32_16x16x32_bf16 v[60:63], v[48:51], v[194:197], v[44:47]
	s_nop 5
	ds_read_b128 v[44:47], v176
	ds_read_b128 v[48:51], v176 offset:64
	s_waitcnt lgkmcnt(1)
	v_mfma_f32_16x16x32_bf16 v[44:47], v[44:47], v[40:43], 0
	s_waitcnt lgkmcnt(0)
	v_mfma_f32_16x16x32_bf16 v[56:59], v[48:51], v[194:197], v[44:47]
	s_nop 5
	ds_read_b128 v[44:47], v177
	ds_read_b128 v[48:51], v177 offset:64
	s_waitcnt lgkmcnt(1)
	v_mfma_f32_16x16x32_bf16 v[44:47], v[44:47], v[40:43], 0
	s_waitcnt lgkmcnt(0)
	v_mfma_f32_16x16x32_bf16 v[52:55], v[48:51], v[194:197], v[44:47]
	s_nop 5
	ds_read_b128 v[44:47], v183
	ds_read_b128 v[48:51], v183 offset:64
	s_waitcnt lgkmcnt(1)
	v_mfma_f32_16x16x32_bf16 v[44:47], v[44:47], v[40:43], 0
	s_waitcnt lgkmcnt(0)
	v_mfma_f32_16x16x32_bf16 v[48:51], v[48:51], v[194:197], v[44:47]
	s_nop 5
	ds_read_b128 v[44:47], v192
	ds_read_b128 v[198:201], v192 offset:64
	s_waitcnt lgkmcnt(1)
	v_mfma_f32_16x16x32_bf16 v[44:47], v[44:47], v[40:43], 0
	s_waitcnt lgkmcnt(0)
	v_mfma_f32_16x16x32_bf16 v[44:47], v[198:201], v[194:197], v[44:47]
	ds_read_b128 v[198:201], v193
	ds_read_b128 v[202:205], v193 offset:64
	s_waitcnt lgkmcnt(1)
	v_mfma_f32_16x16x32_bf16 v[40:43], v[198:201], v[40:43], 0
	s_waitcnt lgkmcnt(0)
	v_mfma_f32_16x16x32_bf16 v[40:43], v[202:205], v[194:197], v[40:43]
	v_lshrrev_b32_e32 v178, 6, v224
	v_lshlrev_b32_e32 v178, 4, v178
	v_and_b32_e32 v179, 15, v224
	v_add_u32_e32 v179, v178, v179
	s_sub_i32 s0, 0, s48
	v_max_i32_e32 v180, s0, v179
	s_sub_i32 s1, s53, s48
	s_add_i32 s1, s1, -1
	v_add_u32_e32 v179, 0x80, v179
	v_min_i32_e32 v181, s1, v179
	v_bfe_u32 v179, v224, 4, 2
	v_lshl_add_u32 v178, v179, 2, v178
	v_sub_u32_e32 v188, v178, v180
	v_sub_u32_e32 v189, v181, v180
	v_mov_b32_e32 v179, 0xf149f2ca
	v_add_u32_e32 v190, 0, v188
	v_cmp_ge_u32_e32 vcc, v189, v190
	v_fmac_f32_e32 v212, 0x3e000000, v74
	v_add_u32_e32 v191, 1, v188
	v_cndmask_b32_e32 v195, v179, v212, vcc
	ds_read_b32 v212, v152
	v_cmp_ge_u32_e32 vcc, v189, v191
	v_fmac_f32_e32 v213, 0x3e000000, v75
	v_add_u32_e32 v190, 2, v188
	v_cndmask_b32_e32 v91, v179, v213, vcc
	ds_read_b32 v213, v154
	v_cmp_ge_u32_e32 vcc, v189, v190
	v_fmac_f32_e32 v214, 0x3e000000, v76
	v_add_u32_e32 v191, 3, v188
	v_cndmask_b32_e32 v194, v179, v214, vcc
	ds_read_b32 v214, v156
	v_cmp_ge_u32_e32 vcc, v189, v191
	v_fmac_f32_e32 v215, 0x3e000000, v77
	v_add_u32_e32 v190, 16, v188
	v_cndmask_b32_e32 v79, v179, v215, vcc
	ds_read_b32 v215, v158
	v_cmp_ge_u32_e32 vcc, v189, v190
	v_fmac_f32_e32 v223, 0x3e000000, v70
	v_add_u32_e32 v191, 17, v188
	v_cndmask_b32_e32 v74, v179, v223, vcc
	ds_read_b32 v223, v160
	v_cmp_ge_u32_e32 vcc, v189, v191
	v_fmac_f32_e32 v228, 0x3e000000, v71
	v_add_u32_e32 v190, 18, v188
	v_cndmask_b32_e32 v64, v179, v228, vcc
	ds_read_b32 v228, v162
	v_cmp_ge_u32_e32 vcc, v189, v190
	v_fmac_f32_e32 v229, 0x3e000000, v72
	v_add_u32_e32 v191, 19, v188
	v_cndmask_b32_e32 v75, v179, v229, vcc
	ds_read_b32 v229, v164
	v_cmp_ge_u32_e32 vcc, v189, v191
	v_fmac_f32_e32 v230, 0x3e000000, v73
	v_add_u32_e32 v190, 32, v188
	v_cndmask_b32_e32 v70, v179, v230, vcc
	ds_read_b32 v230, v166
	v_cmp_ge_u32_e32 vcc, v189, v190
	v_fmac_f32_e32 v231, 0x3e000000, v66
	v_add_u32_e32 v191, 33, v188
	v_cndmask_b32_e32 v72, v179, v231, vcc
	ds_read_b32 v231, v168
	v_cmp_ge_u32_e32 vcc, v189, v191
	v_fmac_f32_e32 v232, 0x3e000000, v67
	v_add_u32_e32 v190, 34, v188
	v_cndmask_b32_e32 v71, v179, v232, vcc
	v_cmp_ge_u32_e32 vcc, v189, v190
	v_fmac_f32_e32 v233, 0x3e000000, v68
	v_add_u32_e32 v191, 35, v188
	v_cndmask_b32_e32 v73, v179, v233, vcc
	v_cmp_ge_u32_e32 vcc, v189, v191
; __device__ __forceinline__ unsigned cvt_pk_bf16(float lo, float hi) { f32x2_t v = {lo, hi}; bf2_t r = __builtin_convertvector(v, bf2_t); return __builtin_bit_cast(unsigned, r); }
; __device__ __forceinline__ void attn_item(const Ctx& C, int it, int itn, u32x4 (&kv)[4], u32x4 (&vv)[4], u32x4 (&qv)[2]) {
;     ...
;     const int a = 16 * w + fr;
;     float mx = -1e30f;
; #pragma unroll
;     for (int kt = 0; kt < 9; ++kt)
; #pragma unroll
;         for (int rg = 0; rg < 4; ++rg) { const int cidx = 16 * (w + kt) + 4 * quad + rg, rel = cidx - 64 - a, ik = 128 * jb - 64 + cidx;
;             const bool valid = (rel >= -64) && (rel <= 64) && (ik >= 0) && (ik < n);
;             const int bi = rel < -64 ? 0 : (rel > 64 ? 128 : rel + 64);
;             const float s = valid ? sc[kt][rg] * 0.125f + bt[bi] : -1e30f;
;             sc[kt][rg] = s; mx = fmaxf(mx, s); }
;     mx = fmaxf(mx, __shfl_xor(mx, 16)); mx = fmaxf(mx, __shfl_xor(mx, 32));
;     float lsum = 0.f;
; #pragma unroll
;     for (int kt = 0; kt < 9; ++kt)
; #pragma unroll
;         for (int rg = 0; rg < 4; ++rg) { const float s = sc[kt][rg]; const float p = (s > -1e29f) ? __expf(s - mx) : 0.f; sc[kt][rg] = p; lsum += p; }
;     lsum += __shfl_xor(lsum, 16); lsum += __shfl_xor(lsum, 32);
;     f32x4 oo[4];
; #pragma unroll
;     for (int dt = 0; dt < 4; ++dt) oo[dt] = (f32x4){0.f, 0.f, 0.f, 0.f};
; #pragma unroll
;     for (int pp = 0; pp < 5; ++pp) { const int ktA = 2 * pp, ktB = 2 * pp + 1, ktBc = ktB < 9 ? ktB : 8;
;         union { bf16x8 v; unsigned u[4]; } pf;
;         pf.u[0] = cvt_pk_bf16(sc[ktA][0], sc[ktA][1]); pf.u[1] = cvt_pk_bf16(sc[ktA][2], sc[ktA][3]);
;         if (ktB < 9) { pf.u[2] = cvt_pk_bf16(sc[ktBc][0], sc[ktBc][1]); pf.u[3] = cvt_pk_bf16(sc[ktBc][2], sc[ktBc][3]); } else { pf.u[2] = 0u; pf.u[3] = 0u; }
	v_fmac_f32_e32 v234, 0x3e000000, v69
	v_add_u32_e32 v190, 48, v188
	v_cndmask_b32_e32 v66, v179, v234, vcc
	v_cmp_ge_u32_e32 vcc, v189, v190
	v_fmac_f32_e32 v235, 0x3e000000, v60
	v_add_u32_e32 v191, 49, v188
	v_cndmask_b32_e32 v69, v179, v235, vcc
	v_cmp_ge_u32_e32 vcc, v189, v191
	v_fmac_f32_e32 v236, 0x3e000000, v61
	v_add_u32_e32 v190, 50, v188
	v_cndmask_b32_e32 v67, v179, v236, vcc
	v_cmp_ge_u32_e32 vcc, v189, v190
	v_fmac_f32_e32 v237, 0x3e000000, v62
	v_add_u32_e32 v191, 51, v188
	v_cndmask_b32_e32 v68, v179, v237, vcc
	v_cmp_ge_u32_e32 vcc, v189, v191
	v_fmac_f32_e32 v238, 0x3e000000, v63
	v_add_u32_e32 v190, 64, v188
	v_cndmask_b32_e32 v60, v179, v238, vcc
	v_cmp_ge_u32_e32 vcc, v189, v190
	v_fmac_f32_e32 v240, 0x3e000000, v56
	v_add_u32_e32 v191, 0x41, v188
	v_cndmask_b32_e32 v62, v179, v240, vcc
	v_cmp_ge_u32_e32 vcc, v189, v191
	v_fmac_f32_e32 v241, 0x3e000000, v57
	v_add_u32_e32 v190, 0x42, v188
	v_cndmask_b32_e32 v61, v179, v241, vcc
	v_cmp_ge_u32_e32 vcc, v189, v190
	v_fmac_f32_e32 v242, 0x3e000000, v58
	v_add_u32_e32 v191, 0x43, v188
	v_cndmask_b32_e32 v63, v179, v242, vcc
	v_cmp_ge_u32_e32 vcc, v189, v191
	v_fmac_f32_e32 v243, 0x3e000000, v59
	v_add_u32_e32 v190, 0x50, v188
	v_cndmask_b32_e32 v57, v179, v243, vcc
	v_cmp_ge_u32_e32 vcc, v189, v190
	v_fmac_f32_e32 v244, 0x3e000000, v52
	v_add_u32_e32 v191, 0x51, v188
	v_cndmask_b32_e32 v59, v179, v244, vcc
	v_cmp_ge_u32_e32 vcc, v189, v191
	v_fmac_f32_e32 v245, 0x3e000000, v53
	v_add_u32_e32 v190, 0x52, v188
	v_cndmask_b32_e32 v56, v179, v245, vcc
	v_cmp_ge_u32_e32 vcc, v189, v190
	v_fmac_f32_e32 v246, 0x3e000000, v54
	v_add_u32_e32 v191, 0x53, v188
	v_cndmask_b32_e32 v58, v179, v246, vcc
	v_cmp_ge_u32_e32 vcc, v189, v191
	v_fmac_f32_e32 v247, 0x3e000000, v55
	v_add_u32_e32 v190, 0x60, v188
	v_cndmask_b32_e32 v53, v179, v247, vcc
	v_cmp_ge_u32_e32 vcc, v189, v190
	v_fmac_f32_e32 v248, 0x3e000000, v48
	v_add_u32_e32 v191, 0x61, v188
	v_cndmask_b32_e32 v55, v179, v248, vcc
	v_cmp_ge_u32_e32 vcc, v189, v191
	v_fmac_f32_e32 v249, 0x3e000000, v49
	v_add_u32_e32 v190, 0x62, v188
	v_cndmask_b32_e32 v52, v179, v249, vcc
	v_cmp_ge_u32_e32 vcc, v189, v190
	v_fmac_f32_e32 v250, 0x3e000000, v50
	v_add_u32_e32 v191, 0x63, v188
	v_cndmask_b32_e32 v54, v179, v250, vcc
	s_waitcnt lgkmcnt(0)
	v_cmp_ge_u32_e32 vcc, v189, v191
	v_fmac_f32_e32 v212, 0x3e000000, v51
	v_add_u32_e32 v190, 0x70, v188
	v_cndmask_b32_e32 v49, v179, v212, vcc
	v_cmp_ge_u32_e32 vcc, v189, v190
	v_fmac_f32_e32 v213, 0x3e000000, v44
	v_add_u32_e32 v191, 0x71, v188
	v_cndmask_b32_e32 v50, v179, v213, vcc
	v_cmp_ge_u32_e32 vcc, v189, v191
	v_fmac_f32_e32 v214, 0x3e000000, v45
	v_add_u32_e32 v190, 0x72, v188
	v_cndmask_b32_e32 v48, v179, v214, vcc
	v_cmp_ge_u32_e32 vcc, v189, v190
	v_fmac_f32_e32 v215, 0x3e000000, v46
	v_add_u32_e32 v191, 0x73, v188
	v_cndmask_b32_e32 v45, v179, v215, vcc
	v_cmp_ge_u32_e32 vcc, v189, v191
	v_fmac_f32_e32 v223, 0x3e000000, v47
	v_add_u32_e32 v190, 0x80, v188
	v_cndmask_b32_e32 v44, v179, v223, vcc
	v_cmp_ge_u32_e32 vcc, v189, v190
	v_fmac_f32_e32 v228, 0x3e000000, v40
	v_add_u32_e32 v191, 0x81, v188
	v_cndmask_b32_e32 v47, v179, v228, vcc
	v_cmp_ge_u32_e32 vcc, v189, v191
	v_fmac_f32_e32 v229, 0x3e000000, v41
	v_add_u32_e32 v190, 0x82, v188
	v_cndmask_b32_e32 v46, v179, v229, vcc
	v_cmp_ge_u32_e32 vcc, v189, v190
	v_fmac_f32_e32 v230, 0x3e000000, v42
	v_add_u32_e32 v191, 0x83, v188
	v_cndmask_b32_e32 v51, v179, v230, vcc
	v_cmp_ge_u32_e32 vcc, v189, v191
	v_fmac_f32_e32 v231, 0x3e000000, v43
	s_nop 0
	v_cndmask_b32_e32 v41, v179, v231, vcc
	s_mov_b32 s0, 0xf149f2ca
	v_max3_f32 v40, v195, s0, v91
	v_max3_f32 v40, v40, v194, v79
	v_max3_f32 v40, v40, v74, v64
	v_max3_f32 v40, v40, v75, v70
	v_max3_f32 v40, v40, v72, v71
	v_max3_f32 v40, v40, v73, v66
	v_max3_f32 v40, v40, v69, v67
	v_max3_f32 v40, v40, v68, v60
	v_max3_f32 v40, v40, v62, v61
	v_max3_f32 v40, v40, v63, v57
	v_max3_f32 v40, v40, v59, v56
	v_max3_f32 v40, v40, v58, v53
	v_max3_f32 v40, v40, v55, v52
	v_max3_f32 v40, v40, v54, v49
	v_max3_f32 v40, v40, v50, v48
	v_max3_f32 v40, v40, v45, v44
	v_max3_f32 v40, v40, v47, v46
	v_max3_f32 v40, v40, v51, v41
	ds_bpermute_b32 v42, v169, v40
	s_mov_b32 s1, 0x3fb8aa3b
	s_sub_i32 s0, 5, s52
	s_lshr_b32 s0, s47, s0
	s_waitcnt lgkmcnt(0)
	v_max_f32_e32 v42, v42, v42
	v_max_f32_e32 v40, v40, v42
	ds_bpermute_b32 v42, v170, v40
	s_waitcnt lgkmcnt(0)
	v_max_f32_e32 v42, v42, v42
	v_max_f32_e32 v42, v40, v42
	v_mul_f32_e32 v178, 0xbfb8aa3b, v42
	v_fma_f32 v40, v195, s1, v178
	v_fma_f32 v43, v91, s1, v178
	v_exp_f32_e32 v40, v40
	v_exp_f32_e32 v43, v43
	v_add_f32_e32 v76, 0, v40
	v_add_f32_e32 v77, v43, v76
	v_fma_f32 v76, v194, s1, v178
	v_exp_f32_e32 v76, v76
	v_cvt_pk_bf16_f32 v196, v40, v43
	v_add_f32_e32 v91, v76, v77
	v_fma_f32 v77, v79, s1, v178
	v_exp_f32_e32 v77, v77
	v_fma_f32 v74, v74, s1, v178
	v_exp_f32_e32 v74, v74
	v_add_f32_e32 v79, v77, v91
	v_cvt_pk_bf16_f32 v197, v76, v77
	v_fma_f32 v64, v64, s1, v178
	v_exp_f32_e32 v64, v64
	v_add_f32_e32 v91, v74, v79
	v_mov_b32_e32 v79, v64
	v_fma_f32 v75, v75, s1, v178
	v_exp_f32_e32 v75, v75
	v_add_f32_e32 v64, v79, v91
	v_cvt_pk_bf16_f32 v198, v74, v79
	v_fma_f32 v70, v70, s1, v178
	v_exp_f32_e32 v70, v70
	v_add_f32_e32 v64, v75, v64
	v_mov_b32_e32 v91, v70
	v_add_f32_e32 v70, v91, v64
	v_fma_f32 v64, v72, s1, v178
	v_exp_f32_e32 v64, v64
	v_cvt_pk_bf16_f32 v199, v75, v91
	ds_read_b64_tr_b16 v[76:77], v171 offset:57600
	ds_read_b64_tr_b16 v[74:75], v171 offset:55296
	ds_read_b64_tr_b16 v[200:201], v171 offset:55328
	v_add_f32_e32 v72, v64, v70
	v_fma_f32 v70, v71, s1, v178
	v_fma_f32 v71, v73, s1, v178
	v_exp_f32_e32 v70, v70
	v_exp_f32_e32 v71, v71
	ds_read_b64_tr_b16 v[202:203], v171 offset:57632
	v_add_f32_e32 v72, v70, v72
	ds_read_b64_tr_b16 v[204:205], v171 offset:55360
	ds_read_b64_tr_b16 v[206:207], v171 offset:57664
	v_fma_f32 v66, v66, s1, v178
	v_exp_f32_e32 v66, v66
	v_add_f32_e32 v72, v71, v72
	ds_read_b64_tr_b16 v[208:209], v171 offset:55392
	ds_read_b64_tr_b16 v[210:211], v171 offset:57696
	s_waitcnt lgkmcnt(6)
; __device__ __forceinline__ unsigned cvt_pk_bf16(float lo, float hi) { f32x2_t v = {lo, hi}; bf2_t r = __builtin_convertvector(v, bf2_t); return __builtin_bit_cast(unsigned, r); }
; __device__ __forceinline__ s16x4_t lds_tr_b64(const bf16_t* p) { return __builtin_amdgcn_ds_read_tr16_b64_v4i16((LAS s16x4_t*)p); }
; __device__ __forceinline__ void attn_item(const Ctx& C, int it, int itn, u32x4 (&kv)[4], u32x4 (&vv)[4], u32x4 (&qv)[2]) {
;     ...
;     float lsum = 0.f;
; #pragma unroll
;     for (int kt = 0; kt < 9; ++kt)
; #pragma unroll
;         for (int rg = 0; rg < 4; ++rg) { const float s = sc[kt][rg]; const float p = (s > -1e29f) ? __expf(s - mx) : 0.f; sc[kt][rg] = p; lsum += p; }
;     lsum += __shfl_xor(lsum, 16); lsum += __shfl_xor(lsum, 32);
;     f32x4 oo[4];
; #pragma unroll
;     for (int dt = 0; dt < 4; ++dt) oo[dt] = (f32x4){0.f, 0.f, 0.f, 0.f};
; #pragma unroll
;     for (int pp = 0; pp < 5; ++pp) { const int ktA = 2 * pp, ktB = 2 * pp + 1, ktBc = ktB < 9 ? ktB : 8;
;         union { bf16x8 v; unsigned u[4]; } pf;
;         pf.u[0] = cvt_pk_bf16(sc[ktA][0], sc[ktA][1]); pf.u[1] = cvt_pk_bf16(sc[ktA][2], sc[ktA][3]);
;         if (ktB < 9) { pf.u[2] = cvt_pk_bf16(sc[ktBc][0], sc[ktBc][1]); pf.u[3] = cvt_pk_bf16(sc[ktBc][2], sc[ktBc][3]); } else { pf.u[2] = 0u; pf.u[3] = 0u; }
; #pragma unroll
;         for (int dt = 0; dt < 4; ++dt) { const bf16_t* vr = Vs + (16 * w + 4 * quad + (fr >> 2)) * 72 + 16 * dt + 4 * (fr & 3);
;             union { bf16x8 v; s16x4_t h[2]; } vf; vf.h[0] = lds_tr_b64(vr + 16 * ktA * 72); vf.h[1] = lds_tr_b64(vr + 16 * ktBc * 72);
;             oo[dt] = __builtin_amdgcn_mfma_f32_16x16x32_bf16(vf.v, pf.v, oo[dt], 0, 0, 0); } }
;     const float inv = 1.0f / lsum;
	v_mfma_f32_16x16x32_bf16 v[74:77], v[74:77], v[196:199], 0
	v_fma_f32 v69, v69, s1, v178
	v_exp_f32_e32 v69, v69
	v_add_f32_e32 v72, v66, v72
	s_waitcnt lgkmcnt(4)
	v_mfma_f32_16x16x32_bf16 v[200:203], v[200:203], v[196:199], 0
	v_mov_b32_e32 v91, v65
	v_fma_f32 v67, v67, s1, v178
	v_exp_f32_e32 v67, v67
	v_add_f32_e32 v72, v69, v72
	s_waitcnt lgkmcnt(2)
	v_mfma_f32_16x16x32_bf16 v[204:207], v[204:207], v[196:199], 0
	v_fma_f32 v68, v68, s1, v178
	v_exp_f32_e32 v68, v68
	v_add_f32_e32 v72, v67, v72
	s_waitcnt lgkmcnt(0)
	v_mfma_f32_16x16x32_bf16 v[196:199], v[208:211], v[196:199], 0
	v_cvt_pk_bf16_f32 v209, v71, v66
	v_fma_f32 v60, v60, s1, v178
	v_exp_f32_e32 v60, v60
	v_add_f32_e32 v73, v68, v72
	v_cvt_pk_bf16_f32 v210, v69, v67
	v_cvt_pk_bf16_f32 v208, v64, v70
	v_mov_b32_e32 v72, v60
	v_fma_f32 v60, v62, s1, v178
	v_exp_f32_e32 v60, v60
	v_add_f32_e32 v73, v72, v73
	v_cvt_pk_bf16_f32 v211, v68, v72
	v_fma_f32 v61, v61, s1, v178
	v_exp_f32_e32 v61, v61
	v_add_f32_e32 v62, v60, v73
	ds_read_b64_tr_b16 v[66:67], v171 offset:59904
	ds_read_b64_tr_b16 v[68:69], v171 offset:62208
	s_waitcnt lgkmcnt(0)
	v_mfma_f32_16x16x32_bf16 v[66:69], v[66:69], v[208:211], v[74:77]
	v_add_f32_e32 v73, v61, v62
	v_fma_f32 v62, v63, s1, v178
	v_exp_f32_e32 v62, v62
	ds_read_b64_tr_b16 v[74:75], v171 offset:59936
	ds_read_b64_tr_b16 v[76:77], v171 offset:62240
	s_waitcnt lgkmcnt(0)
	v_mfma_f32_16x16x32_bf16 v[74:77], v[74:77], v[208:211], v[200:203]
	v_fma_f32 v57, v57, s1, v178
	v_exp_f32_e32 v57, v57
	v_add_f32_e32 v63, v62, v73
	ds_read_b64_tr_b16 v[200:201], v171 offset:59968
	ds_read_b64_tr_b16 v[202:203], v171 offset:62272
	s_waitcnt lgkmcnt(0)
	v_mfma_f32_16x16x32_bf16 v[200:203], v[200:203], v[208:211], v[204:207]
	v_fma_f32 v59, v59, s1, v178
	v_exp_f32_e32 v59, v59
	v_add_f32_e32 v63, v57, v63
	ds_read_b64_tr_b16 v[204:205], v171 offset:60000
	ds_read_b64_tr_b16 v[206:207], v171 offset:62304
	v_cvt_pk_bf16_f32 v60, v60, v61
	v_fma_f32 v56, v56, s1, v178
	v_exp_f32_e32 v56, v56
	v_add_f32_e32 v63, v59, v63
	v_cvt_pk_bf16_f32 v61, v62, v57
	s_waitcnt lgkmcnt(0)
	v_mfma_f32_16x16x32_bf16 v[196:199], v[204:207], v[208:211], v[196:199]
	v_fma_f32 v58, v58, s1, v178
	v_exp_f32_e32 v58, v58
	v_add_f32_e32 v63, v56, v63
	v_cvt_pk_bf16_f32 v62, v59, v56
	v_mov_b32_e32 v64, v65
	v_fma_f32 v53, v53, s1, v178
	v_exp_f32_e32 v53, v53
	v_add_f32_e32 v73, v58, v63
	v_mov_b32_e32 v63, v53
	v_fma_f32 v53, v55, s1, v178
	v_exp_f32_e32 v53, v53
	v_add_f32_e32 v73, v63, v73
	v_cvt_pk_bf16_f32 v63, v58, v63
	v_fma_f32 v52, v52, s1, v178
	v_exp_f32_e32 v52, v52
	ds_read_b64_tr_b16 v[56:57], v171 offset:64512
	ds_read_b64_tr_b16 v[58:59], v172 offset:11520
	ds_read_b64_tr_b16 v[70:71], v172 offset:11552
	v_add_f32_e32 v55, v53, v73
	s_waitcnt lgkmcnt(1)
	v_mfma_f32_16x16x32_bf16 v[56:59], v[56:59], v[60:63], v[66:69]
	v_fma_f32 v54, v54, s1, v178
	v_exp_f32_e32 v54, v54
	v_add_f32_e32 v55, v52, v55
	ds_read_b64_tr_b16 v[68:69], v171 offset:64544
	s_waitcnt lgkmcnt(0)
	v_mfma_f32_16x16x32_bf16 v[66:69], v[68:71], v[60:63], v[74:77]
	v_fma_f32 v49, v49, s1, v178
	v_exp_f32_e32 v49, v49
	v_add_f32_e32 v55, v54, v55
	ds_read_b64_tr_b16 v[74:75], v171 offset:64576
	ds_read_b64_tr_b16 v[76:77], v172 offset:11584
	s_waitcnt lgkmcnt(0)
	v_mfma_f32_16x16x32_bf16 v[74:77], v[74:77], v[60:63], v[200:203]
	v_fma_f32 v50, v50, s1, v178
	v_exp_f32_e32 v50, v50
	v_add_f32_e32 v55, v49, v55
	ds_read_b64_tr_b16 v[200:201], v171 offset:64608
	ds_read_b64_tr_b16 v[202:203], v172 offset:11616
	v_cvt_pk_bf16_f32 v52, v53, v52
	v_fma_f32 v48, v48, s1, v178
	v_exp_f32_e32 v48, v48
	v_add_f32_e32 v73, v50, v55
	v_cvt_pk_bf16_f32 v53, v54, v49
	s_waitcnt lgkmcnt(0)
	v_mfma_f32_16x16x32_bf16 v[60:63], v[200:203], v[60:63], v[196:199]
	v_mov_b32_e32 v55, v48
	v_fma_f32 v45, v45, s1, v178
	v_exp_f32_e32 v45, v45
	v_add_f32_e32 v48, v55, v73
	v_cvt_pk_bf16_f32 v54, v50, v55
	v_mov_b32_e32 v73, v45
	v_fma_f32 v44, v44, s1, v178
	v_exp_f32_e32 v44, v44
	v_add_f32_e32 v45, v73, v48
	v_mov_b32_e32 v194, v44
	v_add_f32_e32 v44, v194, v45
	v_fma_f32 v45, v47, s1, v178
	v_cvt_pk_bf16_f32 v55, v73, v194
	ds_read_b64_tr_b16 v[70:71], v172 offset:13824
	ds_read_b64_tr_b16 v[72:73], v172 offset:16128
	v_exp_f32_e32 v45, v45
	s_waitcnt lgkmcnt(0)
	v_mfma_f32_16x16x32_bf16 v[56:59], v[70:73], v[52:55], v[56:59]
	ds_read_b64_tr_b16 v[70:71], v172 offset:13856
	ds_read_b64_tr_b16 v[72:73], v172 offset:16160
	v_fma_f32 v46, v46, s1, v178
	v_fma_f32 v47, v51, s1, v178
	v_exp_f32_e32 v46, v46
	v_exp_f32_e32 v47, v47
	s_waitcnt lgkmcnt(0)
	v_mfma_f32_16x16x32_bf16 v[66:69], v[70:73], v[52:55], v[66:69]
	ds_read_b64_tr_b16 v[70:71], v172 offset:13888
	ds_read_b64_tr_b16 v[72:73], v172 offset:16192
	s_waitcnt lgkmcnt(0)
	v_mfma_f32_16x16x32_bf16 v[70:73], v[70:73], v[52:55], v[74:77]
	v_fma_f32 v41, v41, s1, v178
	v_exp_f32_e32 v41, v41
	ds_read_b64_tr_b16 v[74:75], v172 offset:13920
	ds_read_b64_tr_b16 v[76:77], v172 offset:16224
	v_add_f32_e32 v44, v45, v44
	v_add_f32_e32 v44, v46, v44
	v_mov_b32_e32 v48, v41
	v_add_f32_e32 v44, v47, v44
	s_waitcnt lgkmcnt(0)
	v_mfma_f32_16x16x32_bf16 v[50:53], v[74:77], v[52:55], v[60:63]
	v_add_f32_e32 v41, v48, v44
	ds_bpermute_b32 v44, v169, v41
	ds_read_b64_tr_b16 v[54:55], v172 offset:18464
	v_cvt_pk_bf16_f32 v62, v45, v46
	v_cvt_pk_bf16_f32 v63, v47, v48
	ds_read_b64_tr_b16 v[46:47], v172 offset:18432
	s_waitcnt lgkmcnt(2)
	v_add_f32_e32 v41, v41, v44
	ds_bpermute_b32 v44, v170, v41
	s_lshl_b32 s1, s51, 12
	s_or_b32 s0, s0, s1
	s_waitcnt lgkmcnt(1)
	v_mov_b32_e32 v48, v46
	v_mov_b32_e32 v49, v47
	s_waitcnt lgkmcnt(0)
	v_add_f32_e32 v41, v41, v44
	v_div_scale_f32 v40, s[48:49], v41, v41, 1.0
	v_mfma_f32_16x16x32_bf16 v[46:49], v[46:49], v[62:65], v[56:59]
	v_rcp_f32_e32 v43, v40
	s_nop 1
	v_mov_b32_e32 v56, v54
	v_mov_b32_e32 v57, v55
	ds_read_b64_tr_b16 v[58:59], v172 offset:18496
	v_fma_f32 v44, -v40, v43, 1.0
	v_mfma_f32_16x16x32_bf16 v[54:57], v[54:57], v[62:65], v[66:69]
	v_fmac_f32_e32 v43, v44, v43
	ds_read_b64_tr_b16 v[66:67], v172 offset:18528
	s_waitcnt lgkmcnt(1)
	v_mov_b32_e32 v60, v58
	v_mov_b32_e32 v61, v59
	v_div_scale_f32 v44, vcc, 1.0, v41, 1.0
	s_waitcnt lgkmcnt(0)
	v_mov_b32_e32 v68, v66
	v_mov_b32_e32 v69, v67
	v_mul_f32_e32 v45, v44, v43
	v_mfma_f32_16x16x32_bf16 v[58:61], v[58:61], v[62:65], v[70:73]
	s_barrier
; __device__ __forceinline__ unsigned cvt_pk_bf16(float lo, float hi) { f32x2_t v = {lo, hi}; bf2_t r = __builtin_convertvector(v, bf2_t); return __builtin_bit_cast(unsigned, r); }
;     __device__ __forceinline__ float* fp(size_t off) const { return (float*)(ws + off); }
; __device__ __forceinline__ void attn_item(const Ctx& C, int it, int itn, u32x4 (&kv)[4], u32x4 (&vv)[4], u32x4 (&qv)[2]) {
;     ...
;     const float inv = 1.0f / lsum;
;     const size_t tok = (size_t)(b * SEQ + r + dil * (128 * jb + a));
;     __syncthreads();
; #pragma unroll
;     for (int dt = 0; dt < 4; ++dt) { u32x2 o; o.x = cvt_pk_bf16(oo[dt][0] * inv, oo[dt][1] * inv); o.y = cvt_pk_bf16(oo[dt][2] * inv, oo[dt][3] * inv);
;         *(u32x2*)(pd + tok * 2304 + hq * 64 + 16 * dt + 4 * quad) = o; }
;     if (quad == 0) C.fp(OFF_LSE)[((size_t)g * M_TOK + tok) * 4 + (hq & 3)] = mx + __logf(lsum);
	v_mfma_f32_16x16x32_bf16 v[50:53], v[66:69], v[62:65], v[50:53]
	v_fma_f32 v62, -v40, v45, v44
	v_fmac_f32_e32 v45, v62, v43
	v_fma_f32 v40, -v40, v45, v44
	v_div_fmas_f32 v40, v40, v43, v45
	v_div_fixup_f32 v44, v40, v41, 1.0
	v_add_u32_e32 v40, s46, v83
	v_lshlrev_b32_e32 v40, s52, v40
	v_add_u32_e32 v40, s0, v40
	v_mov_b64_e32 v[62:63], s[42:43]
	v_mad_i64_i32 v[62:63], s[0:1], v40, s66, v[62:63]
	s_lshl_b32 s0, s41, 6
	s_ashr_i32 s1, s0, 31
	v_lshl_add_u64 v[62:63], s[0:1], 1, v[62:63]
	v_pk_mul_f32 v[46:47], v[44:45], v[46:47] op_sel_hi:[0,1]
	v_pk_mul_f32 v[48:49], v[44:45], v[48:49] op_sel_hi:[0,1]
	v_lshl_add_u64 v[62:63], v[62:63], 0, v[90:91]
	v_cvt_pk_bf16_f32 v46, v46, v47
	v_cvt_pk_bf16_f32 v47, v48, v49
	global_store_dwordx2 v[62:63], v[46:47], off
	v_pk_mul_f32 v[46:47], v[44:45], v[54:55] op_sel_hi:[0,1]
	v_pk_mul_f32 v[48:49], v[44:45], v[56:57] op_sel_hi:[0,1]
	v_cvt_pk_bf16_f32 v46, v46, v47
	v_cvt_pk_bf16_f32 v47, v48, v49
	global_store_dwordx2 v[62:63], v[46:47], off offset:32
	v_pk_mul_f32 v[46:47], v[44:45], v[58:59] op_sel_hi:[0,1]
	v_pk_mul_f32 v[48:49], v[44:45], v[60:61] op_sel_hi:[0,1]
	v_cvt_pk_bf16_f32 v46, v46, v47
	v_cvt_pk_bf16_f32 v47, v48, v49
	global_store_dwordx2 v[62:63], v[46:47], off offset:64
	v_pk_mul_f32 v[46:47], v[44:45], v[50:51] op_sel_hi:[0,1]
	v_pk_mul_f32 v[44:45], v[44:45], v[52:53] op_sel_hi:[0,1]
	v_cvt_pk_bf16_f32 v46, v46, v47
	v_cvt_pk_bf16_f32 v47, v44, v45
	global_store_dwordx2 v[62:63], v[46:47], off offset:96
	s_and_saveexec_b64 s[0:1], s[20:21]
	s_cbranch_execz .LBB0_344
	v_cmp_gt_f32_e32 vcc, s54, v41
	s_ashr_i32 s41, s40, 31
	s_lshl_b64 s[40:41], s[40:41], 19
	v_cndmask_b32_e64 v43, 0, 32, vcc
	v_ldexp_f32 v41, v41, v43
	v_log_f32_e32 v43, v41
	v_readlane_b32 s46, v255, 43
	v_cndmask_b32_e32 v44, 0, v225, vcc
	s_add_u32 s40, s46, s40
	v_mul_f32_e32 v45, 0x3f317217, v43
	v_fma_f32 v45, v43, s56, -v45
	v_fmac_f32_e32 v45, 0x3377d1cf, v43
	v_fmac_f32_e32 v45, 0x3f317217, v43
	v_cmp_lt_f32_e64 vcc, |v43|, s57
	v_readlane_b32 s46, v255, 44
	v_ashrrev_i32_e32 v41, 31, v40
	v_cndmask_b32_e32 v43, v43, v45, vcc
	s_addc_u32 s41, s46, s41
	s_lshr_b32 s36, s36, 3
	v_sub_f32_e32 v43, v43, v44
	v_lshl_add_u64 v[40:41], v[40:41], 4, s[40:41]
	s_and_b32 s36, s36, 12
	v_add_f32_e32 v42, v42, v43
	v_lshl_add_u64 v[40:41], v[40:41], 0, s[36:37]
	global_store_dword v[40:41], v42, off
	s_branch .LBB0_344

; __device__ __forceinline__ float hgrn_lb(const Ctx& C, int l, int ch) {
;     if (l == 0) return 0.f;
;     const float a0 = C.P->in[3][ch], a1 = C.P->in[3][256 + ch];
;     return 1.0f / (1.0f + __expf(a0 - a1));
; }
.LBB0_470:
	s_lshl_b32 s0, s18, 1
	s_and_b32 s4, s0, 0xc0
	v_readlane_b32 s0, v255, 1
	v_readlane_b32 s1, v255, 2
	v_or_b32_e32 v2, s4, v64
	s_and_b64 vcc, exec, s[0:1]
	s_cbranch_vccz .LBB0_472
	v_readlane_b32 s68, v251, 4
	v_lshlrev_b32_e32 v0, 2, v2
	v_readlane_b32 s74, v251, 10
	v_readlane_b32 s75, v251, 11
	s_nop 4
	global_load_dword v1, v0, s[74:75]
	global_load_dword v0, v0, s[74:75] offset:1024
	v_readlane_b32 s69, v251, 5
	v_readlane_b32 s70, v251, 6
	v_readlane_b32 s71, v251, 7
	v_readlane_b32 s72, v251, 8
	v_readlane_b32 s73, v251, 9
	v_readlane_b32 s76, v251, 12
	v_readlane_b32 s77, v251, 13
	v_readlane_b32 s78, v251, 14
	v_readlane_b32 s79, v251, 15
	v_readlane_b32 s80, v251, 16
	v_readlane_b32 s81, v251, 17
	v_readlane_b32 s82, v251, 18
	v_readlane_b32 s83, v251, 19
	v_readlane_b32 s22, v253, 26
	s_waitcnt vmcnt(0)
	v_sub_f32_e32 v0, v1, v0
	v_mul_f32_e32 v0, 0x3fb8aa3b, v0
	v_exp_f32_e32 v0, v0
	s_nop 0
	v_add_f32_e32 v0, 1.0, v0
	v_rcp_f32_e32 v130, v0
	s_cbranch_execz .LBB0_473
	s_branch .LBB0_474

; __device__ __forceinline__ bf16_t f2bf(float f) { return (bf16_t)(cvt_pk_bf16(f, 0.f) & 0xffffu); }
; __device__ __forceinline__ float bf2f(bf16_t b) { return __uint_as_float(((unsigned)b) << 16); }
; __device__ __forceinline__ float sigmoidf_(float x) { return 1.0f / (1.0f + __expf(-x)); }
; template <int MODE>
; __device__ __forceinline__ void hgrn_mfma(const Ctx& C, int l, int z, int b, int hd, int c, f32x4 (&Sacc)[4][4], float& dectot, unsigned char* wl, float lb) {
;     ...
;             bf16_t fv[16], qv[16], vv[16];
;             const int st0 = c * 128 + sc * 32 + g8 * 16; const int tq0 = z ? 4095 - st0 : st0;
;             const bf16_t* row0 = pa + (size_t)(b * SEQ + tq0) * 1280; const ptrdiff_t rstep = z ? -1280 : 1280;
; #pragma unroll
;             for (int t = 0; t < 16; ++t) { const bf16_t* row = row0 + rstep * t; fv[t] = row[fcol]; vv[t] = row[vcol]; if (MODE != 0) qv[t] = row[qcol]; }
; #pragma unroll
;             for (int t = 0; t < 16; ++t) {
;                 const float fl = bf2f(fv[t]);
;                 const float sg = sigmoidf_(fl);
;                 const float f = lb + (1.0f - lb) * sg, kk = (1.0f - lb) * (1.0f - sg);
;                 bacc += __logf(fmaxf(f, 1e-30f));
;                 Kb[(g8 * 16 + t) * HPT + lane] = f2bf(kk * __expf(fminf(-bacc, 80.f)));
;                 if (MODE != 0) Qt[(g8 * 16 + t) * HPT + lane] = f2bf(bf2f(qv[t]) * __expf(fmaxf(bacc, -80.f)));
;                 Vv[(g8 * 16 + t) * HPT + lane] = vv[t];
;             }
.LBB0_476:
	s_lshl_b32 s0, s70, 4
	s_or_b32 s6, s0, s67
	v_cndmask_b32_e64 v67, 0, 1, s[44:45]
	s_mul_i32 s1, s70, 0x480
	s_sub_i32 s7, 0xfff, s6
	v_cmp_ne_u32_e64 s[4:5], 1, v67
	v_or_b32_e32 v67, s1, v64
	s_and_b64 s[0:1], s[38:39], exec
	s_cselect_b32 s0, s6, s7
	s_add_i32 s0, s0, s68
	s_mul_i32 s36, s0, 0x500
	s_lshl_b64 s[0:1], s[36:37], 1
	s_add_u32 s0, s47, s0
	s_addc_u32 s1, s48, s1
	global_load_ushort v68, v132, s[0:1]
	global_load_ushort v69, v133, s[0:1] offset:1536
	s_add_u32 s0, s0, s42
	s_addc_u32 s1, s1, s43
	global_load_ushort v70, v132, s[0:1]
	global_load_ushort v71, v133, s[0:1] offset:1536
	s_add_u32 s0, s0, s42
	s_addc_u32 s1, s1, s43
	global_load_ushort v72, v132, s[0:1]
	global_load_ushort v73, v133, s[0:1] offset:1536
	s_add_u32 s0, s0, s42
	s_addc_u32 s1, s1, s43
	global_load_ushort v74, v132, s[0:1]
	global_load_ushort v75, v133, s[0:1] offset:1536
	s_add_u32 s0, s0, s42
	s_addc_u32 s1, s1, s43
	global_load_ushort v76, v132, s[0:1]
	global_load_ushort v77, v133, s[0:1] offset:1536
	s_add_u32 s0, s0, s42
	s_addc_u32 s1, s1, s43
	global_load_ushort v78, v132, s[0:1]
	global_load_ushort v79, v133, s[0:1] offset:1536
	s_add_u32 s0, s0, s42
	s_addc_u32 s1, s1, s43
	s_add_u32 s6, s0, s42
	s_addc_u32 s7, s1, s43
	global_load_ushort v80, v133, s[0:1] offset:1536
	global_load_ushort v81, v132, s[0:1]
	global_load_ushort v134, v133, s[6:7] offset:1536
	global_load_ushort v135, v132, s[6:7]
	s_add_u32 s0, s6, s42
	s_addc_u32 s1, s7, s43
	s_add_u32 s6, s0, s42
	global_load_ushort v136, v133, s[0:1] offset:1536
	global_load_ushort v137, v132, s[0:1]
	s_addc_u32 s7, s1, s43
	global_load_ushort v138, v133, s[6:7] offset:1536
	global_load_ushort v139, v132, s[6:7]
	s_add_u32 s0, s6, s42
	s_addc_u32 s1, s7, s43
	global_load_ushort v140, v133, s[0:1] offset:1536
	global_load_ushort v141, v132, s[0:1]
	s_add_u32 s6, s0, s42
	s_addc_u32 s7, s1, s43
	s_add_u32 s0, s6, s42
	global_load_ushort v142, v133, s[6:7] offset:1536
	global_load_ushort v143, v132, s[6:7]
	s_addc_u32 s1, s7, s43
	global_load_ushort v144, v133, s[0:1] offset:1536
	global_load_ushort v145, v132, s[0:1]
	s_add_u32 s6, s0, s42
	s_addc_u32 s7, s1, s43
	global_load_ushort v146, v133, s[6:7] offset:1536
	global_load_ushort v147, v132, s[6:7]
	s_add_u32 s0, s6, s42
	s_addc_u32 s1, s7, s43
	global_load_ushort v148, v133, s[0:1] offset:1536
	global_load_ushort v149, v132, s[0:1]
	s_add_u32 s6, s0, s42
	s_addc_u32 s7, s1, s43
	global_load_ushort v150, v133, s[6:7] offset:1536
	global_load_ushort v151, v132, s[6:7]
	v_lshl_add_u32 v67, v67, 1, s46
	s_mov_b64 s[44:45], 0
	s_mov_b32 s70, 1
	s_waitcnt vmcnt(31)
	v_lshlrev_b32_e32 v68, 16, v68
	v_mul_f32_e32 v68, 0xbfb8aa3b, v68
	v_exp_f32_e32 v68, v68
	s_waitcnt vmcnt(30)
	ds_write_b16 v67, v69 offset:9216
	s_waitcnt vmcnt(29)
	v_lshlrev_b32_e32 v69, 16, v70
	v_mul_f32_e32 v69, 0xbfb8aa3b, v69
	v_exp_f32_e32 v69, v69
	s_waitcnt vmcnt(27)
	v_lshlrev_b32_e32 v70, 16, v72
	v_mul_f32_e32 v70, 0xbfb8aa3b, v70
	v_add_f32_e32 v68, 1.0, v68
	ds_write_b16 v67, v71 offset:9360
	v_exp_f32_e32 v70, v70
	s_waitcnt vmcnt(25)
	v_lshlrev_b32_e32 v71, 16, v74
	v_mul_f32_e32 v71, 0xbfb8aa3b, v71
	v_add_f32_e32 v69, 1.0, v69
	v_exp_f32_e32 v71, v71
	s_waitcnt vmcnt(24)
	ds_write_b16 v67, v75 offset:9648
	s_waitcnt vmcnt(23)
	v_lshlrev_b32_e32 v75, 16, v76
	v_mul_f32_e32 v75, 0xbfb8aa3b, v75
	v_add_f32_e32 v70, 1.0, v70
	s_waitcnt vmcnt(21)
	v_lshlrev_b32_e32 v78, 16, v78
	v_exp_f32_e32 v75, v75
	s_waitcnt vmcnt(20)
	ds_write_b16 v67, v79 offset:9936
	v_mul_f32_e32 v78, 0xbfb8aa3b, v78
	ds_write_b16 v67, v73 offset:9504
	v_add_f32_e32 v71, 1.0, v71
	v_exp_f32_e32 v78, v78
	s_waitcnt vmcnt(19)
	ds_write_b16 v67, v80 offset:10080
	s_waitcnt vmcnt(16)
	v_lshlrev_b32_e32 v135, 16, v135
	ds_write_b16 v67, v134 offset:10224
	v_mul_f32_e32 v135, 0xbfb8aa3b, v135
	ds_write_b16 v67, v77 offset:9792
	v_lshlrev_b32_e32 v81, 16, v81
	v_add_f32_e32 v75, 1.0, v75
	v_exp_f32_e32 v135, v135
	v_mul_f32_e32 v81, 0xbfb8aa3b, v81
	v_add_f32_e32 v78, 1.0, v78
	s_waitcnt vmcnt(14)
	v_lshlrev_b32_e32 v137, 16, v137
	v_exp_f32_e32 v81, v81
	ds_write_b16 v67, v136 offset:10368
	v_mul_f32_e32 v137, 0xbfb8aa3b, v137
	v_exp_f32_e32 v137, v137
	s_waitcnt vmcnt(12)
	v_lshlrev_b32_e32 v139, 16, v139
	v_rcp_f32_e32 v68, v68
	v_mul_f32_e32 v74, 0xbfb8aa3b, v139
	v_fma_f32 v139, v131, v68, v130
	v_sub_f32_e32 v68, 1.0, v68
	v_add_f32_e32 v135, 1.0, v135
	v_mul_f32_e32 v76, v131, v68
	v_max_f32_e32 v68, 0xda24260, v139
	v_add_f32_e32 v81, 1.0, v81
	v_exp_f32_e32 v163, v74
	s_waitcnt vmcnt(10)
	v_lshlrev_b32_e32 v74, 16, v141
	v_rcp_f32_e32 v69, v69
	v_cmp_gt_f32_e64 s[0:1], s54, v68
	v_mul_f32_e32 v74, 0xbfb8aa3b, v74
	s_nop 0
	v_cndmask_b32_e64 v141, 0, 32, s[0:1]
	v_fma_f32 v152, v131, v69, v130
	v_sub_f32_e32 v69, 1.0, v69
	v_add_f32_e32 v137, 1.0, v137
	v_exp_f32_e32 v155, v74
	v_ldexp_f32 v68, v68, v141
	v_cndmask_b32_e64 v141, 0, v225, s[0:1]
	v_mul_f32_e32 v74, v131, v69
	v_max_f32_e32 v69, 0xda24260, v152
	v_rcp_f32_e32 v70, v70
	v_cmp_gt_f32_e64 s[0:1], s54, v69
	s_waitcnt vmcnt(8)
	v_lshlrev_b32_e32 v143, 16, v143
	v_log_f32_e32 v152, v68
	v_cndmask_b32_e64 v68, 0, 32, s[0:1]
	v_fma_f32 v154, v131, v70, v130
	v_add_f32_e32 v163, 1.0, v163
	v_mul_f32_e32 v143, 0xbfb8aa3b, v143
	v_sub_f32_e32 v70, 1.0, v70
	s_waitcnt vmcnt(7)
	ds_write_b16 v67, v144 offset:10944
	v_ldexp_f32 v68, v69, v68
	v_cndmask_b32_e64 v144, 0, v225, s[0:1]
	v_max_f32_e32 v69, 0xda24260, v154
	v_exp_f32_e32 v143, v143
	v_mul_f32_e32 v72, v131, v70
	v_rcp_f32_e32 v70, v71
	v_cmp_gt_f32_e64 s[0:1], s54, v69
	ds_write_b16 v67, v138 offset:10512
	s_waitcnt vmcnt(6)
; __device__ __forceinline__ bf16_t f2bf(float f) { return (bf16_t)(cvt_pk_bf16(f, 0.f) & 0xffffu); }
; __device__ __forceinline__ float bf2f(bf16_t b) { return __uint_as_float(((unsigned)b) << 16); }
; __device__ __forceinline__ float sigmoidf_(float x) { return 1.0f / (1.0f + __expf(-x)); }
; template <int MODE>
; __device__ __forceinline__ void hgrn_mfma(const Ctx& C, int l, int z, int b, int hd, int c, f32x4 (&Sacc)[4][4], float& dectot, unsigned char* wl, float lb) {
;     ...
;             for (int t = 0; t < 16; ++t) {
;                 const float fl = bf2f(fv[t]);
;                 const float sg = sigmoidf_(fl);
;                 const float f = lb + (1.0f - lb) * sg, kk = (1.0f - lb) * (1.0f - sg);
;                 bacc += __logf(fmaxf(f, 1e-30f));
;                 Kb[(g8 * 16 + t) * HPT + lane] = f2bf(kk * __expf(fminf(-bacc, 80.f)));
;                 if (MODE != 0) Qt[(g8 * 16 + t) * HPT + lane] = f2bf(bf2f(qv[t]) * __expf(fmaxf(bacc, -80.f)));
;                 Vv[(g8 * 16 + t) * HPT + lane] = vv[t];
	v_lshlrev_b32_e32 v145, 16, v145
	v_log_f32_e32 v158, v68
	v_cndmask_b32_e64 v68, 0, 32, s[0:1]
	v_fma_f32 v159, v131, v70, v130
	v_sub_f32_e32 v70, 1.0, v70
	v_add_f32_e32 v155, 1.0, v155
	v_mul_f32_e32 v145, 0xbfb8aa3b, v145
	s_waitcnt vmcnt(5)
	ds_write_b16 v67, v146 offset:11088
	v_ldexp_f32 v68, v69, v68
	v_cndmask_b32_e64 v146, 0, v225, s[0:1]
	v_mul_f32_e32 v71, v131, v70
	v_max_f32_e32 v69, 0xda24260, v159
	v_rcp_f32_e32 v70, v75
	v_exp_f32_e32 v145, v145
	s_waitcnt vmcnt(4)
	v_lshlrev_b32_e32 v147, 16, v147
	v_cmp_gt_f32_e64 s[0:1], s54, v69
	ds_write_b16 v67, v140 offset:10656
	v_mul_f32_e32 v147, 0xbfb8aa3b, v147
	v_mul_f32_e32 v160, 0x3f317217, v152
	v_log_f32_e32 v161, v68
	v_cndmask_b32_e64 v68, 0, 32, s[0:1]
	v_fma_f32 v166, v131, v70, v130
	v_sub_f32_e32 v70, 1.0, v70
	v_add_f32_e32 v143, 1.0, v143
	v_exp_f32_e32 v147, v147
	s_waitcnt vmcnt(3)
	ds_write_b16 v67, v148 offset:11232
	v_fma_f32 v148, v152, s56, -v160
	v_ldexp_f32 v68, v69, v68
	v_cndmask_b32_e64 v160, 0, v225, s[0:1]
	v_mul_f32_e32 v69, v131, v70
	v_max_f32_e32 v70, 0xda24260, v166
	ds_write_b16 v67, v142 offset:10800
	s_waitcnt vmcnt(2)
	v_lshlrev_b32_e32 v149, 16, v149
	v_rcp_f32_e32 v73, v78
	v_cmp_gt_f32_e64 s[0:1], s54, v70
	v_mul_f32_e32 v80, 0xbfb8aa3b, v149
	v_fmac_f32_e32 v148, 0x3377d1cf, v152
	v_mul_f32_e32 v149, 0x3f317217, v158
	v_log_f32_e32 v167, v68
	v_cndmask_b32_e64 v68, 0, 32, s[0:1]
	v_fma_f32 v168, v131, v73, v130
	v_sub_f32_e32 v73, 1.0, v73
	v_add_f32_e32 v78, 1.0, v145
	v_exp_f32_e32 v80, v80
	s_waitcnt vmcnt(1)
	ds_write_b16 v67, v150 offset:11376
	v_fmac_f32_e32 v148, 0x3f317217, v152
	v_fma_f32 v149, v158, s56, -v149
	v_ldexp_f32 v70, v70, v68
	v_cndmask_b32_e64 v150, 0, v225, s[0:1]
	v_mul_f32_e32 v68, v131, v73
	v_max_f32_e32 v73, 0xda24260, v168
	v_rcp_f32_e32 v77, v81
	v_cmp_lt_f32_e64 vcc, |v152|, s57
	s_waitcnt vmcnt(0)
	v_lshlrev_b32_e32 v145, 16, v151
	v_cndmask_b32_e32 v148, v152, v148, vcc
	v_fmac_f32_e32 v149, 0x3377d1cf, v158
	v_mul_f32_e32 v152, 0x3f317217, v161
	v_cmp_gt_f32_e64 s[0:1], s54, v73
	v_fma_f32 v168, v131, v77, v130
	v_sub_f32_e32 v170, 1.0, v77
	v_add_f32_e32 v77, 1.0, v147
	v_mul_f32_e32 v145, 0xbfb8aa3b, v145
	v_log_f32_e32 v162, v70
	v_cndmask_b32_e64 v70, 0, 32, s[0:1]
	v_sub_f32_e32 v141, v148, v141
	v_fmac_f32_e32 v149, 0x3f317217, v158
	v_cmp_lt_f32_e64 vcc, |v158|, s57
	v_fma_f32 v147, v161, s56, -v152
	v_cndmask_b32_e64 v148, 0, v225, s[0:1]
	v_max_f32_e32 v152, 0xda24260, v168
	v_exp_f32_e32 v145, v145
	v_ldexp_f32 v73, v73, v70
	v_rcp_f32_e32 v75, v135
	v_add_f32_e32 v141, v66, v141
	v_cndmask_b32_e32 v66, v158, v149, vcc
	v_cmp_gt_f32_e64 s[0:1], s54, v152
	v_log_f32_e32 v158, v73
	s_nop 0
	v_cndmask_b32_e64 v73, 0, 32, s[0:1]
	v_fma_f32 v168, v131, v75, v130
	v_sub_f32_e32 v75, 1.0, v75
	v_add_f32_e32 v79, 1.0, v80
	v_fmac_f32_e32 v147, 0x3377d1cf, v161
	v_mul_f32_e32 v149, 0x3f317217, v167
	v_sub_f32_e32 v144, v66, v144
	v_ldexp_f32 v73, v152, v73
	v_cndmask_b32_e64 v152, 0, v225, s[0:1]
	v_mul_f32_e32 v66, v131, v75
	v_max_f32_e32 v75, 0xda24260, v168
	v_rcp_f32_e32 v134, v137
	v_min_f32_e64 v80, -v141, s60
	v_fmac_f32_e32 v147, 0x3f317217, v161
	v_cmp_lt_f32_e64 vcc, |v161|, s57
	v_fma_f32 v149, v167, s56, -v149
	v_cmp_gt_f32_e64 s[0:1], s54, v75
	v_mul_f32_e32 v70, v131, v170
	v_mul_f32_e32 v168, 0x3fb8aa3b, v80
	v_add_f32_e32 v141, v141, v144
	v_cndmask_b32_e32 v144, v161, v147, vcc
	v_fmac_f32_e32 v149, 0x3377d1cf, v167
	v_mul_f32_e32 v147, 0x3f317217, v162
	v_log_f32_e32 v161, v73
	v_cndmask_b32_e64 v73, 0, 32, s[0:1]
	v_fma_f32 v171, v131, v134, v130
	v_sub_f32_e32 v134, 1.0, v134
	v_add_f32_e32 v80, 1.0, v145
	v_sub_f32_e32 v144, v144, v146
	v_fmac_f32_e32 v149, 0x3f317217, v167
	v_cmp_lt_f32_e64 vcc, |v167|, s57
	v_fma_f32 v146, v162, s56, -v147
	v_ldexp_f32 v75, v75, v73
	v_cndmask_b32_e64 v147, 0, v225, s[0:1]
	v_mul_f32_e32 v73, v131, v134
	v_max_f32_e32 v134, 0xda24260, v171
	v_exp_f32_e32 v145, v168
	v_min_f32_e64 v168, -v141, s60
	v_rcp_f32_e32 v81, v163
	v_add_f32_e32 v141, v141, v144
	v_cndmask_b32_e32 v144, v167, v149, vcc
	v_fmac_f32_e32 v146, 0x3377d1cf, v162
	v_cmp_gt_f32_e64 s[0:1], s54, v134
	v_mul_f32_e32 v168, 0x3fb8aa3b, v168
	v_mul_f32_e32 v149, 0x3f317217, v158
	v_log_f32_e32 v167, v75
	v_cndmask_b32_e64 v75, 0, 32, s[0:1]
	v_fma_f32 v171, v131, v81, v130
	v_sub_f32_e32 v81, 1.0, v81
	v_sub_f32_e32 v144, v144, v160
	v_fmac_f32_e32 v146, 0x3f317217, v162
	v_cmp_lt_f32_e64 vcc, |v162|, s57
	v_exp_f32_e32 v168, v168
	v_min_f32_e64 v172, -v141, s60
	v_fma_f32 v149, v158, s56, -v149
	v_ldexp_f32 v134, v134, v75
	v_mul_f32_e32 v75, v131, v81
	v_max_f32_e32 v81, 0xda24260, v171
	v_add_f32_e32 v141, v141, v144
	v_cndmask_b32_e32 v144, v162, v146, vcc
	v_cndmask_b32_e64 v160, 0, v225, s[0:1]
	v_rcp_f32_e32 v135, v155
	v_fmac_f32_e32 v149, 0x3377d1cf, v158
	v_mul_f32_e32 v146, 0x3f317217, v161
	v_cmp_gt_f32_e64 s[0:1], s54, v81
	v_mul_f32_e32 v156, 0x3fb8aa3b, v172
	v_log_f32_e32 v134, v134
	v_cndmask_b32_e64 v162, 0, 32, s[0:1]
	v_fma_f32 v166, v131, v135, v130
	v_sub_f32_e32 v135, 1.0, v135
	v_mul_f32_e32 v145, v76, v145
	v_sub_f32_e32 v144, v144, v150
	v_fmac_f32_e32 v149, 0x3f317217, v158
	v_cmp_lt_f32_e64 vcc, |v158|, s57
	v_fma_f32 v146, v161, s56, -v146
	v_rcp_f32_e32 v137, v143
	v_exp_f32_e32 v156, v156
	v_min_f32_e64 v169, -v141, s60
	v_ldexp_f32 v81, v81, v162
	v_mul_f32_e32 v76, v131, v135
	v_max_f32_e32 v135, 0xda24260, v166
	v_cvt_pk_bf16_f32 v145, v145, s0
	v_add_f32_e32 v141, v141, v144
	v_cndmask_b32_e32 v144, v158, v149, vcc
	v_fmac_f32_e32 v146, 0x3377d1cf, v161
	v_fma_f32 v158, v131, v137, v130
	v_sub_f32_e32 v137, 1.0, v137
	v_cndmask_b32_e64 v150, 0, v225, s[0:1]
; __device__ __forceinline__ bf16_t f2bf(float f) { return (bf16_t)(cvt_pk_bf16(f, 0.f) & 0xffffu); }
; __device__ __forceinline__ float bf2f(bf16_t b) { return __uint_as_float(((unsigned)b) << 16); }
; __device__ __forceinline__ float sigmoidf_(float x) { return 1.0f / (1.0f + __expf(-x)); }
; template <int MODE>
; __device__ __forceinline__ void hgrn_mfma(const Ctx& C, int l, int z, int b, int hd, int c, f32x4 (&Sacc)[4][4], float& dectot, unsigned char* wl, float lb) {
;     ...
;             for (int t = 0; t < 16; ++t) {
;                 const float fl = bf2f(fv[t]);
;                 const float sg = sigmoidf_(fl);
;                 const float f = lb + (1.0f - lb) * sg, kk = (1.0f - lb) * (1.0f - sg);
;                 bacc += __logf(fmaxf(f, 1e-30f));
;                 Kb[(g8 * 16 + t) * HPT + lane] = f2bf(kk * __expf(fminf(-bacc, 80.f)));
;                 if (MODE != 0) Qt[(g8 * 16 + t) * HPT + lane] = f2bf(bf2f(qv[t]) * __expf(fmaxf(bacc, -80.f)));
;                 Vv[(g8 * 16 + t) * HPT + lane] = vv[t];
	v_mul_f32_e32 v151, 0x3fb8aa3b, v169
	v_mul_f32_e32 v149, 0x3f317217, v167
	v_log_f32_e32 v81, v81
	v_cmp_gt_f32_e64 s[0:1], s54, v135
	ds_write_b16 v67, v145 offset:4608
	v_mul_f32_e32 v145, v74, v168
	v_sub_f32_e32 v144, v144, v148
	v_fmac_f32_e32 v146, 0x3f317217, v161
	v_cmp_lt_f32_e64 vcc, |v161|, s57
	v_mul_f32_e32 v74, v131, v137
	v_max_f32_e32 v137, 0xda24260, v158
	v_cndmask_b32_e64 v155, 0, 32, s[0:1]
	v_exp_f32_e32 v151, v151
	v_min_f32_e64 v153, -v141, s60
	v_fma_f32 v148, v167, s56, -v149
	v_cndmask_b32_e64 v149, 0, v225, s[0:1]
	v_rcp_f32_e32 v78, v78
	v_cvt_pk_bf16_f32 v142, v145, s0
	v_add_f32_e32 v141, v141, v144
	v_cndmask_b32_e32 v144, v161, v146, vcc
	v_cmp_gt_f32_e64 s[0:1], s54, v137
	v_mul_f32_e32 v143, 0x3fb8aa3b, v153
	v_fmac_f32_e32 v148, 0x3377d1cf, v167
	v_mul_f32_e32 v145, 0x3f317217, v134
	v_cndmask_b32_e64 v146, 0, 32, s[0:1]
	v_fma_f32 v153, v131, v78, v130
	v_ldexp_f32 v135, v135, v155
	ds_write_b16 v67, v142 offset:4752
	v_mul_f32_e32 v72, v72, v156
	v_exp_f32_e32 v139, v143
	v_min_f32_e64 v142, -v141, s60
	v_sub_f32_e32 v143, v144, v152
	v_fmac_f32_e32 v148, 0x3f317217, v167
	v_cmp_lt_f32_e64 vcc, |v167|, s57
	v_fma_f32 v144, v134, s56, -v145
	v_ldexp_f32 v137, v137, v146
	v_max_f32_e32 v146, 0xda24260, v153
	v_rcp_f32_e32 v77, v77
	v_log_f32_e32 v135, v135
	v_cndmask_b32_e64 v145, 0, v225, s[0:1]
	v_cvt_pk_bf16_f32 v72, v72, s0
	v_mul_f32_e32 v142, 0x3fb8aa3b, v142
	v_add_f32_e32 v141, v141, v143
	v_cndmask_b32_e32 v143, v167, v148, vcc
	v_fmac_f32_e32 v144, 0x3377d1cf, v134
	v_mul_f32_e32 v148, 0x3f317217, v81
	v_cmp_gt_f32_e64 s[0:1], s54, v146
	v_fma_f32 v155, v131, v77, v130
	s_nop 0
	v_cndmask_b32_e64 v153, 0, 32, s[0:1]
	ds_write_b16 v67, v72 offset:4896
	v_mul_f32_e32 v71, v71, v151
	v_exp_f32_e32 v72, v142
	v_sub_f32_e32 v142, v143, v147
	v_fmac_f32_e32 v144, 0x3f317217, v134
	v_cmp_lt_f32_e64 vcc, |v134|, s57
	v_fma_f32 v143, v81, s56, -v148
	v_max_f32_e32 v148, 0xda24260, v155
	v_log_f32_e32 v137, v137
	v_min_f32_e64 v140, -v141, s60
	v_ldexp_f32 v146, v146, v153
	v_cndmask_b32_e64 v147, 0, v225, s[0:1]
	v_rcp_f32_e32 v79, v79
	v_cvt_pk_bf16_f32 v71, v71, s0
	v_cndmask_b32_e32 v134, v134, v144, vcc
	v_cmp_gt_f32_e64 s[0:1], s54, v148
	v_mul_f32_e32 v140, 0x3fb8aa3b, v140
	v_fmac_f32_e32 v143, 0x3377d1cf, v81
	v_log_f32_e32 v144, v146
	v_cndmask_b32_e64 v146, 0, 32, s[0:1]
	v_fma_f32 v151, v131, v79, v130
	v_add_f32_e32 v141, v141, v142
	v_mul_f32_e32 v142, 0x3f317217, v135
	s_and_b64 vcc, exec, s[4:5]
	ds_write_b16 v67, v71 offset:5040
	v_mul_f32_e32 v69, v69, v139
	v_exp_f32_e32 v71, v140
	v_fmac_f32_e32 v143, 0x3f317217, v81
	v_cmp_lt_f32_e64 s[4:5], |v81|, s57
	v_ldexp_f32 v140, v148, v146
	v_max_f32_e32 v146, 0xda24260, v151
	v_rcp_f32_e32 v80, v80
	v_min_f32_e64 v138, -v141, s60
	v_sub_f32_e32 v134, v134, v160
	v_fma_f32 v139, v135, s56, -v142
	v_cndmask_b32_e64 v142, 0, v225, s[0:1]
	v_cvt_pk_bf16_f32 v69, v69, s0
	v_cndmask_b32_e64 v81, v81, v143, s[4:5]
	v_cmp_gt_f32_e64 s[0:1], s54, v146
	v_fma_f32 v143, v131, v80, v130
	v_mul_f32_e32 v136, 0x3fb8aa3b, v138
	v_add_f32_e32 v134, v141, v134
	v_fmac_f32_e32 v139, 0x3377d1cf, v135
	v_mul_f32_e32 v138, 0x3f317217, v137
	v_log_f32_e32 v140, v140
	v_cndmask_b32_e64 v141, 0, 32, s[0:1]
	v_mul_f32_e32 v68, v68, v72
	v_max_f32_e32 v143, 0xda24260, v143
	ds_write_b16 v67, v69 offset:5184
	v_exp_f32_e32 v69, v136
	v_min_f32_e64 v72, -v134, s60
	v_sub_f32_e32 v81, v81, v150
	v_fmac_f32_e32 v139, 0x3f317217, v135
	v_cmp_lt_f32_e64 s[4:5], |v135|, s57
	v_fma_f32 v136, v137, s56, -v138
	v_ldexp_f32 v138, v146, v141
	v_cndmask_b32_e64 v141, 0, v225, s[0:1]
	v_cvt_pk_bf16_f32 v68, v68, s0
	v_cmp_gt_f32_e64 s[0:1], s54, v143
	v_mul_f32_e32 v72, 0x3fb8aa3b, v72
	v_add_f32_e32 v81, v134, v81
	v_cndmask_b32_e64 v134, v135, v139, s[4:5]
	v_fmac_f32_e32 v136, 0x3377d1cf, v137
	v_mul_f32_e32 v135, 0x3f317217, v144
	v_log_f32_e32 v138, v138
	v_cndmask_b32_e64 v139, 0, 32, s[0:1]
	ds_write_b16 v67, v68 offset:5328
	v_mul_f32_e32 v68, v70, v71
	v_exp_f32_e32 v70, v72
	v_min_f32_e64 v71, -v81, s60
	v_sub_f32_e32 v72, v134, v149
	v_fmac_f32_e32 v136, 0x3f317217, v137
	v_cmp_lt_f32_e64 s[4:5], |v137|, s57
	v_fma_f32 v134, v144, s56, -v135
	v_ldexp_f32 v135, v143, v139
	v_cvt_pk_bf16_f32 v68, v68, s0
	v_mul_f32_e32 v71, 0x3fb8aa3b, v71
	v_add_f32_e32 v72, v81, v72
	v_cndmask_b32_e64 v81, v137, v136, s[4:5]
	v_fmac_f32_e32 v134, 0x3377d1cf, v144
	v_mul_f32_e32 v136, 0x3f317217, v140
	v_log_f32_e32 v135, v135
	v_cndmask_b32_e64 v139, 0, v225, s[0:1]
	ds_write_b16 v67, v68 offset:5472
	v_mul_f32_e32 v66, v66, v69
	v_exp_f32_e32 v68, v71
	v_min_f32_e64 v69, -v72, s60
	v_sub_f32_e32 v71, v81, v145
	v_fmac_f32_e32 v134, 0x3f317217, v144
	v_cmp_lt_f32_e64 s[0:1], |v144|, s57
	v_fma_f32 v81, v140, s56, -v136
	v_mul_f32_e32 v69, 0x3fb8aa3b, v69
	v_cvt_pk_bf16_f32 v66, v66, s0
	v_add_f32_e32 v71, v72, v71
	v_cndmask_b32_e64 v72, v144, v134, s[0:1]
	v_fmac_f32_e32 v81, 0x3377d1cf, v140
	v_mul_f32_e32 v134, 0x3f317217, v138
	ds_write_b16 v67, v66 offset:5616
	v_mul_f32_e32 v66, v73, v70
	v_exp_f32_e32 v69, v69
	v_min_f32_e64 v70, -v71, s60
	v_sub_f32_e32 v72, v72, v147
	v_fmac_f32_e32 v81, 0x3f317217, v140
	v_cmp_lt_f32_e64 s[0:1], |v140|, s57
	v_fma_f32 v73, v138, s56, -v134
	v_mul_f32_e32 v70, 0x3fb8aa3b, v70
	v_cvt_pk_bf16_f32 v66, v66, s0
	v_add_f32_e32 v71, v71, v72
	v_cndmask_b32_e64 v72, v140, v81, s[0:1]
	v_fmac_f32_e32 v73, 0x3377d1cf, v138
	v_mul_f32_e32 v81, 0x3f317217, v135
	ds_write_b16 v67, v66 offset:5760
	v_mul_f32_e32 v66, v75, v68
	v_exp_f32_e32 v68, v70
	v_min_f32_e64 v70, -v71, s60
	v_sub_f32_e32 v72, v72, v142
	v_fmac_f32_e32 v73, 0x3f317217, v138
; __device__ __forceinline__ bf16_t f2bf(float f) { return (bf16_t)(cvt_pk_bf16(f, 0.f) & 0xffffu); }
; __device__ __forceinline__ float bf2f(bf16_t b) { return __uint_as_float(((unsigned)b) << 16); }
; __device__ __forceinline__ float sigmoidf_(float x) { return 1.0f / (1.0f + __expf(-x)); }
; __device__ __forceinline__ void wave_lds_fence() { asm volatile("s_waitcnt lgkmcnt(0)" ::: "memory"); __builtin_amdgcn_wave_barrier(); }
; template <int MODE>
; __device__ __forceinline__ void hgrn_mfma(const Ctx& C, int l, int z, int b, int hd, int c, f32x4 (&Sacc)[4][4], float& dectot, unsigned char* wl, float lb) {
;     ...
;             for (int t = 0; t < 16; ++t) {
;                 const float fl = bf2f(fv[t]);
;                 const float sg = sigmoidf_(fl);
;                 const float f = lb + (1.0f - lb) * sg, kk = (1.0f - lb) * (1.0f - sg);
;                 bacc += __logf(fmaxf(f, 1e-30f));
;                 Kb[(g8 * 16 + t) * HPT + lane] = f2bf(kk * __expf(fminf(-bacc, 80.f)));
;                 if (MODE != 0) Qt[(g8 * 16 + t) * HPT + lane] = f2bf(bf2f(qv[t]) * __expf(fmaxf(bacc, -80.f)));
;                 Vv[(g8 * 16 + t) * HPT + lane] = vv[t];
;             }
;         }
;         { const float eb = __expf(bacc); dl[lane] = eb; dectot *= eb; }
;         wave_lds_fence();
;     ...
;             bf16x8 vB[4];
; #pragma unroll
;             for (int vt = 0; vt < 4; ++vt) { const bf16_t* vp = Vv + (8 * quad + (fr >> 2)) * HPT + 16 * vt + 4 * (fr & 3);
;                 union { bf16x8 v; s16x4 h[2]; } vb; vb.h[0] = lds_tr(vp); vb.h[1] = lds_tr(vp + 4 * HPT); vB[vt] = vb.v; }
; #pragma unroll
;             for (int kt = 0; kt < 4; ++kt) { const bf16_t* kp = Kb + (8 * quad + (fr >> 2)) * HPT + 16 * kt + 4 * (fr & 3);
;                 union { bf16x8 v; s16x4 h[2]; } ka; ka.h[0] = lds_tr(kp); ka.h[1] = lds_tr(kp + 4 * HPT);
;                 const f32x4 d4 = *(const f32x4*)(dl + 16 * kt + 4 * quad);
; #pragma unroll
;                 for (int vt = 0; vt < 4; ++vt) { Sacc[kt][vt] = __builtin_amdgcn_mfma_f32_16x16x32_bf16(ka.v, vB[vt], Sacc[kt][vt], 0, 0, 0); Sacc[kt][vt] *= d4; } }
	v_cmp_lt_f32_e64 s[0:1], |v138|, s57
	v_fma_f32 v75, v135, s56, -v81
	v_mul_f32_e32 v70, 0x3fb8aa3b, v70
	v_cvt_pk_bf16_f32 v66, v66, s0
	v_add_f32_e32 v71, v71, v72
	v_cndmask_b32_e64 v72, v138, v73, s[0:1]
	v_fmac_f32_e32 v75, 0x3377d1cf, v135
	ds_write_b16 v67, v66 offset:5904
	v_mul_f32_e32 v66, v76, v69
	v_exp_f32_e32 v69, v70
	v_min_f32_e64 v70, -v71, s60
	v_sub_f32_e32 v72, v72, v141
	v_fmac_f32_e32 v75, 0x3f317217, v135
	v_cmp_lt_f32_e64 s[0:1], |v135|, s57
	v_mul_f32_e32 v70, 0x3fb8aa3b, v70
	v_add_f32_e32 v71, v71, v72
	v_cvt_pk_bf16_f32 v66, v66, s0
	v_cndmask_b32_e64 v72, v135, v75, s[0:1]
	v_sub_f32_e32 v78, 1.0, v78
	ds_write_b16 v67, v66 offset:6048
	v_mul_f32_e32 v66, v74, v68
	v_exp_f32_e32 v68, v70
	v_min_f32_e64 v70, -v71, s60
	v_sub_f32_e32 v72, v72, v139
	v_mul_f32_e32 v78, v131, v78
	v_cvt_pk_bf16_f32 v73, v66, s0
	v_mul_f32_e32 v70, 0x3fb8aa3b, v70
	v_add_f32_e32 v66, v71, v72
	v_sub_f32_e32 v77, 1.0, v77
	v_mul_f32_e32 v69, v78, v69
	v_exp_f32_e32 v70, v70
	v_min_f32_e64 v71, -v66, s60
	v_mul_f32_e32 v77, v131, v77
	v_cvt_pk_bf16_f32 v69, v69, s0
	v_mul_f32_e32 v71, 0x3fb8aa3b, v71
	v_sub_f32_e32 v79, 1.0, v79
	ds_write_b16 v67, v69 offset:6336
	v_mul_f32_e32 v68, v77, v68
	v_exp_f32_e32 v69, v71
	v_mul_f32_e32 v79, v131, v79
	v_cvt_pk_bf16_f32 v68, v68, s0
	v_sub_f32_e32 v80, 1.0, v80
	ds_write_b16 v67, v68 offset:6480
	v_mul_f32_e32 v68, v79, v70
	v_mul_f32_e32 v80, v131, v80
	v_cvt_pk_bf16_f32 v68, v68, s0
	ds_write_b16 v67, v68 offset:6624
	v_mul_f32_e32 v68, v80, v69
	v_cvt_pk_bf16_f32 v68, v68, s0
	ds_write_b16 v67, v73 offset:6192
	ds_write_b16 v67, v68 offset:6768
	s_cbranch_vccz .LBB0_476
	v_mul_f32_e32 v66, 0x3fb8aa3b, v66
	v_exp_f32_e32 v66, v66
	s_add_i32 s69, s69, 1
	s_cmp_eq_u32 s69, 4
	ds_write_b32 v82, v66 offset:13824
	v_mul_f32_e32 v129, v129, v66
	s_waitcnt lgkmcnt(0)
	ds_read_b64_tr_b16 v[78:79], v83 offset:9216
	ds_read_b64_tr_b16 v[80:81], v83 offset:9792
	ds_read_b64_tr_b16 v[74:75], v83 offset:9248
	ds_read_b64_tr_b16 v[76:77], v83 offset:9824
	ds_read_b64_tr_b16 v[70:71], v83 offset:9280
	ds_read_b64_tr_b16 v[72:73], v83 offset:9856
	ds_read_b64_tr_b16 v[66:67], v83 offset:9312
	ds_read_b64_tr_b16 v[68:69], v83 offset:9888
	ds_read_b64_tr_b16 v[136:137], v83 offset:5184
	ds_read_b64_tr_b16 v[134:135], v83 offset:4608
	ds_read_b64_tr_b16 v[138:139], v83 offset:4640
	ds_read_b128 v[140:143], v84 offset:13824
	s_waitcnt lgkmcnt(2)
	v_mfma_f32_16x16x32_bf16 v[60:63], v[134:137], v[78:81], v[60:63]
	v_mfma_f32_16x16x32_bf16 v[56:59], v[134:137], v[74:77], v[56:59]
	s_waitcnt lgkmcnt(0)
	s_nop 5
	v_pk_mul_f32 v[60:61], v[140:141], v[60:61]
	v_pk_mul_f32 v[62:63], v[142:143], v[62:63]
	v_mfma_f32_16x16x32_bf16 v[52:55], v[134:137], v[70:73], v[52:55]
	v_mfma_f32_16x16x32_bf16 v[48:51], v[134:137], v[66:69], v[48:51]
	v_mul_f32_e64 v56, v140, v56
	v_mul_f32_e64 v57, v141, v57
	s_nop 4
	v_pk_mul_f32 v[52:53], v[140:141], v[52:53]
	v_pk_mul_f32 v[58:59], v[142:143], v[58:59]
	v_pk_mul_f32 v[54:55], v[142:143], v[54:55]
	v_pk_mul_f32 v[48:49], v[140:141], v[48:49]
	ds_read_b64_tr_b16 v[140:141], v83 offset:5216
	ds_read_b128 v[134:137], v84 offset:13888
	s_waitcnt lgkmcnt(1)
	v_mfma_f32_16x16x32_bf16 v[44:47], v[138:141], v[78:81], v[44:47]
	v_mul_f32_e64 v50, v142, v50
	v_mul_f32_e64 v51, v143, v51
	v_mfma_f32_16x16x32_bf16 v[40:43], v[138:141], v[74:77], v[40:43]
	s_waitcnt lgkmcnt(0)
	s_nop 3
	v_pk_mul_f32 v[46:47], v[136:137], v[46:47]
	v_pk_mul_f32 v[44:45], v[134:135], v[44:45]
	v_mfma_f32_16x16x32_bf16 v[36:39], v[138:141], v[70:73], v[36:39]
	v_mfma_f32_16x16x32_bf16 v[32:35], v[138:141], v[66:69], v[32:35]
	v_mul_f32_e64 v42, v136, v42
	v_mul_f32_e64 v43, v137, v43
	v_pk_mul_f32 v[40:41], v[134:135], v[40:41]
	s_nop 3
	v_pk_mul_f32 v[38:39], v[136:137], v[38:39]
	v_pk_mul_f32 v[36:37], v[134:135], v[36:37]
	v_pk_mul_f32 v[34:35], v[136:137], v[34:35]
	v_pk_mul_f32 v[32:33], v[134:135], v[32:33]
	ds_read_b64_tr_b16 v[134:135], v83 offset:4672
	ds_read_b64_tr_b16 v[136:137], v83 offset:5248
	ds_read_b128 v[138:141], v84 offset:13952
	s_waitcnt lgkmcnt(1)
	v_mfma_f32_16x16x32_bf16 v[28:31], v[134:137], v[78:81], v[28:31]
	v_mfma_f32_16x16x32_bf16 v[24:27], v[134:137], v[74:77], v[24:27]
	s_waitcnt lgkmcnt(0)
	s_nop 5
	v_pk_mul_f32 v[30:31], v[140:141], v[30:31]
	v_pk_mul_f32 v[28:29], v[138:139], v[28:29]
	v_mfma_f32_16x16x32_bf16 v[20:23], v[134:137], v[70:73], v[20:23]
	v_mfma_f32_16x16x32_bf16 v[16:19], v[134:137], v[66:69], v[16:19]
	v_mul_f32_e64 v26, v140, v26
	v_mul_f32_e64 v27, v141, v27
	v_pk_mul_f32 v[24:25], v[138:139], v[24:25]
	s_nop 3
	v_pk_mul_f32 v[22:23], v[140:141], v[22:23]
	v_pk_mul_f32 v[20:21], v[138:139], v[20:21]
	v_pk_mul_f32 v[18:19], v[140:141], v[18:19]
	v_pk_mul_f32 v[16:17], v[138:139], v[16:17]
	ds_read_b64_tr_b16 v[134:135], v83 offset:4704
	ds_read_b64_tr_b16 v[136:137], v83 offset:5280
	ds_read_b128 v[138:141], v84 offset:14016
	s_waitcnt lgkmcnt(1)
	v_mfma_f32_16x16x32_bf16 v[8:11], v[134:137], v[78:81], v[8:11]
	s_waitcnt lgkmcnt(0)
	v_mfma_f32_16x16x32_bf16 v[12:15], v[134:137], v[74:77], v[12:15]
	s_waitcnt lgkmcnt(0)
	s_nop 4
	v_pk_mul_f32 v[10:11], v[140:141], v[10:11]
	v_pk_mul_f32 v[8:9], v[138:139], v[8:9]
	v_mfma_f32_16x16x32_bf16 v[4:7], v[134:137], v[70:73], v[4:7]
	v_mfma_f32_16x16x32_bf16 v[0:3], v[134:137], v[66:69], v[0:3]
	v_mul_f32_e64 v14, v140, v14
	v_mul_f32_e64 v15, v141, v15
	v_pk_mul_f32 v[12:13], v[138:139], v[12:13]
	s_nop 3
	v_pk_mul_f32 v[6:7], v[140:141], v[6:7]
	v_pk_mul_f32 v[4:5], v[138:139], v[4:5]
	v_pk_mul_f32 v[2:3], v[140:141], v[2:3]
	v_pk_mul_f32 v[0:1], v[138:139], v[0:1]
	s_cbranch_scc0 .LBB0_475
;     __device__ __forceinline__ float* fp(size_t off) const { return (float*)(ws + off); }
; __device__ __forceinline__ void hgrn_pass1_item(const Ctx& C, int l, int item) {
;     ...
;     float* sb = C.fp(OFF_S) + (size_t)item * 4096;
;     const int fr = C.lane & 15, quad = C.lane >> 4;
; #pragma unroll
;     for (int kt = 0; kt < 4; ++kt)
; #pragma unroll
;         for (int vt = 0; vt < 4; ++vt)
; #pragma unroll
;             for (int r = 0; r < 4; ++r) sb[(16 * kt + 4 * quad + r) * 64 + 16 * vt + fr] = Sacc[kt][vt][r];
;     C.fp(OFF_DEC)[item * 64 + C.lane] = dectot;
	s_ashr_i32 s19, s18, 31
	s_lshl_b64 s[0:1], s[18:19], 14
	s_add_u32 s0, s49, s0
	s_addc_u32 s1, s53, s1
	global_store_dword v85, v60, s[0:1]
	global_store_dword v85, v61, s[0:1] offset:256
	global_store_dword v85, v62, s[0:1] offset:512
	global_store_dword v86, v63, s[0:1]
	global_store_dword v85, v56, s[0:1] offset:64
	global_store_dword v87, v57, s[0:1] offset:256
	global_store_dword v87, v58, s[0:1] offset:512
	global_store_dword v86, v59, s[0:1] offset:64
	global_store_dword v85, v52, s[0:1] offset:128
	global_store_dword v88, v53, s[0:1] offset:256
	global_store_dword v88, v54, s[0:1] offset:512
	global_store_dword v86, v55, s[0:1] offset:128
	global_store_dword v85, v48, s[0:1] offset:192
	global_store_dword v89, v49, s[0:1] offset:256
	global_store_dword v89, v50, s[0:1] offset:512
	global_store_dword v86, v51, s[0:1] offset:192
	global_store_dword v90, v44, s[0:1]
	global_store_dword v91, v45, s[0:1]
	global_store_dword v92, v46, s[0:1]
	global_store_dword v93, v47, s[0:1]
	global_store_dword v94, v40, s[0:1]
	global_store_dword v95, v41, s[0:1]
	global_store_dword v96, v42, s[0:1]
	global_store_dword v93, v43, s[0:1] offset:64
	global_store_dword v97, v36, s[0:1]
	global_store_dword v98, v37, s[0:1]
	global_store_dword v99, v38, s[0:1]
	global_store_dword v93, v39, s[0:1] offset:128
	global_store_dword v100, v32, s[0:1]
	global_store_dword v101, v33, s[0:1]
	global_store_dword v102, v34, s[0:1]
	global_store_dword v93, v35, s[0:1] offset:192
	global_store_dword v103, v28, s[0:1]
	global_store_dword v104, v29, s[0:1]
	global_store_dword v105, v30, s[0:1]
	global_store_dword v106, v31, s[0:1]
	global_store_dword v107, v24, s[0:1]
	global_store_dword v108, v25, s[0:1]
	global_store_dword v109, v26, s[0:1]
	global_store_dword v106, v27, s[0:1] offset:64
	global_store_dword v110, v20, s[0:1]
	global_store_dword v111, v21, s[0:1]
	global_store_dword v112, v22, s[0:1]
	global_store_dword v106, v23, s[0:1] offset:128
	global_store_dword v113, v16, s[0:1]
	global_store_dword v114, v17, s[0:1]
	global_store_dword v115, v18, s[0:1]
	global_store_dword v106, v19, s[0:1] offset:192
	global_store_dword v116, v8, s[0:1]
	global_store_dword v117, v9, s[0:1]
	global_store_dword v118, v10, s[0:1]
	global_store_dword v119, v11, s[0:1]
	global_store_dword v120, v12, s[0:1]
	global_store_dword v121, v13, s[0:1]
	global_store_dword v122, v14, s[0:1]
	global_store_dword v119, v15, s[0:1] offset:64
	global_store_dword v123, v4, s[0:1]
	global_store_dword v124, v5, s[0:1]
	global_store_dword v125, v6, s[0:1]
	global_store_dword v119, v7, s[0:1] offset:128
	global_store_dword v126, v0, s[0:1]
	global_store_dword v127, v1, s[0:1]
	global_store_dword v128, v2, s[0:1]
	global_store_dword v119, v3, s[0:1] offset:192
	v_lshl_or_b32 v0, s18, 6, v64
	v_readlane_b32 s0, v254, 20
	v_ashrrev_i32_e32 v1, 31, v0
	s_add_i32 s18, s18, s0
	v_lshl_add_u64 v[0:1], v[0:1], 2, s[20:21]
	s_cmpk_gt_i32 s18, 0x7ff
	v_readlane_b32 s1, v254, 21
	global_store_dword v[0:1], v129, off
	s_cbranch_scc0 .LBB0_470

; __device__ __forceinline__ float hgrn_lb(const Ctx& C, int l, int ch) {
;     if (l == 0) return 0.f;
;     const float a0 = C.P->in[3][ch], a1 = C.P->in[3][256 + ch];
;     return 1.0f / (1.0f + __expf(a0 - a1));
; }
; template <int DIR>
; __device__ __forceinline__ void hgrn_pass3_item(const Ctx& C, int l, int item) {
;     const int c = item & 31, hd = (item >> 5) & 3, b = item >> 7;
;     unsigned char* wl = C.lds + C.wave * 14336;
;     const float lb = hgrn_lb(C, l, hd * 64 + C.lane);
.LBB0_641:
	s_bfe_u32 s1, s48, 0x20005
	v_readlane_b32 s4, v255, 1
	s_lshl_b32 s0, s1, 6
	v_readlane_b32 s5, v255, 2
	v_or_b32_e32 v192, s0, v118
	s_andn2_b64 vcc, exec, s[4:5]
	v_mov_b32_e32 v193, 0
	s_cbranch_vccnz .LBB0_643
	v_readlane_b32 s4, v251, 4
	v_lshlrev_b32_e32 v0, 2, v192
	v_readlane_b32 s10, v251, 10
	v_readlane_b32 s11, v251, 11
	s_nop 4
	global_load_dword v1, v0, s[10:11]
	global_load_dword v0, v0, s[10:11] offset:1024
	v_readlane_b32 s5, v251, 5
	v_readlane_b32 s6, v251, 6
	v_readlane_b32 s7, v251, 7
	v_readlane_b32 s8, v251, 8
	v_readlane_b32 s9, v251, 9
	v_readlane_b32 s12, v251, 12
	v_readlane_b32 s13, v251, 13
	v_readlane_b32 s14, v251, 14
	v_readlane_b32 s15, v251, 15
	v_readlane_b32 s16, v251, 16
	v_readlane_b32 s17, v251, 17
	v_readlane_b32 s18, v251, 18
	v_readlane_b32 s19, v251, 19
	s_waitcnt vmcnt(0)
	v_sub_f32_e32 v0, v1, v0
	v_mul_f32_e32 v0, 0x3fb8aa3b, v0
	v_exp_f32_e32 v0, v0
	s_nop 0
	v_add_f32_e32 v0, 1.0, v0
	v_rcp_f32_e32 v193, v0

; __device__ __forceinline__ bf16_t f2bf(float f) { return (bf16_t)(cvt_pk_bf16(f, 0.f) & 0xffffu); }
; __device__ __forceinline__ float bf2f(bf16_t b) { return __uint_as_float(((unsigned)b) << 16); }
; __device__ __forceinline__ float sigmoidf_(float x) { return 1.0f / (1.0f + __expf(-x)); }
; template <int MODE>
; __device__ __forceinline__ void hgrn_mfma(const Ctx& C, int l, int z, int b, int hd, int c, f32x4 (&Sacc)[4][4], float& dectot, unsigned char* wl, float lb) {
;     ...
;             const int st0 = c * 128 + sc * 32 + g8 * 16; const int tq0 = z ? 4095 - st0 : st0;
;             const bf16_t* row0 = pa + (size_t)(b * SEQ + tq0) * 1280; const ptrdiff_t rstep = z ? -1280 : 1280;
; #pragma unroll
;             for (int t = 0; t < 16; ++t) { const bf16_t* row = row0 + rstep * t; fv[t] = row[fcol]; vv[t] = row[vcol]; if (MODE != 0) qv[t] = row[qcol]; }
; #pragma unroll
;             for (int t = 0; t < 16; ++t) {
;                 const float fl = bf2f(fv[t]);
;                 const float sg = sigmoidf_(fl);
;                 const float f = lb + (1.0f - lb) * sg, kk = (1.0f - lb) * (1.0f - sg);
;                 bacc += __logf(fmaxf(f, 1e-30f));
;                 Kb[(g8 * 16 + t) * HPT + lane] = f2bf(kk * __expf(fminf(-bacc, 80.f)));
;                 if (MODE != 0) Qt[(g8 * 16 + t) * HPT + lane] = f2bf(bf2f(qv[t]) * __expf(fmaxf(bacc, -80.f)));
;                 Vv[(g8 * 16 + t) * HPT + lane] = vv[t];
.LBB0_645:
	s_lshl_b32 s0, s67, 4
	v_cndmask_b32_e64 v60, 0, 1, s[46:47]
	s_mul_i32 s1, s67, 0x480
	s_sub_i32 s0, s74, s0
	v_cmp_ne_u32_e64 s[4:5], 1, v60
	v_or_b32_e32 v60, s1, v118
	s_mul_hi_i32 s1, s0, 0xa00
	s_mulk_i32 s0, 0xa00
	s_add_u32 s0, s69, s0
	v_lshlrev_b32_e32 v64, 1, v192
	s_addc_u32 s1, s70, s1
	global_load_ushort v70, v64, s[0:1] offset:1536
	global_load_ushort v71, v64, s[0:1] offset:1024
	global_load_ushort v72, v64, s[0:1]
	global_load_ushort v73, v64, s[0:1] offset:-1024
	global_load_ushort v74, v64, s[0:1] offset:-1536
	global_load_ushort v75, v64, s[0:1] offset:-2560
	global_load_ushort v76, v64, s[0:1] offset:-3584
	global_load_ushort v77, v64, s[0:1] offset:-4096
	s_add_u32 s6, s0, 0xffffe200
	s_addc_u32 s7, s1, -1
	global_load_ushort v78, v203, s[6:7]
	global_load_ushort v82, v64, s[6:7]
	global_load_ushort v83, v204, s[6:7]
	s_add_u32 s6, s0, 0xffffd800
	s_addc_u32 s7, s1, -1
	global_load_ushort v84, v203, s[6:7]
	global_load_ushort v85, v64, s[6:7]
	global_load_ushort v86, v204, s[6:7]
	s_add_u32 s6, s0, 0xffffce00
	v_lshl_add_u64 v[62:63], s[0:1], 0, v[64:65]
	s_movk_i32 s8, 0xf000
	s_addc_u32 s7, s1, -1
	v_add_co_u32_e32 v62, vcc, s8, v62
	s_add_u32 s8, s0, 0xffffc400
	global_load_ushort v89, v203, s[6:7]
	global_load_ushort v90, v64, s[6:7]
	global_load_ushort v91, v204, s[6:7]
	s_addc_u32 s9, s1, -1
	s_add_u32 s6, s0, 0xffffba00
	global_load_ushort v92, v204, s[8:9]
	global_load_ushort v93, v203, s[8:9]
	global_load_ushort v94, v64, s[8:9]
	s_addc_u32 s7, s1, -1
	s_add_u32 s8, s0, 0xffffb000
	global_load_ushort v95, v204, s[6:7]
	global_load_ushort v96, v203, s[6:7]
	global_load_ushort v97, v64, s[6:7]
	s_addc_u32 s9, s1, -1
	s_add_u32 s6, s0, 0xffffa600
	global_load_ushort v98, v204, s[8:9]
	global_load_ushort v99, v203, s[8:9]
	global_load_ushort v100, v64, s[8:9]
	s_addc_u32 s7, s1, -1
	s_add_u32 s8, s0, 0xffff9c00
	global_load_ushort v101, v204, s[6:7]
	global_load_ushort v102, v203, s[6:7]
	global_load_ushort v103, v64, s[6:7]
	s_addc_u32 s9, s1, -1
	global_load_ushort v104, v204, s[8:9]
	global_load_ushort v105, v203, s[8:9]
	global_load_ushort v106, v64, s[8:9]
	s_add_u32 s6, s0, 0xffff9200
	s_addc_u32 s7, s1, -1
	s_add_u32 s8, s0, 0xffff8800
	global_load_ushort v108, v204, s[6:7]
	global_load_ushort v109, v203, s[6:7]
	global_load_ushort v110, v64, s[6:7]
	s_addc_u32 s9, s1, -1
	s_add_u32 s6, s0, 0xffff7e00
	global_load_ushort v111, v204, s[8:9]
	global_load_ushort v178, v203, s[8:9]
	global_load_ushort v179, v64, s[8:9]
	s_addc_u32 s7, s1, -1
	s_add_u32 s8, s0, 0xffff7400
	global_load_ushort v180, v204, s[6:7]
	global_load_ushort v181, v203, s[6:7]
	global_load_ushort v188, v64, s[6:7]
	s_addc_u32 s9, s1, -1
	global_load_ushort v189, v204, s[8:9]
	global_load_ushort v190, v203, s[8:9]
	global_load_ushort v191, v64, s[8:9]
	s_add_u32 s0, s0, 0xffff6a00
	s_addc_u32 s1, s1, -1
	v_addc_co_u32_e32 v63, vcc, -1, v63, vcc
	global_load_ushort v87, v204, s[0:1]
	global_load_ushort v208, v[62:63], off offset:-1024
	global_load_ushort v79, v203, s[0:1]
	global_load_ushort v88, v64, s[0:1]
	v_lshl_add_u32 v60, v60, 1, s49
	s_mov_b64 s[46:47], 0
	s_mov_b32 s67, 1
	s_waitcnt vmcnt(47)
	ds_write_b16 v60, v70 offset:9216
	s_waitcnt vmcnt(46)
	v_lshlrev_b32_e32 v62, 16, v71
	v_mul_f32_e32 v62, 0xbfb8aa3b, v62
	v_exp_f32_e32 v62, v62
	s_waitcnt vmcnt(43)
	v_lshlrev_b32_e32 v63, 16, v74
	v_mul_f32_e32 v63, 0xbfb8aa3b, v63
	v_exp_f32_e32 v63, v63
	s_waitcnt vmcnt(40)
	v_lshlrev_b32_e32 v64, 16, v77
	v_mul_f32_e32 v64, 0xbfb8aa3b, v64
	v_exp_f32_e32 v64, v64
	s_waitcnt vmcnt(39)
	v_lshlrev_b32_e32 v70, 16, v78
	v_mul_f32_e32 v70, 0xbfb8aa3b, v70
	v_exp_f32_e32 v70, v70
	s_waitcnt vmcnt(36)
	v_lshlrev_b32_e32 v71, 16, v84
	v_lshlrev_b32_e32 v78, 16, v82
	v_mul_f32_e32 v71, 0xbfb8aa3b, v71
	v_add_f32_e32 v82, 1.0, v62
	v_add_f32_e32 v63, 1.0, v63
	v_add_f32_e32 v64, 1.0, v64
	ds_write_b16 v60, v83 offset:9648
	s_waitcnt vmcnt(35)
	v_lshlrev_b32_e32 v77, 16, v85
	v_exp_f32_e32 v62, v71
	s_waitcnt vmcnt(33)
	v_lshlrev_b32_e32 v71, 16, v89
	s_waitcnt vmcnt(31)
	ds_write_b16 v60, v91 offset:9936
	v_mul_f32_e32 v71, 0xbfb8aa3b, v71
	v_lshlrev_b32_e32 v81, 16, v72
	v_add_f32_e32 v70, 1.0, v70
	v_exp_f32_e32 v71, v71
	s_waitcnt vmcnt(29)
	v_lshlrev_b32_e32 v72, 16, v93
	v_mul_f32_e32 v72, 0xbfb8aa3b, v72
	v_add_f32_e32 v211, 1.0, v62
	v_exp_f32_e32 v62, v72
	s_waitcnt vmcnt(26)
	v_lshlrev_b32_e32 v72, 16, v96
	ds_write_b16 v60, v92 offset:10080
	ds_write_b16 v60, v95 offset:10224
	v_mul_f32_e32 v72, 0xbfb8aa3b, v72
	ds_write_b16 v60, v76 offset:9504
	ds_write_b16 v60, v86 offset:9792
	v_lshlrev_b32_e32 v76, 16, v90
	v_add_f32_e32 v213, 1.0, v71
	v_exp_f32_e32 v71, v72
	s_waitcnt vmcnt(23)
	v_lshlrev_b32_e32 v72, 16, v99
	ds_write_b16 v60, v98 offset:10368
	v_mul_f32_e32 v72, 0xbfb8aa3b, v72
	s_waitcnt vmcnt(20)
	v_lshlrev_b32_e32 v99, 16, v102
	v_add_f32_e32 v107, 1.0, v62
	v_exp_f32_e32 v62, v72
	s_waitcnt vmcnt(19)
	v_lshlrev_b32_e32 v72, 16, v103
	ds_write_b16 v60, v101 offset:10512
	v_mul_f32_e32 v99, 0xbfb8aa3b, v99
	v_lshlrev_b32_e32 v80, 16, v75
	v_lshlrev_b32_e32 v75, 16, v94
	v_exp_f32_e32 v229, v99
	s_waitcnt vmcnt(17)
	v_lshlrev_b32_e32 v99, 16, v105
	v_mul_f32_e32 v89, 0xbfb8aa3b, v99
	v_lshlrev_b32_e32 v74, 16, v97
	v_add_f32_e32 v103, 1.0, v71
	v_exp_f32_e32 v89, v89
	s_waitcnt vmcnt(14)
	v_lshlrev_b32_e32 v91, 16, v109
	v_rcp_f32_e32 v82, v82
	ds_write_b16 v60, v73 offset:9360
	v_lshlrev_b32_e32 v73, 16, v100
	v_add_f32_e32 v99, 1.0, v62
	v_mul_f32_e32 v86, 0xbfb8aa3b, v91
	v_fma_f32 v91, v194, v82, v193
	v_sub_f32_e32 v82, 1.0, v82
	v_rcp_f32_e32 v83, v63
	v_add_f32_e32 v96, 1.0, v229
	ds_write_b16 v60, v104 offset:10656
	v_exp_f32_e32 v104, v86
	s_waitcnt vmcnt(11)
; __device__ __forceinline__ bf16_t f2bf(float f) { return (bf16_t)(cvt_pk_bf16(f, 0.f) & 0xffffu); }
; __device__ __forceinline__ float bf2f(bf16_t b) { return __uint_as_float(((unsigned)b) << 16); }
; __device__ __forceinline__ float sigmoidf_(float x) { return 1.0f / (1.0f + __expf(-x)); }
; template <int MODE>
; __device__ __forceinline__ void hgrn_mfma(const Ctx& C, int l, int z, int b, int hd, int c, f32x4 (&Sacc)[4][4], float& dectot, unsigned char* wl, float lb) {
;     ...
;             for (int t = 0; t < 16; ++t) {
;                 const float fl = bf2f(fv[t]);
;                 const float sg = sigmoidf_(fl);
;                 const float f = lb + (1.0f - lb) * sg, kk = (1.0f - lb) * (1.0f - sg);
;                 bacc += __logf(fmaxf(f, 1e-30f));
;                 Kb[(g8 * 16 + t) * HPT + lane] = f2bf(kk * __expf(fminf(-bacc, 80.f)));
;                 if (MODE != 0) Qt[(g8 * 16 + t) * HPT + lane] = f2bf(bf2f(qv[t]) * __expf(fmaxf(bacc, -80.f)));
	v_lshlrev_b32_e32 v102, 16, v178
	v_mul_f32_e32 v86, v194, v82
	v_max_f32_e32 v82, 0xda24260, v91
	v_fma_f32 v91, v194, v83, v193
	v_sub_f32_e32 v83, 1.0, v83
	v_rcp_f32_e32 v64, v64
	v_lshlrev_b32_e32 v71, 16, v106
	ds_write_b16 v60, v108 offset:10800
	v_mul_f32_e32 v101, 0xbfb8aa3b, v102
	v_cmp_gt_f32_e64 s[0:1], s54, v82
	v_mul_f32_e32 v84, v194, v83
	v_max_f32_e32 v83, 0xda24260, v91
	v_fma_f32 v106, v194, v64, v193
	v_rcp_f32_e32 v70, v70
	v_add_f32_e32 v93, 1.0, v89
	s_waitcnt vmcnt(10)
	v_lshlrev_b32_e32 v63, 16, v179
	v_cndmask_b32_e64 v102, 0, 32, s[0:1]
	v_exp_f32_e32 v179, v101
	s_waitcnt vmcnt(9)
	ds_write_b16 v60, v180 offset:11088
	v_cndmask_b32_e64 v105, 0, v225, s[0:1]
	v_cmp_gt_f32_e32 vcc, s54, v83
	v_max_f32_e32 v180, 0xda24260, v106
	v_fma_f32 v106, v194, v70, v193
	v_lshlrev_b32_e32 v62, 16, v110
	v_sub_f32_e32 v110, 1.0, v64
	s_waitcnt vmcnt(8)
	v_lshlrev_b32_e32 v89, 16, v181
	s_waitcnt vmcnt(7)
	v_lshlrev_b32_e32 v64, 16, v188
	v_cndmask_b32_e64 v97, 0, 32, vcc
	v_rcp_f32_e32 v90, v211
	v_cndmask_b32_e32 v100, 0, v225, vcc
	v_cmp_gt_f32_e64 s[0:1], s54, v180
	v_max_f32_e32 v188, 0xda24260, v106
	v_ldexp_f32 v82, v82, v102
	v_sub_f32_e32 v70, 1.0, v70
	v_mul_f32_e32 v95, 0xbfb8aa3b, v89
	v_ldexp_f32 v83, v83, v97
	v_cndmask_b32_e64 v97, 0, 32, s[0:1]
	v_fma_f32 v209, v194, v90, v193
	v_add_f32_e32 v89, 1.0, v104
	v_cmp_gt_f32_e32 vcc, s54, v188
	v_mul_f32_e32 v85, v194, v110
	v_log_f32_e32 v110, v82
	v_mul_f32_e32 v82, v194, v70
	v_exp_f32_e32 v211, v95
	s_waitcnt vmcnt(5)
	v_lshlrev_b32_e32 v104, 16, v190
	s_waitcnt vmcnt(4)
	v_lshlrev_b32_e32 v70, 16, v191
	ds_write_b16 v60, v189 offset:11232
	v_ldexp_f32 v180, v180, v97
	v_cndmask_b32_e64 v97, 0, v225, s[0:1]
	v_cndmask_b32_e64 v189, 0, 32, vcc
	v_max_f32_e32 v190, 0xda24260, v209
	v_rcp_f32_e32 v191, v213
	v_sub_f32_e32 v90, 1.0, v90
	v_log_f32_e32 v106, v83
	v_mul_f32_e32 v210, 0xbfb8aa3b, v104
	v_log_f32_e32 v104, v180
	v_ldexp_f32 v180, v188, v189
	v_cndmask_b32_e32 v188, 0, v225, vcc
	v_cmp_gt_f32_e64 s[0:1], s54, v190
	v_mul_f32_e32 v83, v194, v90
	s_waitcnt vmcnt(2)
	v_lshlrev_b32_e32 v90, 16, v208
	v_cndmask_b32_e64 v189, 0, 32, s[0:1]
	v_fma_f32 v213, v194, v191, v193
	v_sub_f32_e32 v191, 1.0, v191
	v_add_f32_e32 v208, 1.0, v179
	v_exp_f32_e32 v179, v210
	s_waitcnt vmcnt(1)
	v_lshlrev_b32_e32 v210, 16, v79
	s_waitcnt vmcnt(0)
	v_lshlrev_b32_e32 v79, 16, v88
	ds_write_b16 v60, v87 offset:11376
	v_ldexp_f32 v87, v190, v189
	v_cndmask_b32_e64 v189, 0, v225, s[0:1]
	v_mul_f32_e32 v92, v194, v191
	v_max_f32_e32 v88, 0xda24260, v213
	v_rcp_f32_e32 v107, v107
	ds_write_b16 v60, v111 offset:10944
	v_log_f32_e32 v180, v180
	v_mul_f32_e32 v207, 0xbfb8aa3b, v210
	v_mul_f32_e32 v210, 0x3f317217, v110
	v_cmp_gt_f32_e64 s[0:1], s54, v88
	v_fma_f32 v213, v194, v107, v193
	v_sub_f32_e32 v215, 1.0, v107
	v_add_f32_e32 v107, 1.0, v211
	v_log_f32_e32 v212, v87
	v_cndmask_b32_e64 v87, 0, 32, s[0:1]
	v_exp_f32_e32 v207, v207
	v_fma_f32 v210, v110, s56, -v210
	v_mul_f32_e32 v211, 0x3f317217, v106
	v_cndmask_b32_e64 v223, 0, v225, s[0:1]
	v_max_f32_e32 v213, 0xda24260, v213
	v_rcp_f32_e32 v103, v103
	v_ldexp_f32 v87, v88, v87
	v_fmac_f32_e32 v210, 0x3377d1cf, v110
	v_fma_f32 v211, v106, s56, -v211
	v_cmp_gt_f32_e64 s[0:1], s54, v213
	v_fma_f32 v229, v194, v103, v193
	v_sub_f32_e32 v230, 1.0, v103
	v_add_f32_e32 v103, 1.0, v179
	v_mul_f32_e32 v88, v194, v215
	v_mul_f32_e32 v215, 0x3f317217, v104
	v_log_f32_e32 v228, v87
	v_cndmask_b32_e64 v87, 0, 32, s[0:1]
	v_fmac_f32_e32 v210, 0x3f317217, v110
	v_fmac_f32_e32 v211, 0x3377d1cf, v106
	v_cndmask_b32_e64 v231, 0, v225, s[0:1]
	v_max_f32_e32 v229, 0xda24260, v229
	v_rcp_f32_e32 v99, v99
	v_cmp_lt_f32_e64 vcc, |v110|, s57
	v_fma_f32 v179, v104, s56, -v215
	v_mul_f32_e32 v215, 0x3f317217, v180
	v_ldexp_f32 v213, v213, v87
	v_cndmask_b32_e32 v110, v110, v210, vcc
	v_fmac_f32_e32 v211, 0x3f317217, v106
	v_cmp_lt_f32_e64 s[0:1], |v106|, s57
	v_cmp_gt_f32_e64 s[18:19], s54, v229
	v_fma_f32 v232, v194, v99, v193
	v_mul_f32_e32 v87, v194, v230
	v_fmac_f32_e32 v179, 0x3377d1cf, v104
	v_fma_f32 v113, v180, s56, -v215
	v_mul_f32_e32 v210, 0x3f317217, v212
	v_log_f32_e32 v213, v213
	v_cndmask_b32_e64 v215, 0, 32, s[18:19]
	v_sub_f32_e32 v233, 1.0, v99
	v_add_f32_e32 v99, 1.0, v207
	v_cndmask_b32_e64 v106, v106, v211, s[0:1]
	v_max_f32_e32 v211, 0xda24260, v232
	v_sub_f32_e32 v105, v110, v105
	v_fmac_f32_e32 v179, 0x3f317217, v104
	v_cmp_lt_f32_e64 vcc, |v104|, s57
	v_fmac_f32_e32 v113, 0x3377d1cf, v180
	v_fma_f32 v110, v212, s56, -v210
	v_ldexp_f32 v207, v229, v215
	v_cndmask_b32_e64 v210, 0, v225, s[18:19]
	v_rcp_f32_e32 v111, v96
	v_cmp_gt_f32_e64 s[18:19], s54, v211
	v_add_f32_e32 v61, v61, v105
	v_sub_f32_e32 v100, v106, v100
	v_cndmask_b32_e32 v104, v104, v179, vcc
	v_fmac_f32_e32 v113, 0x3f317217, v180
	v_cmp_lt_f32_e64 s[0:1], |v180|, s57
	v_fmac_f32_e32 v110, 0x3377d1cf, v212
	v_mul_f32_e32 v105, 0x3f317217, v228
	v_log_f32_e32 v106, v207
	v_cndmask_b32_e64 v179, 0, 32, s[18:19]
	v_fma_f32 v207, v194, v111, v193
	v_sub_f32_e32 v111, 1.0, v111
	v_min_f32_e64 v229, -v61, s60
	v_max_f32_e32 v230, 0xc2a00000, v61
	v_add_f32_e32 v100, v61, v100
	v_sub_f32_e32 v97, v104, v97
	v_cndmask_b32_e64 v104, v180, v113, s[0:1]
	v_fmac_f32_e32 v110, 0x3f317217, v212
	v_cmp_lt_f32_e64 vcc, |v212|, s57
	v_fma_f32 v105, v228, s56, -v105
	v_ldexp_f32 v113, v211, v179
	v_mul_f32_e32 v61, v194, v111
	v_max_f32_e32 v111, 0xda24260, v207
	v_rcp_f32_e32 v93, v93
	v_min_f32_e64 v180, -v100, s60
	v_max_f32_e32 v207, 0xc2a00000, v100
	v_add_f32_e32 v97, v100, v97
	v_sub_f32_e32 v100, v104, v188
	v_cndmask_b32_e32 v104, v212, v110, vcc
	v_fmac_f32_e32 v105, 0x3377d1cf, v228
; __device__ __forceinline__ bf16_t f2bf(float f) { return (bf16_t)(cvt_pk_bf16(f, 0.f) & 0xffffu); }
; __device__ __forceinline__ float bf2f(bf16_t b) { return __uint_as_float(((unsigned)b) << 16); }
; __device__ __forceinline__ float sigmoidf_(float x) { return 1.0f / (1.0f + __expf(-x)); }
; template <int MODE>
; __device__ __forceinline__ void hgrn_mfma(const Ctx& C, int l, int z, int b, int hd, int c, f32x4 (&Sacc)[4][4], float& dectot, unsigned char* wl, float lb) {
;     ...
;             for (int t = 0; t < 16; ++t) {
;                 const float fl = bf2f(fv[t]);
;                 const float sg = sigmoidf_(fl);
;                 const float f = lb + (1.0f - lb) * sg, kk = (1.0f - lb) * (1.0f - sg);
;                 bacc += __logf(fmaxf(f, 1e-30f));
;                 Kb[(g8 * 16 + t) * HPT + lane] = f2bf(kk * __expf(fminf(-bacc, 80.f)));
;                 if (MODE != 0) Qt[(g8 * 16 + t) * HPT + lane] = f2bf(bf2f(qv[t]) * __expf(fmaxf(bacc, -80.f)));
;                 Vv[(g8 * 16 + t) * HPT + lane] = vv[t];
	v_mul_f32_e32 v110, 0x3f317217, v213
	v_log_f32_e32 v113, v113
	v_cmp_gt_f32_e64 s[0:1], s54, v111
	v_mul_f32_e32 v98, 0x3fb8aa3b, v229
	v_mul_f32_e32 v112, 0x3fb8aa3b, v230
	v_cndmask_b32_e64 v188, 0, 32, s[0:1]
	v_fma_f32 v211, v194, v93, v193
	v_mul_f32_e32 v207, 0x3fb8aa3b, v207
	v_min_f32_e64 v212, -v97, s60
	v_max_f32_e32 v214, 0xc2a00000, v97
	v_add_f32_e32 v97, v97, v100
	v_sub_f32_e32 v100, v104, v189
	v_fmac_f32_e32 v105, 0x3f317217, v228
	v_cmp_lt_f32_e64 vcc, |v228|, s57
	v_fma_f32 v104, v213, s56, -v110
	v_exp_f32_e32 v98, v98
	v_exp_f32_e32 v112, v112
	v_mul_f32_e32 v180, 0x3fb8aa3b, v180
	v_ldexp_f32 v110, v111, v188
	v_max_f32_e32 v188, 0xda24260, v211
	v_rcp_f32_e32 v89, v89
	v_exp_f32_e32 v181, v207
	v_min_f32_e64 v207, -v97, s60
	v_max_f32_e32 v211, 0xc2a00000, v97
	v_add_f32_e32 v97, v97, v100
	v_cndmask_b32_e32 v100, v228, v105, vcc
	v_fmac_f32_e32 v104, 0x3377d1cf, v213
	v_mul_f32_e32 v105, 0x3f317217, v106
	v_cndmask_b32_e64 v111, 0, v225, s[0:1]
	v_exp_f32_e32 v180, v180
	v_mul_f32_e32 v191, 0x3fb8aa3b, v212
	v_mul_f32_e32 v206, 0x3fb8aa3b, v214
	v_cmp_gt_f32_e64 s[0:1], s54, v188
	v_fma_f32 v214, v194, v89, v193
	v_sub_f32_e32 v100, v100, v223
	v_fmac_f32_e32 v104, 0x3f317217, v213
	v_cmp_lt_f32_e64 vcc, |v213|, s57
	v_fma_f32 v105, v106, s56, -v105
	v_log_f32_e32 v110, v110
	v_cndmask_b32_e64 v212, 0, 32, s[0:1]
	v_exp_f32_e32 v191, v191
	v_exp_f32_e32 v205, v206
	v_mul_f32_e32 v206, 0x3fb8aa3b, v207
	v_mul_f32_e32 v207, 0x3fb8aa3b, v211
	v_min_f32_e64 v211, -v97, s60
	v_max_f32_e32 v228, 0xc2a00000, v97
	v_max_f32_e32 v214, 0xda24260, v214
	v_rcp_f32_e32 v94, v208
	v_add_f32_e32 v97, v97, v100
	v_cndmask_b32_e32 v100, v213, v104, vcc
	v_fmac_f32_e32 v105, 0x3377d1cf, v106
	v_mul_f32_e32 v104, 0x3f317217, v113
	v_ldexp_f32 v188, v188, v212
	v_cndmask_b32_e64 v212, 0, v225, s[0:1]
	v_exp_f32_e32 v189, v206
	v_exp_f32_e32 v206, v207
	v_mul_f32_e32 v207, 0x3fb8aa3b, v211
	v_mul_f32_e32 v208, 0x3fb8aa3b, v228
	v_cmp_gt_f32_e64 s[0:1], s54, v214
	v_fma_f32 v213, v194, v94, v193
	v_sub_f32_e32 v94, 1.0, v94
	v_sub_f32_e32 v100, v100, v231
	v_fmac_f32_e32 v105, 0x3f317217, v106
	v_cmp_lt_f32_e64 vcc, |v106|, s57
	v_fma_f32 v104, v113, s56, -v104
	v_log_f32_e32 v188, v188
	v_cndmask_b32_e64 v211, 0, 32, s[0:1]
	v_mul_f32_e32 v86, v86, v98
	v_mul_f32_e32 v98, v112, v81
	v_exp_f32_e32 v112, v207
	v_exp_f32_e32 v190, v208
	v_min_f32_e64 v207, -v97, s60
	v_max_f32_e32 v208, 0xc2a00000, v97
	v_mul_f32_e32 v81, v194, v94
	v_max_f32_e32 v94, 0xda24260, v213
	v_rcp_f32_e32 v95, v107
	v_add_f32_e32 v97, v97, v100
	v_cndmask_b32_e32 v100, v106, v105, vcc
	v_fmac_f32_e32 v104, 0x3377d1cf, v113
	v_ldexp_f32 v209, v214, v211
	v_cndmask_b32_e64 v211, 0, v225, s[0:1]
	v_cvt_pk_bf16_f32 v86, v86, s0
	v_cvt_pk_bf16_f32 v98, v98, s0
	v_mul_f32_e32 v84, v84, v180
	v_mul_f32_e32 v80, v181, v80
	v_mul_f32_e32 v109, 0x3fb8aa3b, v207
	v_mul_f32_e32 v180, 0x3fb8aa3b, v208
	v_cmp_gt_f32_e64 s[0:1], s54, v94
	v_fma_f32 v207, v194, v95, v193
	v_sub_f32_e32 v95, 1.0, v95
	v_sub_f32_e32 v100, v100, v210
	v_fmac_f32_e32 v104, 0x3f317217, v113
	v_cmp_lt_f32_e64 vcc, |v113|, s57
	v_mul_f32_e32 v105, 0x3f317217, v110
	v_log_f32_e32 v106, v209
	v_cndmask_b32_e64 v181, 0, 32, s[0:1]
	ds_write_b16 v60, v86 offset:4608
	ds_write_b16 v60, v98
	v_cvt_pk_bf16_f32 v84, v84, s0
	v_cvt_pk_bf16_f32 v86, v80, s0
	v_mul_f32_e32 v85, v85, v191
	v_mul_f32_e32 v90, v205, v90
	v_exp_f32_e32 v98, v109
	v_exp_f32_e32 v107, v180
	v_min_f32_e64 v108, -v97, s60
	v_max_f32_e32 v109, 0xc2a00000, v97
	v_mul_f32_e32 v80, v194, v95
	v_max_f32_e32 v95, 0xda24260, v207
	v_rcp_f32_e32 v102, v103
	v_add_f32_e32 v97, v97, v100
	v_cndmask_b32_e32 v100, v113, v104, vcc
	v_cndmask_b32_e64 v179, 0, v225, s[18:19]
	v_fma_f32 v105, v110, s56, -v105
	v_ldexp_f32 v94, v94, v181
	v_cndmask_b32_e64 v180, 0, v225, s[0:1]
	ds_write_b16 v60, v84 offset:4752
	ds_write_b16 v60, v86 offset:144
	v_cvt_pk_bf16_f32 v84, v85, s0
	v_cvt_pk_bf16_f32 v85, v90, s0
	v_mul_f32_e32 v82, v82, v189
	v_mul_f32_e32 v78, v206, v78
	v_mul_f32_e32 v86, 0x3fb8aa3b, v108
	v_cmp_gt_f32_e64 s[0:1], s54, v95
	v_fma_f32 v104, v194, v102, v193
	v_mul_f32_e32 v90, 0x3fb8aa3b, v109
	v_fmac_f32_e32 v105, 0x3377d1cf, v110
	v_mul_f32_e32 v101, 0x3f317217, v188
	v_log_f32_e32 v94, v94
	v_cndmask_b32_e64 v103, 0, 32, s[0:1]
	ds_write_b16 v60, v84 offset:4896
	ds_write_b16 v60, v85 offset:288
	v_cvt_pk_bf16_f32 v82, v82, s0
	v_cvt_pk_bf16_f32 v78, v78, s0
	v_mul_f32_e32 v83, v83, v112
	v_mul_f32_e32 v77, v190, v77
	v_exp_f32_e32 v84, v86
	v_min_f32_e64 v86, -v97, s60
	v_sub_f32_e32 v100, v100, v179
	v_max_f32_e32 v104, 0xda24260, v104
	v_rcp_f32_e32 v96, v99
	s_and_b64 vcc, exec, s[4:5]
	v_exp_f32_e32 v85, v90
	v_max_f32_e32 v90, 0xc2a00000, v97
	v_fmac_f32_e32 v105, 0x3f317217, v110
	v_cmp_lt_f32_e64 s[4:5], |v110|, s57
	v_fma_f32 v101, v188, s56, -v101
	v_ldexp_f32 v95, v95, v103
	v_cndmask_b32_e64 v103, 0, v225, s[0:1]
	ds_write_b16 v60, v82 offset:5040
	ds_write_b16 v60, v78 offset:432
	v_cvt_pk_bf16_f32 v78, v83, s0
	v_cvt_pk_bf16_f32 v77, v77, s0
	v_mul_f32_e32 v82, 0x3fb8aa3b, v86
	v_add_f32_e32 v86, v97, v100
	v_cmp_gt_f32_e64 s[0:1], s54, v104
	v_fma_f32 v100, v194, v96, v193
	v_mul_f32_e32 v83, 0x3fb8aa3b, v90
	v_cndmask_b32_e64 v90, v110, v105, s[4:5]
	v_fmac_f32_e32 v101, 0x3377d1cf, v188
	v_mul_f32_e32 v97, 0x3f317217, v106
	v_log_f32_e32 v95, v95
	v_cndmask_b32_e64 v99, 0, 32, s[0:1]
	ds_write_b16 v60, v78 offset:5184
	ds_write_b16 v60, v77 offset:576
	v_mul_f32_e32 v77, v92, v98
	v_mul_f32_e32 v76, v107, v76
	v_max_f32_e32 v100, 0xda24260, v100
	v_exp_f32_e32 v78, v82
	v_exp_f32_e32 v82, v83
	v_min_f32_e64 v83, -v86, s60
; __device__ __forceinline__ bf16_t f2bf(float f) { return (bf16_t)(cvt_pk_bf16(f, 0.f) & 0xffffu); }
; __device__ __forceinline__ float bf2f(bf16_t b) { return __uint_as_float(((unsigned)b) << 16); }
; __device__ __forceinline__ float sigmoidf_(float x) { return 1.0f / (1.0f + __expf(-x)); }
; template <int MODE>
; __device__ __forceinline__ void hgrn_mfma(const Ctx& C, int l, int z, int b, int hd, int c, f32x4 (&Sacc)[4][4], float& dectot, unsigned char* wl, float lb) {
;     ...
;             for (int t = 0; t < 16; ++t) {
;                 const float fl = bf2f(fv[t]);
;                 const float sg = sigmoidf_(fl);
;                 const float f = lb + (1.0f - lb) * sg, kk = (1.0f - lb) * (1.0f - sg);
;                 bacc += __logf(fmaxf(f, 1e-30f));
;                 Kb[(g8 * 16 + t) * HPT + lane] = f2bf(kk * __expf(fminf(-bacc, 80.f)));
;                 if (MODE != 0) Qt[(g8 * 16 + t) * HPT + lane] = f2bf(bf2f(qv[t]) * __expf(fmaxf(bacc, -80.f)));
;                 Vv[(g8 * 16 + t) * HPT + lane] = vv[t];
;             }
	v_max_f32_e32 v92, 0xc2a00000, v86
	v_sub_f32_e32 v90, v90, v111
	v_fmac_f32_e32 v101, 0x3f317217, v188
	v_cmp_lt_f32_e64 s[4:5], |v188|, s57
	v_fma_f32 v97, v106, s56, -v97
	v_ldexp_f32 v98, v104, v99
	v_cndmask_b32_e64 v99, 0, v225, s[0:1]
	v_cvt_pk_bf16_f32 v77, v77, s0
	v_cvt_pk_bf16_f32 v76, v76, s0
	v_cmp_gt_f32_e64 s[0:1], s54, v100
	v_mul_f32_e32 v83, 0x3fb8aa3b, v83
	v_mul_f32_e32 v92, 0x3fb8aa3b, v92
	v_add_f32_e32 v86, v86, v90
	v_cndmask_b32_e64 v90, v188, v101, s[4:5]
	v_fmac_f32_e32 v97, 0x3377d1cf, v106
	v_mul_f32_e32 v101, 0x3f317217, v94
	v_log_f32_e32 v98, v98
	v_cndmask_b32_e64 v104, 0, 32, s[0:1]
	ds_write_b16 v60, v77 offset:5328
	ds_write_b16 v60, v76 offset:720
	v_mul_f32_e32 v76, v88, v84
	v_mul_f32_e32 v75, v85, v75
	v_exp_f32_e32 v77, v83
	v_exp_f32_e32 v83, v92
	v_min_f32_e64 v84, -v86, s60
	v_max_f32_e32 v85, 0xc2a00000, v86
	v_sub_f32_e32 v88, v90, v212
	v_fmac_f32_e32 v97, 0x3f317217, v106
	v_cmp_lt_f32_e64 s[4:5], |v106|, s57
	v_fma_f32 v90, v94, s56, -v101
	v_ldexp_f32 v92, v100, v104
	v_cvt_pk_bf16_f32 v76, v76, s0
	v_cvt_pk_bf16_f32 v75, v75, s0
	v_mul_f32_e32 v84, 0x3fb8aa3b, v84
	v_mul_f32_e32 v85, 0x3fb8aa3b, v85
	v_add_f32_e32 v86, v86, v88
	v_cndmask_b32_e64 v88, v106, v97, s[4:5]
	v_fmac_f32_e32 v90, 0x3377d1cf, v94
	v_mul_f32_e32 v97, 0x3f317217, v95
	v_log_f32_e32 v92, v92
	v_cndmask_b32_e64 v100, 0, v225, s[0:1]
	ds_write_b16 v60, v76 offset:5472
	ds_write_b16 v60, v75 offset:864
	v_mul_f32_e32 v75, v87, v78
	v_mul_f32_e32 v74, v82, v74
	v_exp_f32_e32 v76, v84
	v_exp_f32_e32 v78, v85
	v_min_f32_e64 v82, -v86, s60
	v_max_f32_e32 v84, 0xc2a00000, v86
	v_sub_f32_e32 v85, v88, v211
	v_fmac_f32_e32 v90, 0x3f317217, v94
	v_cmp_lt_f32_e64 s[0:1], |v94|, s57
	v_fma_f32 v87, v95, s56, -v97
	v_mul_f32_e32 v91, v194, v233
	v_cvt_pk_bf16_f32 v75, v75, s0
	v_cvt_pk_bf16_f32 v74, v74, s0
	v_mul_f32_e32 v82, 0x3fb8aa3b, v82
	v_mul_f32_e32 v84, 0x3fb8aa3b, v84
	v_add_f32_e32 v85, v86, v85
	v_cndmask_b32_e64 v86, v94, v90, s[0:1]
	v_fmac_f32_e32 v87, 0x3377d1cf, v95
	v_mul_f32_e32 v88, 0x3f317217, v98
	ds_write_b16 v60, v75 offset:5616
	ds_write_b16 v60, v74 offset:1008
	v_mul_f32_e32 v74, v91, v77
	v_mul_f32_e32 v73, v83, v73
	v_exp_f32_e32 v75, v82
	v_exp_f32_e32 v77, v84
	v_min_f32_e64 v82, -v85, s60
	v_max_f32_e32 v83, 0xc2a00000, v85
	v_sub_f32_e32 v84, v86, v180
	v_fmac_f32_e32 v87, 0x3f317217, v95
	v_cmp_lt_f32_e64 s[0:1], |v95|, s57
	v_fma_f32 v86, v98, s56, -v88
	v_mul_f32_e32 v82, 0x3fb8aa3b, v82
	v_cvt_pk_bf16_f32 v74, v74, s0
	v_cvt_pk_bf16_f32 v73, v73, s0
	v_mul_f32_e32 v83, 0x3fb8aa3b, v83
	v_add_f32_e32 v84, v85, v84
	v_cndmask_b32_e64 v85, v95, v87, s[0:1]
	v_fmac_f32_e32 v86, 0x3377d1cf, v98
	v_mul_f32_e32 v87, 0x3f317217, v92
	v_sub_f32_e32 v93, 1.0, v93
	ds_write_b16 v60, v74 offset:5760
	ds_write_b16 v60, v73 offset:1152
	v_mul_f32_e32 v61, v61, v76
	v_mul_f32_e32 v72, v78, v72
	v_exp_f32_e32 v73, v82
	v_exp_f32_e32 v74, v83
	v_min_f32_e64 v76, -v84, s60
	v_max_f32_e32 v78, 0xc2a00000, v84
	v_sub_f32_e32 v82, v85, v103
	v_fmac_f32_e32 v86, 0x3f317217, v98
	v_cmp_lt_f32_e64 s[0:1], |v98|, s57
	v_fma_f32 v83, v92, s56, -v87
	v_mul_f32_e32 v93, v194, v93
	v_cvt_pk_bf16_f32 v61, v61, s0
	v_cvt_pk_bf16_f32 v72, v72, s0
	v_mul_f32_e32 v76, 0x3fb8aa3b, v76
	v_mul_f32_e32 v78, 0x3fb8aa3b, v78
	v_add_f32_e32 v82, v84, v82
	v_cndmask_b32_e64 v84, v98, v86, s[0:1]
	v_fmac_f32_e32 v83, 0x3377d1cf, v92
	v_sub_f32_e32 v89, 1.0, v89
	ds_write_b16 v60, v61 offset:5904
	ds_write_b16 v60, v72 offset:1296
	v_mul_f32_e32 v61, v93, v75
	v_mul_f32_e32 v71, v77, v71
	v_exp_f32_e32 v72, v76
	v_exp_f32_e32 v75, v78
	v_min_f32_e64 v76, -v82, s60
	v_max_f32_e32 v77, 0xc2a00000, v82
	v_sub_f32_e32 v78, v84, v99
	v_fmac_f32_e32 v83, 0x3f317217, v92
	v_cmp_lt_f32_e64 s[0:1], |v92|, s57
	v_mul_f32_e32 v89, v194, v89
	v_mul_f32_e32 v76, 0x3fb8aa3b, v76
	v_cvt_pk_bf16_f32 v61, v61, s0
	v_cvt_pk_bf16_f32 v71, v71, s0
	v_mul_f32_e32 v77, 0x3fb8aa3b, v77
	v_add_f32_e32 v78, v82, v78
	v_cndmask_b32_e64 v82, v92, v83, s[0:1]
	ds_write_b16 v60, v61 offset:6048
	ds_write_b16 v60, v71 offset:1440
	v_mul_f32_e32 v61, v89, v73
	v_mul_f32_e32 v62, v74, v62
	v_exp_f32_e32 v71, v76
	v_exp_f32_e32 v73, v77
	v_min_f32_e64 v74, -v78, s60
	v_sub_f32_e32 v77, v82, v100
	v_max_f32_e32 v76, 0xc2a00000, v78
	v_cvt_pk_bf16_f32 v82, v61, s0
	v_cvt_pk_bf16_f32 v62, v62, s0
	v_mul_f32_e32 v74, 0x3fb8aa3b, v74
	v_add_f32_e32 v61, v78, v77
	v_mul_f32_e32 v76, 0x3fb8aa3b, v76
	ds_write_b16 v60, v82 offset:6192
	ds_write_b16 v60, v62 offset:1584
	v_mul_f32_e32 v62, v81, v72
	v_mul_f32_e32 v63, v75, v63
	v_exp_f32_e32 v72, v74
	v_min_f32_e64 v75, -v61, s60
	v_exp_f32_e32 v74, v76
	v_max_f32_e32 v76, 0xc2a00000, v61
	v_cvt_pk_bf16_f32 v62, v62, s0
	v_cvt_pk_bf16_f32 v63, v63, s0
	v_mul_f32_e32 v75, 0x3fb8aa3b, v75
	v_sub_f32_e32 v102, 1.0, v102
	v_mul_f32_e32 v76, 0x3fb8aa3b, v76
	ds_write_b16 v60, v62 offset:6336
	ds_write_b16 v60, v63 offset:1728
	v_mul_f32_e32 v62, v80, v71
	v_mul_f32_e32 v63, v73, v64
	v_exp_f32_e32 v64, v75
	v_mul_f32_e32 v102, v194, v102
	v_exp_f32_e32 v71, v76
	v_cvt_pk_bf16_f32 v62, v62, s0
	v_sub_f32_e32 v96, 1.0, v96
	v_cvt_pk_bf16_f32 v63, v63, s0
	ds_write_b16 v60, v62 offset:6480
	ds_write_b16 v60, v63 offset:1872
	v_mul_f32_e32 v62, v102, v72
	v_mul_f32_e32 v96, v194, v96
	v_mul_f32_e32 v63, v74, v70
	v_cvt_pk_bf16_f32 v62, v62, s0
	v_cvt_pk_bf16_f32 v63, v63, s0
	ds_write_b16 v60, v62 offset:6624
	ds_write_b16 v60, v63 offset:2016
	v_mul_f32_e32 v62, v96, v64
	v_mul_f32_e32 v63, v71, v79
	v_cvt_pk_bf16_f32 v62, v62, s0
	v_cvt_pk_bf16_f32 v63, v63, s0
	ds_write_b16 v60, v62 offset:6768
	ds_write_b16 v60, v63 offset:2160
	s_cbranch_vccz .LBB0_645
; template <int MODE>
; __device__ __forceinline__ void hgrn_mfma(const Ctx& C, int l, int z, int b, int hd, int c, f32x4 (&Sacc)[4][4], float& dectot, unsigned char* wl, float lb) {
;     ...
;         { const float eb = __expf(bacc); dl[lane] = eb; dectot *= eb; }
;         wave_lds_fence();
;         f32x4 Oacc[2][4];
;         if (MODE != 0) {
;             bf16x8 Sb[2][4];
; #pragma unroll
;             for (int ks = 0; ks < 2; ++ks)
; #pragma unroll
;                 for (int vt = 0; vt < 4; ++vt) { union { bf16x8 v; unsigned u[4]; } t_;
;                     t_.u[0] = cvt_pk_bf16(Sacc[2 * ks][vt][0], Sacc[2 * ks][vt][1]); t_.u[1] = cvt_pk_bf16(Sacc[2 * ks][vt][2], Sacc[2 * ks][vt][3]);
;                     t_.u[2] = cvt_pk_bf16(Sacc[2 * ks + 1][vt][0], Sacc[2 * ks + 1][vt][1]); t_.u[3] = cvt_pk_bf16(Sacc[2 * ks + 1][vt][2], Sacc[2 * ks + 1][vt][3]); Sb[ks][vt] = t_.v; }
;             float zz = 0.f; asm volatile("" : "+v"(zz));
; #pragma unroll
;             for (int tt = 0; tt < 2; ++tt)
; #pragma unroll
;                 for (int vt = 0; vt < 4; ++vt) Oacc[tt][vt] = (f32x4){zz, zz, zz, zz};
; #pragma unroll
;             for (int tt = 0; tt < 2; ++tt)
; #pragma unroll
;                 for (int ks = 0; ks < 2; ++ks) { const bf16_t* qp = Qt + (16 * tt + fr) * HPT + 32 * ks + 4 * quad;
;                     union { bf16x8 v; u32x2 h[2]; } a_; a_.h[0] = *(const u32x2*)qp; a_.h[1] = *(const u32x2*)(qp + 16);
; #pragma unroll
;                     for (int vt = 0; vt < 4; ++vt) Oacc[tt][vt] = __builtin_amdgcn_mfma_f32_16x16x32_bf16(a_.v, Sb[ks][vt], Oacc[tt][vt], 0, 0, 0); }
;             f32x4 P00 = {zz, zz, zz, zz}, P01 = {zz, zz, zz, zz}, P11 = {zz, zz, zz, zz};
; #pragma unroll
;             for (int ks = 0; ks < 2; ++ks) {
;                 const bf16x8 kA0 = *(const bf16x8*)(Kb + fr * HPT + 32 * ks + 8 * quad), kA1 = *(const bf16x8*)(Kb + (16 + fr) * HPT + 32 * ks + 8 * quad);
;                 const bf16x8 qB0 = *(const bf16x8*)(Qt + fr * HPT + 32 * ks + 8 * quad), qB1 = *(const bf16x8*)(Qt + (16 + fr) * HPT + 32 * ks + 8 * quad);
;                 P00 = __builtin_amdgcn_mfma_f32_16x16x32_bf16(kA0, qB0, P00, 0, 0, 0);
;                 P01 = __builtin_amdgcn_mfma_f32_16x16x32_bf16(kA0, qB1, P01, 0, 0, 0);
;                 P11 = __builtin_amdgcn_mfma_f32_16x16x32_bf16(kA1, qB1, P11, 0, 0, 0);
;             }
; #pragma unroll
	v_mul_f32_e32 v60, 0x3fb8aa3b, v61
	v_exp_f32_e32 v60, v60
	v_mov_b32_e32 v98, v65
	v_cvt_pk_bf16_f32 v61, v2, v3
	v_cvt_pk_bf16_f32 v62, v16, v17
	ds_write_b32 v119, v60 offset:13824
	s_waitcnt lgkmcnt(0)
	ds_read2_b64 v[102:105], v126 offset1:4
	ds_read2_b64 v[188:191], v126 offset0:8 offset1:12
	v_cvt_pk_bf16_f32 v60, v0, v1
	v_cvt_pk_bf16_f32 v63, v18, v19
	v_cvt_pk_bf16_f32 v70, v4, v5
	v_cvt_pk_bf16_f32 v71, v6, v7
	v_cvt_pk_bf16_f32 v72, v20, v21
	v_cvt_pk_bf16_f32 v73, v22, v23
	v_cvt_pk_bf16_f32 v78, v8, v9
	v_cvt_pk_bf16_f32 v79, v10, v11
	v_cvt_pk_bf16_f32 v80, v24, v25
	v_cvt_pk_bf16_f32 v81, v26, v27
	v_cvt_pk_bf16_f32 v86, v12, v13
	v_cvt_pk_bf16_f32 v87, v14, v15
	v_cvt_pk_bf16_f32 v88, v28, v29
	v_cvt_pk_bf16_f32 v89, v30, v31
	v_mov_b32_e32 v99, v98
	v_mov_b32_e32 v100, v98
	v_mov_b32_e32 v101, v98
	v_cvt_pk_bf16_f32 v74, v32, v33
	v_cvt_pk_bf16_f32 v75, v34, v35
	s_waitcnt lgkmcnt(1)
	v_mfma_f32_16x16x32_bf16 v[106:109], v[102:105], v[60:63], v[98:101]
	v_cvt_pk_bf16_f32 v76, v48, v49
	v_cvt_pk_bf16_f32 v77, v50, v51
	v_cvt_pk_bf16_f32 v82, v36, v37
	v_mfma_f32_16x16x32_bf16 v[110:113], v[102:105], v[70:73], v[98:101]
	v_cvt_pk_bf16_f32 v83, v38, v39
	v_cvt_pk_bf16_f32 v84, v66, v67
	v_cvt_pk_bf16_f32 v85, v68, v69
	v_mfma_f32_16x16x32_bf16 v[178:181], v[102:105], v[78:81], v[98:101]
	v_cvt_pk_bf16_f32 v90, v40, v41
	v_cvt_pk_bf16_f32 v91, v42, v43
	v_cvt_pk_bf16_f32 v92, v56, v57
	v_mfma_f32_16x16x32_bf16 v[102:105], v[102:105], v[86:89], v[98:101]
	v_cvt_pk_bf16_f32 v93, v58, v59
	v_cvt_pk_bf16_f32 v94, v44, v45
	v_cvt_pk_bf16_f32 v95, v46, v47
	v_cvt_pk_bf16_f32 v96, v52, v53
	v_cvt_pk_bf16_f32 v97, v54, v55
	v_add_u32_e32 v64, 0x800, v126
	s_waitcnt lgkmcnt(0)
	v_mfma_f32_16x16x32_bf16 v[106:109], v[188:191], v[74:77], v[106:109]
	s_add_i32 s72, s72, 1
	s_cmp_eq_u32 s72, 4
	v_mfma_f32_16x16x32_bf16 v[110:113], v[188:191], v[82:85], v[110:113]
	v_mfma_f32_16x16x32_bf16 v[178:181], v[188:191], v[90:93], v[178:181]
	v_mfma_f32_16x16x32_bf16 v[102:105], v[188:191], v[94:97], v[102:105]
	ds_read2_b64 v[188:191], v64 offset0:32 offset1:36
	s_waitcnt lgkmcnt(0)
	v_mfma_f32_16x16x32_bf16 v[60:63], v[188:191], v[60:63], v[98:101]
	v_mfma_f32_16x16x32_bf16 v[70:73], v[188:191], v[70:73], v[98:101]
	v_mfma_f32_16x16x32_bf16 v[78:81], v[188:191], v[78:81], v[98:101]
	v_mfma_f32_16x16x32_bf16 v[86:89], v[188:191], v[86:89], v[98:101]
	ds_read2_b64 v[188:191], v64 offset0:40 offset1:44
	s_waitcnt lgkmcnt(0)
	v_mfma_f32_16x16x32_bf16 v[74:77], v[188:191], v[74:77], v[60:63]
	v_mfma_f32_16x16x32_bf16 v[206:209], v[188:191], v[82:85], v[70:73]
	v_mfma_f32_16x16x32_bf16 v[78:81], v[188:191], v[90:93], v[78:81]
	v_mfma_f32_16x16x32_bf16 v[188:191], v[188:191], v[94:97], v[86:89]
	ds_read_b128 v[60:63], v123 offset:4608
	ds_read_b128 v[70:73], v123 offset:6912
	ds_read_b128 v[82:85], v123
	ds_read_b128 v[86:89], v123 offset:2304
	ds_read_b128 v[90:93], v123 offset:4672
	ds_read_b128 v[94:97], v123 offset:6976
	ds_read_b128 v[210:213], v123 offset:64
	ds_read_b128 v[228:231], v123 offset:2368
	s_waitcnt lgkmcnt(5)
	v_mfma_f32_16x16x32_bf16 v[82:85], v[60:63], v[82:85], v[98:101]
	s_waitcnt lgkmcnt(4)
	v_mfma_f32_16x16x32_bf16 v[70:73], v[70:73], v[86:89], v[98:101]
	s_waitcnt lgkmcnt(1)
	v_mfma_f32_16x16x32_bf16 v[82:85], v[90:93], v[210:213], v[82:85]
	s_waitcnt lgkmcnt(0)
	v_mfma_f32_16x16x32_bf16 v[70:73], v[94:97], v[228:231], v[70:73]
	v_mfma_f32_16x16x32_bf16 v[60:63], v[60:63], v[86:89], v[98:101]
	s_nop 4
	v_cndmask_b32_e64 v64, v85, 0, s[42:43]
	s_nop 0
	v_cndmask_b32_e64 v85, v73, 0, s[42:43]
	v_cndmask_b32_e64 v94, v72, 0, s[20:21]
	v_cndmask_b32_e64 v95, v71, 0, s[38:39]
	v_cndmask_b32_e64 v96, v70, 0, s[44:45]
	v_mfma_f32_16x16x32_bf16 v[70:73], v[90:93], v[228:231], v[60:63]
	v_cndmask_b32_e64 v84, v84, 0, s[20:21]
	v_cndmask_b32_e64 v83, v83, 0, s[38:39]
	v_cndmask_b32_e64 v82, v82, 0, s[44:45]
	v_cvt_pk_bf16_f32 v62, v82, v83
	v_cvt_pk_bf16_f32 v63, v84, v64
	v_mov_b32_e32 v64, v65
	s_nop 1
	v_cvt_pk_bf16_f32 v98, v70, v71
	v_cvt_pk_bf16_f32 v99, v72, v73
	ds_read_b64_tr_b16 v[72:73], v124 offset:11520
	ds_read_b64_tr_b16 v[70:71], v124 offset:9216
	ds_read_b64_tr_b16 v[90:91], v124 offset:9248
	v_cvt_pk_bf16_f32 v100, v96, v95
	v_cvt_pk_bf16_f32 v101, v94, v85
	s_waitcnt lgkmcnt(1)
	v_mfma_f32_16x16x32_bf16 v[82:85], v[62:65], v[70:73], v[106:109]
	ds_read_b64_tr_b16 v[92:93], v124 offset:11552
	ds_read_b64_tr_b16 v[94:95], v124 offset:9280
	ds_read_b64_tr_b16 v[96:97], v124 offset:11584
	ds_read_b64_tr_b16 v[106:107], v124 offset:9312
	ds_read_b64_tr_b16 v[108:109], v124 offset:11616
	v_mfma_f32_16x16x32_bf16 v[70:73], v[98:101], v[70:73], v[74:77]
	s_waitcnt lgkmcnt(4)
	v_mfma_f32_16x16x32_bf16 v[86:89], v[62:65], v[90:93], v[110:113]
	v_mfma_f32_16x16x32_bf16 v[74:77], v[98:101], v[90:93], v[206:209]
	s_waitcnt lgkmcnt(2)
	v_mfma_f32_16x16x32_bf16 v[90:93], v[62:65], v[94:97], v[178:181]
	v_mfma_f32_16x16x32_bf16 v[78:81], v[98:101], v[94:97], v[78:81]
	s_waitcnt lgkmcnt(0)
	v_mfma_f32_16x16x32_bf16 v[94:97], v[62:65], v[106:109], v[102:105]
	v_add_u32_e32 v64, v122, v121
	v_mfma_f32_16x16x32_bf16 v[60:63], v[98:101], v[106:109], v[188:191]
	ds_read_b64_tr_b16 v[110:111], v125 offset:9216
	ds_read_b64_tr_b16 v[112:113], v125 offset:9792
	ds_read_b64_tr_b16 v[106:107], v125 offset:9248
	ds_read_b64_tr_b16 v[108:109], v125 offset:9824
	ds_read_b64_tr_b16 v[102:103], v125 offset:9280
	ds_read_b64_tr_b16 v[104:105], v125 offset:9856
	ds_read_b64_tr_b16 v[98:99], v125 offset:9312
	ds_read_b64_tr_b16 v[100:101], v125 offset:9888
	ds_read_b64_tr_b16 v[180:181], v125 offset:5184
	ds_read_b64_tr_b16 v[178:179], v125 offset:4608
	ds_read_b64_tr_b16 v[188:189], v125 offset:4640
	ds_read_b128 v[206:209], v64 offset:13824
	v_cvt_pk_bf16_f32 v60, v60, s0
	s_waitcnt lgkmcnt(2)
; __device__ __forceinline__ bf16_t f2bf(float f) { return (bf16_t)(cvt_pk_bf16(f, 0.f) & 0xffffu); }
; template <int MODE>
; __device__ __forceinline__ void hgrn_mfma(const Ctx& C, int l, int z, int b, int hd, int c, f32x4 (&Sacc)[4][4], float& dectot, unsigned char* wl, float lb) {
;     ...
;             bf16x8 vB[4];
; #pragma unroll
;             for (int vt = 0; vt < 4; ++vt) { const bf16_t* vp = Vv + (8 * quad + (fr >> 2)) * HPT + 16 * vt + 4 * (fr & 3);
;                 union { bf16x8 v; s16x4 h[2]; } vb; vb.h[0] = lds_tr(vp); vb.h[1] = lds_tr(vp + 4 * HPT); vB[vt] = vb.v; }
; #pragma unroll
;             for (int kt = 0; kt < 4; ++kt) { const bf16_t* kp = Kb + (8 * quad + (fr >> 2)) * HPT + 16 * kt + 4 * (fr & 3);
;                 union { bf16x8 v; s16x4 h[2]; } ka; ka.h[0] = lds_tr(kp); ka.h[1] = lds_tr(kp + 4 * HPT);
;                 const f32x4 d4 = *(const f32x4*)(dl + 16 * kt + 4 * quad);
; #pragma unroll
;                 for (int vt = 0; vt < 4; ++vt) { Sacc[kt][vt] = __builtin_amdgcn_mfma_f32_16x16x32_bf16(ka.v, vB[vt], Sacc[kt][vt], 0, 0, 0); Sacc[kt][vt] *= d4; } }
;         }
;         if (MODE == 1) {
; #pragma unroll
;             for (int tt = 0; tt < 2; ++tt)
; #pragma unroll
;                 for (int r = 0; r < 4; ++r) { const int st = c * 128 + sc * 32 + 16 * tt + 4 * quad + r; const int tq = z ? 4095 - st : st;
;                     bf16_t* yp = ya + (size_t)(b * SEQ + tq) * 256 + hd * 64 + fr;
; #pragma unroll
;                     for (int vt = 0; vt < 4; ++vt) yp[16 * vt] = f2bf(Oacc[tt][vt][r]); }
	v_mfma_f32_16x16x32_bf16 v[0:3], v[178:181], v[110:113], v[0:3]
	v_cvt_pk_bf16_f32 v62, v62, s0
	v_mfma_f32_16x16x32_bf16 v[4:7], v[178:181], v[106:109], v[4:7]
	v_mfma_f32_16x16x32_bf16 v[8:11], v[178:181], v[102:105], v[8:11]
	s_waitcnt lgkmcnt(0)
	s_nop 3
	v_pk_mul_f32 v[2:3], v[208:209], v[2:3]
	v_pk_mul_f32 v[0:1], v[206:207], v[0:1]
	v_pk_mul_f32 v[6:7], v[208:209], v[6:7]
	v_mfma_f32_16x16x32_bf16 v[12:15], v[178:181], v[98:101], v[12:15]
	ds_read_b64_tr_b16 v[190:191], v125 offset:5216
	ds_read_b128 v[178:181], v64 offset:13888
	v_pk_mul_f32 v[4:5], v[206:207], v[4:5]
	v_pk_mul_f32 v[10:11], v[208:209], v[10:11]
	s_waitcnt lgkmcnt(1)
	v_mfma_f32_16x16x32_bf16 v[16:19], v[188:191], v[110:113], v[16:19]
	v_mul_f32_e64 v8, v206, v8
	v_mul_f32_e64 v9, v207, v9
	v_pk_mul_f32 v[14:15], v[208:209], v[14:15]
	v_pk_mul_f32 v[12:13], v[206:207], v[12:13]
	v_mfma_f32_16x16x32_bf16 v[20:23], v[188:191], v[106:109], v[20:23]
	s_waitcnt lgkmcnt(0)
	s_nop 1
	v_pk_mul_f32 v[18:19], v[180:181], v[18:19]
	v_pk_mul_f32 v[16:17], v[178:179], v[16:17]
	v_mfma_f32_16x16x32_bf16 v[24:27], v[188:191], v[102:105], v[24:27]
	v_mfma_f32_16x16x32_bf16 v[28:31], v[188:191], v[98:101], v[28:31]
	s_nop 0
	v_mul_f32_e64 v22, v180, v22
	v_mul_f32_e64 v23, v181, v23
	v_pk_mul_f32 v[20:21], v[178:179], v[20:21]
	s_nop 2
	v_pk_mul_f32 v[26:27], v[180:181], v[26:27]
	v_pk_mul_f32 v[24:25], v[178:179], v[24:25]
	s_nop 2
	v_pk_mul_f32 v[30:31], v[180:181], v[30:31]
	v_pk_mul_f32 v[28:29], v[178:179], v[28:29]
	ds_read_b64_tr_b16 v[178:179], v125 offset:4672
	ds_read_b64_tr_b16 v[180:181], v125 offset:5248
	ds_read_b128 v[188:191], v64 offset:13952
	s_waitcnt lgkmcnt(1)
	v_mfma_f32_16x16x32_bf16 v[32:35], v[178:181], v[110:113], v[32:35]
	v_mfma_f32_16x16x32_bf16 v[36:39], v[178:181], v[106:109], v[36:39]
	s_waitcnt lgkmcnt(0)
	s_nop 5
	v_pk_mul_f32 v[34:35], v[190:191], v[34:35]
	v_pk_mul_f32 v[32:33], v[188:189], v[32:33]
	v_mfma_f32_16x16x32_bf16 v[40:43], v[178:181], v[102:105], v[40:43]
	v_mfma_f32_16x16x32_bf16 v[44:47], v[178:181], v[98:101], v[44:47]
	v_mul_f32_e64 v38, v190, v38
	v_mul_f32_e64 v39, v191, v39
	v_pk_mul_f32 v[36:37], v[188:189], v[36:37]
	s_nop 3
	v_pk_mul_f32 v[42:43], v[190:191], v[42:43]
	v_pk_mul_f32 v[40:41], v[188:189], v[40:41]
	v_pk_mul_f32 v[46:47], v[190:191], v[46:47]
	v_pk_mul_f32 v[44:45], v[188:189], v[44:45]
	ds_read_b64_tr_b16 v[178:179], v125 offset:4704
	ds_read_b64_tr_b16 v[180:181], v125 offset:5280
	ds_read_b128 v[188:191], v64 offset:14016
	s_waitcnt lgkmcnt(1)
	v_mfma_f32_16x16x32_bf16 v[52:55], v[178:181], v[98:101], v[52:55]
	v_add_u32_e32 v98, s36, v195
	v_ashrrev_i32_e32 v99, 31, v98
	v_lshlrev_b64 v[98:99], 9, v[98:99]
	v_lshl_add_u64 v[98:99], v[116:117], 0, v[98:99]
	v_cvt_pk_bf16_f32 v64, v82, s0
	global_store_short v[98:99], v64, off
	v_cvt_pk_bf16_f32 v64, v86, s0
	global_store_short v[98:99], v64, off offset:32
	v_cvt_pk_bf16_f32 v64, v90, s0
	global_store_short v[98:99], v64, off offset:64
	v_cvt_pk_bf16_f32 v64, v94, s0
	global_store_short v[98:99], v64, off offset:96
	v_add_u32_e32 v98, s36, v196
	v_ashrrev_i32_e32 v99, 31, v98
	v_lshlrev_b64 v[98:99], 9, v[98:99]
	v_lshl_add_u64 v[98:99], v[116:117], 0, v[98:99]
	v_cvt_pk_bf16_f32 v64, v83, s0
	global_store_short v[98:99], v64, off
	v_cvt_pk_bf16_f32 v64, v87, s0
	v_add_u32_e32 v82, s36, v197
	global_store_short v[98:99], v64, off offset:32
	v_cvt_pk_bf16_f32 v64, v91, s0
	v_ashrrev_i32_e32 v83, 31, v82
	global_store_short v[98:99], v64, off offset:64
	v_cvt_pk_bf16_f32 v64, v95, s0
	v_lshlrev_b64 v[82:83], 9, v[82:83]
	global_store_short v[98:99], v64, off offset:96
	v_lshl_add_u64 v[82:83], v[116:117], 0, v[82:83]
	v_cvt_pk_bf16_f32 v64, v84, s0
	global_store_short v[82:83], v64, off
	v_cvt_pk_bf16_f32 v64, v88, s0
	global_store_short v[82:83], v64, off offset:32
	v_cvt_pk_bf16_f32 v64, v92, s0
	global_store_short v[82:83], v64, off offset:64
	v_cvt_pk_bf16_f32 v64, v96, s0
	global_store_short v[82:83], v64, off offset:96
	v_add_u32_e32 v82, s36, v198
	v_ashrrev_i32_e32 v83, 31, v82
	v_lshlrev_b64 v[82:83], 9, v[82:83]
	v_lshl_add_u64 v[82:83], v[116:117], 0, v[82:83]
	v_cvt_pk_bf16_f32 v64, v85, s0
	global_store_short v[82:83], v64, off
	v_cvt_pk_bf16_f32 v64, v89, s0
	global_store_short v[82:83], v64, off offset:32
	v_cvt_pk_bf16_f32 v64, v93, s0
	global_store_short v[82:83], v64, off offset:64
	v_cvt_pk_bf16_f32 v64, v97, s0
	global_store_short v[82:83], v64, off offset:96
	v_add_u32_e32 v82, s36, v199
	v_ashrrev_i32_e32 v83, 31, v82
	v_lshlrev_b64 v[82:83], 9, v[82:83]
	v_lshl_add_u64 v[82:83], v[116:117], 0, v[82:83]
	v_cvt_pk_bf16_f32 v64, v70, s0
	global_store_short v[82:83], v64, off
	v_cvt_pk_bf16_f32 v64, v74, s0
	global_store_short v[82:83], v64, off offset:32
	v_cvt_pk_bf16_f32 v64, v78, s0
	global_store_short v[82:83], v64, off offset:64
	global_store_short v[82:83], v60, off offset:96
	v_add_u32_e32 v82, s36, v200
	v_ashrrev_i32_e32 v83, 31, v82
	v_lshlrev_b64 v[82:83], 9, v[82:83]
	v_lshl_add_u64 v[82:83], v[116:117], 0, v[82:83]
	v_cvt_pk_bf16_f32 v60, v71, s0
	global_store_short v[82:83], v60, off
	v_cvt_pk_bf16_f32 v60, v75, s0
	global_store_short v[82:83], v60, off offset:32
	v_cvt_pk_bf16_f32 v60, v79, s0
	global_store_short v[82:83], v60, off offset:64
	v_cvt_pk_bf16_f32 v60, v61, s0
	global_store_short v[82:83], v60, off offset:96
	v_add_u32_e32 v60, s36, v201
	v_ashrrev_i32_e32 v61, 31, v60
	v_lshlrev_b64 v[60:61], 9, v[60:61]
	v_lshl_add_u64 v[60:61], v[116:117], 0, v[60:61]
	v_cvt_pk_bf16_f32 v64, v72, s0
	global_store_short v[60:61], v64, off
	v_cvt_pk_bf16_f32 v64, v76, s0
	global_store_short v[60:61], v64, off offset:32
	v_cvt_pk_bf16_f32 v64, v80, s0
	global_store_short v[60:61], v64, off offset:64
	global_store_short v[60:61], v62, off offset:96
	v_add_u32_e32 v60, s36, v202
	v_ashrrev_i32_e32 v61, 31, v60
	v_lshlrev_b64 v[60:61], 9, v[60:61]
	v_lshl_add_u64 v[60:61], v[116:117], 0, v[60:61]
	v_cvt_pk_bf16_f32 v62, v73, s0
	global_store_short v[60:61], v62, off
	v_cvt_pk_bf16_f32 v62, v77, s0
	global_store_short v[60:61], v62, off offset:32
	v_cvt_pk_bf16_f32 v62, v81, s0
	v_mfma_f32_16x16x32_bf16 v[48:51], v[178:181], v[110:113], v[48:51]
	global_store_short v[60:61], v62, off offset:64
	v_cvt_pk_bf16_f32 v62, v63, s0
	global_store_short v[60:61], v62, off offset:96
	v_mfma_f32_16x16x32_bf16 v[66:69], v[178:181], v[106:109], v[66:69]
	s_waitcnt lgkmcnt(0)
	s_waitcnt lgkmcnt(0)
	s_nop 1
	v_pk_mul_f32 v[50:51], v[190:191], v[50:51]
	v_pk_mul_f32 v[48:49], v[188:189], v[48:49]
	v_mfma_f32_16x16x32_bf16 v[56:59], v[178:181], v[102:105], v[56:59]
	v_mul_f32_e64 v54, v190, v54
	v_mul_f32_e64 v55, v191, v55
	v_pk_mul_f32 v[68:69], v[190:191], v[68:69]
	v_pk_mul_f32 v[66:67], v[188:189], v[66:67]
	v_pk_mul_f32 v[52:53], v[188:189], v[52:53]
	s_nop 2
	v_pk_mul_f32 v[58:59], v[190:191], v[58:59]
	v_pk_mul_f32 v[56:57], v[188:189], v[56:57]
	s_cbranch_scc0 .LBB0_644
	v_readlane_b32 s0, v254, 20
	s_add_i32 s48, s48, s0
	s_cmpk_gt_i32 s48, 0x3ff
	v_readlane_b32 s1, v254, 21
	s_cbranch_scc0 .LBB0_641

; __device__ __forceinline__ float hgrn_lb(const Ctx& C, int l, int ch) {
;     if (l == 0) return 0.f;
;     const float a0 = C.P->in[3][ch], a1 = C.P->in[3][256 + ch];
;     return 1.0f / (1.0f + __expf(a0 - a1));
; }
; template <int DIR>
; __device__ __forceinline__ void hgrn_pass3_item(const Ctx& C, int l, int item) {
;     const int c = item & 31, hd = (item >> 5) & 3, b = item >> 7;
;     unsigned char* wl = C.lds + C.wave * 14336;
;     const float lb = hgrn_lb(C, l, hd * 64 + C.lane);
.LBB0_739:
	s_bfe_u32 s1, s73, 0x20005
	v_readlane_b32 s4, v255, 1
	s_lshl_b32 s0, s1, 6
	v_readlane_b32 s5, v255, 2
	v_or_b32_e32 v207, s0, v132
	s_andn2_b64 vcc, exec, s[4:5]
	v_mov_b32_e32 v208, 0
	s_cbranch_vccnz .LBB0_741
	v_readlane_b32 s4, v251, 4
	v_lshlrev_b32_e32 v0, 2, v207
	v_readlane_b32 s10, v251, 10
	v_readlane_b32 s11, v251, 11
	s_nop 4
	global_load_dword v1, v0, s[10:11]
	global_load_dword v0, v0, s[10:11] offset:1024
	v_readlane_b32 s5, v251, 5
	v_readlane_b32 s6, v251, 6
	v_readlane_b32 s7, v251, 7
	v_readlane_b32 s8, v251, 8
	v_readlane_b32 s9, v251, 9
	v_readlane_b32 s12, v251, 12
	v_readlane_b32 s13, v251, 13
	v_readlane_b32 s14, v251, 14
	v_readlane_b32 s15, v251, 15
	v_readlane_b32 s16, v251, 16
	v_readlane_b32 s17, v251, 17
	v_readlane_b32 s18, v251, 18
	v_readlane_b32 s19, v251, 19
	s_waitcnt vmcnt(0)
	v_sub_f32_e32 v0, v1, v0
	v_mul_f32_e32 v0, 0x3fb8aa3b, v0
	v_exp_f32_e32 v0, v0
	s_nop 0
	v_add_f32_e32 v0, 1.0, v0
	v_rcp_f32_e32 v208, v0

; __device__ __forceinline__ bf16_t f2bf(float f) { return (bf16_t)(cvt_pk_bf16(f, 0.f) & 0xffffu); }
; __device__ __forceinline__ float bf2f(bf16_t b) { return __uint_as_float(((unsigned)b) << 16); }
; __device__ __forceinline__ float sigmoidf_(float x) { return 1.0f / (1.0f + __expf(-x)); }
; template <int MODE>
; __device__ __forceinline__ void hgrn_mfma(const Ctx& C, int l, int z, int b, int hd, int c, f32x4 (&Sacc)[4][4], float& dectot, unsigned char* wl, float lb) {
;     ...
;             const int st0 = c * 128 + sc * 32 + g8 * 16; const int tq0 = z ? 4095 - st0 : st0;
;             const bf16_t* row0 = pa + (size_t)(b * SEQ + tq0) * 1280; const ptrdiff_t rstep = z ? -1280 : 1280;
; #pragma unroll
;             for (int t = 0; t < 16; ++t) { const bf16_t* row = row0 + rstep * t; fv[t] = row[fcol]; vv[t] = row[vcol]; if (MODE != 0) qv[t] = row[qcol]; }
; #pragma unroll
;             for (int t = 0; t < 16; ++t) {
;                 const float fl = bf2f(fv[t]);
;                 const float sg = sigmoidf_(fl);
;                 const float f = lb + (1.0f - lb) * sg, kk = (1.0f - lb) * (1.0f - sg);
;                 bacc += __logf(fmaxf(f, 1e-30f));
;                 Kb[(g8 * 16 + t) * HPT + lane] = f2bf(kk * __expf(fminf(-bacc, 80.f)));
;                 if (MODE != 0) Qt[(g8 * 16 + t) * HPT + lane] = f2bf(bf2f(qv[t]) * __expf(fmaxf(bacc, -80.f)));
;                 Vv[(g8 * 16 + t) * HPT + lane] = vv[t];
.LBB0_743:
	s_lshl_b32 s0, s67, 4
	v_cndmask_b32_e64 v61, 0, 1, s[52:53]
	s_mul_i32 s1, s67, 0x480
	s_or_b32 s0, s0, s76
	v_cmp_ne_u32_e64 s[4:5], 1, v61
	v_or_b32_e32 v61, s1, v132
	s_mul_hi_i32 s1, s0, 0xa00
	s_mulk_i32 s0, 0xa00
	s_add_u32 s0, s44, s0
	v_lshlrev_b32_e32 v62, 1, v207
	s_addc_u32 s1, s45, s1
	global_load_ushort v63, v62, s[0:1] offset:512
	global_load_ushort v64, v62, s[0:1] offset:1536
	global_load_ushort v70, v62, s[0:1] offset:3072
	global_load_ushort v71, v215, s[0:1] offset:2560
	s_add_u32 s6, s0, 0x1400
	s_addc_u32 s7, s1, 0
	global_load_ushort v72, v228, s[6:7]
	global_load_ushort v73, v62, s[6:7]
	global_load_ushort v74, v215, s[6:7]
	s_add_u32 s6, s0, 0x1e00
	s_addc_u32 s7, s1, 0
	global_load_ushort v75, v228, s[6:7]
	global_load_ushort v76, v62, s[6:7]
	global_load_ushort v77, v215, s[6:7]
	s_add_u32 s6, s0, 0x2800
	s_addc_u32 s7, s1, 0
	global_load_ushort v78, v62, s[6:7]
	global_load_ushort v81, v62, s[0:1] offset:2560
	global_load_ushort v82, v62, s[0:1]
	global_load_ushort v83, v228, s[6:7]
	global_load_ushort v84, v215, s[6:7]
	s_add_u32 s6, s0, 0x3200
	s_addc_u32 s7, s1, 0
	s_add_u32 s8, s0, 0x3c00
	global_load_ushort v85, v215, s[6:7]
	global_load_ushort v86, v228, s[6:7]
	global_load_ushort v87, v62, s[6:7]
	s_addc_u32 s9, s1, 0
	s_add_u32 s6, s0, 0x4600
	global_load_ushort v88, v215, s[8:9]
	global_load_ushort v89, v228, s[8:9]
	global_load_ushort v90, v62, s[8:9]
	s_addc_u32 s7, s1, 0
	s_add_u32 s8, s0, 0x5000
	global_load_ushort v91, v215, s[6:7]
	global_load_ushort v92, v228, s[6:7]
	global_load_ushort v93, v62, s[6:7]
	s_addc_u32 s9, s1, 0
	s_add_u32 s6, s0, 0x5a00
	global_load_ushort v94, v215, s[8:9]
	global_load_ushort v95, v228, s[8:9]
	global_load_ushort v96, v62, s[8:9]
	s_addc_u32 s7, s1, 0
	s_add_u32 s8, s0, 0x6400
	global_load_ushort v97, v215, s[6:7]
	global_load_ushort v98, v228, s[6:7]
	global_load_ushort v99, v62, s[6:7]
	s_addc_u32 s9, s1, 0
	s_add_u32 s6, s0, 0x6e00
	global_load_ushort v100, v215, s[8:9]
	global_load_ushort v101, v228, s[8:9]
	global_load_ushort v110, v62, s[8:9]
	s_addc_u32 s7, s1, 0
	s_add_u32 s8, s0, 0x7800
	global_load_ushort v111, v215, s[6:7]
	global_load_ushort v112, v228, s[6:7]
	global_load_ushort v113, v62, s[6:7]
	s_addc_u32 s9, s1, 0
	global_load_ushort v114, v215, s[8:9]
	global_load_ushort v115, v228, s[8:9]
	global_load_ushort v116, v62, s[8:9]
	s_add_u32 s6, s0, 0x8200
	s_addc_u32 s7, s1, 0
	s_add_u32 s8, s0, 0x8c00
	global_load_ushort v117, v215, s[6:7]
	global_load_ushort v118, v228, s[6:7]
	global_load_ushort v119, v62, s[6:7]
	s_addc_u32 s9, s1, 0
	s_add_u32 s0, s0, 0x9600
	global_load_ushort v120, v215, s[8:9]
	global_load_ushort v121, v228, s[8:9]
	global_load_ushort v122, v62, s[8:9]
	s_addc_u32 s1, s1, 0
	global_load_ushort v123, v215, s[0:1]
	global_load_ushort v124, v228, s[0:1]
	global_load_ushort v125, v62, s[0:1]
	v_lshl_add_u32 v61, v61, 1, s70
	s_mov_b64 s[52:53], 0
	s_mov_b32 s67, 1
	s_waitcnt vmcnt(47)
	v_lshlrev_b32_e32 v62, 16, v63
	v_mul_f32_e32 v62, 0xbfb8aa3b, v62
	s_waitcnt vmcnt(45)
	v_lshlrev_b32_e32 v63, 16, v70
	v_mul_f32_e32 v63, 0xbfb8aa3b, v63
	ds_write_b16 v61, v64 offset:9216
	v_exp_f32_e32 v62, v62
	v_exp_f32_e32 v63, v63
	s_waitcnt vmcnt(43)
	v_lshlrev_b32_e32 v64, 16, v72
	v_mul_f32_e32 v64, 0xbfb8aa3b, v64
	v_exp_f32_e32 v64, v64
	s_waitcnt vmcnt(40)
	v_lshlrev_b32_e32 v70, 16, v75
	v_mul_f32_e32 v70, 0xbfb8aa3b, v70
	v_lshlrev_b32_e32 v80, 16, v73
	v_add_f32_e32 v73, 1.0, v62
	v_add_f32_e32 v63, 1.0, v63
	v_exp_f32_e32 v62, v70
	s_waitcnt vmcnt(34)
	v_lshlrev_b32_e32 v70, 16, v83
	v_mul_f32_e32 v70, 0xbfb8aa3b, v70
	v_add_f32_e32 v128, 1.0, v64
	v_exp_f32_e32 v64, v70
	s_waitcnt vmcnt(31)
	v_lshlrev_b32_e32 v70, 16, v86
	ds_write_b16 v61, v85 offset:9936
	ds_write_b16 v61, v77 offset:9648
	s_waitcnt vmcnt(30)
	v_lshlrev_b32_e32 v77, 16, v87
	v_mul_f32_e32 v70, 0xbfb8aa3b, v70
	v_add_f32_e32 v129, 1.0, v62
	v_exp_f32_e32 v62, v70
	s_waitcnt vmcnt(28)
	v_lshlrev_b32_e32 v70, 16, v89
	ds_write_b16 v61, v88 offset:10080
	ds_write_b16 v61, v71 offset:9360
	ds_write_b16 v61, v74 offset:9504
	s_waitcnt vmcnt(27)
	v_lshlrev_b32_e32 v74, 16, v90
	v_mul_f32_e32 v70, 0xbfb8aa3b, v70
	v_lshlrev_b32_e32 v79, 16, v76
	ds_write_b16 v61, v84 offset:9792
	v_add_f32_e32 v131, 1.0, v64
	v_exp_f32_e32 v64, v70
	s_waitcnt vmcnt(25)
	v_lshlrev_b32_e32 v70, 16, v92
	s_waitcnt vmcnt(24)
	v_lshlrev_b32_e32 v72, 16, v93
	v_mul_f32_e32 v70, 0xbfb8aa3b, v70
	v_add_f32_e32 v180, 1.0, v62
	v_exp_f32_e32 v62, v70
	s_waitcnt vmcnt(22)
	v_lshlrev_b32_e32 v70, 16, v95
	ds_write_b16 v61, v94 offset:10368
	s_waitcnt vmcnt(21)
	v_lshlrev_b32_e32 v71, 16, v96
	v_mul_f32_e32 v70, 0xbfb8aa3b, v70
	v_add_f32_e32 v188, 1.0, v64
	v_exp_f32_e32 v70, v70
	s_waitcnt vmcnt(19)
	v_lshlrev_b32_e32 v98, 16, v98
	ds_write_b16 v61, v97 offset:10512
	v_mul_f32_e32 v97, 0xbfb8aa3b, v98
	s_waitcnt vmcnt(18)
	v_lshlrev_b32_e32 v64, 16, v99
	v_add_f32_e32 v99, 1.0, v62
	v_exp_f32_e32 v97, v97
	s_waitcnt vmcnt(16)
	v_lshlrev_b32_e32 v101, 16, v101
	v_rcp_f32_e32 v73, v73
	ds_write_b16 v61, v91 offset:10224
	ds_write_b16 v61, v100 offset:10656
	v_mul_f32_e32 v93, 0xbfb8aa3b, v101
	v_fma_f32 v100, v213, v73, v208
	v_sub_f32_e32 v73, 1.0, v73
	v_rcp_f32_e32 v75, v63
	s_waitcnt vmcnt(15)
	v_lshlrev_b32_e32 v62, 16, v110
	v_add_f32_e32 v101, 1.0, v70
	v_exp_f32_e32 v93, v93
	s_waitcnt vmcnt(13)
	v_lshlrev_b32_e32 v70, 16, v112
	v_mul_f32_e32 v110, v213, v73
	v_max_f32_e32 v73, 0xda24260, v100
	v_fma_f32 v100, v213, v75, v208
	v_sub_f32_e32 v75, 1.0, v75
	v_rcp_f32_e32 v76, v128
	v_mul_f32_e32 v70, 0xbfb8aa3b, v70
	v_mul_f32_e32 v112, v213, v75
	v_max_f32_e32 v75, 0xda24260, v100
	v_cmp_gt_f32_e32 vcc, s54, v73
	s_waitcnt vmcnt(12)
; __device__ __forceinline__ bf16_t f2bf(float f) { return (bf16_t)(cvt_pk_bf16(f, 0.f) & 0xffffu); }
; __device__ __forceinline__ float bf2f(bf16_t b) { return __uint_as_float(((unsigned)b) << 16); }
; __device__ __forceinline__ float sigmoidf_(float x) { return 1.0f / (1.0f + __expf(-x)); }
; template <int MODE>
; __device__ __forceinline__ void hgrn_mfma(const Ctx& C, int l, int z, int b, int hd, int c, f32x4 (&Sacc)[4][4], float& dectot, unsigned char* wl, float lb) {
;     ...
;             for (int t = 0; t < 16; ++t) {
;                 const float fl = bf2f(fv[t]);
;                 const float sg = sigmoidf_(fl);
;                 const float f = lb + (1.0f - lb) * sg, kk = (1.0f - lb) * (1.0f - sg);
;                 bacc += __logf(fmaxf(f, 1e-30f));
;                 Kb[(g8 * 16 + t) * HPT + lane] = f2bf(kk * __expf(fminf(-bacc, 80.f)));
;                 if (MODE != 0) Qt[(g8 * 16 + t) * HPT + lane] = f2bf(bf2f(qv[t]) * __expf(fmaxf(bacc, -80.f)));
	v_lshlrev_b32_e32 v63, 16, v113
	v_fma_f32 v100, v213, v76, v208
	v_sub_f32_e32 v76, 1.0, v76
	v_add_f32_e32 v97, 1.0, v97
	v_exp_f32_e32 v126, v70
	s_waitcnt vmcnt(9)
	v_lshlrev_b32_e32 v70, 16, v116
	ds_write_b16 v61, v114 offset:10944
	v_cndmask_b32_e64 v114, 0, 32, vcc
	v_cndmask_b32_e32 v116, 0, v225, vcc
	v_cmp_gt_f32_e32 vcc, s54, v75
	v_lshlrev_b32_e32 v115, 16, v115
	v_mul_f32_e32 v127, v213, v76
	v_max_f32_e32 v76, 0xda24260, v100
	v_rcp_f32_e32 v83, v129
	v_cndmask_b32_e64 v128, 0, 32, vcc
	v_cndmask_b32_e32 v129, 0, v225, vcc
	v_mul_f32_e32 v115, 0xbfb8aa3b, v115
	v_ldexp_f32 v114, v73, v114
	v_fma_f32 v130, v213, v83, v208
	v_add_f32_e32 v93, 1.0, v93
	v_cmp_gt_f32_e32 vcc, s54, v76
	v_exp_f32_e32 v115, v115
	s_waitcnt vmcnt(7)
	v_lshlrev_b32_e32 v118, 16, v118
	s_waitcnt vmcnt(6)
	v_lshlrev_b32_e32 v73, 16, v119
	ds_write_b16 v61, v117 offset:11088
	v_log_f32_e32 v114, v114
	v_ldexp_f32 v75, v75, v128
	v_cndmask_b32_e64 v117, 0, 32, vcc
	v_cndmask_b32_e32 v119, 0, v225, vcc
	v_max_f32_e32 v128, 0xda24260, v130
	v_rcp_f32_e32 v85, v131
	v_mul_f32_e32 v118, 0xbfb8aa3b, v118
	v_log_f32_e32 v178, v75
	v_ldexp_f32 v76, v76, v117
	v_fma_f32 v117, v213, v85, v208
	v_cmp_gt_f32_e32 vcc, s54, v128
	ds_write_b16 v61, v111 offset:10800
	v_add_f32_e32 v126, 1.0, v126
	v_exp_f32_e32 v118, v118
	s_waitcnt vmcnt(4)
	v_lshlrev_b32_e32 v121, 16, v121
	s_waitcnt vmcnt(3)
	v_lshlrev_b32_e32 v75, 16, v122
	ds_write_b16 v61, v120 offset:11232
	v_log_f32_e32 v120, v76
	v_cndmask_b32_e64 v76, 0, 32, vcc
	v_cndmask_b32_e32 v122, 0, v225, vcc
	v_max_f32_e32 v117, 0xda24260, v117
	v_rcp_f32_e32 v88, v180
	v_mul_f32_e32 v121, 0xbfb8aa3b, v121
	v_ldexp_f32 v128, v128, v76
	v_fma_f32 v189, v213, v88, v208
	v_cmp_gt_f32_e32 vcc, s54, v117
	v_add_f32_e32 v115, 1.0, v115
	v_exp_f32_e32 v121, v121
	s_waitcnt vmcnt(1)
	v_lshlrev_b32_e32 v124, 16, v124
	s_waitcnt vmcnt(0)
	v_lshlrev_b32_e32 v76, 16, v125
	ds_write_b16 v61, v123 offset:11376
	v_mul_f32_e32 v123, 0x3f317217, v114
	v_log_f32_e32 v125, v128
	v_cndmask_b32_e64 v128, 0, 32, vcc
	v_cndmask_b32_e32 v190, 0, v225, vcc
	v_max_f32_e32 v189, 0xda24260, v189
	v_rcp_f32_e32 v84, v188
	v_mul_f32_e32 v124, 0xbfb8aa3b, v124
	v_fma_f32 v123, v114, s56, -v123
	v_mul_f32_e32 v191, 0x3f317217, v178
	v_ldexp_f32 v117, v117, v128
	v_fma_f32 v128, v213, v84, v208
	v_cmp_gt_f32_e32 vcc, s54, v189
	v_add_f32_e32 v118, 1.0, v118
	v_exp_f32_e32 v124, v124
	v_fmac_f32_e32 v123, 0x3377d1cf, v114
	v_fma_f32 v191, v178, s56, -v191
	v_mul_f32_e32 v223, 0x3f317217, v120
	v_log_f32_e32 v117, v117
	v_cndmask_b32_e64 v229, 0, 32, vcc
	v_cndmask_b32_e32 v230, 0, v225, vcc
	v_max_f32_e32 v128, 0xda24260, v128
	v_rcp_f32_e32 v86, v99
	v_fmac_f32_e32 v123, 0x3f317217, v114
	v_cmp_lt_f32_e64 s[0:1], |v114|, s57
	v_fmac_f32_e32 v191, 0x3377d1cf, v178
	v_fma_f32 v223, v120, s56, -v223
	v_ldexp_f32 v189, v189, v229
	v_fma_f32 v229, v213, v86, v208
	v_cmp_gt_f32_e32 vcc, s54, v128
	v_fmac_f32_e32 v191, 0x3f317217, v178
	v_cmp_lt_f32_e64 s[18:19], |v178|, s57
	v_add_f32_e32 v121, 1.0, v121
	v_cndmask_b32_e64 v114, v114, v123, s[0:1]
	v_fmac_f32_e32 v223, 0x3377d1cf, v120
	v_mul_f32_e32 v123, 0x3f317217, v125
	v_log_f32_e32 v189, v189
	v_cndmask_b32_e64 v231, 0, 32, vcc
	v_cndmask_b32_e32 v232, 0, v225, vcc
	v_max_f32_e32 v229, 0xda24260, v229
	v_rcp_f32_e32 v87, v101
	v_fmac_f32_e32 v223, 0x3f317217, v120
	v_cmp_lt_f32_e64 s[0:1], |v120|, s57
	v_sub_f32_e32 v114, v114, v116
	v_cndmask_b32_e64 v116, v178, v191, s[18:19]
	v_fma_f32 v123, v125, s56, -v123
	v_ldexp_f32 v128, v128, v231
	v_fma_f32 v178, v213, v87, v208
	v_cmp_gt_f32_e32 vcc, s54, v229
	v_add_f32_e32 v124, 1.0, v124
	v_add_f32_e32 v60, v60, v114
	v_sub_f32_e32 v114, v116, v129
	v_cndmask_b32_e64 v116, v120, v223, s[0:1]
	v_fmac_f32_e32 v123, 0x3377d1cf, v125
	v_mul_f32_e32 v120, 0x3f317217, v117
	v_log_f32_e32 v128, v128
	v_cndmask_b32_e64 v129, 0, 32, vcc
	v_cndmask_b32_e32 v191, 0, v225, vcc
	v_max_f32_e32 v178, 0xda24260, v178
	v_fmac_f32_e32 v123, 0x3f317217, v125
	v_cmp_lt_f32_e64 s[0:1], |v125|, s57
	v_rcp_f32_e32 v89, v97
	v_min_f32_e64 v223, -v60, s60
	v_max_f32_e32 v231, 0xc2a00000, v60
	v_add_f32_e32 v60, v60, v114
	v_sub_f32_e32 v114, v116, v119
	v_fma_f32 v116, v117, s56, -v120
	v_ldexp_f32 v119, v229, v129
	v_cmp_gt_f32_e32 vcc, s54, v178
	v_fma_f32 v120, v213, v89, v208
	v_mul_f32_e32 v181, 0x3fb8aa3b, v223
	v_mul_f32_e32 v223, 0x3fb8aa3b, v231
	v_min_f32_e64 v229, -v60, s60
	v_max_f32_e32 v231, 0xc2a00000, v60
	v_add_f32_e32 v60, v60, v114
	v_cndmask_b32_e64 v114, v125, v123, s[0:1]
	v_fmac_f32_e32 v116, 0x3377d1cf, v117
	v_mul_f32_e32 v123, 0x3f317217, v189
	v_log_f32_e32 v119, v119
	v_cndmask_b32_e64 v125, 0, 32, vcc
	v_fmac_f32_e32 v116, 0x3f317217, v117
	v_cmp_lt_f32_e64 s[0:1], |v117|, s57
	v_cndmask_b32_e32 v233, 0, v225, vcc
	v_max_f32_e32 v120, 0xda24260, v120
	v_rcp_f32_e32 v90, v93
	v_exp_f32_e32 v97, v181
	v_exp_f32_e32 v180, v223
	v_mul_f32_e32 v181, 0x3fb8aa3b, v229
	v_mul_f32_e32 v223, 0x3fb8aa3b, v231
	v_min_f32_e64 v229, -v60, s60
	v_max_f32_e32 v231, 0xc2a00000, v60
	v_sub_f32_e32 v114, v114, v122
	v_fma_f32 v122, v189, s56, -v123
	v_ldexp_f32 v123, v178, v125
	v_fma_f32 v125, v213, v90, v208
	v_exp_f32_e32 v130, v181
	v_exp_f32_e32 v178, v223
	v_mul_f32_e32 v181, 0x3fb8aa3b, v229
	v_mul_f32_e32 v223, 0x3fb8aa3b, v231
	v_add_f32_e32 v60, v60, v114
	v_cndmask_b32_e64 v114, v117, v116, s[0:1]
	v_fmac_f32_e32 v122, 0x3377d1cf, v189
	v_mul_f32_e32 v116, 0x3f317217, v128
	v_log_f32_e32 v117, v123
	v_cmp_gt_f32_e32 vcc, s54, v120
	s_nop 1
	v_cndmask_b32_e64 v123, 0, 32, vcc
	v_fmac_f32_e32 v122, 0x3f317217, v189
	v_cmp_lt_f32_e64 s[0:1], |v189|, s57
; __device__ __forceinline__ bf16_t f2bf(float f) { return (bf16_t)(cvt_pk_bf16(f, 0.f) & 0xffffu); }
; __device__ __forceinline__ float bf2f(bf16_t b) { return __uint_as_float(((unsigned)b) << 16); }
; __device__ __forceinline__ float sigmoidf_(float x) { return 1.0f / (1.0f + __expf(-x)); }
; template <int MODE>
; __device__ __forceinline__ void hgrn_mfma(const Ctx& C, int l, int z, int b, int hd, int c, f32x4 (&Sacc)[4][4], float& dectot, unsigned char* wl, float lb) {
;     ...
;             for (int t = 0; t < 16; ++t) {
;                 const float fl = bf2f(fv[t]);
;                 const float sg = sigmoidf_(fl);
;                 const float f = lb + (1.0f - lb) * sg, kk = (1.0f - lb) * (1.0f - sg);
;                 bacc += __logf(fmaxf(f, 1e-30f));
;                 Kb[(g8 * 16 + t) * HPT + lane] = f2bf(kk * __expf(fminf(-bacc, 80.f)));
;                 if (MODE != 0) Qt[(g8 * 16 + t) * HPT + lane] = f2bf(bf2f(qv[t]) * __expf(fmaxf(bacc, -80.f)));
;                 Vv[(g8 * 16 + t) * HPT + lane] = vv[t];
	v_cndmask_b32_e32 v229, 0, v225, vcc
	v_max_f32_e32 v125, 0xda24260, v125
	v_rcp_f32_e32 v92, v126
	v_exp_f32_e32 v98, v181
	v_exp_f32_e32 v181, v223
	v_min_f32_e64 v188, -v60, s60
	v_max_f32_e32 v223, 0xc2a00000, v60
	v_sub_f32_e32 v114, v114, v190
	v_fma_f32 v116, v128, s56, -v116
	v_lshlrev_b32_e32 v82, 16, v82
	v_ldexp_f32 v120, v120, v123
	v_fma_f32 v123, v213, v92, v208
	v_mul_f32_e32 v126, 0x3fb8aa3b, v188
	v_mul_f32_e32 v188, 0x3fb8aa3b, v223
	v_add_f32_e32 v60, v60, v114
	v_cndmask_b32_e64 v114, v189, v122, s[0:1]
	v_fmac_f32_e32 v116, 0x3377d1cf, v128
	v_mul_f32_e32 v122, 0x3f317217, v119
	v_cmp_gt_f32_e32 vcc, s54, v125
	v_lshlrev_b32_e32 v81, 16, v81
	v_log_f32_e32 v120, v120
	v_cndmask_b32_e64 v189, 0, 32, vcc
	v_fmac_f32_e32 v116, 0x3f317217, v128
	v_cmp_lt_f32_e64 s[0:1], |v128|, s57
	v_cndmask_b32_e32 v190, 0, v225, vcc
	v_max_f32_e32 v123, 0xda24260, v123
	v_rcp_f32_e32 v91, v115
	v_mul_f32_e32 v96, v110, v97
	v_mul_f32_e32 v82, v180, v82
	v_exp_f32_e32 v97, v126
	v_exp_f32_e32 v110, v188
	v_min_f32_e64 v115, -v60, s60
	v_max_f32_e32 v126, 0xc2a00000, v60
	v_sub_f32_e32 v114, v114, v230
	v_fma_f32 v122, v119, s56, -v122
	v_ldexp_f32 v125, v125, v189
	v_fma_f32 v180, v213, v91, v208
	v_cvt_pk_bf16_f32 v96, v96, s0
	v_cvt_pk_bf16_f32 v82, v82, s0
	v_mul_f32_e32 v111, v112, v130
	v_mul_f32_e32 v81, v178, v81
	v_mul_f32_e32 v112, 0x3fb8aa3b, v115
	v_mul_f32_e32 v113, 0x3fb8aa3b, v126
	v_add_f32_e32 v60, v60, v114
	v_cndmask_b32_e64 v114, v128, v116, s[0:1]
	v_fmac_f32_e32 v122, 0x3377d1cf, v119
	v_mul_f32_e32 v115, 0x3f317217, v117
	v_cmp_gt_f32_e32 vcc, s54, v123
	v_cmp_lt_f32_e64 s[0:1], |v119|, s57
	v_sub_f32_e32 v83, 1.0, v83
	v_log_f32_e32 v116, v125
	v_cndmask_b32_e64 v125, 0, 32, vcc
	v_fmac_f32_e32 v122, 0x3f317217, v119
	v_cndmask_b32_e32 v126, 0, v225, vcc
	v_max_f32_e32 v128, 0xda24260, v180
	v_rcp_f32_e32 v93, v118
	ds_write_b16 v61, v96 offset:4608
	ds_write_b16 v61, v82
	v_cvt_pk_bf16_f32 v82, v111, s0
	v_cvt_pk_bf16_f32 v81, v81, s0
	v_mul_f32_e32 v96, v127, v98
	v_mul_f32_e32 v80, v181, v80
	v_exp_f32_e32 v98, v112
	v_exp_f32_e32 v111, v113
	v_min_f32_e64 v112, -v60, s60
	v_max_f32_e32 v113, 0xc2a00000, v60
	v_fma_f32 v115, v117, s56, -v115
	v_mul_f32_e32 v83, v213, v83
	v_sub_f32_e32 v114, v114, v232
	v_ldexp_f32 v118, v123, v125
	v_fma_f32 v123, v213, v93, v208
	ds_write_b16 v61, v82 offset:4752
	ds_write_b16 v61, v81 offset:144
	v_cvt_pk_bf16_f32 v81, v96, s0
	v_cvt_pk_bf16_f32 v80, v80, s0
	v_mul_f32_e32 v82, 0x3fb8aa3b, v112
	v_mul_f32_e32 v96, 0x3fb8aa3b, v113
	v_cndmask_b32_e64 v99, v119, v122, s[0:1]
	v_fmac_f32_e32 v115, 0x3377d1cf, v117
	v_cmp_gt_f32_e32 vcc, s54, v128
	v_sub_f32_e32 v85, 1.0, v85
	v_add_f32_e32 v60, v60, v114
	v_mul_f32_e32 v101, 0x3f317217, v120
	v_log_f32_e32 v112, v118
	v_cndmask_b32_e64 v113, 0, 32, vcc
	v_fmac_f32_e32 v115, 0x3f317217, v117
	v_cmp_lt_f32_e64 s[0:1], |v117|, s57
	v_cndmask_b32_e32 v114, 0, v225, vcc
	v_max_f32_e32 v118, 0xda24260, v123
	v_rcp_f32_e32 v95, v121
	ds_write_b16 v61, v81 offset:4896
	ds_write_b16 v61, v80 offset:288
	v_mul_f32_e32 v80, v83, v97
	v_mul_f32_e32 v79, v110, v79
	v_exp_f32_e32 v81, v82
	v_exp_f32_e32 v82, v96
	v_sub_f32_e32 v97, v99, v191
	v_lshlrev_b32_e32 v78, 16, v78
	v_mul_f32_e32 v85, v213, v85
	v_min_f32_e64 v83, -v60, s60
	v_max_f32_e32 v96, 0xc2a00000, v60
	v_fma_f32 v99, v120, s56, -v101
	v_ldexp_f32 v101, v128, v113
	v_fma_f32 v110, v213, v95, v208
	v_cvt_pk_bf16_f32 v80, v80, s0
	v_cvt_pk_bf16_f32 v79, v79, s0
	v_add_f32_e32 v60, v60, v97
	v_cndmask_b32_e64 v97, v117, v115, s[0:1]
	v_cmp_gt_f32_e64 s[0:1], s54, v118
	v_sub_f32_e32 v88, 1.0, v88
	v_mul_f32_e32 v83, 0x3fb8aa3b, v83
	v_mul_f32_e32 v96, 0x3fb8aa3b, v96
	v_fmac_f32_e32 v99, 0x3377d1cf, v120
	v_mul_f32_e32 v100, 0x3f317217, v116
	v_log_f32_e32 v101, v101
	v_cndmask_b32_e64 v113, 0, 32, s[0:1]
	v_max_f32_e32 v110, 0xda24260, v110
	v_rcp_f32_e32 v94, v124
	ds_write_b16 v61, v80 offset:5040
	ds_write_b16 v61, v79 offset:432
	v_mul_f32_e32 v79, v85, v98
	v_mul_f32_e32 v78, v111, v78
	v_mul_f32_e32 v88, v213, v88
	s_and_b64 vcc, exec, s[4:5]
	v_fmac_f32_e32 v99, 0x3f317217, v120
	v_cmp_lt_f32_e64 s[4:5], |v120|, s57
	v_cndmask_b32_e64 v115, 0, v225, s[0:1]
	v_exp_f32_e32 v80, v83
	v_exp_f32_e32 v83, v96
	v_min_f32_e64 v85, -v60, s60
	v_max_f32_e32 v96, 0xc2a00000, v60
	v_sub_f32_e32 v97, v97, v233
	v_fma_f32 v98, v116, s56, -v100
	v_ldexp_f32 v100, v118, v113
	v_fma_f32 v111, v213, v94, v208
	v_cvt_pk_bf16_f32 v79, v79, s0
	v_cvt_pk_bf16_f32 v78, v78, s0
	v_cmp_gt_f32_e64 s[0:1], s54, v110
	v_mul_f32_e32 v85, 0x3fb8aa3b, v85
	v_mul_f32_e32 v96, 0x3fb8aa3b, v96
	v_add_f32_e32 v60, v60, v97
	v_cndmask_b32_e64 v97, v120, v99, s[4:5]
	v_fmac_f32_e32 v98, 0x3377d1cf, v116
	v_mul_f32_e32 v99, 0x3f317217, v112
	v_log_f32_e32 v100, v100
	v_cndmask_b32_e64 v113, 0, 32, s[0:1]
	v_max_f32_e32 v111, 0xda24260, v111
	ds_write_b16 v61, v79 offset:5184
	ds_write_b16 v61, v78 offset:576
	v_mul_f32_e32 v78, v88, v81
	v_mul_f32_e32 v77, v82, v77
	v_sub_f32_e32 v84, 1.0, v84
	v_fmac_f32_e32 v98, 0x3f317217, v116
	v_cmp_lt_f32_e64 s[4:5], |v116|, s57
	v_cndmask_b32_e64 v117, 0, v225, s[0:1]
	v_exp_f32_e32 v79, v85
	v_exp_f32_e32 v81, v96
	v_min_f32_e64 v82, -v60, s60
	v_max_f32_e32 v85, 0xc2a00000, v60
	v_sub_f32_e32 v88, v97, v229
	v_fma_f32 v96, v112, s56, -v99
	v_ldexp_f32 v97, v110, v113
	v_cvt_pk_bf16_f32 v78, v78, s0
	v_cvt_pk_bf16_f32 v77, v77, s0
	v_cmp_gt_f32_e64 s[0:1], s54, v111
	v_mul_f32_e32 v84, v213, v84
	v_mul_f32_e32 v82, 0x3fb8aa3b, v82
	v_mul_f32_e32 v85, 0x3fb8aa3b, v85
	v_add_f32_e32 v60, v60, v88
	v_cndmask_b32_e64 v88, v116, v98, s[4:5]
	v_fmac_f32_e32 v96, 0x3377d1cf, v112
; __device__ __forceinline__ bf16_t f2bf(float f) { return (bf16_t)(cvt_pk_bf16(f, 0.f) & 0xffffu); }
; __device__ __forceinline__ float bf2f(bf16_t b) { return __uint_as_float(((unsigned)b) << 16); }
; __device__ __forceinline__ float sigmoidf_(float x) { return 1.0f / (1.0f + __expf(-x)); }
; template <int MODE>
; __device__ __forceinline__ void hgrn_mfma(const Ctx& C, int l, int z, int b, int hd, int c, f32x4 (&Sacc)[4][4], float& dectot, unsigned char* wl, float lb) {
;     ...
;             for (int t = 0; t < 16; ++t) {
;                 const float fl = bf2f(fv[t]);
;                 const float sg = sigmoidf_(fl);
;                 const float f = lb + (1.0f - lb) * sg, kk = (1.0f - lb) * (1.0f - sg);
;                 bacc += __logf(fmaxf(f, 1e-30f));
;                 Kb[(g8 * 16 + t) * HPT + lane] = f2bf(kk * __expf(fminf(-bacc, 80.f)));
;                 if (MODE != 0) Qt[(g8 * 16 + t) * HPT + lane] = f2bf(bf2f(qv[t]) * __expf(fmaxf(bacc, -80.f)));
;                 Vv[(g8 * 16 + t) * HPT + lane] = vv[t];
;             }
	v_mul_f32_e32 v98, 0x3f317217, v101
	v_log_f32_e32 v97, v97
	v_cndmask_b32_e64 v99, 0, 32, s[0:1]
	v_sub_f32_e32 v86, 1.0, v86
	v_fmac_f32_e32 v96, 0x3f317217, v112
	v_cmp_lt_f32_e64 s[4:5], |v112|, s57
	ds_write_b16 v61, v78 offset:5328
	ds_write_b16 v61, v77 offset:720
	v_mul_f32_e32 v77, v84, v80
	v_mul_f32_e32 v74, v83, v74
	v_exp_f32_e32 v78, v82
	v_exp_f32_e32 v80, v85
	v_min_f32_e64 v82, -v60, s60
	v_max_f32_e32 v83, 0xc2a00000, v60
	v_sub_f32_e32 v84, v88, v190
	v_fma_f32 v85, v101, s56, -v98
	v_ldexp_f32 v88, v111, v99
	v_mul_f32_e32 v86, v213, v86
	v_cvt_pk_bf16_f32 v77, v77, s0
	v_cvt_pk_bf16_f32 v74, v74, s0
	v_mul_f32_e32 v82, 0x3fb8aa3b, v82
	v_mul_f32_e32 v83, 0x3fb8aa3b, v83
	v_add_f32_e32 v60, v60, v84
	v_cndmask_b32_e64 v84, v112, v96, s[4:5]
	v_fmac_f32_e32 v85, 0x3377d1cf, v101
	v_mul_f32_e32 v96, 0x3f317217, v100
	v_log_f32_e32 v88, v88
	v_sub_f32_e32 v87, 1.0, v87
	v_cndmask_b32_e64 v110, 0, v225, s[0:1]
	v_fmac_f32_e32 v85, 0x3f317217, v101
	v_cmp_lt_f32_e64 s[0:1], |v101|, s57
	ds_write_b16 v61, v77 offset:5472
	ds_write_b16 v61, v74 offset:864
	v_mul_f32_e32 v74, v86, v79
	v_mul_f32_e32 v72, v81, v72
	v_exp_f32_e32 v77, v82
	v_exp_f32_e32 v79, v83
	v_min_f32_e64 v81, -v60, s60
	v_max_f32_e32 v82, 0xc2a00000, v60
	v_sub_f32_e32 v83, v84, v126
	v_fma_f32 v84, v100, s56, -v96
	v_mul_f32_e32 v87, v213, v87
	v_cvt_pk_bf16_f32 v74, v74, s0
	v_cvt_pk_bf16_f32 v72, v72, s0
	v_mul_f32_e32 v81, 0x3fb8aa3b, v81
	v_mul_f32_e32 v82, 0x3fb8aa3b, v82
	v_add_f32_e32 v60, v60, v83
	v_cndmask_b32_e64 v83, v101, v85, s[0:1]
	v_fmac_f32_e32 v84, 0x3377d1cf, v100
	v_mul_f32_e32 v85, 0x3f317217, v97
	v_sub_f32_e32 v89, 1.0, v89
	v_fmac_f32_e32 v84, 0x3f317217, v100
	v_cmp_lt_f32_e64 s[0:1], |v100|, s57
	ds_write_b16 v61, v74 offset:5616
	ds_write_b16 v61, v72 offset:1008
	v_mul_f32_e32 v72, v87, v78
	v_mul_f32_e32 v71, v80, v71
	v_exp_f32_e32 v74, v81
	v_exp_f32_e32 v78, v82
	v_min_f32_e64 v80, -v60, s60
	v_max_f32_e32 v81, 0xc2a00000, v60
	v_sub_f32_e32 v82, v83, v114
	v_fma_f32 v83, v97, s56, -v85
	v_mul_f32_e32 v89, v213, v89
	v_cvt_pk_bf16_f32 v72, v72, s0
	v_cvt_pk_bf16_f32 v71, v71, s0
	v_mul_f32_e32 v80, 0x3fb8aa3b, v80
	v_mul_f32_e32 v81, 0x3fb8aa3b, v81
	v_add_f32_e32 v60, v60, v82
	v_cndmask_b32_e64 v82, v100, v84, s[0:1]
	v_fmac_f32_e32 v83, 0x3377d1cf, v97
	v_mul_f32_e32 v84, 0x3f317217, v88
	v_sub_f32_e32 v90, 1.0, v90
	v_fmac_f32_e32 v83, 0x3f317217, v97
	v_cmp_lt_f32_e64 s[0:1], |v97|, s57
	ds_write_b16 v61, v72 offset:5760
	ds_write_b16 v61, v71 offset:1152
	v_mul_f32_e32 v71, v89, v77
	v_mul_f32_e32 v64, v79, v64
	v_exp_f32_e32 v72, v80
	v_exp_f32_e32 v77, v81
	v_min_f32_e64 v79, -v60, s60
	v_max_f32_e32 v80, 0xc2a00000, v60
	v_sub_f32_e32 v81, v82, v115
	v_fma_f32 v82, v88, s56, -v84
	v_mul_f32_e32 v90, v213, v90
	v_cvt_pk_bf16_f32 v71, v71, s0
	v_cvt_pk_bf16_f32 v64, v64, s0
	v_mul_f32_e32 v79, 0x3fb8aa3b, v79
	v_mul_f32_e32 v80, 0x3fb8aa3b, v80
	v_add_f32_e32 v60, v60, v81
	v_cndmask_b32_e64 v81, v97, v83, s[0:1]
	v_fmac_f32_e32 v82, 0x3377d1cf, v88
	v_sub_f32_e32 v92, 1.0, v92
	v_fmac_f32_e32 v82, 0x3f317217, v88
	v_cmp_lt_f32_e64 s[0:1], |v88|, s57
	ds_write_b16 v61, v71 offset:5904
	ds_write_b16 v61, v64 offset:1296
	v_mul_f32_e32 v64, v90, v74
	v_mul_f32_e32 v62, v78, v62
	v_exp_f32_e32 v71, v79
	v_exp_f32_e32 v74, v80
	v_min_f32_e64 v78, -v60, s60
	v_max_f32_e32 v79, 0xc2a00000, v60
	v_sub_f32_e32 v80, v81, v117
	v_mul_f32_e32 v92, v213, v92
	v_cvt_pk_bf16_f32 v64, v64, s0
	v_cvt_pk_bf16_f32 v62, v62, s0
	v_mul_f32_e32 v78, 0x3fb8aa3b, v78
	v_mul_f32_e32 v79, 0x3fb8aa3b, v79
	v_add_f32_e32 v60, v60, v80
	v_cndmask_b32_e64 v80, v88, v82, s[0:1]
	v_sub_f32_e32 v91, 1.0, v91
	ds_write_b16 v61, v64 offset:6048
	ds_write_b16 v61, v62 offset:1440
	v_mul_f32_e32 v62, v92, v72
	v_mul_f32_e32 v63, v77, v63
	v_exp_f32_e32 v64, v78
	v_exp_f32_e32 v72, v79
	v_min_f32_e64 v77, -v60, s60
	v_sub_f32_e32 v79, v80, v110
	v_mul_f32_e32 v91, v213, v91
	v_max_f32_e32 v78, 0xc2a00000, v60
	v_cvt_pk_bf16_f32 v62, v62, s0
	v_cvt_pk_bf16_f32 v63, v63, s0
	v_mul_f32_e32 v77, 0x3fb8aa3b, v77
	v_add_f32_e32 v60, v60, v79
	v_sub_f32_e32 v93, 1.0, v93
	v_mul_f32_e32 v78, 0x3fb8aa3b, v78
	ds_write_b16 v61, v62 offset:6192
	ds_write_b16 v61, v63 offset:1584
	v_mul_f32_e32 v62, v91, v71
	v_mul_f32_e32 v63, v74, v70
	v_exp_f32_e32 v70, v77
	v_min_f32_e64 v74, -v60, s60
	v_mul_f32_e32 v93, v213, v93
	v_exp_f32_e32 v71, v78
	v_max_f32_e32 v77, 0xc2a00000, v60
	v_cvt_pk_bf16_f32 v62, v62, s0
	v_mul_f32_e32 v74, 0x3fb8aa3b, v74
	v_sub_f32_e32 v95, 1.0, v95
	v_cvt_pk_bf16_f32 v63, v63, s0
	v_mul_f32_e32 v77, 0x3fb8aa3b, v77
	ds_write_b16 v61, v62 offset:6336
	ds_write_b16 v61, v63 offset:1728
	v_mul_f32_e32 v62, v93, v64
	v_exp_f32_e32 v64, v74
	v_mul_f32_e32 v95, v213, v95
	v_mul_f32_e32 v63, v72, v73
	v_exp_f32_e32 v72, v77
	v_cvt_pk_bf16_f32 v62, v62, s0
	v_sub_f32_e32 v94, 1.0, v94
	v_cvt_pk_bf16_f32 v63, v63, s0
	ds_write_b16 v61, v62 offset:6480
	ds_write_b16 v61, v63 offset:1872
	v_mul_f32_e32 v62, v95, v70
	v_mul_f32_e32 v94, v213, v94
	v_mul_f32_e32 v63, v71, v75
	v_cvt_pk_bf16_f32 v62, v62, s0
	v_cvt_pk_bf16_f32 v63, v63, s0
	ds_write_b16 v61, v62 offset:6624
	ds_write_b16 v61, v63 offset:2016
	v_mul_f32_e32 v62, v94, v64
	v_mul_f32_e32 v63, v72, v76
	v_cvt_pk_bf16_f32 v62, v62, s0
	v_cvt_pk_bf16_f32 v63, v63, s0
	ds_write_b16 v61, v62 offset:6768
	ds_write_b16 v61, v63 offset:2160
	s_cbranch_vccz .LBB0_743
; template <int MODE>
; __device__ __forceinline__ void hgrn_mfma(const Ctx& C, int l, int z, int b, int hd, int c, f32x4 (&Sacc)[4][4], float& dectot, unsigned char* wl, float lb) {
;     ...
;         { const float eb = __expf(bacc); dl[lane] = eb; dectot *= eb; }
;         wave_lds_fence();
;         f32x4 Oacc[2][4];
;         if (MODE != 0) {
;             bf16x8 Sb[2][4];
; #pragma unroll
;             for (int ks = 0; ks < 2; ++ks)
; #pragma unroll
;                 for (int vt = 0; vt < 4; ++vt) { union { bf16x8 v; unsigned u[4]; } t_;
;                     t_.u[0] = cvt_pk_bf16(Sacc[2 * ks][vt][0], Sacc[2 * ks][vt][1]); t_.u[1] = cvt_pk_bf16(Sacc[2 * ks][vt][2], Sacc[2 * ks][vt][3]);
;                     t_.u[2] = cvt_pk_bf16(Sacc[2 * ks + 1][vt][0], Sacc[2 * ks + 1][vt][1]); t_.u[3] = cvt_pk_bf16(Sacc[2 * ks + 1][vt][2], Sacc[2 * ks + 1][vt][3]); Sb[ks][vt] = t_.v; }
;             float zz = 0.f; asm volatile("" : "+v"(zz));
; #pragma unroll
;             for (int tt = 0; tt < 2; ++tt)
; #pragma unroll
;                 for (int vt = 0; vt < 4; ++vt) Oacc[tt][vt] = (f32x4){zz, zz, zz, zz};
; #pragma unroll
;             for (int tt = 0; tt < 2; ++tt)
; #pragma unroll
;                 for (int ks = 0; ks < 2; ++ks) { const bf16_t* qp = Qt + (16 * tt + fr) * HPT + 32 * ks + 4 * quad;
;                     union { bf16x8 v; u32x2 h[2]; } a_; a_.h[0] = *(const u32x2*)qp; a_.h[1] = *(const u32x2*)(qp + 16);
; #pragma unroll
;                     for (int vt = 0; vt < 4; ++vt) Oacc[tt][vt] = __builtin_amdgcn_mfma_f32_16x16x32_bf16(a_.v, Sb[ks][vt], Oacc[tt][vt], 0, 0, 0); }
;             f32x4 P00 = {zz, zz, zz, zz}, P01 = {zz, zz, zz, zz}, P11 = {zz, zz, zz, zz};
; #pragma unroll
;             for (int ks = 0; ks < 2; ++ks) {
;                 const bf16x8 kA0 = *(const bf16x8*)(Kb + fr * HPT + 32 * ks + 8 * quad), kA1 = *(const bf16x8*)(Kb + (16 + fr) * HPT + 32 * ks + 8 * quad);
;                 const bf16x8 qB0 = *(const bf16x8*)(Qt + fr * HPT + 32 * ks + 8 * quad), qB1 = *(const bf16x8*)(Qt + (16 + fr) * HPT + 32 * ks + 8 * quad);
;                 P00 = __builtin_amdgcn_mfma_f32_16x16x32_bf16(kA0, qB0, P00, 0, 0, 0);
;                 P01 = __builtin_amdgcn_mfma_f32_16x16x32_bf16(kA0, qB1, P01, 0, 0, 0);
;                 P11 = __builtin_amdgcn_mfma_f32_16x16x32_bf16(kA1, qB1, P11, 0, 0, 0);
;             }
; #pragma unroll
	v_mul_f32_e32 v60, 0x3fb8aa3b, v60
	v_exp_f32_e32 v60, v60
	v_mov_b32_e32 v98, v65
	v_cvt_pk_bf16_f32 v61, v2, v3
	v_cvt_pk_bf16_f32 v62, v16, v17
	ds_write_b32 v134, v60 offset:13824
	s_waitcnt lgkmcnt(0)
	ds_read2_b64 v[110:113], v141 offset1:4
	ds_read2_b64 v[126:129], v141 offset0:8 offset1:12
	v_cvt_pk_bf16_f32 v60, v0, v1
	v_cvt_pk_bf16_f32 v63, v18, v19
	v_cvt_pk_bf16_f32 v70, v4, v5
	v_cvt_pk_bf16_f32 v71, v6, v7
	v_cvt_pk_bf16_f32 v72, v20, v21
	v_cvt_pk_bf16_f32 v73, v22, v23
	v_cvt_pk_bf16_f32 v78, v8, v9
	v_cvt_pk_bf16_f32 v79, v10, v11
	v_cvt_pk_bf16_f32 v80, v24, v25
	v_cvt_pk_bf16_f32 v81, v26, v27
	v_cvt_pk_bf16_f32 v86, v12, v13
	v_cvt_pk_bf16_f32 v87, v14, v15
	v_cvt_pk_bf16_f32 v88, v28, v29
	v_cvt_pk_bf16_f32 v89, v30, v31
	v_mov_b32_e32 v99, v98
	v_mov_b32_e32 v100, v98
	v_mov_b32_e32 v101, v98
	v_cvt_pk_bf16_f32 v74, v32, v33
	v_cvt_pk_bf16_f32 v75, v34, v35
	s_waitcnt lgkmcnt(1)
	v_mfma_f32_16x16x32_bf16 v[114:117], v[110:113], v[60:63], v[98:101]
	v_cvt_pk_bf16_f32 v76, v48, v49
	v_cvt_pk_bf16_f32 v77, v50, v51
	v_cvt_pk_bf16_f32 v82, v36, v37
	v_mfma_f32_16x16x32_bf16 v[118:121], v[110:113], v[70:73], v[98:101]
	v_cvt_pk_bf16_f32 v83, v38, v39
	v_cvt_pk_bf16_f32 v84, v52, v53
	v_cvt_pk_bf16_f32 v85, v54, v55
	v_mfma_f32_16x16x32_bf16 v[122:125], v[110:113], v[78:81], v[98:101]
	v_cvt_pk_bf16_f32 v90, v40, v41
	v_cvt_pk_bf16_f32 v91, v42, v43
	v_cvt_pk_bf16_f32 v92, v56, v57
	v_mfma_f32_16x16x32_bf16 v[110:113], v[110:113], v[86:89], v[98:101]
	v_cvt_pk_bf16_f32 v93, v58, v59
	v_cvt_pk_bf16_f32 v94, v44, v45
	v_cvt_pk_bf16_f32 v95, v46, v47
	v_cvt_pk_bf16_f32 v96, v66, v67
	v_cvt_pk_bf16_f32 v97, v68, v69
	v_add_u32_e32 v64, 0x800, v141
	s_waitcnt lgkmcnt(0)
	v_mfma_f32_16x16x32_bf16 v[114:117], v[126:129], v[74:77], v[114:117]
	s_add_i32 s36, s36, 1
	s_cmp_eq_u32 s36, 4
	v_mfma_f32_16x16x32_bf16 v[118:121], v[126:129], v[82:85], v[118:121]
	v_mfma_f32_16x16x32_bf16 v[122:125], v[126:129], v[90:93], v[122:125]
	v_mfma_f32_16x16x32_bf16 v[110:113], v[126:129], v[94:97], v[110:113]
	ds_read2_b64 v[126:129], v64 offset0:32 offset1:36
	s_waitcnt lgkmcnt(0)
	v_mfma_f32_16x16x32_bf16 v[60:63], v[126:129], v[60:63], v[98:101]
	v_mfma_f32_16x16x32_bf16 v[70:73], v[126:129], v[70:73], v[98:101]
	v_mfma_f32_16x16x32_bf16 v[78:81], v[126:129], v[78:81], v[98:101]
	v_mfma_f32_16x16x32_bf16 v[86:89], v[126:129], v[86:89], v[98:101]
	ds_read2_b64 v[126:129], v64 offset0:40 offset1:44
	s_waitcnt lgkmcnt(0)
	v_mfma_f32_16x16x32_bf16 v[74:77], v[126:129], v[74:77], v[60:63]
	v_mfma_f32_16x16x32_bf16 v[178:181], v[126:129], v[82:85], v[70:73]
	v_mfma_f32_16x16x32_bf16 v[78:81], v[126:129], v[90:93], v[78:81]
	v_mfma_f32_16x16x32_bf16 v[126:129], v[126:129], v[94:97], v[86:89]
	ds_read_b128 v[60:63], v138 offset:4608
	ds_read_b128 v[70:73], v138 offset:6912
	ds_read_b128 v[82:85], v138
	ds_read_b128 v[86:89], v138 offset:2304
	ds_read_b128 v[90:93], v138 offset:4672
	ds_read_b128 v[94:97], v138 offset:6976
	ds_read_b128 v[188:191], v138 offset:64
	ds_read_b128 v[230:233], v138 offset:2368
	s_waitcnt lgkmcnt(5)
	v_mfma_f32_16x16x32_bf16 v[82:85], v[60:63], v[82:85], v[98:101]
	s_waitcnt lgkmcnt(4)
	v_mfma_f32_16x16x32_bf16 v[70:73], v[70:73], v[86:89], v[98:101]
	s_waitcnt lgkmcnt(1)
	v_mfma_f32_16x16x32_bf16 v[82:85], v[90:93], v[188:191], v[82:85]
	s_waitcnt lgkmcnt(0)
	v_mfma_f32_16x16x32_bf16 v[70:73], v[94:97], v[230:233], v[70:73]
	v_mfma_f32_16x16x32_bf16 v[60:63], v[60:63], v[86:89], v[98:101]
	s_nop 4
	v_cndmask_b32_e64 v64, v85, 0, s[42:43]
	s_nop 0
	v_cndmask_b32_e64 v85, v73, 0, s[42:43]
	v_cndmask_b32_e64 v94, v72, 0, s[46:47]
	v_cndmask_b32_e64 v95, v71, 0, s[48:49]
	v_cndmask_b32_e64 v96, v70, 0, s[50:51]
	v_mfma_f32_16x16x32_bf16 v[70:73], v[90:93], v[230:233], v[60:63]
	v_cndmask_b32_e64 v84, v84, 0, s[46:47]
	v_cndmask_b32_e64 v83, v83, 0, s[48:49]
	v_cndmask_b32_e64 v82, v82, 0, s[50:51]
	v_cvt_pk_bf16_f32 v62, v82, v83
	v_cvt_pk_bf16_f32 v63, v84, v64
	v_mov_b32_e32 v64, v65
	s_nop 1
	v_cvt_pk_bf16_f32 v98, v70, v71
	v_cvt_pk_bf16_f32 v99, v72, v73
	ds_read_b64_tr_b16 v[72:73], v139 offset:11520
	ds_read_b64_tr_b16 v[70:71], v139 offset:9216
	ds_read_b64_tr_b16 v[90:91], v139 offset:9248
	v_cvt_pk_bf16_f32 v100, v96, v95
	v_cvt_pk_bf16_f32 v101, v94, v85
	s_waitcnt lgkmcnt(1)
	v_mfma_f32_16x16x32_bf16 v[82:85], v[62:65], v[70:73], v[114:117]
	ds_read_b64_tr_b16 v[92:93], v139 offset:11552
	ds_read_b64_tr_b16 v[94:95], v139 offset:9280
	ds_read_b64_tr_b16 v[96:97], v139 offset:11584
	ds_read_b64_tr_b16 v[114:115], v139 offset:9312
	ds_read_b64_tr_b16 v[116:117], v139 offset:11616
	v_mfma_f32_16x16x32_bf16 v[70:73], v[98:101], v[70:73], v[74:77]
	s_waitcnt lgkmcnt(4)
	v_mfma_f32_16x16x32_bf16 v[86:89], v[62:65], v[90:93], v[118:121]
	v_mfma_f32_16x16x32_bf16 v[74:77], v[98:101], v[90:93], v[178:181]
	s_waitcnt lgkmcnt(2)
	v_mfma_f32_16x16x32_bf16 v[90:93], v[62:65], v[94:97], v[122:125]
	v_mfma_f32_16x16x32_bf16 v[78:81], v[98:101], v[94:97], v[78:81]
	s_waitcnt lgkmcnt(0)
	v_mfma_f32_16x16x32_bf16 v[94:97], v[62:65], v[114:117], v[110:113]
	v_add_u32_e32 v64, v137, v136
	v_mfma_f32_16x16x32_bf16 v[60:63], v[98:101], v[114:117], v[126:129]
	ds_read_b64_tr_b16 v[98:99], v140 offset:9216
	ds_read_b64_tr_b16 v[100:101], v140 offset:9792
	ds_read_b64_tr_b16 v[110:111], v140 offset:9248
	ds_read_b64_tr_b16 v[112:113], v140 offset:9824
	ds_read_b64_tr_b16 v[114:115], v140 offset:9280
	ds_read_b64_tr_b16 v[116:117], v140 offset:9856
	ds_read_b64_tr_b16 v[118:119], v140 offset:9312
	ds_read_b64_tr_b16 v[120:121], v140 offset:9888
	ds_read_b64_tr_b16 v[124:125], v140 offset:5184
	ds_read_b64_tr_b16 v[122:123], v140 offset:4608
	ds_read_b64_tr_b16 v[126:127], v140 offset:4640
	ds_read_b128 v[128:131], v64 offset:13824
	s_waitcnt lgkmcnt(2)
; __device__ __forceinline__ bf16_t f2bf(float f) { return (bf16_t)(cvt_pk_bf16(f, 0.f) & 0xffffu); }
; template <int MODE>
; __device__ __forceinline__ void hgrn_mfma(const Ctx& C, int l, int z, int b, int hd, int c, f32x4 (&Sacc)[4][4], float& dectot, unsigned char* wl, float lb) {
;     ...
;             bf16x8 vB[4];
; #pragma unroll
;             for (int vt = 0; vt < 4; ++vt) { const bf16_t* vp = Vv + (8 * quad + (fr >> 2)) * HPT + 16 * vt + 4 * (fr & 3);
;                 union { bf16x8 v; s16x4 h[2]; } vb; vb.h[0] = lds_tr(vp); vb.h[1] = lds_tr(vp + 4 * HPT); vB[vt] = vb.v; }
; #pragma unroll
;             for (int kt = 0; kt < 4; ++kt) { const bf16_t* kp = Kb + (8 * quad + (fr >> 2)) * HPT + 16 * kt + 4 * (fr & 3);
;                 union { bf16x8 v; s16x4 h[2]; } ka; ka.h[0] = lds_tr(kp); ka.h[1] = lds_tr(kp + 4 * HPT);
;                 const f32x4 d4 = *(const f32x4*)(dl + 16 * kt + 4 * quad);
; #pragma unroll
;                 for (int vt = 0; vt < 4; ++vt) { Sacc[kt][vt] = __builtin_amdgcn_mfma_f32_16x16x32_bf16(ka.v, vB[vt], Sacc[kt][vt], 0, 0, 0); Sacc[kt][vt] *= d4; } }
;         }
;         if (MODE == 1) {
; #pragma unroll
;             for (int tt = 0; tt < 2; ++tt)
; #pragma unroll
;                 for (int r = 0; r < 4; ++r) { const int st = c * 128 + sc * 32 + 16 * tt + 4 * quad + r; const int tq = z ? 4095 - st : st;
;                     bf16_t* yp = ya + (size_t)(b * SEQ + tq) * 256 + hd * 64 + fr;
; #pragma unroll
;                     for (int vt = 0; vt < 4; ++vt) yp[16 * vt] = f2bf(Oacc[tt][vt][r]); }
;         }
;         if (MODE == 2) {
; #pragma unroll
;             for (int tt = 0; tt < 2; ++tt) {
;                 bf16_t tmpv[4][4], gtv[4][4];
; #pragma unroll
;                 for (int r = 0; r < 4; ++r) { const int st = c * 128 + sc * 32 + 16 * tt + 4 * quad + r; const int tq = z ? 4095 - st : st;
;                     const size_t tok = (size_t)(b * SEQ + tq); const bf16_t* yp = ya + tok * 256 + hd * 64 + fr; const bf16_t* gp = pa + tok * 1280 + 1024 + hd * 64 + fr;
; #pragma unroll
;                     for (int vt = 0; vt < 4; ++vt) { tmpv[r][vt] = yp[16 * vt]; gtv[r][vt] = gp[16 * vt]; } }
	v_mfma_f32_16x16x32_bf16 v[0:3], v[122:125], v[98:101], v[0:3]
	v_mfma_f32_16x16x32_bf16 v[4:7], v[122:125], v[110:113], v[4:7]
	s_waitcnt lgkmcnt(0)
	s_nop 5
	v_pk_mul_f32 v[0:1], v[128:129], v[0:1]
	v_pk_mul_f32 v[2:3], v[130:131], v[2:3]
	v_mfma_f32_16x16x32_bf16 v[8:11], v[122:125], v[114:117], v[8:11]
	v_mfma_f32_16x16x32_bf16 v[12:15], v[122:125], v[118:121], v[12:15]
	v_mul_f32_e64 v4, v128, v4
	v_mul_f32_e64 v5, v129, v5
	s_nop 4
	v_pk_mul_f32 v[8:9], v[128:129], v[8:9]
	v_pk_mul_f32 v[6:7], v[130:131], v[6:7]
	v_pk_mul_f32 v[10:11], v[130:131], v[10:11]
	v_pk_mul_f32 v[12:13], v[128:129], v[12:13]
	ds_read_b64_tr_b16 v[128:129], v140 offset:5216
	ds_read_b128 v[122:125], v64 offset:13888
	s_waitcnt lgkmcnt(1)
	v_mfma_f32_16x16x32_bf16 v[16:19], v[126:129], v[98:101], v[16:19]
	v_mul_f32_e64 v14, v130, v14
	v_mul_f32_e64 v15, v131, v15
	v_mfma_f32_16x16x32_bf16 v[20:23], v[126:129], v[110:113], v[20:23]
	s_waitcnt lgkmcnt(0)
	s_nop 3
	v_pk_mul_f32 v[18:19], v[124:125], v[18:19]
	v_pk_mul_f32 v[16:17], v[122:123], v[16:17]
	v_mfma_f32_16x16x32_bf16 v[24:27], v[126:129], v[114:117], v[24:27]
	v_mfma_f32_16x16x32_bf16 v[28:31], v[126:129], v[118:121], v[28:31]
	v_mul_f32_e64 v22, v124, v22
	v_mul_f32_e64 v23, v125, v23
	v_pk_mul_f32 v[20:21], v[122:123], v[20:21]
	s_nop 3
	v_pk_mul_f32 v[26:27], v[124:125], v[26:27]
	v_pk_mul_f32 v[24:25], v[122:123], v[24:25]
	v_pk_mul_f32 v[30:31], v[124:125], v[30:31]
	v_pk_mul_f32 v[28:29], v[122:123], v[28:29]
	ds_read_b64_tr_b16 v[122:123], v140 offset:4672
	ds_read_b64_tr_b16 v[124:125], v140 offset:5248
	ds_read_b128 v[126:129], v64 offset:13952
	s_waitcnt lgkmcnt(1)
	v_mfma_f32_16x16x32_bf16 v[32:35], v[122:125], v[98:101], v[32:35]
	v_mfma_f32_16x16x32_bf16 v[36:39], v[122:125], v[110:113], v[36:39]
	s_waitcnt lgkmcnt(0)
	s_nop 5
	v_pk_mul_f32 v[34:35], v[128:129], v[34:35]
	v_pk_mul_f32 v[32:33], v[126:127], v[32:33]
	v_mfma_f32_16x16x32_bf16 v[40:43], v[122:125], v[114:117], v[40:43]
	v_mfma_f32_16x16x32_bf16 v[44:47], v[122:125], v[118:121], v[44:47]
	v_mul_f32_e64 v38, v128, v38
	v_mul_f32_e64 v39, v129, v39
	v_pk_mul_f32 v[36:37], v[126:127], v[36:37]
	s_nop 3
	v_pk_mul_f32 v[42:43], v[128:129], v[42:43]
	v_pk_mul_f32 v[40:41], v[126:127], v[40:41]
	v_pk_mul_f32 v[46:47], v[128:129], v[46:47]
	v_pk_mul_f32 v[44:45], v[126:127], v[44:45]
	ds_read_b64_tr_b16 v[122:123], v140 offset:4704
	ds_read_b64_tr_b16 v[124:125], v140 offset:5280
	ds_read_b128 v[126:129], v64 offset:14016
	s_waitcnt lgkmcnt(1)
	v_mfma_f32_16x16x32_bf16 v[48:51], v[122:125], v[98:101], v[48:51]
	v_and_b32_e32 v99, 64, v221
	v_xor_b32_e32 v64, 1, v221
	v_add_u32_e32 v99, 64, v99
	v_cmp_lt_i32_e32 vcc, v64, v99
	v_add_u32_e32 v98, s75, v214
	v_mfma_f32_16x16x32_bf16 v[56:59], v[122:125], v[114:117], v[56:59]
	v_cndmask_b32_e32 v64, v221, v64, vcc
	v_lshlrev_b32_e32 v231, 2, v64
	v_xor_b32_e32 v64, 2, v221
	v_cmp_lt_i32_e32 vcc, v64, v99
	v_mfma_f32_16x16x32_bf16 v[52:55], v[122:125], v[110:113], v[52:55]
	v_or_b32_e32 v116, 3, v98
	v_cndmask_b32_e32 v64, v221, v64, vcc
	v_lshlrev_b32_e32 v230, 2, v64
	v_xor_b32_e32 v64, 4, v221
	v_cmp_lt_i32_e32 vcc, v64, v99
	v_mfma_f32_16x16x32_bf16 v[66:69], v[122:125], v[118:121], v[66:69]
	v_ashrrev_i32_e32 v117, 31, v116
	v_cndmask_b32_e32 v64, v221, v64, vcc
	v_lshlrev_b32_e32 v229, 2, v64
	v_xor_b32_e32 v64, 8, v221
	v_cmp_lt_i32_e32 vcc, v64, v99
	v_ashrrev_i32_e32 v99, 31, v98
	v_lshlrev_b64 v[100:101], 9, v[98:99]
	v_lshl_add_u64 v[114:115], v[106:107], 0, v[100:101]
	v_or_b32_e32 v100, 1, v98
	v_ashrrev_i32_e32 v101, 31, v100
	v_lshlrev_b64 v[110:111], 9, v[100:101]
	v_mad_i64_i32 v[124:125], s[0:1], v100, s62, v[108:109]
	v_or_b32_e32 v100, 2, v98
	v_ashrrev_i32_e32 v101, 31, v100
	v_lshl_add_u64 v[112:113], v[106:107], 0, v[110:111]
	v_lshlrev_b64 v[110:111], 9, v[100:101]
	v_mad_i64_i32 v[120:121], s[0:1], v100, s62, v[108:109]
	v_lshlrev_b64 v[100:101], 9, v[116:117]
	s_waitcnt lgkmcnt(0)
	v_pk_mul_f32 v[48:49], v[126:127], v[48:49]
	v_pk_mul_f32 v[52:53], v[126:127], v[52:53]
	v_pk_mul_f32 v[56:57], v[126:127], v[56:57]
	v_pk_mul_f32 v[66:67], v[126:127], v[66:67]
	v_mad_i64_i32 v[126:127], s[0:1], v98, s62, v[108:109]
	v_lshl_add_u64 v[110:111], v[106:107], 0, v[110:111]
	v_lshl_add_u64 v[100:101], v[106:107], 0, v[100:101]
	global_load_ushort v118, v[114:115], off
	global_load_ushort v119, v[114:115], off offset:32
	global_load_ushort v130, v[114:115], off offset:64
	global_load_ushort v131, v[114:115], off offset:96
	global_load_ushort v244, v[112:113], off
	global_load_ushort v245, v[112:113], off offset:32
	global_load_ushort v242, v[112:113], off offset:64
	global_load_ushort v243, v[112:113], off offset:96
	global_load_ushort v237, v[110:111], off
	global_load_ushort v238, v[110:111], off offset:32
	global_load_ushort v235, v[110:111], off offset:64
	global_load_ushort v236, v[110:111], off offset:96
	global_load_ushort v233, v[100:101], off
	global_load_ushort v234, v[100:101], off offset:32
	global_load_ushort v99, v[100:101], off offset:64
	global_load_ushort v232, v[100:101], off offset:96
	v_mov_b32_e32 v122, v82
	global_load_ushort v82, v[126:127], off offset:2048
	v_mov_b32_e32 v123, v86
	v_cndmask_b32_e32 v64, v221, v64, vcc
	v_pk_mul_f32 v[50:51], v[128:129], v[50:51]
	v_pk_mul_f32 v[54:55], v[128:129], v[54:55]
	v_pk_mul_f32 v[58:59], v[128:129], v[58:59]
	v_pk_mul_f32 v[68:69], v[128:129], v[68:69]
	v_lshlrev_b32_e32 v64, 2, v64
	v_mad_i64_i32 v[116:117], s[0:1], v116, s62, v[108:109]
	s_waitcnt vmcnt(16)
	v_lshlrev_b32_e32 v118, 16, v118
	s_waitcnt vmcnt(15)
	v_lshlrev_b32_e32 v119, 16, v119
	v_pk_add_f32 v[122:123], v[122:123], v[118:119]
	s_waitcnt vmcnt(14)
; __device__ __forceinline__ bf16_t f2bf(float f) { return (bf16_t)(cvt_pk_bf16(f, 0.f) & 0xffffu); }
; __device__ __forceinline__ float bf2f(bf16_t b) { return __uint_as_float(((unsigned)b) << 16); }
; __device__ __forceinline__ float siluf_(float x) { return x * sigmoidf_(x); }
; template <int MODE>
; __device__ __forceinline__ void hgrn_mfma(const Ctx& C, int l, int z, int b, int hd, int c, f32x4 (&Sacc)[4][4], float& dectot, unsigned char* wl, float lb) {
;     ...
;                 bf16_t tmpv[4][4], gtv[4][4];
; #pragma unroll
;                 for (int r = 0; r < 4; ++r) { const int st = c * 128 + sc * 32 + 16 * tt + 4 * quad + r; const int tq = z ? 4095 - st : st;
;                     const size_t tok = (size_t)(b * SEQ + tq); const bf16_t* yp = ya + tok * 256 + hd * 64 + fr; const bf16_t* gp = pa + tok * 1280 + 1024 + hd * 64 + fr;
; #pragma unroll
;                     for (int vt = 0; vt < 4; ++vt) { tmpv[r][vt] = yp[16 * vt]; gtv[r][vt] = gp[16 * vt]; } }
; #pragma unroll
;                 for (int r = 0; r < 4; ++r) { const int st = c * 128 + sc * 32 + 16 * tt + 4 * quad + r; const int tq = z ? 4095 - st : st;
;                     bf16_t* yp = ya + (size_t)(b * SEQ + tq) * 256 + hd * 64 + fr;
;                     float o[4]; float ss = 0.f;
; #pragma unroll
;                     for (int vt = 0; vt < 4; ++vt) { o[vt] = Oacc[tt][vt][r] + bf2f(tmpv[r][vt]); ss += o[vt] * o[vt]; }
;                     ss += __shfl_xor(ss, 1); ss += __shfl_xor(ss, 2); ss += __shfl_xor(ss, 4); ss += __shfl_xor(ss, 8);
;                     const float rs = rsqrtf(ss * (1.f / 64.f) + 1e-6f);
; #pragma unroll
;                     for (int vt = 0; vt < 4; ++vt) yp[16 * vt] = f2bf(o[vt] * rs * gnv[vt] * siluf_(bf2f(gtv[r][vt]))); }
	v_lshlrev_b32_e32 v118, 16, v130
	v_mov_b32_e32 v130, v90
	s_waitcnt vmcnt(13)
	v_lshlrev_b32_e32 v119, 16, v131
	v_mov_b32_e32 v131, v94
	v_pk_mul_f32 v[128:129], v[122:123], v[122:123]
	s_waitcnt vmcnt(0)
	v_lshlrev_b32_e32 v82, 16, v82
	v_mul_f32_e32 v86, 0xbfb8aa3b, v82
	v_exp_f32_e32 v86, v86
	v_pk_add_f32 v[118:119], v[130:131], v[118:119]
	v_add_f32_e32 v86, 1.0, v86
	v_pk_mul_f32 v[130:131], v[118:119], v[118:119]
	v_rcp_f32_e32 v86, v86
	s_nop 0
	v_mul_f32_e32 v246, v86, v82
	global_load_ushort v82, v[126:127], off offset:2080
	s_waitcnt vmcnt(0)
	v_lshlrev_b32_e32 v82, 16, v82
	v_mul_f32_e32 v86, 0xbfb8aa3b, v82
	v_exp_f32_e32 v86, v86
	s_nop 0
	v_add_f32_e32 v86, 1.0, v86
	v_rcp_f32_e32 v86, v86
	s_nop 0
	v_mul_f32_e32 v239, v86, v82
	global_load_ushort v82, v[126:127], off offset:2112
	s_waitcnt vmcnt(0)
	v_lshlrev_b32_e32 v82, 16, v82
	v_mul_f32_e32 v86, 0xbfb8aa3b, v82
	v_exp_f32_e32 v86, v86
	s_nop 0
	v_add_f32_e32 v86, 1.0, v86
	v_rcp_f32_e32 v86, v86
	s_nop 0
	v_mul_f32_e32 v240, v86, v82
	global_load_ushort v82, v[126:127], off offset:2144
	s_waitcnt vmcnt(0)
	v_lshlrev_b32_e32 v82, 16, v82
	v_mul_f32_e32 v86, 0xbfb8aa3b, v82
	v_exp_f32_e32 v86, v86
	s_nop 0
	v_add_f32_e32 v86, 1.0, v86
	v_rcp_f32_e32 v86, v86
	s_nop 0
	v_mul_f32_e32 v241, v86, v82
	v_lshlrev_b32_e32 v127, 16, v245
	v_lshlrev_b32_e32 v126, 16, v244
	v_mov_b32_e32 v86, v83
	v_pk_add_f32 v[126:127], v[86:87], v[126:127]
	v_lshlrev_b32_e32 v87, 16, v243
	v_lshlrev_b32_e32 v86, 16, v242
	v_mov_b32_e32 v94, v91
	v_pk_mul_f32 v[82:83], v[126:127], v[126:127]
	v_pk_add_f32 v[86:87], v[94:95], v[86:87]
	v_mov_b32_e32 v94, v82
	v_pk_mul_f32 v[90:91], v[86:87], v[86:87]
	v_mov_b32_e32 v95, v128
	v_mov_b32_e32 v128, v83
	v_pk_add_f32 v[82:83], v[94:95], v[128:129]
	v_mov_b32_e32 v94, v90
	v_mov_b32_e32 v95, v130
	v_pk_add_f32 v[82:83], v[82:83], v[94:95]
	v_mov_b32_e32 v130, v91
	v_pk_add_f32 v[82:83], v[82:83], v[130:131]
	ds_bpermute_b32 v91, v231, v83
	ds_bpermute_b32 v90, v231, v82
	s_waitcnt lgkmcnt(0)
	v_pk_add_f32 v[82:83], v[82:83], v[90:91]
	ds_bpermute_b32 v91, v230, v83
	ds_bpermute_b32 v90, v230, v82
	s_waitcnt lgkmcnt(0)
	v_pk_add_f32 v[82:83], v[82:83], v[90:91]
	ds_bpermute_b32 v91, v229, v83
	ds_bpermute_b32 v90, v229, v82
	s_waitcnt lgkmcnt(0)
	v_pk_add_f32 v[82:83], v[82:83], v[90:91]
	ds_bpermute_b32 v91, v64, v83
	ds_bpermute_b32 v90, v64, v82
	s_waitcnt lgkmcnt(0)
	v_pk_add_f32 v[90:91], v[82:83], v[90:91]
	v_mov_b64_e32 v[82:83], s[66:67]
	v_pk_fma_f32 v[90:91], v[90:91], s[2:3], v[82:83] op_sel_hi:[1,0,0]
	v_mul_f32_e32 v94, 0x4b800000, v91
	v_cmp_gt_f32_e64 s[0:1], s54, v91
	v_cmp_gt_f32_e32 vcc, s54, v90
	s_nop 0
	v_cndmask_b32_e64 v91, v91, v94, s[0:1]
	v_rsq_f32_e32 v91, v91
	s_nop 0
	v_mul_f32_e32 v94, 0x45800000, v91
	v_cndmask_b32_e64 v91, v91, v94, s[0:1]
	v_mul_f32_e32 v94, v122, v91
	global_load_ushort v95, v[124:125], off offset:2048
	global_load_ushort v128, v[124:125], off offset:2080
	global_load_ushort v129, v[124:125], off offset:2112
	global_load_ushort v130, v[124:125], off offset:2144
	global_load_ushort v131, v[120:121], off offset:2048
	global_load_ushort v178, v[120:121], off offset:2080
	global_load_ushort v125, v[120:121], off offset:2112
	global_load_ushort v124, v[120:121], off offset:2144
	global_load_ushort v122, v[116:117], off offset:2048
	global_load_ushort v121, v[116:117], off offset:2080
	global_load_ushort v120, v[116:117], off offset:2112
	global_load_ushort v116, v[116:117], off offset:2144
	v_mul_f32_e32 v94, v209, v94
	v_mul_f32_e32 v94, v246, v94
	v_cvt_pk_bf16_f32 v94, v94, s0
	global_store_short v[114:115], v94, off
	v_mul_f32_e32 v94, v123, v91
	v_mul_f32_e32 v94, v210, v94
	v_mul_f32_e32 v94, v239, v94
	v_cvt_pk_bf16_f32 v94, v94, s0
	global_store_short v[114:115], v94, off offset:32
	v_mul_f32_e32 v94, v118, v91
	v_mul_f32_e32 v94, v211, v94
	v_mul_f32_e32 v94, v240, v94
	v_cvt_pk_bf16_f32 v94, v94, s0
	global_store_short v[114:115], v94, off offset:64
	v_mul_f32_e32 v91, v119, v91
	v_mul_f32_e32 v91, v212, v91
	v_mul_f32_e32 v91, v241, v91
	v_cvt_pk_bf16_f32 v91, v91, s0
	global_store_short v[114:115], v91, off offset:96
	v_mul_f32_e32 v91, 0x4b800000, v90
	v_cndmask_b32_e32 v90, v90, v91, vcc
	v_rsq_f32_e32 v90, v90
	s_waitcnt vmcnt(15)
	v_lshlrev_b32_e32 v94, 16, v95
	v_mul_f32_e32 v95, 0xbfb8aa3b, v94
	v_exp_f32_e32 v95, v95
	v_mul_f32_e32 v91, 0x45800000, v90
	v_cndmask_b32_e32 v90, v90, v91, vcc
	v_mul_f32_e32 v91, v126, v90
	v_add_f32_e32 v95, 1.0, v95
	v_mul_f32_e32 v91, v209, v91
	v_mul_f32_e32 v86, v86, v90
	v_mul_f32_e32 v86, v211, v86
	v_rcp_f32_e32 v95, v95
	s_nop 0
	v_mul_f32_e32 v94, v95, v94
	v_mul_f32_e32 v91, v94, v91
	s_waitcnt vmcnt(14)
	v_lshlrev_b32_e32 v94, 16, v128
	v_mul_f32_e32 v95, 0xbfb8aa3b, v94
	v_exp_f32_e32 v95, v95
	v_cvt_pk_bf16_f32 v91, v91, s0
	global_store_short v[112:113], v91, off
	v_mul_f32_e32 v91, v127, v90
	v_add_f32_e32 v95, 1.0, v95
	v_mul_f32_e32 v91, v210, v91
	v_rcp_f32_e32 v95, v95
	s_nop 0
	v_mul_f32_e32 v94, v95, v94
	v_mul_f32_e32 v91, v94, v91
	v_cvt_pk_bf16_f32 v91, v91, s0
	global_store_short v[112:113], v91, off offset:32
	s_waitcnt vmcnt(15)
	v_lshlrev_b32_e32 v91, 16, v129
	v_mul_f32_e32 v94, 0xbfb8aa3b, v91
	v_exp_f32_e32 v94, v94
	s_nop 0
	v_add_f32_e32 v94, 1.0, v94
	v_rcp_f32_e32 v94, v94
	s_nop 0
	v_mul_f32_e32 v91, v94, v91
	v_mul_f32_e32 v86, v91, v86
	v_cvt_pk_bf16_f32 v86, v86, s0
	global_store_short v[112:113], v86, off offset:64
	v_mul_f32_e32 v86, v87, v90
	s_waitcnt vmcnt(15)
	v_lshlrev_b32_e32 v87, 16, v130
	v_mul_f32_e32 v90, 0xbfb8aa3b, v87
	v_exp_f32_e32 v90, v90
	v_mul_f32_e32 v86, v212, v86
	v_add_f32_e32 v90, 1.0, v90
	v_rcp_f32_e32 v90, v90
	s_nop 0
	v_mul_f32_e32 v87, v90, v87
	v_mov_b32_e32 v90, v84
	s_waitcnt vmcnt(14)
; __device__ __forceinline__ bf16_t f2bf(float f) { return (bf16_t)(cvt_pk_bf16(f, 0.f) & 0xffffu); }
; __device__ __forceinline__ float bf2f(bf16_t b) { return __uint_as_float(((unsigned)b) << 16); }
; __device__ __forceinline__ float siluf_(float x) { return x * sigmoidf_(x); }
; template <int MODE>
; __device__ __forceinline__ void hgrn_mfma(const Ctx& C, int l, int z, int b, int hd, int c, f32x4 (&Sacc)[4][4], float& dectot, unsigned char* wl, float lb) {
;     ...
;                 for (int r = 0; r < 4; ++r) { const int st = c * 128 + sc * 32 + 16 * tt + 4 * quad + r; const int tq = z ? 4095 - st : st;
;                     bf16_t* yp = ya + (size_t)(b * SEQ + tq) * 256 + hd * 64 + fr;
;                     float o[4]; float ss = 0.f;
; #pragma unroll
;                     for (int vt = 0; vt < 4; ++vt) { o[vt] = Oacc[tt][vt][r] + bf2f(tmpv[r][vt]); ss += o[vt] * o[vt]; }
;                     ss += __shfl_xor(ss, 1); ss += __shfl_xor(ss, 2); ss += __shfl_xor(ss, 4); ss += __shfl_xor(ss, 8);
;                     const float rs = rsqrtf(ss * (1.f / 64.f) + 1e-6f);
; #pragma unroll
;                     for (int vt = 0; vt < 4; ++vt) yp[16 * vt] = f2bf(o[vt] * rs * gnv[vt] * siluf_(bf2f(gtv[r][vt]))); }
	v_lshlrev_b32_e32 v84, 16, v131
	v_mov_b32_e32 v91, v88
	v_mul_f32_e32 v88, 0xbfb8aa3b, v84
	v_exp_f32_e32 v88, v88
	v_mul_f32_e32 v86, v87, v86
	v_cvt_pk_bf16_f32 v86, v86, s0
	v_mov_b32_e32 v94, v92
	v_add_f32_e32 v88, 1.0, v88
	v_mov_b32_e32 v95, v96
	global_store_short v[112:113], v86, off offset:96
	v_lshlrev_b32_e32 v87, 16, v238
	v_lshlrev_b32_e32 v86, 16, v237
	v_rcp_f32_e32 v88, v88
	s_nop 0
	v_mul_f32_e32 v117, v88, v84
	s_waitcnt vmcnt(14)
	v_lshlrev_b32_e32 v84, 16, v178
	v_mul_f32_e32 v88, 0xbfb8aa3b, v84
	v_exp_f32_e32 v88, v88
	v_pk_add_f32 v[90:91], v[90:91], v[86:87]
	v_lshlrev_b32_e32 v87, 16, v236
	v_lshlrev_b32_e32 v86, 16, v235
	v_add_f32_e32 v88, 1.0, v88
	v_pk_mul_f32 v[112:113], v[90:91], v[90:91]
	v_pk_add_f32 v[86:87], v[94:95], v[86:87]
	v_rcp_f32_e32 v88, v88
	s_nop 0
	v_mul_f32_e32 v118, v88, v84
	s_waitcnt vmcnt(13)
	v_lshlrev_b32_e32 v84, 16, v125
	v_mul_f32_e32 v88, 0xbfb8aa3b, v84
	v_exp_f32_e32 v88, v88
	v_pk_mul_f32 v[94:95], v[86:87], v[86:87]
	v_add_f32_e32 v88, 1.0, v88
	v_rcp_f32_e32 v88, v88
	s_nop 0
	v_mul_f32_e32 v119, v88, v84
	s_waitcnt vmcnt(12)
	v_lshlrev_b32_e32 v84, 16, v124
	v_mul_f32_e32 v88, 0xbfb8aa3b, v84
	v_exp_f32_e32 v88, v88
	s_nop 0
	v_add_f32_e32 v88, 1.0, v88
	v_rcp_f32_e32 v88, v88
	s_nop 0
	v_mul_f32_e32 v123, v88, v84
	v_lshlrev_b32_e32 v115, 16, v234
	v_lshlrev_b32_e32 v114, 16, v233
	v_mov_b32_e32 v88, v85
	v_pk_add_f32 v[88:89], v[88:89], v[114:115]
	v_lshlrev_b32_e32 v85, 16, v232
	v_lshlrev_b32_e32 v84, 16, v99
	v_mov_b32_e32 v96, v93
	v_pk_mul_f32 v[114:115], v[88:89], v[88:89]
	v_pk_add_f32 v[84:85], v[96:97], v[84:85]
	v_mov_b32_e32 v96, v114
	v_pk_mul_f32 v[92:93], v[84:85], v[84:85]
	v_mov_b32_e32 v97, v112
	v_mov_b32_e32 v112, v115
	v_pk_add_f32 v[96:97], v[96:97], v[112:113]
	v_mov_b32_e32 v112, v92
	v_mov_b32_e32 v113, v94
	v_pk_add_f32 v[96:97], v[96:97], v[112:113]
	v_mov_b32_e32 v94, v93
	v_pk_add_f32 v[92:93], v[96:97], v[94:95]
	ds_bpermute_b32 v95, v231, v93
	ds_bpermute_b32 v94, v231, v92
	v_mov_b32_e32 v99, v74
	s_waitcnt lgkmcnt(0)
	v_pk_add_f32 v[92:93], v[92:93], v[94:95]
	ds_bpermute_b32 v95, v230, v93
	ds_bpermute_b32 v94, v230, v92
	s_waitcnt lgkmcnt(0)
	v_pk_add_f32 v[92:93], v[92:93], v[94:95]
	ds_bpermute_b32 v95, v229, v93
	ds_bpermute_b32 v94, v229, v92
	s_waitcnt lgkmcnt(0)
	v_pk_add_f32 v[92:93], v[92:93], v[94:95]
	ds_bpermute_b32 v95, v64, v93
	ds_bpermute_b32 v94, v64, v92
	s_waitcnt lgkmcnt(0)
	v_pk_add_f32 v[92:93], v[92:93], v[94:95]
	v_pk_fma_f32 v[92:93], v[92:93], s[2:3], v[82:83] op_sel_hi:[1,0,0]
	v_mul_f32_e32 v94, 0x4b800000, v93
	v_cmp_gt_f32_e64 s[0:1], s54, v93
	v_cmp_gt_f32_e32 vcc, s54, v92
	s_nop 0
	v_cndmask_b32_e64 v93, v93, v94, s[0:1]
	v_rsq_f32_e32 v93, v93
	s_nop 0
	v_mul_f32_e32 v94, 0x45800000, v93
	v_cndmask_b32_e64 v93, v93, v94, s[0:1]
	v_mul_f32_e32 v86, v86, v93
	v_mul_f32_e32 v86, v211, v86
	v_mul_f32_e32 v86, v119, v86
	v_cvt_pk_bf16_f32 v86, v86, s0
	global_store_short v[110:111], v86, off offset:64
	v_mul_f32_e32 v86, v87, v93
	v_mul_f32_e32 v86, v212, v86
	v_mul_f32_e32 v86, v123, v86
	v_cvt_pk_bf16_f32 v86, v86, s0
	global_store_short v[110:111], v86, off offset:96
	v_mul_f32_e32 v86, 0x4b800000, v92
	v_mul_f32_e32 v90, v90, v93
	v_cndmask_b32_e32 v86, v92, v86, vcc
	v_mul_f32_e32 v90, v209, v90
	v_rsq_f32_e32 v86, v86
	v_mul_f32_e32 v90, v117, v90
	v_cvt_pk_bf16_f32 v90, v90, s0
	global_store_short v[110:111], v90, off
	v_mul_f32_e32 v90, v91, v93
	v_mul_f32_e32 v90, v210, v90
	v_mul_f32_e32 v87, 0x45800000, v86
	v_mul_f32_e32 v90, v118, v90
	v_cndmask_b32_e32 v86, v86, v87, vcc
	v_cvt_pk_bf16_f32 v90, v90, s0
	v_mul_f32_e32 v87, v88, v86
	s_waitcnt vmcnt(14)
	v_lshlrev_b32_e32 v88, 16, v122
	global_store_short v[110:111], v90, off offset:32
	v_mul_f32_e32 v90, 0xbfb8aa3b, v88
	v_exp_f32_e32 v90, v90
	v_mul_f32_e32 v87, v209, v87
	v_mul_f32_e32 v84, v84, v86
	v_mul_f32_e32 v84, v211, v84
	v_add_f32_e32 v90, 1.0, v90
	v_rcp_f32_e32 v90, v90
	s_nop 0
	v_mul_f32_e32 v88, v90, v88
	v_mul_f32_e32 v87, v88, v87
	v_cvt_pk_bf16_f32 v87, v87, s0
	s_waitcnt vmcnt(14)
	v_lshlrev_b32_e32 v88, 16, v121
	global_store_short v[100:101], v87, off
	v_mul_f32_e32 v87, v89, v86
	v_mul_f32_e32 v89, 0xbfb8aa3b, v88
	v_exp_f32_e32 v89, v89
	v_mul_f32_e32 v87, v210, v87
	v_add_f32_e32 v89, 1.0, v89
	v_rcp_f32_e32 v89, v89
	s_nop 0
	v_mul_f32_e32 v88, v89, v88
	v_mul_f32_e32 v87, v88, v87
	v_cvt_pk_bf16_f32 v87, v87, s0
	global_store_short v[100:101], v87, off offset:32
	s_waitcnt vmcnt(15)
	v_lshlrev_b32_e32 v87, 16, v120
	v_mul_f32_e32 v88, 0xbfb8aa3b, v87
	v_exp_f32_e32 v88, v88
	s_nop 0
	v_add_f32_e32 v88, 1.0, v88
	v_rcp_f32_e32 v88, v88
	s_nop 0
	v_mul_f32_e32 v87, v88, v87
	v_mul_f32_e32 v84, v87, v84
	v_cvt_pk_bf16_f32 v84, v84, s0
	global_store_short v[100:101], v84, off offset:64
	v_mul_f32_e32 v84, v85, v86
	s_waitcnt vmcnt(15)
; __device__ __forceinline__ bf16_t f2bf(float f) { return (bf16_t)(cvt_pk_bf16(f, 0.f) & 0xffffu); }
; __device__ __forceinline__ float bf2f(bf16_t b) { return __uint_as_float(((unsigned)b) << 16); }
; __device__ __forceinline__ float siluf_(float x) { return x * sigmoidf_(x); }
; template <int MODE>
; __device__ __forceinline__ void hgrn_mfma(const Ctx& C, int l, int z, int b, int hd, int c, f32x4 (&Sacc)[4][4], float& dectot, unsigned char* wl, float lb) {
;     ...
;                 bf16_t tmpv[4][4], gtv[4][4];
; #pragma unroll
;                 for (int r = 0; r < 4; ++r) { const int st = c * 128 + sc * 32 + 16 * tt + 4 * quad + r; const int tq = z ? 4095 - st : st;
;                     const size_t tok = (size_t)(b * SEQ + tq); const bf16_t* yp = ya + tok * 256 + hd * 64 + fr; const bf16_t* gp = pa + tok * 1280 + 1024 + hd * 64 + fr;
; #pragma unroll
;                     for (int vt = 0; vt < 4; ++vt) { tmpv[r][vt] = yp[16 * vt]; gtv[r][vt] = gp[16 * vt]; } }
; #pragma unroll
;                 for (int r = 0; r < 4; ++r) { const int st = c * 128 + sc * 32 + 16 * tt + 4 * quad + r; const int tq = z ? 4095 - st : st;
;                     bf16_t* yp = ya + (size_t)(b * SEQ + tq) * 256 + hd * 64 + fr;
;                     float o[4]; float ss = 0.f;
; #pragma unroll
;                     for (int vt = 0; vt < 4; ++vt) { o[vt] = Oacc[tt][vt][r] + bf2f(tmpv[r][vt]); ss += o[vt] * o[vt]; }
;                     ss += __shfl_xor(ss, 1); ss += __shfl_xor(ss, 2); ss += __shfl_xor(ss, 4); ss += __shfl_xor(ss, 8);
;                     const float rs = rsqrtf(ss * (1.f / 64.f) + 1e-6f);
; #pragma unroll
;                     for (int vt = 0; vt < 4; ++vt) yp[16 * vt] = f2bf(o[vt] * rs * gnv[vt] * siluf_(bf2f(gtv[r][vt]))); }
	v_lshlrev_b32_e32 v85, 16, v116
	v_mul_f32_e32 v86, 0xbfb8aa3b, v85
	v_exp_f32_e32 v86, v86
	v_mul_f32_e32 v84, v212, v84
	v_or_b32_e32 v92, 19, v98
	v_ashrrev_i32_e32 v93, 31, v92
	v_add_f32_e32 v86, 1.0, v86
	v_rcp_f32_e32 v86, v86
	s_nop 0
	v_mul_f32_e32 v85, v86, v85
	v_mul_f32_e32 v84, v85, v84
	v_cvt_pk_bf16_f32 v84, v84, s0
	global_store_short v[100:101], v84, off offset:96
	v_or_b32_e32 v84, 16, v98
	v_ashrrev_i32_e32 v85, 31, v84
	v_lshlrev_b64 v[86:87], 9, v[84:85]
	v_lshl_add_u64 v[90:91], v[106:107], 0, v[86:87]
	global_load_ushort v94, v[90:91], off
	global_load_ushort v95, v[90:91], off offset:32
	global_load_ushort v114, v[90:91], off offset:64
	global_load_ushort v115, v[90:91], off offset:96
	v_mad_i64_i32 v[110:111], s[0:1], v84, s62, v[108:109]
	v_or_b32_e32 v84, 17, v98
	v_ashrrev_i32_e32 v85, 31, v84
	v_lshlrev_b64 v[86:87], 9, v[84:85]
	v_mad_i64_i32 v[100:101], s[0:1], v84, s62, v[108:109]
	v_or_b32_e32 v84, 18, v98
	v_ashrrev_i32_e32 v85, 31, v84
	v_lshl_add_u64 v[88:89], v[106:107], 0, v[86:87]
	v_lshlrev_b64 v[86:87], 9, v[84:85]
	v_mad_i64_i32 v[96:97], s[0:1], v84, s62, v[108:109]
	v_lshlrev_b64 v[84:85], 9, v[92:93]
	v_lshl_add_u64 v[86:87], v[106:107], 0, v[86:87]
	v_lshl_add_u64 v[84:85], v[106:107], 0, v[84:85]
	v_mov_b32_e32 v98, v70
	global_load_ushort v127, v[88:89], off
	global_load_ushort v128, v[88:89], off offset:32
	global_load_ushort v125, v[88:89], off offset:64
	global_load_ushort v126, v[88:89], off offset:96
	global_load_ushort v122, v[86:87], off
	global_load_ushort v123, v[86:87], off offset:32
	global_load_ushort v120, v[86:87], off offset:64
	global_load_ushort v121, v[86:87], off offset:96
	global_load_ushort v118, v[84:85], off
	global_load_ushort v119, v[84:85], off offset:32
	global_load_ushort v116, v[84:85], off offset:64
	global_load_ushort v117, v[84:85], off offset:96
	v_mad_i64_i32 v[92:93], s[0:1], v92, s62, v[108:109]
	s_waitcnt vmcnt(15)
	v_lshlrev_b32_e32 v94, 16, v94
	s_waitcnt vmcnt(14)
	v_lshlrev_b32_e32 v95, 16, v95
	v_pk_add_f32 v[98:99], v[98:99], v[94:95]
	s_waitcnt vmcnt(12)
	v_lshlrev_b32_e32 v95, 16, v115
	v_mov_b32_e32 v115, v60
	global_load_ushort v60, v[110:111], off offset:2048
	v_lshlrev_b32_e32 v94, 16, v114
	v_mov_b32_e32 v114, v78
	v_pk_mul_f32 v[112:113], v[98:99], v[98:99]
	v_pk_add_f32 v[94:95], v[114:115], v[94:95]
	s_waitcnt vmcnt(0)
	v_lshlrev_b32_e32 v60, 16, v60
	v_mul_f32_e32 v70, 0xbfb8aa3b, v60
	v_exp_f32_e32 v70, v70
	v_pk_mul_f32 v[114:115], v[94:95], v[94:95]
	v_add_f32_e32 v70, 1.0, v70
	v_rcp_f32_e32 v70, v70
	s_nop 0
	v_mul_f32_e32 v129, v70, v60
	global_load_ushort v60, v[110:111], off offset:2080
	s_waitcnt vmcnt(0)
	v_lshlrev_b32_e32 v60, 16, v60
	v_mul_f32_e32 v70, 0xbfb8aa3b, v60
	v_exp_f32_e32 v70, v70
	s_nop 0
	v_add_f32_e32 v70, 1.0, v70
	v_rcp_f32_e32 v70, v70
	s_nop 0
	v_mul_f32_e32 v78, v70, v60
	global_load_ushort v60, v[110:111], off offset:2112
	s_waitcnt vmcnt(0)
	v_lshlrev_b32_e32 v60, 16, v60
	v_mul_f32_e32 v70, 0xbfb8aa3b, v60
	v_exp_f32_e32 v70, v70
	s_nop 0
	v_add_f32_e32 v70, 1.0, v70
	v_rcp_f32_e32 v70, v70
	s_nop 0
	v_mul_f32_e32 v124, v70, v60
	global_load_ushort v60, v[110:111], off offset:2144
	s_waitcnt vmcnt(0)
	v_lshlrev_b32_e32 v60, 16, v60
	v_mul_f32_e32 v70, 0xbfb8aa3b, v60
	v_exp_f32_e32 v70, v70
	s_nop 0
	v_add_f32_e32 v70, 1.0, v70
	v_rcp_f32_e32 v70, v70
	v_lshlrev_b32_e32 v131, 16, v128
	v_lshlrev_b32_e32 v130, 16, v127
	v_mov_b32_e32 v74, v71
	v_mul_f32_e32 v110, v70, v60
	v_pk_add_f32 v[70:71], v[74:75], v[130:131]
	v_lshlrev_b32_e32 v127, 16, v126
	v_lshlrev_b32_e32 v126, 16, v125
	v_mov_b32_e32 v60, v79
	v_pk_mul_f32 v[74:75], v[70:71], v[70:71]
	v_pk_add_f32 v[60:61], v[60:61], v[126:127]
	v_mov_b32_e32 v130, v74
	v_pk_mul_f32 v[126:127], v[60:61], v[60:61]
	v_mov_b32_e32 v131, v112
	v_mov_b32_e32 v112, v75
	v_pk_add_f32 v[74:75], v[130:131], v[112:113]
	v_mov_b32_e32 v112, v126
	v_mov_b32_e32 v113, v114
	v_pk_add_f32 v[74:75], v[74:75], v[112:113]
	v_mov_b32_e32 v114, v127
	v_pk_add_f32 v[74:75], v[74:75], v[114:115]
	ds_bpermute_b32 v113, v231, v75
	ds_bpermute_b32 v112, v231, v74
	s_waitcnt lgkmcnt(0)
	v_pk_add_f32 v[74:75], v[74:75], v[112:113]
	ds_bpermute_b32 v113, v230, v75
	ds_bpermute_b32 v112, v230, v74
	s_waitcnt lgkmcnt(0)
	v_pk_add_f32 v[74:75], v[74:75], v[112:113]
	ds_bpermute_b32 v113, v229, v75
	ds_bpermute_b32 v112, v229, v74
	s_waitcnt lgkmcnt(0)
	v_pk_add_f32 v[74:75], v[74:75], v[112:113]
	ds_bpermute_b32 v113, v64, v75
	ds_bpermute_b32 v112, v64, v74
	s_waitcnt lgkmcnt(0)
	v_pk_add_f32 v[74:75], v[74:75], v[112:113]
	v_pk_fma_f32 v[74:75], v[74:75], s[2:3], v[82:83] op_sel_hi:[1,0,0]
	v_mul_f32_e32 v79, 0x4b800000, v75
	v_cmp_gt_f32_e64 s[0:1], s54, v75
	v_cmp_gt_f32_e32 vcc, s54, v74
	s_nop 0
	v_cndmask_b32_e64 v75, v75, v79, s[0:1]
	v_rsq_f32_e32 v75, v75
	s_nop 0
	v_mul_f32_e32 v79, 0x45800000, v75
	v_cndmask_b32_e64 v75, v75, v79, s[0:1]
	v_mul_f32_e32 v79, v98, v75
	global_load_ushort v111, v[100:101], off offset:2048
	global_load_ushort v112, v[100:101], off offset:2080
	global_load_ushort v113, v[100:101], off offset:2112
	global_load_ushort v114, v[100:101], off offset:2144
	global_load_ushort v115, v[96:97], off offset:2048
	global_load_ushort v125, v[96:97], off offset:2080
	global_load_ushort v101, v[96:97], off offset:2112
	global_load_ushort v100, v[96:97], off offset:2144
	global_load_ushort v98, v[92:93], off offset:2048
	global_load_ushort v97, v[92:93], off offset:2080
	global_load_ushort v96, v[92:93], off offset:2112
	global_load_ushort v92, v[92:93], off offset:2144
	v_mul_f32_e32 v79, v209, v79
	v_mul_f32_e32 v79, v129, v79
	v_cvt_pk_bf16_f32 v79, v79, s0
	global_store_short v[90:91], v79, off
	v_mul_f32_e32 v79, v99, v75
	v_mul_f32_e32 v79, v210, v79
	v_mul_f32_e32 v78, v78, v79
	v_cvt_pk_bf16_f32 v78, v78, s0
	global_store_short v[90:91], v78, off offset:32
	v_mul_f32_e32 v78, v94, v75
	v_mul_f32_e32 v75, v95, v75
	v_mul_f32_e32 v75, v212, v75
	v_mul_f32_e32 v75, v110, v75
	v_cvt_pk_bf16_f32 v75, v75, s0
	global_store_short v[90:91], v75, off offset:96
	v_mul_f32_e32 v75, 0x4b800000, v74
	v_cndmask_b32_e32 v74, v74, v75, vcc
	v_rsq_f32_e32 v74, v74
	v_mul_f32_e32 v78, v211, v78
	v_mul_f32_e32 v78, v124, v78
	v_cvt_pk_bf16_f32 v78, v78, s0
	v_mul_f32_e32 v75, 0x45800000, v74
	v_cndmask_b32_e32 v74, v74, v75, vcc
	global_store_short v[90:91], v78, off offset:64
	v_mul_f32_e32 v70, v70, v74
	v_mul_f32_e32 v70, v209, v70
	v_mul_f32_e32 v60, v60, v74
	v_mul_f32_e32 v60, v211, v60
	s_waitcnt vmcnt(15)
; __device__ __forceinline__ bf16_t f2bf(float f) { return (bf16_t)(cvt_pk_bf16(f, 0.f) & 0xffffu); }
; __device__ __forceinline__ float bf2f(bf16_t b) { return __uint_as_float(((unsigned)b) << 16); }
; __device__ __forceinline__ float siluf_(float x) { return x * sigmoidf_(x); }
; __device__ __forceinline__ void wave_lds_fence() { asm volatile("s_waitcnt lgkmcnt(0)" ::: "memory"); __builtin_amdgcn_wave_barrier(); }
; template <int MODE>
; __device__ __forceinline__ void hgrn_mfma(const Ctx& C, int l, int z, int b, int hd, int c, f32x4 (&Sacc)[4][4], float& dectot, unsigned char* wl, float lb) {
;     ...
;                 for (int r = 0; r < 4; ++r) { const int st = c * 128 + sc * 32 + 16 * tt + 4 * quad + r; const int tq = z ? 4095 - st : st;
;                     bf16_t* yp = ya + (size_t)(b * SEQ + tq) * 256 + hd * 64 + fr;
;                     float o[4]; float ss = 0.f;
; #pragma unroll
;                     for (int vt = 0; vt < 4; ++vt) { o[vt] = Oacc[tt][vt][r] + bf2f(tmpv[r][vt]); ss += o[vt] * o[vt]; }
;                     ss += __shfl_xor(ss, 1); ss += __shfl_xor(ss, 2); ss += __shfl_xor(ss, 4); ss += __shfl_xor(ss, 8);
;                     const float rs = rsqrtf(ss * (1.f / 64.f) + 1e-6f);
; #pragma unroll
;                     for (int vt = 0; vt < 4; ++vt) yp[16 * vt] = f2bf(o[vt] * rs * gnv[vt] * siluf_(bf2f(gtv[r][vt]))); }
;                 asm volatile("" ::: "memory");
;             }
;         }
;         wave_lds_fence();
	v_lshlrev_b32_e32 v75, 16, v111
	v_mul_f32_e32 v78, 0xbfb8aa3b, v75
	v_exp_f32_e32 v78, v78
	s_nop 0
	v_add_f32_e32 v78, 1.0, v78
	v_rcp_f32_e32 v78, v78
	s_nop 0
	v_mul_f32_e32 v75, v78, v75
	v_mul_f32_e32 v70, v75, v70
	v_cvt_pk_bf16_f32 v70, v70, s0
	global_store_short v[88:89], v70, off
	v_mul_f32_e32 v70, v71, v74
	s_waitcnt vmcnt(15)
	v_lshlrev_b32_e32 v71, 16, v112
	v_mul_f32_e32 v75, 0xbfb8aa3b, v71
	v_exp_f32_e32 v75, v75
	v_mul_f32_e32 v70, v210, v70
	v_add_f32_e32 v75, 1.0, v75
	v_rcp_f32_e32 v75, v75
	s_nop 0
	v_mul_f32_e32 v71, v75, v71
	v_mul_f32_e32 v70, v71, v70
	v_cvt_pk_bf16_f32 v70, v70, s0
	global_store_short v[88:89], v70, off offset:32
	s_waitcnt vmcnt(15)
	v_lshlrev_b32_e32 v70, 16, v113
	v_mul_f32_e32 v71, 0xbfb8aa3b, v70
	v_exp_f32_e32 v71, v71
	s_nop 0
	v_add_f32_e32 v71, 1.0, v71
	v_rcp_f32_e32 v71, v71
	s_nop 0
	v_mul_f32_e32 v70, v71, v70
	v_mul_f32_e32 v60, v70, v60
	v_cvt_pk_bf16_f32 v60, v60, s0
	global_store_short v[88:89], v60, off offset:64
	v_mul_f32_e32 v60, v61, v74
	s_waitcnt vmcnt(15)
	v_lshlrev_b32_e32 v61, 16, v114
	v_mul_f32_e32 v70, 0xbfb8aa3b, v61
	v_exp_f32_e32 v70, v70
	v_mul_f32_e32 v60, v212, v60
	v_add_f32_e32 v70, 1.0, v70
	v_rcp_f32_e32 v70, v70
	v_mov_b32_e32 v75, v62
	s_waitcnt vmcnt(14)
	v_lshlrev_b32_e32 v62, 16, v115
	v_mul_f32_e32 v61, v70, v61
	v_mov_b32_e32 v70, v72
	v_mul_f32_e32 v72, 0xbfb8aa3b, v62
	v_exp_f32_e32 v72, v72
	v_mul_f32_e32 v60, v61, v60
	v_cvt_pk_bf16_f32 v60, v60, s0
	v_mov_b32_e32 v71, v76
	v_add_f32_e32 v72, 1.0, v72
	v_mov_b32_e32 v74, v80
	global_store_short v[88:89], v60, off offset:96
	v_lshlrev_b32_e32 v61, 16, v123
	v_lshlrev_b32_e32 v60, 16, v122
	v_rcp_f32_e32 v72, v72
	s_nop 0
	v_mul_f32_e32 v90, v72, v62
	s_waitcnt vmcnt(14)
	v_lshlrev_b32_e32 v62, 16, v125
	v_mul_f32_e32 v72, 0xbfb8aa3b, v62
	v_exp_f32_e32 v72, v72
	v_pk_add_f32 v[70:71], v[70:71], v[60:61]
	v_lshlrev_b32_e32 v61, 16, v121
	v_lshlrev_b32_e32 v60, 16, v120
	v_add_f32_e32 v72, 1.0, v72
	v_pk_mul_f32 v[78:79], v[70:71], v[70:71]
	v_pk_add_f32 v[60:61], v[74:75], v[60:61]
	v_rcp_f32_e32 v72, v72
	s_nop 0
	v_mul_f32_e32 v91, v72, v62
	s_waitcnt vmcnt(13)
	v_lshlrev_b32_e32 v62, 16, v101
	v_mul_f32_e32 v72, 0xbfb8aa3b, v62
	v_exp_f32_e32 v72, v72
	v_pk_mul_f32 v[74:75], v[60:61], v[60:61]
	v_add_f32_e32 v72, 1.0, v72
	v_rcp_f32_e32 v72, v72
	s_nop 0
	v_mul_f32_e32 v93, v72, v62
	s_waitcnt vmcnt(12)
	v_lshlrev_b32_e32 v62, 16, v100
	v_mul_f32_e32 v72, 0xbfb8aa3b, v62
	v_exp_f32_e32 v72, v72
	s_nop 0
	v_add_f32_e32 v72, 1.0, v72
	v_rcp_f32_e32 v72, v72
	v_lshlrev_b32_e32 v89, 16, v119
	v_lshlrev_b32_e32 v88, 16, v118
	v_mov_b32_e32 v76, v73
	v_mul_f32_e32 v94, v72, v62
	v_pk_add_f32 v[72:73], v[76:77], v[88:89]
	v_lshlrev_b32_e32 v89, 16, v117
	v_lshlrev_b32_e32 v88, 16, v116
	v_mov_b32_e32 v62, v81
	v_pk_mul_f32 v[76:77], v[72:73], v[72:73]
	v_pk_add_f32 v[62:63], v[62:63], v[88:89]
	v_mov_b32_e32 v88, v76
	v_pk_mul_f32 v[80:81], v[62:63], v[62:63]
	v_mov_b32_e32 v89, v78
	v_mov_b32_e32 v78, v77
	v_pk_add_f32 v[76:77], v[88:89], v[78:79]
	v_mov_b32_e32 v78, v80
	v_mov_b32_e32 v79, v74
	v_pk_add_f32 v[76:77], v[76:77], v[78:79]
	v_mov_b32_e32 v74, v81
	v_pk_add_f32 v[74:75], v[76:77], v[74:75]
	ds_bpermute_b32 v77, v231, v75
	ds_bpermute_b32 v76, v231, v74
	s_waitcnt lgkmcnt(0)
	v_pk_add_f32 v[74:75], v[74:75], v[76:77]
	ds_bpermute_b32 v77, v230, v75
	ds_bpermute_b32 v76, v230, v74
	s_waitcnt lgkmcnt(0)
	v_pk_add_f32 v[74:75], v[74:75], v[76:77]
	ds_bpermute_b32 v77, v229, v75
	ds_bpermute_b32 v76, v229, v74
	s_waitcnt lgkmcnt(0)
	v_pk_add_f32 v[74:75], v[74:75], v[76:77]
	ds_bpermute_b32 v77, v64, v75
	ds_bpermute_b32 v76, v64, v74
	s_waitcnt lgkmcnt(0)
	v_pk_add_f32 v[74:75], v[74:75], v[76:77]
	v_pk_fma_f32 v[74:75], v[74:75], s[2:3], v[82:83] op_sel_hi:[1,0,0]
	v_mul_f32_e32 v64, 0x4b800000, v75
	v_cmp_gt_f32_e64 s[0:1], s54, v75
	v_cmp_gt_f32_e32 vcc, s54, v74
	s_nop 0
	v_cndmask_b32_e64 v64, v75, v64, s[0:1]
	v_rsq_f32_e32 v64, v64
	s_nop 0
	v_mul_f32_e32 v75, 0x45800000, v64
	v_cndmask_b32_e64 v64, v64, v75, s[0:1]
	v_mul_f32_e32 v60, v60, v64
	v_mul_f32_e32 v70, v70, v64
	v_mul_f32_e32 v60, v211, v60
	v_mul_f32_e32 v70, v209, v70
	v_mul_f32_e32 v60, v93, v60
	v_mul_f32_e32 v70, v90, v70
	v_cvt_pk_bf16_f32 v60, v60, s0
	v_cvt_pk_bf16_f32 v70, v70, s0
	global_store_short v[86:87], v60, off offset:64
	v_mul_f32_e32 v60, v61, v64
	global_store_short v[86:87], v70, off
	v_mul_f32_e32 v70, v71, v64
	v_mul_f32_e32 v60, v212, v60
	v_mul_f32_e32 v70, v210, v70
	v_mul_f32_e32 v60, v94, v60
	v_mul_f32_e32 v70, v91, v70
	v_cvt_pk_bf16_f32 v60, v60, s0
	v_cvt_pk_bf16_f32 v70, v70, s0
	global_store_short v[86:87], v60, off offset:96
	v_mul_f32_e32 v60, 0x4b800000, v74
	s_waitcnt vmcnt(14)
	v_lshlrev_b32_e32 v64, 16, v98
	global_store_short v[86:87], v70, off offset:32
	v_cndmask_b32_e32 v60, v74, v60, vcc
	v_mul_f32_e32 v70, 0xbfb8aa3b, v64
	v_rsq_f32_e32 v60, v60
	v_exp_f32_e32 v70, v70
	v_mul_f32_e32 v61, 0x45800000, v60
	v_add_f32_e32 v70, 1.0, v70
	v_cndmask_b32_e32 v60, v60, v61, vcc
	v_mul_f32_e32 v61, v72, v60
	v_mul_f32_e32 v61, v209, v61
	v_rcp_f32_e32 v70, v70
	s_nop 0
	v_mul_f32_e32 v64, v70, v64
	v_mul_f32_e32 v61, v64, v61
	s_waitcnt vmcnt(14)
	v_lshlrev_b32_e32 v64, 16, v97
	v_mul_f32_e32 v70, 0xbfb8aa3b, v64
	v_exp_f32_e32 v70, v70
	v_cvt_pk_bf16_f32 v61, v61, s0
	global_store_short v[84:85], v61, off
	v_mul_f32_e32 v61, v73, v60
	v_add_f32_e32 v70, 1.0, v70
	v_mul_f32_e32 v61, v210, v61
	v_rcp_f32_e32 v70, v70
	s_nop 0
	v_mul_f32_e32 v64, v70, v64
	v_mul_f32_e32 v61, v64, v61
	v_cvt_pk_bf16_f32 v61, v61, s0
	global_store_short v[84:85], v61, off offset:32
	v_mul_f32_e32 v61, v62, v60
	s_waitcnt vmcnt(15)
	v_lshlrev_b32_e32 v62, 16, v96
	v_mul_f32_e32 v64, 0xbfb8aa3b, v62
	v_exp_f32_e32 v64, v64
	v_mul_f32_e32 v61, v211, v61
	v_mul_f32_e32 v60, v63, v60
	v_mul_f32_e32 v60, v212, v60
	v_add_f32_e32 v64, 1.0, v64
	v_rcp_f32_e32 v64, v64
	s_nop 0
	v_mul_f32_e32 v62, v64, v62
	v_mul_f32_e32 v61, v62, v61
	v_cvt_pk_bf16_f32 v61, v61, s0
	global_store_short v[84:85], v61, off offset:64
	s_waitcnt vmcnt(15)
	v_lshlrev_b32_e32 v61, 16, v92
	v_mul_f32_e32 v62, 0xbfb8aa3b, v61
	v_exp_f32_e32 v62, v62
	s_nop 0
	v_add_f32_e32 v62, 1.0, v62
	v_rcp_f32_e32 v62, v62
	s_nop 0
	v_mul_f32_e32 v61, v62, v61
	v_mul_f32_e32 v60, v61, v60
	v_cvt_pk_bf16_f32 v60, v60, s0
	global_store_short v[84:85], v60, off offset:96
	s_waitcnt lgkmcnt(0)
	s_cbranch_scc0 .LBB0_742
	v_readlane_b32 s0, v254, 20
	s_add_i32 s73, s73, s0
	s_cmpk_gt_i32 s73, 0x3ff
	v_readlane_b32 s1, v254, 21
	s_cbranch_scc0 .LBB0_739

;     __device__ __forceinline__ void operator()(const f32x4 (&acc)[2][2][4][2], const Unit& u, int wr, int wc, int fr, int fq) const {
;         const int j = u.pn >> 2, ct = u.pn & 3;
;         const int row0 = u.pm * BM + wr * 64 + fr, colg = u.pn * BM + wc * 32 + 8 * fq, colm = ct * BM + wc * 32 + 8 * fq;
;         f32x4 bv[2][2];
; #pragma unroll
;         for (int bj = 0; bj < 2; ++bj)
; #pragma unroll
;             for (int n = 0; n < 2; ++n) bv[bj][n] = *(const f32x4*)(bg + colg + bj * HALF + 4 * n);
; #pragma unroll
;         for (int ai = 0; ai < 2; ++ai)
; #pragma unroll
;             for (int m2 = 0; m2 < 2; ++m2) {
;                 u32x4 pvv[2][2], ovv[2][2];
; #pragma unroll
;                 for (int mm = 0; mm < 2; ++mm) { const size_t row = (size_t)(row0 + ai * HALF + (2 * m2 + mm) * 16);
; #pragma unroll
;                     for (int bj = 0; bj < 2; ++bj) { pvv[mm][bj] = *(const u32x4*)(P + row * 4096 + colg + bj * HALF);
;                         if (j > 0) ovv[mm][bj] = *(const u32x4*)(mixed + row * 1024 + colm + bj * HALF); else ovv[mm][bj] = (u32x4){0u, 0u, 0u, 0u}; } }
.LBB0_901:
	s_lshl_b32 s13, s67, 8
	v_or_b32_e32 v130, s13, v229
	v_ashrrev_i32_e32 v131, 31, v130
	v_lshl_add_u32 v206, s71, 8, v183
	v_lshl_add_u64 v[28:29], v[130:131], 2, s[8:9]
	v_ashrrev_i32_e32 v207, 31, v206
	global_load_dwordx4 v[32:35], v[28:29], off offset:16
	global_load_dwordx4 v[40:43], v[28:29], off
	global_load_dwordx4 v[24:27], v[28:29], off offset:528
	global_load_dwordx4 v[28:31], v[28:29], off offset:512
	v_lshl_add_u64 v[204:205], v[130:131], 1, s[4:5]
	v_lshlrev_b64 v[130:131], 13, v[206:207]
	v_lshl_add_u64 v[130:131], v[204:205], 0, v[130:131]
	global_load_dwordx4 v[170:173], v[130:131], off
	s_and_b32 s13, s13, 0x300
	v_or_b32_e32 v64, s13, v229
	v_lshlrev_b32_e32 v64, 1, v64
	s_cmp_gt_i32 s67, 3
	v_lshl_add_u64 v[208:209], s[6:7], 0, v[64:65]
	v_lshlrev_b64 v[212:213], 11, v[206:207]
	s_cselect_b64 s[38:39], -1, 0
	s_cmp_lt_i32 s67, 4
	v_lshl_add_u64 v[132:133], v[208:209], 0, v[212:213]
	v_mov_b32_e32 v154, 0
	v_mov_b32_e32 v174, 0
	v_mov_b32_e32 v175, 0
	v_mov_b32_e32 v176, 0
	v_mov_b32_e32 v177, 0
	s_cbranch_scc1 .LBB0_903
	global_load_dwordx4 v[174:177], v[132:133], off

; __device__ __forceinline__ unsigned cvt_pk_bf16(float lo, float hi) { f32x2_t v = {lo, hi}; bf2_t r = __builtin_convertvector(v, bf2_t); return __builtin_bit_cast(unsigned, r); }
; __device__ __forceinline__ float bflo(unsigned u) { return __uint_as_float(u << 16); }
; __device__ __forceinline__ float bfhi(unsigned u) { return __uint_as_float(u & 0xffff0000u); }
; __device__ __forceinline__ float sigmoidf_(float x) { return 1.0f / (1.0f + __expf(-x)); }
;     __device__ __forceinline__ void operator()(const f32x4 (&acc)[2][2][4][2], const Unit& u, int wr, int wc, int fr, int fq) const {
;     ...
;                 for (int mm = 0; mm < 2; ++mm) { const size_t row = (size_t)(row0 + ai * HALF + (2 * m2 + mm) * 16);
; #pragma unroll
;                     for (int bj = 0; bj < 2; ++bj) { pvv[mm][bj] = *(const u32x4*)(P + row * 4096 + colg + bj * HALF);
;                         if (j > 0) ovv[mm][bj] = *(const u32x4*)(mixed + row * 1024 + colm + bj * HALF); else ovv[mm][bj] = (u32x4){0u, 0u, 0u, 0u}; } }
; #pragma unroll
;                 for (int mm = 0; mm < 2; ++mm) { const int m = 2 * m2 + mm; const size_t row = (size_t)(row0 + ai * HALF + m * 16);
; #pragma unroll
;                     for (int bj = 0; bj < 2; ++bj) {
;                         const u32x4 pv = pvv[mm][bj], ov = ovv[mm][bj];
;                         bf16_t* mp = mixed + row * 1024 + colm + bj * HALF;
;                         const f32x4 a0 = acc[ai][bj][m][0] + bv[bj][0], a1 = acc[ai][bj][m][1] + bv[bj][1];
;                         float r[8];
;                         r[0] = sigmoidf_(a0[0]) * bflo(pv.x); r[1] = sigmoidf_(a0[1]) * bfhi(pv.x); r[2] = sigmoidf_(a0[2]) * bflo(pv.y); r[3] = sigmoidf_(a0[3]) * bfhi(pv.y);
;                         r[4] = sigmoidf_(a1[0]) * bflo(pv.z); r[5] = sigmoidf_(a1[1]) * bfhi(pv.z); r[6] = sigmoidf_(a1[2]) * bflo(pv.w); r[7] = sigmoidf_(a1[3]) * bfhi(pv.w);
;                         r[0] += bflo(ov.x); r[1] += bfhi(ov.x); r[2] += bflo(ov.y); r[3] += bfhi(ov.y); r[4] += bflo(ov.z); r[5] += bfhi(ov.z); r[6] += bflo(ov.w); r[7] += bfhi(ov.w);
;                         u32x4 w; w.x = cvt_pk_bf16(r[0], r[1]); w.y = cvt_pk_bf16(r[2], r[3]); w.z = cvt_pk_bf16(r[4], r[5]); w.w = cvt_pk_bf16(r[6], r[7]);
;                         *(u32x4*)mp = w; } }
.LBB0_909:
	v_or_b32_e32 v236, 32, v206
	v_ashrrev_i32_e32 v237, 31, v236
	v_lshlrev_b64 v[236:237], 13, v[236:237]
	v_lshl_add_u64 v[236:237], v[204:205], 0, v[236:237]
	global_load_dwordx4 v[188:191], v[236:237], off
	global_load_dwordx4 v[232:235], v[236:237], off offset:256
	v_or_b32_e32 v248, 48, v206
	v_ashrrev_i32_e32 v249, 31, v248
	v_lshlrev_b64 v[248:249], 13, v[248:249]
	v_lshl_add_u64 v[248:249], v[204:205], 0, v[248:249]
	global_load_dwordx4 v[240:243], v[248:249], off
	global_load_dwordx4 v[244:247], v[248:249], off offset:256
	s_waitcnt vmcnt(4)
	v_pk_add_f32 v[166:167], v[166:167], v[40:41]
	v_pk_add_f32 v[162:163], v[162:163], v[32:33]
	v_mul_f32_e32 v166, 0xbfb8aa3b, v166
	v_mul_f32_e32 v167, 0xbfb8aa3b, v167
	v_exp_f32_e32 v166, v166
	v_exp_f32_e32 v167, v167
	v_lshl_add_u64 v[178:179], s[6:7], 0, v[212:213]
	v_mul_f32_e32 v162, 0xbfb8aa3b, v162
	v_lshl_add_u64 v[212:213], v[178:179], 0, v[64:65]
	v_pk_add_f32 v[164:165], v[164:165], v[34:35]
	v_exp_f32_e32 v178, v162
	v_mul_f32_e32 v162, 0xbfb8aa3b, v163
	v_exp_f32_e32 v179, v162
	v_mul_f32_e32 v162, 0xbfb8aa3b, v164
	v_mul_f32_e32 v163, 0xbfb8aa3b, v165
	v_pk_add_f32 v[164:165], v[166:167], 1.0 op_sel_hi:[1,0]
	v_pk_add_f32 v[168:169], v[168:169], v[42:43]
	v_mul_f32_e32 v168, 0xbfb8aa3b, v168
	v_mul_f32_e32 v169, 0xbfb8aa3b, v169
	v_exp_f32_e32 v168, v168
	v_rcp_f32_e32 v165, v165
	v_exp_f32_e32 v169, v169
	v_exp_f32_e32 v162, v162
	v_exp_f32_e32 v163, v163
	v_rcp_f32_e32 v164, v164
	v_lshlrev_b32_e32 v166, 16, v170
	v_and_b32_e32 v167, 0xffff0000, v170
	v_lshlrev_b32_e32 v180, 16, v174
	v_and_b32_e32 v181, 0xffff0000, v174
	v_pk_fma_f32 v[164:165], v[164:165], v[166:167], v[180:181]
	v_pk_add_f32 v[166:167], v[168:169], 1.0 op_sel_hi:[1,0]
	v_pk_add_f32 v[162:163], v[162:163], 1.0 op_sel_hi:[1,0]
	v_pk_add_f32 v[142:143], v[142:143], v[28:29]
	v_pk_add_f32 v[138:139], v[138:139], v[24:25]
	v_mul_f32_e32 v142, 0xbfb8aa3b, v142
	v_rcp_f32_e32 v167, v167
	v_mul_f32_e32 v143, 0xbfb8aa3b, v143
	v_exp_f32_e32 v142, v142
	v_exp_f32_e32 v143, v143
	v_rcp_f32_e32 v166, v166
	v_lshlrev_b32_e32 v168, 16, v171
	v_and_b32_e32 v169, 0xffff0000, v171
	v_lshlrev_b32_e32 v170, 16, v175
	v_and_b32_e32 v171, 0xffff0000, v175
	v_pk_fma_f32 v[166:167], v[166:167], v[168:169], v[170:171]
	v_pk_add_f32 v[168:169], v[178:179], 1.0 op_sel_hi:[1,0]
	v_mul_f32_e32 v138, 0xbfb8aa3b, v138
	v_pk_add_f32 v[140:141], v[140:141], v[26:27]
	v_pk_add_f32 v[144:145], v[144:145], v[30:31]
	v_pk_add_f32 v[126:127], v[126:127], v[40:41]
	v_rcp_f32_e32 v169, v169
	v_mul_f32_e32 v144, 0xbfb8aa3b, v144
	v_mul_f32_e32 v145, 0xbfb8aa3b, v145
	v_exp_f32_e32 v144, v144
	v_rcp_f32_e32 v168, v168
	v_lshlrev_b32_e32 v170, 16, v172
	v_and_b32_e32 v171, 0xffff0000, v172
	v_lshlrev_b32_e32 v174, 16, v176
	v_and_b32_e32 v175, 0xffff0000, v176
	v_pk_fma_f32 v[168:169], v[168:169], v[170:171], v[174:175]
	v_exp_f32_e32 v145, v145
	v_mul_f32_e32 v126, 0xbfb8aa3b, v126
	v_mul_f32_e32 v127, 0xbfb8aa3b, v127
	v_rcp_f32_e32 v163, v163
	v_exp_f32_e32 v126, v126
	v_exp_f32_e32 v127, v127
	v_pk_add_f32 v[122:123], v[122:123], v[32:33]
	v_rcp_f32_e32 v162, v162
	v_lshlrev_b32_e32 v170, 16, v173
	v_and_b32_e32 v171, 0xffff0000, v173
	v_lshlrev_b32_e32 v172, 16, v177
	v_and_b32_e32 v173, 0xffff0000, v177
	v_pk_fma_f32 v[170:171], v[162:163], v[170:171], v[172:173]
	v_cvt_pk_bf16_f32 v162, v164, v165
	v_cvt_pk_bf16_f32 v163, v166, v167
	v_cvt_pk_bf16_f32 v164, v168, v169
	v_cvt_pk_bf16_f32 v165, v170, v171
	global_store_dwordx4 v[212:213], v[162:165], off
	v_mul_f32_e32 v122, 0xbfb8aa3b, v122
	v_pk_add_f32 v[124:125], v[124:125], v[34:35]
	v_exp_f32_e32 v162, v138
	v_mul_f32_e32 v138, 0xbfb8aa3b, v139
	v_exp_f32_e32 v163, v138
	v_mul_f32_e32 v138, 0xbfb8aa3b, v140
	v_mul_f32_e32 v139, 0xbfb8aa3b, v141
	v_pk_add_f32 v[140:141], v[142:143], 1.0 op_sel_hi:[1,0]
	v_exp_f32_e32 v138, v138
	v_exp_f32_e32 v139, v139
	v_pk_add_f32 v[128:129], v[128:129], v[42:43]
	v_pk_add_f32 v[118:119], v[118:119], v[28:29]
	v_rcp_f32_e32 v141, v141
	v_pk_add_f32 v[138:139], v[138:139], 1.0 op_sel_hi:[1,0]
	v_mul_f32_e32 v128, 0xbfb8aa3b, v128
	v_mul_f32_e32 v129, 0xbfb8aa3b, v129
	v_rcp_f32_e32 v140, v140
	v_lshlrev_b32_e32 v142, 16, v158
	v_and_b32_e32 v143, 0xffff0000, v158
	v_lshlrev_b32_e32 v164, 16, v154
	v_and_b32_e32 v165, 0xffff0000, v154
	v_pk_fma_f32 v[140:141], v[140:141], v[142:143], v[164:165]
	v_pk_add_f32 v[142:143], v[144:145], 1.0 op_sel_hi:[1,0]
	v_exp_f32_e32 v128, v128
	v_exp_f32_e32 v129, v129
	v_mul_f32_e32 v118, 0xbfb8aa3b, v118
	v_mul_f32_e32 v119, 0xbfb8aa3b, v119
	v_rcp_f32_e32 v143, v143
	v_exp_f32_e32 v118, v118
	v_exp_f32_e32 v119, v119
	v_pk_add_f32 v[114:115], v[114:115], v[24:25]
	v_rcp_f32_e32 v142, v142
	v_lshlrev_b32_e32 v144, 16, v159
	v_and_b32_e32 v145, 0xffff0000, v159
	v_lshlrev_b32_e32 v154, 16, v155
	v_and_b32_e32 v155, 0xffff0000, v155
	v_pk_fma_f32 v[142:143], v[142:143], v[144:145], v[154:155]
	v_pk_add_f32 v[144:145], v[162:163], 1.0 op_sel_hi:[1,0]
	v_mul_f32_e32 v114, 0xbfb8aa3b, v114
; __device__ __forceinline__ unsigned cvt_pk_bf16(float lo, float hi) { f32x2_t v = {lo, hi}; bf2_t r = __builtin_convertvector(v, bf2_t); return __builtin_bit_cast(unsigned, r); }
; __device__ __forceinline__ float bflo(unsigned u) { return __uint_as_float(u << 16); }
; __device__ __forceinline__ float bfhi(unsigned u) { return __uint_as_float(u & 0xffff0000u); }
; __device__ __forceinline__ float sigmoidf_(float x) { return 1.0f / (1.0f + __expf(-x)); }
;     __device__ __forceinline__ void operator()(const f32x4 (&acc)[2][2][4][2], const Unit& u, int wr, int wc, int fr, int fq) const {
;     ...
;                 for (int mm = 0; mm < 2; ++mm) { const int m = 2 * m2 + mm; const size_t row = (size_t)(row0 + ai * HALF + m * 16);
; #pragma unroll
;                     for (int bj = 0; bj < 2; ++bj) {
;                         const u32x4 pv = pvv[mm][bj], ov = ovv[mm][bj];
;                         bf16_t* mp = mixed + row * 1024 + colm + bj * HALF;
;                         const f32x4 a0 = acc[ai][bj][m][0] + bv[bj][0], a1 = acc[ai][bj][m][1] + bv[bj][1];
;                         float r[8];
;                         r[0] = sigmoidf_(a0[0]) * bflo(pv.x); r[1] = sigmoidf_(a0[1]) * bfhi(pv.x); r[2] = sigmoidf_(a0[2]) * bflo(pv.y); r[3] = sigmoidf_(a0[3]) * bfhi(pv.y);
;                         r[4] = sigmoidf_(a1[0]) * bflo(pv.z); r[5] = sigmoidf_(a1[1]) * bfhi(pv.z); r[6] = sigmoidf_(a1[2]) * bflo(pv.w); r[7] = sigmoidf_(a1[3]) * bfhi(pv.w);
;                         r[0] += bflo(ov.x); r[1] += bfhi(ov.x); r[2] += bflo(ov.y); r[3] += bfhi(ov.y); r[4] += bflo(ov.z); r[5] += bfhi(ov.z); r[6] += bflo(ov.w); r[7] += bfhi(ov.w);
;                         u32x4 w; w.x = cvt_pk_bf16(r[0], r[1]); w.y = cvt_pk_bf16(r[2], r[3]); w.z = cvt_pk_bf16(r[4], r[5]); w.w = cvt_pk_bf16(r[6], r[7]);
;                         *(u32x4*)mp = w; } }
	v_pk_add_f32 v[116:117], v[116:117], v[26:27]
	v_pk_add_f32 v[120:121], v[120:121], v[30:31]
	v_rcp_f32_e32 v145, v145
	v_mul_f32_e32 v120, 0xbfb8aa3b, v120
	v_mul_f32_e32 v121, 0xbfb8aa3b, v121
	v_exp_f32_e32 v120, v120
	v_rcp_f32_e32 v144, v144
	v_lshlrev_b32_e32 v154, 16, v160
	v_and_b32_e32 v155, 0xffff0000, v160
	v_lshlrev_b32_e32 v158, 16, v156
	v_and_b32_e32 v159, 0xffff0000, v156
	v_pk_fma_f32 v[144:145], v[144:145], v[154:155], v[158:159]
	v_exp_f32_e32 v121, v121
	v_rcp_f32_e32 v139, v139
	v_rcp_f32_e32 v138, v138
	v_lshlrev_b32_e32 v154, 16, v161
	v_and_b32_e32 v155, 0xffff0000, v161
	v_lshlrev_b32_e32 v156, 16, v157
	v_and_b32_e32 v157, 0xffff0000, v157
	v_pk_fma_f32 v[154:155], v[138:139], v[154:155], v[156:157]
	v_cvt_pk_bf16_f32 v138, v140, v141
	v_cvt_pk_bf16_f32 v139, v142, v143
	v_cvt_pk_bf16_f32 v140, v144, v145
	v_cvt_pk_bf16_f32 v141, v154, v155
	global_store_dwordx4 v[212:213], v[138:141], off offset:256
	v_mov_b32_e32 v145, 0
	s_nop 0
	v_exp_f32_e32 v140, v122
	v_mul_f32_e32 v122, 0xbfb8aa3b, v123
	v_exp_f32_e32 v141, v122
	v_mul_f32_e32 v122, 0xbfb8aa3b, v124
	v_mul_f32_e32 v123, 0xbfb8aa3b, v125
	v_pk_add_f32 v[124:125], v[126:127], 1.0 op_sel_hi:[1,0]
	v_exp_f32_e32 v122, v122
	v_exp_f32_e32 v123, v123
	v_lshl_add_u64 v[138:139], s[6:7], 0, v[210:211]
	v_lshl_add_u64 v[138:139], v[138:139], 0, v[64:65]
	v_rcp_f32_e32 v125, v125
	v_pk_add_f32 v[122:123], v[122:123], 1.0 op_sel_hi:[1,0]
	v_rcp_f32_e32 v124, v124
	v_lshlrev_b32_e32 v126, 16, v146
	v_and_b32_e32 v127, 0xffff0000, v146
	v_lshlrev_b32_e32 v142, 16, v150
	v_and_b32_e32 v143, 0xffff0000, v150
	v_pk_fma_f32 v[124:125], v[124:125], v[126:127], v[142:143]
	v_pk_add_f32 v[126:127], v[128:129], 1.0 op_sel_hi:[1,0]
	v_rcp_f32_e32 v127, v127
	v_rcp_f32_e32 v126, v126
	v_lshlrev_b32_e32 v128, 16, v147
	v_and_b32_e32 v129, 0xffff0000, v147
	v_lshlrev_b32_e32 v142, 16, v151
	v_and_b32_e32 v143, 0xffff0000, v151
	v_pk_fma_f32 v[126:127], v[126:127], v[128:129], v[142:143]
	v_pk_add_f32 v[128:129], v[140:141], 1.0 op_sel_hi:[1,0]
	v_rcp_f32_e32 v129, v129
	v_rcp_f32_e32 v128, v128
	v_lshlrev_b32_e32 v140, 16, v148
	v_and_b32_e32 v141, 0xffff0000, v148
	v_lshlrev_b32_e32 v142, 16, v152
	v_and_b32_e32 v143, 0xffff0000, v152
	v_pk_fma_f32 v[128:129], v[128:129], v[140:141], v[142:143]
	v_rcp_f32_e32 v123, v123
	v_rcp_f32_e32 v122, v122
	v_lshlrev_b32_e32 v140, 16, v149
	v_and_b32_e32 v141, 0xffff0000, v149
	v_lshlrev_b32_e32 v142, 16, v153
	v_and_b32_e32 v143, 0xffff0000, v153
	v_pk_fma_f32 v[140:141], v[122:123], v[140:141], v[142:143]
	v_cvt_pk_bf16_f32 v122, v124, v125
	v_cvt_pk_bf16_f32 v123, v126, v127
	v_cvt_pk_bf16_f32 v124, v128, v129
	v_cvt_pk_bf16_f32 v125, v140, v141
	global_store_dwordx4 v[138:139], v[122:125], off
	v_mov_b32_e32 v142, 0
	v_mov_b32_e32 v143, 0
	v_exp_f32_e32 v122, v114
	v_mul_f32_e32 v114, 0xbfb8aa3b, v115
	v_exp_f32_e32 v123, v114
	v_mul_f32_e32 v114, 0xbfb8aa3b, v116
	v_mul_f32_e32 v115, 0xbfb8aa3b, v117
	v_pk_add_f32 v[116:117], v[118:119], 1.0 op_sel_hi:[1,0]
	v_exp_f32_e32 v114, v114
	v_exp_f32_e32 v115, v115
	v_mov_b32_e32 v144, 0
	v_rcp_f32_e32 v117, v117
	v_pk_add_f32 v[114:115], v[114:115], 1.0 op_sel_hi:[1,0]
	v_rcp_f32_e32 v116, v116
	v_lshlrev_b32_e32 v118, 16, v134
	v_and_b32_e32 v119, 0xffff0000, v134
	v_lshlrev_b32_e32 v124, 16, v130
	v_and_b32_e32 v125, 0xffff0000, v130
	v_pk_fma_f32 v[116:117], v[116:117], v[118:119], v[124:125]
	v_pk_add_f32 v[118:119], v[120:121], 1.0 op_sel_hi:[1,0]
	v_mov_b32_e32 v130, 0
	v_rcp_f32_e32 v119, v119
	v_rcp_f32_e32 v118, v118
	v_lshlrev_b32_e32 v120, 16, v135
	v_and_b32_e32 v121, 0xffff0000, v135
	v_lshlrev_b32_e32 v124, 16, v131
	v_and_b32_e32 v125, 0xffff0000, v131
	v_pk_fma_f32 v[118:119], v[118:119], v[120:121], v[124:125]
	v_pk_add_f32 v[120:121], v[122:123], 1.0 op_sel_hi:[1,0]
	v_rcp_f32_e32 v121, v121
	v_rcp_f32_e32 v120, v120
	v_lshlrev_b32_e32 v122, 16, v136
	v_and_b32_e32 v123, 0xffff0000, v136
	v_lshlrev_b32_e32 v124, 16, v132
	v_and_b32_e32 v125, 0xffff0000, v132
	v_pk_fma_f32 v[120:121], v[120:121], v[122:123], v[124:125]
	v_rcp_f32_e32 v115, v115
	v_rcp_f32_e32 v114, v114
	v_lshlrev_b32_e32 v122, 16, v137
	v_and_b32_e32 v123, 0xffff0000, v137
	v_lshlrev_b32_e32 v124, 16, v133
	v_and_b32_e32 v125, 0xffff0000, v133
	v_pk_fma_f32 v[122:123], v[114:115], v[122:123], v[124:125]
	v_cvt_pk_bf16_f32 v114, v116, v117
	v_cvt_pk_bf16_f32 v115, v118, v119
	v_cvt_pk_bf16_f32 v116, v120, v121
	v_cvt_pk_bf16_f32 v117, v122, v123
	global_store_dwordx4 v[138:139], v[114:117], off offset:256
	s_and_b64 vcc, exec, s[42:43]
	s_nop 0
	v_or_b32_e32 v114, 32, v206
	v_ashrrev_i32_e32 v115, 31, v114
	v_lshlrev_b64 v[116:117], 13, v[114:115]
	v_lshl_add_u64 v[116:117], v[204:205], 0, v[116:117]
	s_waitcnt vmcnt(4)
	v_mov_b64_e32 v[138:139], v[188:189]
	v_mov_b64_e32 v[140:141], v[190:191]
	v_lshlrev_b64 v[148:149], 11, v[114:115]
	v_lshl_add_u64 v[114:115], v[208:209], 0, v[148:149]
	s_cbranch_vccnz .LBB0_911
	global_load_dwordx4 v[142:145], v[114:115], off

; __device__ __forceinline__ unsigned cvt_pk_bf16(float lo, float hi) { f32x2_t v = {lo, hi}; bf2_t r = __builtin_convertvector(v, bf2_t); return __builtin_bit_cast(unsigned, r); }
; __device__ __forceinline__ float bflo(unsigned u) { return __uint_as_float(u << 16); }
; __device__ __forceinline__ float bfhi(unsigned u) { return __uint_as_float(u & 0xffff0000u); }
; __device__ __forceinline__ float sigmoidf_(float x) { return 1.0f / (1.0f + __expf(-x)); }
;     __device__ __forceinline__ void operator()(const f32x4 (&acc)[2][2][4][2], const Unit& u, int wr, int wc, int fr, int fq) const {
;     ...
;             for (int m2 = 0; m2 < 2; ++m2) {
;                 u32x4 pvv[2][2], ovv[2][2];
; #pragma unroll
;                 for (int mm = 0; mm < 2; ++mm) { const size_t row = (size_t)(row0 + ai * HALF + (2 * m2 + mm) * 16);
; #pragma unroll
;                     for (int bj = 0; bj < 2; ++bj) { pvv[mm][bj] = *(const u32x4*)(P + row * 4096 + colg + bj * HALF);
;                         if (j > 0) ovv[mm][bj] = *(const u32x4*)(mixed + row * 1024 + colm + bj * HALF); else ovv[mm][bj] = (u32x4){0u, 0u, 0u, 0u}; } }
; #pragma unroll
;                 for (int mm = 0; mm < 2; ++mm) { const int m = 2 * m2 + mm; const size_t row = (size_t)(row0 + ai * HALF + m * 16);
; #pragma unroll
;                     for (int bj = 0; bj < 2; ++bj) {
;                         const u32x4 pv = pvv[mm][bj], ov = ovv[mm][bj];
;                         bf16_t* mp = mixed + row * 1024 + colm + bj * HALF;
;                         const f32x4 a0 = acc[ai][bj][m][0] + bv[bj][0], a1 = acc[ai][bj][m][1] + bv[bj][1];
;                         float r[8];
;                         r[0] = sigmoidf_(a0[0]) * bflo(pv.x); r[1] = sigmoidf_(a0[1]) * bfhi(pv.x); r[2] = sigmoidf_(a0[2]) * bflo(pv.y); r[3] = sigmoidf_(a0[3]) * bfhi(pv.y);
;                         r[4] = sigmoidf_(a1[0]) * bflo(pv.z); r[5] = sigmoidf_(a1[1]) * bfhi(pv.z); r[6] = sigmoidf_(a1[2]) * bflo(pv.w); r[7] = sigmoidf_(a1[3]) * bfhi(pv.w);
;                         r[0] += bflo(ov.x); r[1] += bfhi(ov.x); r[2] += bflo(ov.y); r[3] += bfhi(ov.y); r[4] += bflo(ov.z); r[5] += bfhi(ov.z); r[6] += bflo(ov.w); r[7] += bfhi(ov.w);
;                         u32x4 w; w.x = cvt_pk_bf16(r[0], r[1]); w.y = cvt_pk_bf16(r[2], r[3]); w.z = cvt_pk_bf16(r[4], r[5]); w.w = cvt_pk_bf16(r[6], r[7]);
;                         *(u32x4*)mp = w; } }
.LBB0_917:
	v_add_u32_e32 v236, 0x80, v206
	v_ashrrev_i32_e32 v237, 31, v236
	v_lshlrev_b64 v[236:237], 13, v[236:237]
	v_lshl_add_u64 v[236:237], v[204:205], 0, v[236:237]
	global_load_dwordx4 v[188:191], v[236:237], off
	global_load_dwordx4 v[232:235], v[236:237], off offset:256
	v_add_u32_e32 v248, 0x90, v206
	v_ashrrev_i32_e32 v249, 31, v248
	v_lshlrev_b64 v[248:249], 13, v[248:249]
	v_lshl_add_u64 v[248:249], v[204:205], 0, v[248:249]
	global_load_dwordx4 v[240:243], v[248:249], off
	global_load_dwordx4 v[244:247], v[248:249], off offset:256
	v_pk_add_f32 v[110:111], v[110:111], v[40:41]
	v_pk_add_f32 v[106:107], v[106:107], v[32:33]
	v_mul_f32_e32 v110, 0xbfb8aa3b, v110
	v_mul_f32_e32 v111, 0xbfb8aa3b, v111
	v_exp_f32_e32 v110, v110
	v_exp_f32_e32 v111, v111
	v_mul_f32_e32 v106, 0xbfb8aa3b, v106
	v_pk_add_f32 v[108:109], v[108:109], v[34:35]
	v_exp_f32_e32 v150, v106
	v_mul_f32_e32 v106, 0xbfb8aa3b, v107
	v_exp_f32_e32 v151, v106
	v_mul_f32_e32 v106, 0xbfb8aa3b, v108
	v_mul_f32_e32 v107, 0xbfb8aa3b, v109
	v_pk_add_f32 v[108:109], v[110:111], 1.0 op_sel_hi:[1,0]
	v_pk_add_f32 v[112:113], v[112:113], v[42:43]
	v_mul_f32_e32 v112, 0xbfb8aa3b, v112
	v_mul_f32_e32 v113, 0xbfb8aa3b, v113
	v_exp_f32_e32 v112, v112
	v_rcp_f32_e32 v109, v109
	v_exp_f32_e32 v113, v113
	v_exp_f32_e32 v106, v106
	v_exp_f32_e32 v107, v107
	v_rcp_f32_e32 v108, v108
	s_waitcnt vmcnt(7)
	v_lshlrev_b32_e32 v110, 16, v138
	v_and_b32_e32 v111, 0xffff0000, v138
	v_lshlrev_b32_e32 v152, 16, v142
	v_and_b32_e32 v153, 0xffff0000, v142
	v_pk_fma_f32 v[108:109], v[108:109], v[110:111], v[152:153]
	v_pk_add_f32 v[110:111], v[112:113], 1.0 op_sel_hi:[1,0]
	v_pk_add_f32 v[106:107], v[106:107], 1.0 op_sel_hi:[1,0]
	v_pk_add_f32 v[102:103], v[102:103], v[28:29]
	v_lshl_add_u64 v[148:149], s[6:7], 0, v[148:149]
	v_mul_f32_e32 v102, 0xbfb8aa3b, v102
	v_rcp_f32_e32 v111, v111
	v_mul_f32_e32 v103, 0xbfb8aa3b, v103
	v_exp_f32_e32 v102, v102
	v_exp_f32_e32 v103, v103
	v_rcp_f32_e32 v110, v110
	v_lshlrev_b32_e32 v112, 16, v139
	v_and_b32_e32 v113, 0xffff0000, v139
	v_lshlrev_b32_e32 v138, 16, v143
	v_and_b32_e32 v139, 0xffff0000, v143
	v_pk_fma_f32 v[110:111], v[110:111], v[112:113], v[138:139]
	v_pk_add_f32 v[112:113], v[150:151], 1.0 op_sel_hi:[1,0]
	v_pk_add_f32 v[98:99], v[98:99], v[24:25]
	v_lshl_add_u64 v[148:149], v[148:149], 0, v[64:65]
	v_mul_f32_e32 v98, 0xbfb8aa3b, v98
	v_pk_add_f32 v[100:101], v[100:101], v[26:27]
	v_rcp_f32_e32 v113, v113
	v_pk_add_f32 v[104:105], v[104:105], v[30:31]
	v_pk_add_f32 v[94:95], v[94:95], v[40:41]
	v_mul_f32_e32 v104, 0xbfb8aa3b, v104
	v_rcp_f32_e32 v112, v112
	v_lshlrev_b32_e32 v138, 16, v140
	v_and_b32_e32 v139, 0xffff0000, v140
	v_lshlrev_b32_e32 v142, 16, v144
	v_and_b32_e32 v143, 0xffff0000, v144
	v_pk_fma_f32 v[112:113], v[112:113], v[138:139], v[142:143]
	v_mul_f32_e32 v105, 0xbfb8aa3b, v105
	v_exp_f32_e32 v104, v104
	v_exp_f32_e32 v105, v105
	v_rcp_f32_e32 v107, v107
	v_mul_f32_e32 v94, 0xbfb8aa3b, v94
	v_mul_f32_e32 v95, 0xbfb8aa3b, v95
	v_exp_f32_e32 v94, v94
	v_rcp_f32_e32 v106, v106
	v_lshlrev_b32_e32 v138, 16, v141
	v_and_b32_e32 v139, 0xffff0000, v141
	v_lshlrev_b32_e32 v140, 16, v145
	v_and_b32_e32 v141, 0xffff0000, v145
	v_pk_fma_f32 v[138:139], v[106:107], v[138:139], v[140:141]
	v_cvt_pk_bf16_f32 v106, v108, v109
	v_cvt_pk_bf16_f32 v107, v110, v111
	v_cvt_pk_bf16_f32 v108, v112, v113
	v_cvt_pk_bf16_f32 v109, v138, v139
	global_store_dwordx4 v[148:149], v[106:109], off
	v_exp_f32_e32 v95, v95
	v_pk_add_f32 v[90:91], v[90:91], v[32:33]
	v_exp_f32_e32 v106, v98
	v_mul_f32_e32 v98, 0xbfb8aa3b, v99
	v_exp_f32_e32 v107, v98
	v_mul_f32_e32 v98, 0xbfb8aa3b, v100
	v_mul_f32_e32 v99, 0xbfb8aa3b, v101
	v_pk_add_f32 v[100:101], v[102:103], 1.0 op_sel_hi:[1,0]
	v_exp_f32_e32 v98, v98
	v_exp_f32_e32 v99, v99
	v_mul_f32_e32 v90, 0xbfb8aa3b, v90
	v_pk_add_f32 v[92:93], v[92:93], v[34:35]
	v_rcp_f32_e32 v101, v101
	v_pk_add_f32 v[98:99], v[98:99], 1.0 op_sel_hi:[1,0]
	v_pk_add_f32 v[96:97], v[96:97], v[42:43]
	v_pk_add_f32 v[86:87], v[86:87], v[28:29]
	v_rcp_f32_e32 v100, v100
	s_waitcnt vmcnt(7)
; __device__ __forceinline__ unsigned cvt_pk_bf16(float lo, float hi) { f32x2_t v = {lo, hi}; bf2_t r = __builtin_convertvector(v, bf2_t); return __builtin_bit_cast(unsigned, r); }
; __device__ __forceinline__ float bflo(unsigned u) { return __uint_as_float(u << 16); }
; __device__ __forceinline__ float bfhi(unsigned u) { return __uint_as_float(u & 0xffff0000u); }
; __device__ __forceinline__ float sigmoidf_(float x) { return 1.0f / (1.0f + __expf(-x)); }
;     __device__ __forceinline__ void operator()(const f32x4 (&acc)[2][2][4][2], const Unit& u, int wr, int wc, int fr, int fq) const {
;     ...
;                 for (int mm = 0; mm < 2; ++mm) { const size_t row = (size_t)(row0 + ai * HALF + (2 * m2 + mm) * 16);
; #pragma unroll
;                     for (int bj = 0; bj < 2; ++bj) { pvv[mm][bj] = *(const u32x4*)(P + row * 4096 + colg + bj * HALF);
;                         if (j > 0) ovv[mm][bj] = *(const u32x4*)(mixed + row * 1024 + colm + bj * HALF); else ovv[mm][bj] = (u32x4){0u, 0u, 0u, 0u}; } }
; #pragma unroll
;                 for (int mm = 0; mm < 2; ++mm) { const int m = 2 * m2 + mm; const size_t row = (size_t)(row0 + ai * HALF + m * 16);
; #pragma unroll
;                     for (int bj = 0; bj < 2; ++bj) {
;                         const u32x4 pv = pvv[mm][bj], ov = ovv[mm][bj];
;                         bf16_t* mp = mixed + row * 1024 + colm + bj * HALF;
;                         const f32x4 a0 = acc[ai][bj][m][0] + bv[bj][0], a1 = acc[ai][bj][m][1] + bv[bj][1];
;                         float r[8];
;                         r[0] = sigmoidf_(a0[0]) * bflo(pv.x); r[1] = sigmoidf_(a0[1]) * bfhi(pv.x); r[2] = sigmoidf_(a0[2]) * bflo(pv.y); r[3] = sigmoidf_(a0[3]) * bfhi(pv.y);
;                         r[4] = sigmoidf_(a1[0]) * bflo(pv.z); r[5] = sigmoidf_(a1[1]) * bfhi(pv.z); r[6] = sigmoidf_(a1[2]) * bflo(pv.w); r[7] = sigmoidf_(a1[3]) * bfhi(pv.w);
;                         r[0] += bflo(ov.x); r[1] += bfhi(ov.x); r[2] += bflo(ov.y); r[3] += bfhi(ov.y); r[4] += bflo(ov.z); r[5] += bfhi(ov.z); r[6] += bflo(ov.w); r[7] += bfhi(ov.w);
;                         u32x4 w; w.x = cvt_pk_bf16(r[0], r[1]); w.y = cvt_pk_bf16(r[2], r[3]); w.z = cvt_pk_bf16(r[4], r[5]); w.w = cvt_pk_bf16(r[6], r[7]);
;                         *(u32x4*)mp = w; } }
	v_lshlrev_b32_e32 v102, 16, v134
	v_and_b32_e32 v103, 0xffff0000, v134
	v_lshlrev_b32_e32 v108, 16, v130
	v_and_b32_e32 v109, 0xffff0000, v130
	v_pk_fma_f32 v[100:101], v[100:101], v[102:103], v[108:109]
	v_pk_add_f32 v[102:103], v[104:105], 1.0 op_sel_hi:[1,0]
	v_mul_f32_e32 v96, 0xbfb8aa3b, v96
	v_mul_f32_e32 v97, 0xbfb8aa3b, v97
	v_exp_f32_e32 v96, v96
	v_exp_f32_e32 v97, v97
	v_rcp_f32_e32 v103, v103
	v_mul_f32_e32 v86, 0xbfb8aa3b, v86
	v_mul_f32_e32 v87, 0xbfb8aa3b, v87
	v_exp_f32_e32 v86, v86
	v_rcp_f32_e32 v102, v102
	v_lshlrev_b32_e32 v104, 16, v135
	v_and_b32_e32 v105, 0xffff0000, v135
	v_lshlrev_b32_e32 v108, 16, v131
	v_and_b32_e32 v109, 0xffff0000, v131
	v_pk_fma_f32 v[102:103], v[102:103], v[104:105], v[108:109]
	v_pk_add_f32 v[104:105], v[106:107], 1.0 op_sel_hi:[1,0]
	v_exp_f32_e32 v87, v87
	v_pk_add_f32 v[82:83], v[82:83], v[24:25]
	v_pk_add_f32 v[84:85], v[84:85], v[26:27]
	v_mul_f32_e32 v82, 0xbfb8aa3b, v82
	v_rcp_f32_e32 v105, v105
	v_pk_add_f32 v[88:89], v[88:89], v[30:31]
	v_mov_b32_e32 v111, 0
	v_mul_f32_e32 v88, 0xbfb8aa3b, v88
	v_rcp_f32_e32 v104, v104
	v_lshlrev_b32_e32 v106, 16, v136
	v_and_b32_e32 v107, 0xffff0000, v136
	v_lshlrev_b32_e32 v108, 16, v132
	v_and_b32_e32 v109, 0xffff0000, v132
	v_pk_fma_f32 v[104:105], v[104:105], v[106:107], v[108:109]
	v_mul_f32_e32 v89, 0xbfb8aa3b, v89
	v_exp_f32_e32 v88, v88
	v_exp_f32_e32 v89, v89
	v_rcp_f32_e32 v99, v99
	v_mov_b32_e32 v112, 0
	v_mov_b32_e32 v113, 0
	v_rcp_f32_e32 v98, v98
	v_lshlrev_b32_e32 v106, 16, v137
	v_and_b32_e32 v107, 0xffff0000, v137
	v_lshlrev_b32_e32 v108, 16, v133
	v_and_b32_e32 v109, 0xffff0000, v133
	v_pk_fma_f32 v[106:107], v[98:99], v[106:107], v[108:109]
	v_cvt_pk_bf16_f32 v98, v100, v101
	v_cvt_pk_bf16_f32 v99, v102, v103
	v_cvt_pk_bf16_f32 v100, v104, v105
	v_cvt_pk_bf16_f32 v101, v106, v107
	global_store_dwordx4 v[148:149], v[98:101], off offset:256
	v_mov_b32_e32 v110, 0
	s_nop 0
	v_exp_f32_e32 v100, v90
	v_mul_f32_e32 v90, 0xbfb8aa3b, v91
	v_exp_f32_e32 v101, v90
	v_mul_f32_e32 v90, 0xbfb8aa3b, v92
	v_mul_f32_e32 v91, 0xbfb8aa3b, v93
	v_pk_add_f32 v[92:93], v[94:95], 1.0 op_sel_hi:[1,0]
	v_exp_f32_e32 v90, v90
	v_exp_f32_e32 v91, v91
	v_lshl_add_u64 v[98:99], s[6:7], 0, v[146:147]
	v_lshl_add_u64 v[98:99], v[98:99], 0, v[64:65]
	v_rcp_f32_e32 v93, v93
	v_pk_add_f32 v[90:91], v[90:91], 1.0 op_sel_hi:[1,0]
	v_rcp_f32_e32 v92, v92
	s_waitcnt vmcnt(7)
	v_lshlrev_b32_e32 v94, 16, v122
	v_and_b32_e32 v95, 0xffff0000, v122
	v_lshlrev_b32_e32 v102, 16, v126
	v_and_b32_e32 v103, 0xffff0000, v126
	v_pk_fma_f32 v[92:93], v[92:93], v[94:95], v[102:103]
	v_pk_add_f32 v[94:95], v[96:97], 1.0 op_sel_hi:[1,0]
	v_rcp_f32_e32 v95, v95
	v_rcp_f32_e32 v94, v94
	v_lshlrev_b32_e32 v96, 16, v123
	v_and_b32_e32 v97, 0xffff0000, v123
	v_lshlrev_b32_e32 v102, 16, v127
	v_and_b32_e32 v103, 0xffff0000, v127
	v_pk_fma_f32 v[94:95], v[94:95], v[96:97], v[102:103]
	v_pk_add_f32 v[96:97], v[100:101], 1.0 op_sel_hi:[1,0]
	v_rcp_f32_e32 v97, v97
	v_rcp_f32_e32 v96, v96
	v_lshlrev_b32_e32 v100, 16, v124
	v_and_b32_e32 v101, 0xffff0000, v124
	v_lshlrev_b32_e32 v102, 16, v128
	v_and_b32_e32 v103, 0xffff0000, v128
	v_pk_fma_f32 v[96:97], v[96:97], v[100:101], v[102:103]
	v_rcp_f32_e32 v91, v91
	v_rcp_f32_e32 v90, v90
	v_lshlrev_b32_e32 v100, 16, v125
	v_and_b32_e32 v101, 0xffff0000, v125
	v_lshlrev_b32_e32 v102, 16, v129
	v_and_b32_e32 v103, 0xffff0000, v129
	v_pk_fma_f32 v[100:101], v[90:91], v[100:101], v[102:103]
	v_cvt_pk_bf16_f32 v90, v92, v93
	v_cvt_pk_bf16_f32 v91, v94, v95
	v_cvt_pk_bf16_f32 v92, v96, v97
	v_cvt_pk_bf16_f32 v93, v100, v101
	global_store_dwordx4 v[98:99], v[90:93], off
	s_nop 1
	v_exp_f32_e32 v90, v82
	v_mul_f32_e32 v82, 0xbfb8aa3b, v83
	v_exp_f32_e32 v91, v82
	v_mul_f32_e32 v82, 0xbfb8aa3b, v84
	v_mul_f32_e32 v83, 0xbfb8aa3b, v85
	v_pk_add_f32 v[84:85], v[86:87], 1.0 op_sel_hi:[1,0]
	v_exp_f32_e32 v82, v82
	v_exp_f32_e32 v83, v83
	v_rcp_f32_e32 v85, v85
	v_pk_add_f32 v[82:83], v[82:83], 1.0 op_sel_hi:[1,0]
	v_rcp_f32_e32 v84, v84
	s_waitcnt vmcnt(7)
	v_lshlrev_b32_e32 v86, 16, v118
	v_and_b32_e32 v87, 0xffff0000, v118
	v_lshlrev_b32_e32 v92, 16, v114
	v_and_b32_e32 v93, 0xffff0000, v114
	v_pk_fma_f32 v[84:85], v[84:85], v[86:87], v[92:93]
	v_pk_add_f32 v[86:87], v[88:89], 1.0 op_sel_hi:[1,0]
	v_rcp_f32_e32 v87, v87
	v_rcp_f32_e32 v86, v86
	v_lshlrev_b32_e32 v88, 16, v119
	v_and_b32_e32 v89, 0xffff0000, v119
	v_lshlrev_b32_e32 v92, 16, v115
	v_and_b32_e32 v93, 0xffff0000, v115
	v_pk_fma_f32 v[86:87], v[86:87], v[88:89], v[92:93]
	v_pk_add_f32 v[88:89], v[90:91], 1.0 op_sel_hi:[1,0]
	v_rcp_f32_e32 v89, v89
	v_rcp_f32_e32 v88, v88
	v_lshlrev_b32_e32 v90, 16, v120
	v_and_b32_e32 v91, 0xffff0000, v120
	v_lshlrev_b32_e32 v92, 16, v116
	v_and_b32_e32 v93, 0xffff0000, v116
	v_pk_fma_f32 v[88:89], v[88:89], v[90:91], v[92:93]
	v_rcp_f32_e32 v83, v83
	v_rcp_f32_e32 v82, v82
	v_lshlrev_b32_e32 v90, 16, v121
	v_and_b32_e32 v91, 0xffff0000, v121
	v_lshlrev_b32_e32 v92, 16, v117
	v_and_b32_e32 v93, 0xffff0000, v117
	v_pk_fma_f32 v[90:91], v[82:83], v[90:91], v[92:93]
	v_cvt_pk_bf16_f32 v82, v84, v85
	v_cvt_pk_bf16_f32 v83, v86, v87
	v_cvt_pk_bf16_f32 v84, v88, v89
	v_cvt_pk_bf16_f32 v85, v90, v91
	global_store_dwordx4 v[98:99], v[82:85], off offset:256
	v_mov_b32_e32 v98, 0
	s_and_b64 vcc, exec, s[42:43]
	v_add_u32_e32 v82, 0x80, v206
	v_ashrrev_i32_e32 v83, 31, v82
	v_lshlrev_b64 v[84:85], 13, v[82:83]
	v_lshl_add_u64 v[84:85], v[204:205], 0, v[84:85]
	s_waitcnt vmcnt(4)
	v_mov_b64_e32 v[106:107], v[188:189]
	v_mov_b64_e32 v[108:109], v[190:191]
	v_lshlrev_b64 v[116:117], 11, v[82:83]
	v_lshl_add_u64 v[82:83], v[208:209], 0, v[116:117]
	s_cbranch_vccnz .LBB0_919
	global_load_dwordx4 v[110:113], v[82:83], off

; __device__ __forceinline__ unsigned cvt_pk_bf16(float lo, float hi) { f32x2_t v = {lo, hi}; bf2_t r = __builtin_convertvector(v, bf2_t); return __builtin_bit_cast(unsigned, r); }
; __device__ __forceinline__ float bflo(unsigned u) { return __uint_as_float(u << 16); }
; __device__ __forceinline__ float bfhi(unsigned u) { return __uint_as_float(u & 0xffff0000u); }
; __device__ __forceinline__ float sigmoidf_(float x) { return 1.0f / (1.0f + __expf(-x)); }
;     __device__ __forceinline__ void operator()(const f32x4 (&acc)[2][2][4][2], const Unit& u, int wr, int wc, int fr, int fq) const {
;     ...
;                 for (int mm = 0; mm < 2; ++mm) { const size_t row = (size_t)(row0 + ai * HALF + (2 * m2 + mm) * 16);
; #pragma unroll
;                     for (int bj = 0; bj < 2; ++bj) { pvv[mm][bj] = *(const u32x4*)(P + row * 4096 + colg + bj * HALF);
;                         if (j > 0) ovv[mm][bj] = *(const u32x4*)(mixed + row * 1024 + colm + bj * HALF); else ovv[mm][bj] = (u32x4){0u, 0u, 0u, 0u}; } }
; #pragma unroll
;                 for (int mm = 0; mm < 2; ++mm) { const int m = 2 * m2 + mm; const size_t row = (size_t)(row0 + ai * HALF + m * 16);
; #pragma unroll
;                     for (int bj = 0; bj < 2; ++bj) {
;                         const u32x4 pv = pvv[mm][bj], ov = ovv[mm][bj];
;                         bf16_t* mp = mixed + row * 1024 + colm + bj * HALF;
;                         const f32x4 a0 = acc[ai][bj][m][0] + bv[bj][0], a1 = acc[ai][bj][m][1] + bv[bj][1];
;                         float r[8];
;                         r[0] = sigmoidf_(a0[0]) * bflo(pv.x); r[1] = sigmoidf_(a0[1]) * bfhi(pv.x); r[2] = sigmoidf_(a0[2]) * bflo(pv.y); r[3] = sigmoidf_(a0[3]) * bfhi(pv.y);
;                         r[4] = sigmoidf_(a1[0]) * bflo(pv.z); r[5] = sigmoidf_(a1[1]) * bfhi(pv.z); r[6] = sigmoidf_(a1[2]) * bflo(pv.w); r[7] = sigmoidf_(a1[3]) * bfhi(pv.w);
;                         r[0] += bflo(ov.x); r[1] += bfhi(ov.x); r[2] += bflo(ov.y); r[3] += bfhi(ov.y); r[4] += bflo(ov.z); r[5] += bfhi(ov.z); r[6] += bflo(ov.w); r[7] += bfhi(ov.w);
;                         u32x4 w; w.x = cvt_pk_bf16(r[0], r[1]); w.y = cvt_pk_bf16(r[2], r[3]); w.z = cvt_pk_bf16(r[4], r[5]); w.w = cvt_pk_bf16(r[6], r[7]);
;                         *(u32x4*)mp = w; } }
.LBB0_925:
	v_add_u32_e32 v236, 0xa0, v206
	v_ashrrev_i32_e32 v237, 31, v236
	v_lshlrev_b64 v[236:237], 13, v[236:237]
	v_lshl_add_u64 v[236:237], v[204:205], 0, v[236:237]
	global_load_dwordx4 v[188:191], v[236:237], off
	global_load_dwordx4 v[232:235], v[236:237], off offset:256
	v_add_u32_e32 v248, 0xb0, v206
	v_ashrrev_i32_e32 v249, 31, v248
	v_lshlrev_b64 v[248:249], 13, v[248:249]
	v_lshl_add_u64 v[248:249], v[204:205], 0, v[248:249]
	global_load_dwordx4 v[240:243], v[248:249], off
	global_load_dwordx4 v[244:247], v[248:249], off offset:256
	v_pk_add_f32 v[78:79], v[78:79], v[40:41]
	v_pk_add_f32 v[74:75], v[74:75], v[32:33]
	v_mul_f32_e32 v78, 0xbfb8aa3b, v78
	v_mul_f32_e32 v79, 0xbfb8aa3b, v79
	v_exp_f32_e32 v78, v78
	v_exp_f32_e32 v79, v79
	v_mul_f32_e32 v74, 0xbfb8aa3b, v74
	v_pk_add_f32 v[76:77], v[76:77], v[34:35]
	v_exp_f32_e32 v118, v74
	v_mul_f32_e32 v74, 0xbfb8aa3b, v75
	v_exp_f32_e32 v119, v74
	v_mul_f32_e32 v74, 0xbfb8aa3b, v76
	v_mul_f32_e32 v75, 0xbfb8aa3b, v77
	v_pk_add_f32 v[76:77], v[78:79], 1.0 op_sel_hi:[1,0]
	v_pk_add_f32 v[80:81], v[80:81], v[42:43]
	v_mul_f32_e32 v80, 0xbfb8aa3b, v80
	v_mul_f32_e32 v81, 0xbfb8aa3b, v81
	v_exp_f32_e32 v80, v80
	v_rcp_f32_e32 v77, v77
	v_exp_f32_e32 v81, v81
	v_exp_f32_e32 v74, v74
	v_exp_f32_e32 v75, v75
	v_rcp_f32_e32 v76, v76
	s_waitcnt vmcnt(7)
	v_lshlrev_b32_e32 v78, 16, v106
	v_and_b32_e32 v79, 0xffff0000, v106
	v_lshlrev_b32_e32 v120, 16, v110
	v_and_b32_e32 v121, 0xffff0000, v110
	v_pk_fma_f32 v[76:77], v[76:77], v[78:79], v[120:121]
	v_pk_add_f32 v[78:79], v[80:81], 1.0 op_sel_hi:[1,0]
	v_pk_add_f32 v[74:75], v[74:75], 1.0 op_sel_hi:[1,0]
	v_pk_add_f32 v[70:71], v[70:71], v[28:29]
	v_lshl_add_u64 v[116:117], s[6:7], 0, v[116:117]
	v_mul_f32_e32 v70, 0xbfb8aa3b, v70
	v_rcp_f32_e32 v79, v79
	v_mul_f32_e32 v71, 0xbfb8aa3b, v71
	v_exp_f32_e32 v70, v70
	v_exp_f32_e32 v71, v71
	v_rcp_f32_e32 v78, v78
	v_lshlrev_b32_e32 v80, 16, v107
	v_and_b32_e32 v81, 0xffff0000, v107
	v_lshlrev_b32_e32 v106, 16, v111
	v_and_b32_e32 v107, 0xffff0000, v111
	v_pk_fma_f32 v[78:79], v[78:79], v[80:81], v[106:107]
	v_pk_add_f32 v[80:81], v[118:119], 1.0 op_sel_hi:[1,0]
	v_pk_add_f32 v[66:67], v[66:67], v[24:25]
	v_lshl_add_u64 v[116:117], v[116:117], 0, v[64:65]
	v_mul_f32_e32 v66, 0xbfb8aa3b, v66
	v_pk_add_f32 v[68:69], v[68:69], v[26:27]
	v_rcp_f32_e32 v81, v81
	v_pk_add_f32 v[72:73], v[72:73], v[30:31]
	v_pk_add_f32 v[60:61], v[60:61], v[40:41]
	v_mul_f32_e32 v72, 0xbfb8aa3b, v72
	v_rcp_f32_e32 v80, v80
	v_lshlrev_b32_e32 v106, 16, v108
	v_and_b32_e32 v107, 0xffff0000, v108
	v_lshlrev_b32_e32 v110, 16, v112
	v_and_b32_e32 v111, 0xffff0000, v112
	v_pk_fma_f32 v[80:81], v[80:81], v[106:107], v[110:111]
	v_mul_f32_e32 v73, 0xbfb8aa3b, v73
	v_exp_f32_e32 v72, v72
	v_exp_f32_e32 v73, v73
	v_rcp_f32_e32 v75, v75
	v_mul_f32_e32 v60, 0xbfb8aa3b, v60
	v_mul_f32_e32 v61, 0xbfb8aa3b, v61
	v_exp_f32_e32 v60, v60
	v_rcp_f32_e32 v74, v74
	v_lshlrev_b32_e32 v106, 16, v109
	v_and_b32_e32 v107, 0xffff0000, v109
	v_lshlrev_b32_e32 v108, 16, v113
	v_and_b32_e32 v109, 0xffff0000, v113
	v_pk_fma_f32 v[106:107], v[74:75], v[106:107], v[108:109]
	v_cvt_pk_bf16_f32 v74, v76, v77
	v_cvt_pk_bf16_f32 v75, v78, v79
	v_cvt_pk_bf16_f32 v76, v80, v81
	v_cvt_pk_bf16_f32 v77, v106, v107
	global_store_dwordx4 v[116:117], v[74:77], off
	v_exp_f32_e32 v61, v61
	v_pk_add_f32 v[56:57], v[56:57], v[32:33]
	v_exp_f32_e32 v74, v66
	v_mul_f32_e32 v66, 0xbfb8aa3b, v67
	v_exp_f32_e32 v75, v66
	v_mul_f32_e32 v66, 0xbfb8aa3b, v68
	v_mul_f32_e32 v67, 0xbfb8aa3b, v69
	v_pk_add_f32 v[68:69], v[70:71], 1.0 op_sel_hi:[1,0]
	v_exp_f32_e32 v66, v66
	v_exp_f32_e32 v67, v67
	v_mul_f32_e32 v56, 0xbfb8aa3b, v56
	v_pk_add_f32 v[58:59], v[58:59], v[34:35]
	v_rcp_f32_e32 v69, v69
	v_pk_add_f32 v[66:67], v[66:67], 1.0 op_sel_hi:[1,0]
	v_pk_add_f32 v[62:63], v[62:63], v[42:43]
	v_pk_add_f32 v[52:53], v[52:53], v[28:29]
	v_rcp_f32_e32 v68, v68
	s_waitcnt vmcnt(7)
; __device__ __forceinline__ unsigned cvt_pk_bf16(float lo, float hi) { f32x2_t v = {lo, hi}; bf2_t r = __builtin_convertvector(v, bf2_t); return __builtin_bit_cast(unsigned, r); }
; __device__ __forceinline__ float bflo(unsigned u) { return __uint_as_float(u << 16); }
; __device__ __forceinline__ float bfhi(unsigned u) { return __uint_as_float(u & 0xffff0000u); }
; __device__ __forceinline__ float sigmoidf_(float x) { return 1.0f / (1.0f + __expf(-x)); }
;     __device__ __forceinline__ void operator()(const f32x4 (&acc)[2][2][4][2], const Unit& u, int wr, int wc, int fr, int fq) const {
;     ...
;                 for (int mm = 0; mm < 2; ++mm) { const size_t row = (size_t)(row0 + ai * HALF + (2 * m2 + mm) * 16);
; #pragma unroll
;                     for (int bj = 0; bj < 2; ++bj) { pvv[mm][bj] = *(const u32x4*)(P + row * 4096 + colg + bj * HALF);
;                         if (j > 0) ovv[mm][bj] = *(const u32x4*)(mixed + row * 1024 + colm + bj * HALF); else ovv[mm][bj] = (u32x4){0u, 0u, 0u, 0u}; } }
; #pragma unroll
;                 for (int mm = 0; mm < 2; ++mm) { const int m = 2 * m2 + mm; const size_t row = (size_t)(row0 + ai * HALF + m * 16);
; #pragma unroll
;                     for (int bj = 0; bj < 2; ++bj) {
;                         const u32x4 pv = pvv[mm][bj], ov = ovv[mm][bj];
;                         bf16_t* mp = mixed + row * 1024 + colm + bj * HALF;
;                         const f32x4 a0 = acc[ai][bj][m][0] + bv[bj][0], a1 = acc[ai][bj][m][1] + bv[bj][1];
;                         float r[8];
;                         r[0] = sigmoidf_(a0[0]) * bflo(pv.x); r[1] = sigmoidf_(a0[1]) * bfhi(pv.x); r[2] = sigmoidf_(a0[2]) * bflo(pv.y); r[3] = sigmoidf_(a0[3]) * bfhi(pv.y);
;                         r[4] = sigmoidf_(a1[0]) * bflo(pv.z); r[5] = sigmoidf_(a1[1]) * bfhi(pv.z); r[6] = sigmoidf_(a1[2]) * bflo(pv.w); r[7] = sigmoidf_(a1[3]) * bfhi(pv.w);
;                         r[0] += bflo(ov.x); r[1] += bfhi(ov.x); r[2] += bflo(ov.y); r[3] += bfhi(ov.y); r[4] += bflo(ov.z); r[5] += bfhi(ov.z); r[6] += bflo(ov.w); r[7] += bfhi(ov.w);
;                         u32x4 w; w.x = cvt_pk_bf16(r[0], r[1]); w.y = cvt_pk_bf16(r[2], r[3]); w.z = cvt_pk_bf16(r[4], r[5]); w.w = cvt_pk_bf16(r[6], r[7]);
;                         *(u32x4*)mp = w; } }
	v_lshlrev_b32_e32 v70, 16, v102
	v_and_b32_e32 v71, 0xffff0000, v102
	v_lshlrev_b32_e32 v76, 16, v98
	v_and_b32_e32 v77, 0xffff0000, v98
	v_pk_fma_f32 v[68:69], v[68:69], v[70:71], v[76:77]
	v_pk_add_f32 v[70:71], v[72:73], 1.0 op_sel_hi:[1,0]
	v_mul_f32_e32 v62, 0xbfb8aa3b, v62
	v_mul_f32_e32 v63, 0xbfb8aa3b, v63
	v_exp_f32_e32 v62, v62
	v_exp_f32_e32 v63, v63
	v_rcp_f32_e32 v71, v71
	v_mul_f32_e32 v52, 0xbfb8aa3b, v52
	v_mul_f32_e32 v53, 0xbfb8aa3b, v53
	v_exp_f32_e32 v52, v52
	v_rcp_f32_e32 v70, v70
	v_lshlrev_b32_e32 v72, 16, v103
	v_and_b32_e32 v73, 0xffff0000, v103
	v_lshlrev_b32_e32 v76, 16, v99
	v_and_b32_e32 v77, 0xffff0000, v99
	v_pk_fma_f32 v[70:71], v[70:71], v[72:73], v[76:77]
	v_pk_add_f32 v[72:73], v[74:75], 1.0 op_sel_hi:[1,0]
	v_exp_f32_e32 v53, v53
	v_pk_add_f32 v[48:49], v[48:49], v[24:25]
	v_pk_add_f32 v[50:51], v[50:51], v[26:27]
	v_mul_f32_e32 v48, 0xbfb8aa3b, v48
	v_rcp_f32_e32 v73, v73
	v_pk_add_f32 v[54:55], v[54:55], v[30:31]
	v_mov_b32_e32 v79, 0
	v_mul_f32_e32 v54, 0xbfb8aa3b, v54
	v_rcp_f32_e32 v72, v72
	v_lshlrev_b32_e32 v74, 16, v104
	v_and_b32_e32 v75, 0xffff0000, v104
	v_lshlrev_b32_e32 v76, 16, v100
	v_and_b32_e32 v77, 0xffff0000, v100
	v_pk_fma_f32 v[72:73], v[72:73], v[74:75], v[76:77]
	v_mul_f32_e32 v55, 0xbfb8aa3b, v55
	v_exp_f32_e32 v54, v54
	v_exp_f32_e32 v55, v55
	v_rcp_f32_e32 v67, v67
	v_mov_b32_e32 v80, 0
	v_mov_b32_e32 v81, 0
	v_rcp_f32_e32 v66, v66
	v_lshlrev_b32_e32 v74, 16, v105
	v_and_b32_e32 v75, 0xffff0000, v105
	v_lshlrev_b32_e32 v76, 16, v101
	v_and_b32_e32 v77, 0xffff0000, v101
	v_pk_fma_f32 v[74:75], v[66:67], v[74:75], v[76:77]
	v_cvt_pk_bf16_f32 v66, v68, v69
	v_cvt_pk_bf16_f32 v67, v70, v71
	v_cvt_pk_bf16_f32 v68, v72, v73
	v_cvt_pk_bf16_f32 v69, v74, v75
	global_store_dwordx4 v[116:117], v[66:69], off offset:256
	v_mov_b32_e32 v78, 0
	s_nop 0
	v_exp_f32_e32 v68, v56
	v_mul_f32_e32 v56, 0xbfb8aa3b, v57
	v_exp_f32_e32 v69, v56
	v_mul_f32_e32 v56, 0xbfb8aa3b, v58
	v_mul_f32_e32 v57, 0xbfb8aa3b, v59
	v_pk_add_f32 v[58:59], v[60:61], 1.0 op_sel_hi:[1,0]
	v_exp_f32_e32 v56, v56
	v_exp_f32_e32 v57, v57
	v_lshl_add_u64 v[66:67], s[6:7], 0, v[114:115]
	v_lshl_add_u64 v[66:67], v[66:67], 0, v[64:65]
	v_rcp_f32_e32 v59, v59
	v_pk_add_f32 v[56:57], v[56:57], 1.0 op_sel_hi:[1,0]
	v_rcp_f32_e32 v58, v58
	s_waitcnt vmcnt(7)
	v_lshlrev_b32_e32 v60, 16, v90
	v_and_b32_e32 v61, 0xffff0000, v90
	v_lshlrev_b32_e32 v70, 16, v94
	v_and_b32_e32 v71, 0xffff0000, v94
	v_pk_fma_f32 v[58:59], v[58:59], v[60:61], v[70:71]
	v_pk_add_f32 v[60:61], v[62:63], 1.0 op_sel_hi:[1,0]
	v_rcp_f32_e32 v61, v61
	v_rcp_f32_e32 v60, v60
	v_lshlrev_b32_e32 v62, 16, v91
	v_and_b32_e32 v63, 0xffff0000, v91
	v_lshlrev_b32_e32 v70, 16, v95
	v_and_b32_e32 v71, 0xffff0000, v95
	v_pk_fma_f32 v[60:61], v[60:61], v[62:63], v[70:71]
	v_pk_add_f32 v[62:63], v[68:69], 1.0 op_sel_hi:[1,0]
	v_rcp_f32_e32 v63, v63
	v_rcp_f32_e32 v62, v62
	v_lshlrev_b32_e32 v68, 16, v92
	v_and_b32_e32 v69, 0xffff0000, v92
	v_lshlrev_b32_e32 v70, 16, v96
	v_and_b32_e32 v71, 0xffff0000, v96
	v_pk_fma_f32 v[62:63], v[62:63], v[68:69], v[70:71]
	v_rcp_f32_e32 v57, v57
	v_rcp_f32_e32 v56, v56
	v_lshlrev_b32_e32 v68, 16, v93
	v_and_b32_e32 v69, 0xffff0000, v93
	v_lshlrev_b32_e32 v70, 16, v97
	v_and_b32_e32 v71, 0xffff0000, v97
	v_pk_fma_f32 v[68:69], v[56:57], v[68:69], v[70:71]
	v_cvt_pk_bf16_f32 v56, v58, v59
	v_cvt_pk_bf16_f32 v57, v60, v61
	v_cvt_pk_bf16_f32 v58, v62, v63
	v_cvt_pk_bf16_f32 v59, v68, v69
	global_store_dwordx4 v[66:67], v[56:59], off
	s_nop 1
	v_exp_f32_e32 v56, v48
	v_mul_f32_e32 v48, 0xbfb8aa3b, v49
	v_exp_f32_e32 v57, v48
	v_mul_f32_e32 v48, 0xbfb8aa3b, v50
	v_mul_f32_e32 v49, 0xbfb8aa3b, v51
	v_pk_add_f32 v[50:51], v[52:53], 1.0 op_sel_hi:[1,0]
	v_exp_f32_e32 v48, v48
	v_exp_f32_e32 v49, v49
	v_rcp_f32_e32 v51, v51
	v_pk_add_f32 v[48:49], v[48:49], 1.0 op_sel_hi:[1,0]
	v_rcp_f32_e32 v50, v50
	s_waitcnt vmcnt(7)
	v_lshlrev_b32_e32 v52, 16, v86
	v_and_b32_e32 v53, 0xffff0000, v86
	v_lshlrev_b32_e32 v58, 16, v82
	v_and_b32_e32 v59, 0xffff0000, v82
	v_pk_fma_f32 v[50:51], v[50:51], v[52:53], v[58:59]
	v_pk_add_f32 v[52:53], v[54:55], 1.0 op_sel_hi:[1,0]
	v_rcp_f32_e32 v53, v53
	v_rcp_f32_e32 v52, v52
	v_lshlrev_b32_e32 v54, 16, v87
	v_and_b32_e32 v55, 0xffff0000, v87
	v_lshlrev_b32_e32 v58, 16, v83
	v_and_b32_e32 v59, 0xffff0000, v83
	v_pk_fma_f32 v[52:53], v[52:53], v[54:55], v[58:59]
	v_pk_add_f32 v[54:55], v[56:57], 1.0 op_sel_hi:[1,0]
	v_rcp_f32_e32 v55, v55
	v_rcp_f32_e32 v54, v54
	v_lshlrev_b32_e32 v56, 16, v88
	v_and_b32_e32 v57, 0xffff0000, v88
	v_lshlrev_b32_e32 v58, 16, v84
	v_and_b32_e32 v59, 0xffff0000, v84
	v_pk_fma_f32 v[54:55], v[54:55], v[56:57], v[58:59]
	v_rcp_f32_e32 v49, v49
	v_rcp_f32_e32 v48, v48
	v_lshlrev_b32_e32 v56, 16, v89
	v_and_b32_e32 v57, 0xffff0000, v89
	v_lshlrev_b32_e32 v58, 16, v85
	v_and_b32_e32 v59, 0xffff0000, v85
	v_pk_fma_f32 v[56:57], v[48:49], v[56:57], v[58:59]
	v_cvt_pk_bf16_f32 v48, v50, v51
	v_cvt_pk_bf16_f32 v49, v52, v53
	v_cvt_pk_bf16_f32 v50, v54, v55
	v_cvt_pk_bf16_f32 v51, v56, v57
	global_store_dwordx4 v[66:67], v[48:51], off offset:256
	v_mov_b32_e32 v66, 0
	s_and_b64 vcc, exec, s[42:43]
	v_add_u32_e32 v48, 0xa0, v206
	v_ashrrev_i32_e32 v49, 31, v48
	v_lshlrev_b64 v[50:51], 13, v[48:49]
	v_lshl_add_u64 v[50:51], v[204:205], 0, v[50:51]
	s_waitcnt vmcnt(4)
	v_mov_b64_e32 v[74:75], v[188:189]
	v_mov_b64_e32 v[76:77], v[190:191]
	v_lshlrev_b64 v[84:85], 11, v[48:49]
	v_lshl_add_u64 v[48:49], v[208:209], 0, v[84:85]
	s_cbranch_vccnz .LBB0_927
	global_load_dwordx4 v[78:81], v[48:49], off

; __device__ __forceinline__ unsigned cvt_pk_bf16(float lo, float hi) { f32x2_t v = {lo, hi}; bf2_t r = __builtin_convertvector(v, bf2_t); return __builtin_bit_cast(unsigned, r); }
; __device__ __forceinline__ float bflo(unsigned u) { return __uint_as_float(u << 16); }
; __device__ __forceinline__ float bfhi(unsigned u) { return __uint_as_float(u & 0xffff0000u); }
; __device__ __forceinline__ float sigmoidf_(float x) { return 1.0f / (1.0f + __expf(-x)); }
;     __device__ __forceinline__ void operator()(const f32x4 (&acc)[2][2][4][2], const Unit& u, int wr, int wc, int fr, int fq) const {
;     ...
;                 for (int mm = 0; mm < 2; ++mm) { const size_t row = (size_t)(row0 + ai * HALF + (2 * m2 + mm) * 16);
; #pragma unroll
;                     for (int bj = 0; bj < 2; ++bj) { pvv[mm][bj] = *(const u32x4*)(P + row * 4096 + colg + bj * HALF);
;                         if (j > 0) ovv[mm][bj] = *(const u32x4*)(mixed + row * 1024 + colm + bj * HALF); else ovv[mm][bj] = (u32x4){0u, 0u, 0u, 0u}; } }
; #pragma unroll
;                 for (int mm = 0; mm < 2; ++mm) { const int m = 2 * m2 + mm; const size_t row = (size_t)(row0 + ai * HALF + m * 16);
; #pragma unroll
;                     for (int bj = 0; bj < 2; ++bj) {
;                         const u32x4 pv = pvv[mm][bj], ov = ovv[mm][bj];
;                         bf16_t* mp = mixed + row * 1024 + colm + bj * HALF;
;                         const f32x4 a0 = acc[ai][bj][m][0] + bv[bj][0], a1 = acc[ai][bj][m][1] + bv[bj][1];
;                         float r[8];
;                         r[0] = sigmoidf_(a0[0]) * bflo(pv.x); r[1] = sigmoidf_(a0[1]) * bfhi(pv.x); r[2] = sigmoidf_(a0[2]) * bflo(pv.y); r[3] = sigmoidf_(a0[3]) * bfhi(pv.y);
;                         r[4] = sigmoidf_(a1[0]) * bflo(pv.z); r[5] = sigmoidf_(a1[1]) * bfhi(pv.z); r[6] = sigmoidf_(a1[2]) * bflo(pv.w); r[7] = sigmoidf_(a1[3]) * bfhi(pv.w);
;                         r[0] += bflo(ov.x); r[1] += bfhi(ov.x); r[2] += bflo(ov.y); r[3] += bfhi(ov.y); r[4] += bflo(ov.z); r[5] += bfhi(ov.z); r[6] += bflo(ov.w); r[7] += bfhi(ov.w);
;                         u32x4 w; w.x = cvt_pk_bf16(r[0], r[1]); w.y = cvt_pk_bf16(r[2], r[3]); w.z = cvt_pk_bf16(r[4], r[5]); w.w = cvt_pk_bf16(r[6], r[7]);
;                         *(u32x4*)mp = w; } }
.LBB0_933:
	v_pk_add_f32 v[44:45], v[44:45], v[40:41]
	v_pk_add_f32 v[36:37], v[36:37], v[32:33]
	v_mul_f32_e32 v44, 0xbfb8aa3b, v44
	v_mul_f32_e32 v45, 0xbfb8aa3b, v45
	v_exp_f32_e32 v44, v44
	v_exp_f32_e32 v45, v45
	v_mul_f32_e32 v36, 0xbfb8aa3b, v36
	v_pk_add_f32 v[38:39], v[38:39], v[34:35]
	v_exp_f32_e32 v86, v36
	v_mul_f32_e32 v36, 0xbfb8aa3b, v37
	v_exp_f32_e32 v87, v36
	v_mul_f32_e32 v36, 0xbfb8aa3b, v38
	v_mul_f32_e32 v37, 0xbfb8aa3b, v39
	v_pk_add_f32 v[38:39], v[44:45], 1.0 op_sel_hi:[1,0]
	v_pk_add_f32 v[46:47], v[46:47], v[42:43]
	v_mul_f32_e32 v46, 0xbfb8aa3b, v46
	v_mul_f32_e32 v47, 0xbfb8aa3b, v47
	v_exp_f32_e32 v46, v46
	v_rcp_f32_e32 v39, v39
	v_exp_f32_e32 v47, v47
	v_exp_f32_e32 v36, v36
	v_exp_f32_e32 v37, v37
	v_rcp_f32_e32 v38, v38
	s_waitcnt vmcnt(3)
	v_lshlrev_b32_e32 v44, 16, v74
	v_and_b32_e32 v45, 0xffff0000, v74
	v_lshlrev_b32_e32 v88, 16, v78
	v_and_b32_e32 v89, 0xffff0000, v78
	v_pk_fma_f32 v[38:39], v[38:39], v[44:45], v[88:89]
	v_pk_add_f32 v[44:45], v[46:47], 1.0 op_sel_hi:[1,0]
	v_pk_add_f32 v[36:37], v[36:37], 1.0 op_sel_hi:[1,0]
	v_pk_add_f32 v[20:21], v[20:21], v[28:29]
	v_lshl_add_u64 v[84:85], s[6:7], 0, v[84:85]
	v_mul_f32_e32 v20, 0xbfb8aa3b, v20
	v_rcp_f32_e32 v45, v45
	v_mul_f32_e32 v21, 0xbfb8aa3b, v21
	v_exp_f32_e32 v20, v20
	v_exp_f32_e32 v21, v21
	v_rcp_f32_e32 v44, v44
	v_lshlrev_b32_e32 v46, 16, v75
	v_and_b32_e32 v47, 0xffff0000, v75
	v_lshlrev_b32_e32 v74, 16, v79
	v_and_b32_e32 v75, 0xffff0000, v79
	v_pk_fma_f32 v[44:45], v[44:45], v[46:47], v[74:75]
	v_pk_add_f32 v[46:47], v[86:87], 1.0 op_sel_hi:[1,0]
	v_pk_add_f32 v[16:17], v[16:17], v[24:25]
	v_lshl_add_u64 v[84:85], v[84:85], 0, v[64:65]
	v_mul_f32_e32 v16, 0xbfb8aa3b, v16
	v_pk_add_f32 v[18:19], v[18:19], v[26:27]
	v_rcp_f32_e32 v47, v47
	v_pk_add_f32 v[22:23], v[22:23], v[30:31]
	v_pk_add_f32 v[12:13], v[12:13], v[40:41]
	v_mul_f32_e32 v22, 0xbfb8aa3b, v22
	v_rcp_f32_e32 v46, v46
	v_lshlrev_b32_e32 v74, 16, v76
	v_and_b32_e32 v75, 0xffff0000, v76
	v_lshlrev_b32_e32 v78, 16, v80
	v_and_b32_e32 v79, 0xffff0000, v80
	v_pk_fma_f32 v[46:47], v[46:47], v[74:75], v[78:79]
	v_mul_f32_e32 v23, 0xbfb8aa3b, v23
	v_exp_f32_e32 v22, v22
	v_exp_f32_e32 v23, v23
	v_rcp_f32_e32 v37, v37
	v_mul_f32_e32 v12, 0xbfb8aa3b, v12
	v_mul_f32_e32 v13, 0xbfb8aa3b, v13
	v_exp_f32_e32 v12, v12
	v_rcp_f32_e32 v36, v36
	v_lshlrev_b32_e32 v74, 16, v77
	v_and_b32_e32 v75, 0xffff0000, v77
	v_lshlrev_b32_e32 v76, 16, v81
	v_and_b32_e32 v77, 0xffff0000, v81
	v_pk_fma_f32 v[74:75], v[36:37], v[74:75], v[76:77]
	v_cvt_pk_bf16_f32 v36, v38, v39
	v_cvt_pk_bf16_f32 v37, v44, v45
	v_cvt_pk_bf16_f32 v38, v46, v47
	v_cvt_pk_bf16_f32 v39, v74, v75
	global_store_dwordx4 v[84:85], v[36:39], off
	v_exp_f32_e32 v13, v13
	v_pk_add_f32 v[8:9], v[8:9], v[32:33]
	v_exp_f32_e32 v36, v16
	v_mul_f32_e32 v16, 0xbfb8aa3b, v17
	v_exp_f32_e32 v37, v16
	v_mul_f32_e32 v16, 0xbfb8aa3b, v18
	v_mul_f32_e32 v17, 0xbfb8aa3b, v19
	v_pk_add_f32 v[18:19], v[20:21], 1.0 op_sel_hi:[1,0]
	v_exp_f32_e32 v16, v16
	v_exp_f32_e32 v17, v17
	v_mul_f32_e32 v8, 0xbfb8aa3b, v8
	v_pk_add_f32 v[10:11], v[10:11], v[34:35]
	v_rcp_f32_e32 v19, v19
	v_pk_add_f32 v[16:17], v[16:17], 1.0 op_sel_hi:[1,0]
	v_pk_add_f32 v[14:15], v[14:15], v[42:43]
	v_pk_add_f32 v[4:5], v[4:5], v[28:29]
	v_rcp_f32_e32 v18, v18
	s_waitcnt vmcnt(3)
; __device__ __forceinline__ unsigned cvt_pk_bf16(float lo, float hi) { f32x2_t v = {lo, hi}; bf2_t r = __builtin_convertvector(v, bf2_t); return __builtin_bit_cast(unsigned, r); }
; __device__ __forceinline__ float bflo(unsigned u) { return __uint_as_float(u << 16); }
; template <class Epi, class Sched, bool ALIGN_EPI = false, bool SP2 = false>
; __device__ __forceinline__ void gemm_phase(LAS unsigned char* lds, const Gemm g, const Sched& S, const Epi& E) {
;     ...
;         if constexpr (ALIGN_EPI) { if (wr == 0) PG8_BAR; }
;         E(acc, cur, wr, wc, fr, fq);
;         if (!has_next) break;
; #pragma unroll
;         for (int a = 0; a < 2; ++a)
; #pragma unroll
;             for (int b = 0; b < 2; ++b)
; #pragma unroll
;                 for (int m = 0; m < 4; ++m)
; #pragma unroll
;                     for (int n = 0; n < 2; ++n) acc[a][b][m][n] = (f32x4){0.f, 0.f, 0.f, 0.f};
;         cur = nxt; cA = nA; cB = nB; ++ui;
;         if constexpr (ALIGN_EPI) { if (wr == 1) PG8_BAR; }
;     __device__ __forceinline__ void operator()(const f32x4 (&acc)[2][2][4][2], const Unit& u, int wr, int wc, int fr, int fq) const {
;     ...
;                 for (int mm = 0; mm < 2; ++mm) { const int m = 2 * m2 + mm; const size_t row = (size_t)(row0 + ai * HALF + m * 16);
; #pragma unroll
;                     for (int bj = 0; bj < 2; ++bj) {
;                         const u32x4 pv = pvv[mm][bj], ov = ovv[mm][bj];
;                         bf16_t* mp = mixed + row * 1024 + colm + bj * HALF;
;                         const f32x4 a0 = acc[ai][bj][m][0] + bv[bj][0], a1 = acc[ai][bj][m][1] + bv[bj][1];
;                         float r[8];
;                         r[0] = sigmoidf_(a0[0]) * bflo(pv.x); r[1] = sigmoidf_(a0[1]) * bfhi(pv.x); r[2] = sigmoidf_(a0[2]) * bflo(pv.y); r[3] = sigmoidf_(a0[3]) * bfhi(pv.y);
;                         r[4] = sigmoidf_(a1[0]) * bflo(pv.z); r[5] = sigmoidf_(a1[1]) * bfhi(pv.z); r[6] = sigmoidf_(a1[2]) * bflo(pv.w); r[7] = sigmoidf_(a1[3]) * bfhi(pv.w);
;                         r[0] += bflo(ov.x); r[1] += bfhi(ov.x); r[2] += bflo(ov.y); r[3] += bfhi(ov.y); r[4] += bflo(ov.z); r[5] += bfhi(ov.z); r[6] += bflo(ov.w); r[7] += bfhi(ov.w);
;                         u32x4 w; w.x = cvt_pk_bf16(r[0], r[1]); w.y = cvt_pk_bf16(r[2], r[3]); w.z = cvt_pk_bf16(r[4], r[5]); w.w = cvt_pk_bf16(r[6], r[7]);
;                         *(u32x4*)mp = w; } }
	v_lshlrev_b32_e32 v20, 16, v70
	v_and_b32_e32 v21, 0xffff0000, v70
	v_lshlrev_b32_e32 v38, 16, v66
	v_and_b32_e32 v39, 0xffff0000, v66
	v_pk_fma_f32 v[18:19], v[18:19], v[20:21], v[38:39]
	v_pk_add_f32 v[20:21], v[22:23], 1.0 op_sel_hi:[1,0]
	v_mul_f32_e32 v14, 0xbfb8aa3b, v14
	v_mul_f32_e32 v15, 0xbfb8aa3b, v15
	v_exp_f32_e32 v14, v14
	v_exp_f32_e32 v15, v15
	v_rcp_f32_e32 v21, v21
	v_mul_f32_e32 v4, 0xbfb8aa3b, v4
	v_mul_f32_e32 v5, 0xbfb8aa3b, v5
	v_exp_f32_e32 v4, v4
	v_rcp_f32_e32 v20, v20
	v_lshlrev_b32_e32 v22, 16, v71
	v_and_b32_e32 v23, 0xffff0000, v71
	v_lshlrev_b32_e32 v38, 16, v67
	v_and_b32_e32 v39, 0xffff0000, v67
	v_pk_fma_f32 v[20:21], v[20:21], v[22:23], v[38:39]
	v_pk_add_f32 v[22:23], v[36:37], 1.0 op_sel_hi:[1,0]
	v_exp_f32_e32 v5, v5
	v_pk_add_f32 v[0:1], v[0:1], v[24:25]
	v_pk_add_f32 v[2:3], v[2:3], v[26:27]
	v_mul_f32_e32 v0, 0xbfb8aa3b, v0
	v_rcp_f32_e32 v23, v23
	v_pk_add_f32 v[6:7], v[6:7], v[30:31]
	v_rcp_f32_e32 v22, v22
	v_lshlrev_b32_e32 v36, 16, v72
	v_and_b32_e32 v37, 0xffff0000, v72
	v_lshlrev_b32_e32 v38, 16, v68
	v_and_b32_e32 v39, 0xffff0000, v68
	v_pk_fma_f32 v[22:23], v[22:23], v[36:37], v[38:39]
	v_mul_f32_e32 v6, 0xbfb8aa3b, v6
	v_mul_f32_e32 v7, 0xbfb8aa3b, v7
	v_exp_f32_e32 v6, v6
	v_rcp_f32_e32 v17, v17
	v_exp_f32_e32 v7, v7
	v_rcp_f32_e32 v16, v16
	v_lshlrev_b32_e32 v36, 16, v73
	v_and_b32_e32 v37, 0xffff0000, v73
	v_lshlrev_b32_e32 v38, 16, v69
	v_and_b32_e32 v39, 0xffff0000, v69
	v_pk_fma_f32 v[36:37], v[16:17], v[36:37], v[38:39]
	v_cvt_pk_bf16_f32 v16, v18, v19
	v_cvt_pk_bf16_f32 v17, v20, v21
	v_cvt_pk_bf16_f32 v18, v22, v23
	v_cvt_pk_bf16_f32 v19, v36, v37
	global_store_dwordx4 v[84:85], v[16:19], off offset:256
	s_nop 1
	v_exp_f32_e32 v18, v8
	v_mul_f32_e32 v8, 0xbfb8aa3b, v9
	v_exp_f32_e32 v19, v8
	v_mul_f32_e32 v8, 0xbfb8aa3b, v10
	v_mul_f32_e32 v9, 0xbfb8aa3b, v11
	v_pk_add_f32 v[10:11], v[12:13], 1.0 op_sel_hi:[1,0]
	v_exp_f32_e32 v8, v8
	v_exp_f32_e32 v9, v9
	v_lshl_add_u64 v[16:17], s[6:7], 0, v[82:83]
	v_lshl_add_u64 v[16:17], v[16:17], 0, v[64:65]
	v_rcp_f32_e32 v11, v11
	v_pk_add_f32 v[8:9], v[8:9], 1.0 op_sel_hi:[1,0]
	v_rcp_f32_e32 v10, v10
	s_waitcnt vmcnt(3)
	v_lshlrev_b32_e32 v12, 16, v56
	v_and_b32_e32 v13, 0xffff0000, v56
	v_lshlrev_b32_e32 v20, 16, v60
	v_and_b32_e32 v21, 0xffff0000, v60
	v_pk_fma_f32 v[10:11], v[10:11], v[12:13], v[20:21]
	v_pk_add_f32 v[12:13], v[14:15], 1.0 op_sel_hi:[1,0]
	v_rcp_f32_e32 v13, v13
	v_rcp_f32_e32 v12, v12
	v_lshlrev_b32_e32 v14, 16, v57
	v_and_b32_e32 v15, 0xffff0000, v57
	v_lshlrev_b32_e32 v20, 16, v61
	v_and_b32_e32 v21, 0xffff0000, v61
	v_pk_fma_f32 v[12:13], v[12:13], v[14:15], v[20:21]
	v_pk_add_f32 v[14:15], v[18:19], 1.0 op_sel_hi:[1,0]
	v_rcp_f32_e32 v15, v15
	v_rcp_f32_e32 v14, v14
	v_lshlrev_b32_e32 v18, 16, v58
	v_and_b32_e32 v19, 0xffff0000, v58
	v_lshlrev_b32_e32 v20, 16, v62
	v_and_b32_e32 v21, 0xffff0000, v62
	v_pk_fma_f32 v[14:15], v[14:15], v[18:19], v[20:21]
	v_rcp_f32_e32 v9, v9
	v_rcp_f32_e32 v8, v8
	v_lshlrev_b32_e32 v18, 16, v59
	v_and_b32_e32 v19, 0xffff0000, v59
	v_lshlrev_b32_e32 v20, 16, v63
	v_and_b32_e32 v21, 0xffff0000, v63
	v_pk_fma_f32 v[18:19], v[8:9], v[18:19], v[20:21]
	v_cvt_pk_bf16_f32 v8, v10, v11
	v_cvt_pk_bf16_f32 v9, v12, v13
	v_cvt_pk_bf16_f32 v10, v14, v15
	v_cvt_pk_bf16_f32 v11, v18, v19
	global_store_dwordx4 v[16:17], v[8:11], off
	s_nop 1
	v_exp_f32_e32 v8, v0
	v_mul_f32_e32 v0, 0xbfb8aa3b, v1
	v_exp_f32_e32 v9, v0
	v_mul_f32_e32 v0, 0xbfb8aa3b, v2
	v_mul_f32_e32 v1, 0xbfb8aa3b, v3
	v_pk_add_f32 v[2:3], v[4:5], 1.0 op_sel_hi:[1,0]
	v_exp_f32_e32 v0, v0
	v_exp_f32_e32 v1, v1
	v_rcp_f32_e32 v3, v3
	v_pk_add_f32 v[0:1], v[0:1], 1.0 op_sel_hi:[1,0]
	v_rcp_f32_e32 v2, v2
	s_waitcnt vmcnt(3)
	v_lshlrev_b32_e32 v4, 16, v52
	v_and_b32_e32 v5, 0xffff0000, v52
	v_lshlrev_b32_e32 v10, 16, v48
	v_and_b32_e32 v11, 0xffff0000, v48
	v_pk_fma_f32 v[2:3], v[2:3], v[4:5], v[10:11]
	v_pk_add_f32 v[4:5], v[6:7], 1.0 op_sel_hi:[1,0]
	v_rcp_f32_e32 v5, v5
	v_rcp_f32_e32 v4, v4
	v_lshlrev_b32_e32 v6, 16, v53
	v_and_b32_e32 v7, 0xffff0000, v53
	v_lshlrev_b32_e32 v10, 16, v49
	v_and_b32_e32 v11, 0xffff0000, v49
	v_pk_fma_f32 v[4:5], v[4:5], v[6:7], v[10:11]
	v_pk_add_f32 v[6:7], v[8:9], 1.0 op_sel_hi:[1,0]
	v_rcp_f32_e32 v7, v7
	v_rcp_f32_e32 v6, v6
	v_lshlrev_b32_e32 v8, 16, v54
	v_and_b32_e32 v9, 0xffff0000, v54
	v_lshlrev_b32_e32 v10, 16, v50
	v_and_b32_e32 v11, 0xffff0000, v50
	v_pk_fma_f32 v[6:7], v[6:7], v[8:9], v[10:11]
	v_rcp_f32_e32 v1, v1
	s_mov_b64 s[38:39], -1
	v_rcp_f32_e32 v0, v0
	v_lshlrev_b32_e32 v8, 16, v55
	v_and_b32_e32 v9, 0xffff0000, v55
	v_lshlrev_b32_e32 v10, 16, v51
	v_and_b32_e32 v11, 0xffff0000, v51
	v_pk_fma_f32 v[8:9], v[0:1], v[8:9], v[10:11]
	v_cvt_pk_bf16_f32 v0, v2, v3
	v_cvt_pk_bf16_f32 v1, v4, v5
	v_cvt_pk_bf16_f32 v2, v6, v7
	v_cvt_pk_bf16_f32 v3, v8, v9
	global_store_dwordx4 v[16:17], v[0:3], off offset:256
	s_andn2_b64 vcc, exec, s[16:17]
	s_cbranch_vccnz .LBB0_889
	s_andn2_b64 vcc, exec, s[0:1]
	s_cbranch_vccnz .LBB0_888
	s_barrier
	s_branch .LBB0_888

; __device__ __forceinline__ unsigned cvt_pk_bf16(float lo, float hi) { f32x2_t v = {lo, hi}; bf2_t r = __builtin_convertvector(v, bf2_t); return __builtin_bit_cast(unsigned, r); }
; __device__ __forceinline__ float siluf_(float x) { return x * sigmoidf_(x); }
;     __device__ __forceinline__ void operator()(const f32x4 (&acc)[2][2][4][2], const Unit& u, int wr, int wc, int fr, int fq) const {
;     ...
;         for (int ai = 0; ai < 2; ++ai)
; #pragma unroll
;             for (int m = 0; m < 4; ++m) { bf16_t* rowp = U + (size_t)(row0 + ai * HALF + m * 16) * DFF + col0;
;                 const f32x4 g0 = acc[ai][0][m][0], g1 = acc[ai][0][m][1], h0 = acc[ai][1][m][0], h1 = acc[ai][1][m][1];
;                 u32x4 w; w.x = cvt_pk_bf16(siluf_(g0[0]) * h0[0], siluf_(g0[1]) * h0[1]); w.y = cvt_pk_bf16(siluf_(g0[2]) * h0[2], siluf_(g0[3]) * h0[3]);
;                 w.z = cvt_pk_bf16(siluf_(g1[0]) * h1[0], siluf_(g1[1]) * h1[1]); w.w = cvt_pk_bf16(siluf_(g1[2]) * h1[2], siluf_(g1[3]) * h1[3]);
;                 *(u32x4*)rowp = w; }
.LBB0_1129:
	v_mul_f32_e32 v151, 0xbfb8aa3b, v126
	v_exp_f32_e32 v152, v151
	v_mul_f32_e32 v151, 0xbfb8aa3b, v127
	v_exp_f32_e32 v153, v151
	v_lshl_or_b32 v142, s53, 7, v148
	v_lshl_add_u32 v150, s67, 8, v146
	v_ashrrev_i32_e32 v143, 31, v142
	v_pk_add_f32 v[152:153], v[152:153], 1.0 op_sel_hi:[1,0]
	v_mov_b64_e32 v[140:141], s[4:5]
	s_movk_i32 s9, 0x1600
	v_mad_i64_i32 v[144:145], s[16:17], v150, s9, v[140:141]
	v_rcp_f32_e32 v153, v153
	v_lshlrev_b64 v[142:143], 1, v[142:143]
	v_lshl_add_u64 v[144:145], v[144:145], 0, v[142:143]
	v_rcp_f32_e32 v152, v152
	s_nop 0
	v_pk_mul_f32 v[126:127], v[126:127], v[152:153]
	v_pk_mul_f32 v[122:123], v[126:127], v[122:123]
	v_cvt_pk_bf16_f32 v122, v122, v123
	v_mul_f32_e32 v123, 0xbfb8aa3b, v128
	v_exp_f32_e32 v126, v123
	v_mul_f32_e32 v123, 0xbfb8aa3b, v129
	v_exp_f32_e32 v127, v123
	s_nop 0
	v_pk_add_f32 v[126:127], v[126:127], 1.0 op_sel_hi:[1,0]
	v_rcp_f32_e32 v127, v127
	v_rcp_f32_e32 v126, v126
	s_nop 0
	v_pk_mul_f32 v[126:127], v[128:129], v[126:127]
	v_pk_mul_f32 v[124:125], v[126:127], v[124:125]
	v_cvt_pk_bf16_f32 v123, v124, v125
	v_mul_f32_e32 v124, 0xbfb8aa3b, v118
	v_mul_f32_e32 v125, 0xbfb8aa3b, v119
	v_exp_f32_e32 v124, v124
	v_exp_f32_e32 v125, v125
	s_nop 0
	v_pk_add_f32 v[124:125], v[124:125], 1.0 op_sel_hi:[1,0]
	v_rcp_f32_e32 v125, v125
	v_rcp_f32_e32 v124, v124
	s_nop 0
	v_pk_mul_f32 v[118:119], v[118:119], v[124:125]
	v_pk_mul_f32 v[114:115], v[118:119], v[114:115]
	v_cvt_pk_bf16_f32 v124, v114, v115
	v_mul_f32_e32 v114, 0xbfb8aa3b, v120
	v_mul_f32_e32 v115, 0xbfb8aa3b, v121
	v_exp_f32_e32 v114, v114
	v_exp_f32_e32 v115, v115
	s_nop 0
	v_pk_add_f32 v[114:115], v[114:115], 1.0 op_sel_hi:[1,0]
	v_rcp_f32_e32 v115, v115
	v_rcp_f32_e32 v114, v114
	s_nop 0
	v_pk_mul_f32 v[114:115], v[120:121], v[114:115]
	v_pk_mul_f32 v[114:115], v[114:115], v[116:117]
	v_mul_f32_e32 v116, 0xbfb8aa3b, v110
	v_mul_f32_e32 v117, 0xbfb8aa3b, v111
	v_exp_f32_e32 v116, v116
	v_exp_f32_e32 v117, v117
	v_cvt_pk_bf16_f32 v125, v114, v115
	global_store_dwordx4 v[144:145], v[122:125], off
	v_or_b32_e32 v114, 16, v150
	v_pk_add_f32 v[116:117], v[116:117], 1.0 op_sel_hi:[1,0]
	v_mad_i64_i32 v[114:115], s[16:17], v114, s9, v[140:141]
	v_lshl_add_u64 v[114:115], v[114:115], 0, v[142:143]
	v_rcp_f32_e32 v117, v117
	v_rcp_f32_e32 v116, v116
	s_nop 0
	v_pk_mul_f32 v[110:111], v[110:111], v[116:117]
	v_pk_mul_f32 v[106:107], v[110:111], v[106:107]
	v_cvt_pk_bf16_f32 v106, v106, v107
	v_mul_f32_e32 v107, 0xbfb8aa3b, v112
	v_exp_f32_e32 v110, v107
	v_mul_f32_e32 v107, 0xbfb8aa3b, v113
	v_exp_f32_e32 v111, v107
	s_nop 0
	v_pk_add_f32 v[110:111], v[110:111], 1.0 op_sel_hi:[1,0]
	v_rcp_f32_e32 v111, v111
	v_rcp_f32_e32 v110, v110
	s_nop 0
	v_pk_mul_f32 v[110:111], v[112:113], v[110:111]
	v_pk_mul_f32 v[108:109], v[110:111], v[108:109]
	v_cvt_pk_bf16_f32 v107, v108, v109
	v_mul_f32_e32 v108, 0xbfb8aa3b, v102
	v_mul_f32_e32 v109, 0xbfb8aa3b, v103
	v_exp_f32_e32 v108, v108
	v_exp_f32_e32 v109, v109
	s_nop 0
	v_pk_add_f32 v[108:109], v[108:109], 1.0 op_sel_hi:[1,0]
	v_rcp_f32_e32 v109, v109
	v_rcp_f32_e32 v108, v108
	s_nop 0
	v_pk_mul_f32 v[102:103], v[102:103], v[108:109]
	v_pk_mul_f32 v[98:99], v[102:103], v[98:99]
	v_cvt_pk_bf16_f32 v108, v98, v99
	v_mul_f32_e32 v98, 0xbfb8aa3b, v104
	v_mul_f32_e32 v99, 0xbfb8aa3b, v105
	v_exp_f32_e32 v98, v98
	v_exp_f32_e32 v99, v99
	s_nop 0
	v_pk_add_f32 v[98:99], v[98:99], 1.0 op_sel_hi:[1,0]
	v_rcp_f32_e32 v99, v99
	v_rcp_f32_e32 v98, v98
	s_nop 0
	v_pk_mul_f32 v[98:99], v[104:105], v[98:99]
	v_pk_mul_f32 v[98:99], v[98:99], v[100:101]
	v_mul_f32_e32 v100, 0xbfb8aa3b, v94
	v_mul_f32_e32 v101, 0xbfb8aa3b, v95
	v_exp_f32_e32 v100, v100
	v_exp_f32_e32 v101, v101
	v_cvt_pk_bf16_f32 v109, v98, v99
	global_store_dwordx4 v[114:115], v[106:109], off
	v_or_b32_e32 v98, 32, v150
	v_pk_add_f32 v[100:101], v[100:101], 1.0 op_sel_hi:[1,0]
	v_mad_i64_i32 v[98:99], s[16:17], v98, s9, v[140:141]
	v_lshl_add_u64 v[98:99], v[98:99], 0, v[142:143]
	v_rcp_f32_e32 v101, v101
	v_rcp_f32_e32 v100, v100
	s_nop 0
	v_pk_mul_f32 v[94:95], v[94:95], v[100:101]
	v_pk_mul_f32 v[90:91], v[94:95], v[90:91]
	v_cvt_pk_bf16_f32 v90, v90, v91
	v_mul_f32_e32 v91, 0xbfb8aa3b, v96
	v_exp_f32_e32 v94, v91
	v_mul_f32_e32 v91, 0xbfb8aa3b, v97
	v_exp_f32_e32 v95, v91
	s_nop 0
	v_pk_add_f32 v[94:95], v[94:95], 1.0 op_sel_hi:[1,0]
	v_rcp_f32_e32 v95, v95
	v_rcp_f32_e32 v94, v94
	s_nop 0
	v_pk_mul_f32 v[94:95], v[96:97], v[94:95]
	v_pk_mul_f32 v[92:93], v[94:95], v[92:93]
	v_cvt_pk_bf16_f32 v91, v92, v93
	v_mul_f32_e32 v92, 0xbfb8aa3b, v86
	v_mul_f32_e32 v93, 0xbfb8aa3b, v87
	v_exp_f32_e32 v92, v92
	v_exp_f32_e32 v93, v93
	s_nop 0
	v_pk_add_f32 v[92:93], v[92:93], 1.0 op_sel_hi:[1,0]
	v_rcp_f32_e32 v93, v93
	v_rcp_f32_e32 v92, v92
	s_nop 0
	v_pk_mul_f32 v[86:87], v[86:87], v[92:93]
	v_pk_mul_f32 v[82:83], v[86:87], v[82:83]
	v_cvt_pk_bf16_f32 v92, v82, v83
	v_mul_f32_e32 v82, 0xbfb8aa3b, v88
	v_mul_f32_e32 v83, 0xbfb8aa3b, v89
	v_exp_f32_e32 v82, v82
	v_exp_f32_e32 v83, v83
	s_nop 0
	v_pk_add_f32 v[82:83], v[82:83], 1.0 op_sel_hi:[1,0]
	v_rcp_f32_e32 v83, v83
	v_rcp_f32_e32 v82, v82
	s_nop 0
	v_pk_mul_f32 v[82:83], v[88:89], v[82:83]
	v_pk_mul_f32 v[82:83], v[82:83], v[84:85]
	v_mul_f32_e32 v84, 0xbfb8aa3b, v78
	v_mul_f32_e32 v85, 0xbfb8aa3b, v79
	v_exp_f32_e32 v84, v84
	v_exp_f32_e32 v85, v85
	v_cvt_pk_bf16_f32 v93, v82, v83
	global_store_dwordx4 v[98:99], v[90:93], off
	v_or_b32_e32 v82, 48, v150
	v_pk_add_f32 v[84:85], v[84:85], 1.0 op_sel_hi:[1,0]
	v_mad_i64_i32 v[82:83], s[16:17], v82, s9, v[140:141]
	v_lshl_add_u64 v[82:83], v[82:83], 0, v[142:143]
	v_rcp_f32_e32 v85, v85
	v_rcp_f32_e32 v84, v84
	s_nop 0
; __device__ __forceinline__ unsigned cvt_pk_bf16(float lo, float hi) { f32x2_t v = {lo, hi}; bf2_t r = __builtin_convertvector(v, bf2_t); return __builtin_bit_cast(unsigned, r); }
; __device__ __forceinline__ float siluf_(float x) { return x * sigmoidf_(x); }
;     __device__ __forceinline__ void operator()(const f32x4 (&acc)[2][2][4][2], const Unit& u, int wr, int wc, int fr, int fq) const {
;     ...
;         for (int ai = 0; ai < 2; ++ai)
; #pragma unroll
;             for (int m = 0; m < 4; ++m) { bf16_t* rowp = U + (size_t)(row0 + ai * HALF + m * 16) * DFF + col0;
;                 const f32x4 g0 = acc[ai][0][m][0], g1 = acc[ai][0][m][1], h0 = acc[ai][1][m][0], h1 = acc[ai][1][m][1];
;                 u32x4 w; w.x = cvt_pk_bf16(siluf_(g0[0]) * h0[0], siluf_(g0[1]) * h0[1]); w.y = cvt_pk_bf16(siluf_(g0[2]) * h0[2], siluf_(g0[3]) * h0[3]);
;                 w.z = cvt_pk_bf16(siluf_(g1[0]) * h1[0], siluf_(g1[1]) * h1[1]); w.w = cvt_pk_bf16(siluf_(g1[2]) * h1[2], siluf_(g1[3]) * h1[3]);
;                 *(u32x4*)rowp = w; }
	v_pk_mul_f32 v[78:79], v[78:79], v[84:85]
	v_pk_mul_f32 v[74:75], v[78:79], v[74:75]
	v_cvt_pk_bf16_f32 v74, v74, v75
	v_mul_f32_e32 v75, 0xbfb8aa3b, v80
	v_exp_f32_e32 v78, v75
	v_mul_f32_e32 v75, 0xbfb8aa3b, v81
	v_exp_f32_e32 v79, v75
	s_nop 0
	v_pk_add_f32 v[78:79], v[78:79], 1.0 op_sel_hi:[1,0]
	v_rcp_f32_e32 v79, v79
	v_rcp_f32_e32 v78, v78
	s_nop 0
	v_pk_mul_f32 v[78:79], v[80:81], v[78:79]
	v_pk_mul_f32 v[76:77], v[78:79], v[76:77]
	v_cvt_pk_bf16_f32 v75, v76, v77
	v_mul_f32_e32 v76, 0xbfb8aa3b, v70
	v_mul_f32_e32 v77, 0xbfb8aa3b, v71
	v_exp_f32_e32 v76, v76
	v_exp_f32_e32 v77, v77
	s_nop 0
	v_pk_add_f32 v[76:77], v[76:77], 1.0 op_sel_hi:[1,0]
	v_rcp_f32_e32 v77, v77
	v_rcp_f32_e32 v76, v76
	s_nop 0
	v_pk_mul_f32 v[70:71], v[70:71], v[76:77]
	v_pk_mul_f32 v[66:67], v[70:71], v[66:67]
	v_cvt_pk_bf16_f32 v76, v66, v67
	v_mul_f32_e32 v66, 0xbfb8aa3b, v72
	v_mul_f32_e32 v67, 0xbfb8aa3b, v73
	v_exp_f32_e32 v66, v66
	v_exp_f32_e32 v67, v67
	s_nop 0
	v_pk_add_f32 v[66:67], v[66:67], 1.0 op_sel_hi:[1,0]
	v_rcp_f32_e32 v67, v67
	v_rcp_f32_e32 v66, v66
	s_nop 0
	v_pk_mul_f32 v[66:67], v[72:73], v[66:67]
	v_pk_mul_f32 v[66:67], v[66:67], v[68:69]
	v_mul_f32_e32 v68, 0xbfb8aa3b, v60
	v_mul_f32_e32 v69, 0xbfb8aa3b, v61
	v_exp_f32_e32 v68, v68
	v_exp_f32_e32 v69, v69
	v_cvt_pk_bf16_f32 v77, v66, v67
	global_store_dwordx4 v[82:83], v[74:77], off
	v_add_u32_e32 v66, 0x80, v150
	v_pk_add_f32 v[68:69], v[68:69], 1.0 op_sel_hi:[1,0]
	v_mad_i64_i32 v[66:67], s[16:17], v66, s9, v[140:141]
	v_lshl_add_u64 v[66:67], v[66:67], 0, v[142:143]
	v_rcp_f32_e32 v69, v69
	v_rcp_f32_e32 v68, v68
	s_nop 0
	v_pk_mul_f32 v[60:61], v[60:61], v[68:69]
	v_pk_mul_f32 v[56:57], v[60:61], v[56:57]
	v_cvt_pk_bf16_f32 v56, v56, v57
	v_mul_f32_e32 v57, 0xbfb8aa3b, v62
	v_exp_f32_e32 v60, v57
	v_mul_f32_e32 v57, 0xbfb8aa3b, v63
	v_exp_f32_e32 v61, v57
	s_nop 0
	v_pk_add_f32 v[60:61], v[60:61], 1.0 op_sel_hi:[1,0]
	v_rcp_f32_e32 v61, v61
	v_rcp_f32_e32 v60, v60
	s_nop 0
	v_pk_mul_f32 v[60:61], v[62:63], v[60:61]
	v_pk_mul_f32 v[58:59], v[60:61], v[58:59]
	v_cvt_pk_bf16_f32 v57, v58, v59
	v_mul_f32_e32 v58, 0xbfb8aa3b, v52
	v_mul_f32_e32 v59, 0xbfb8aa3b, v53
	v_exp_f32_e32 v58, v58
	v_exp_f32_e32 v59, v59
	s_nop 0
	v_pk_add_f32 v[58:59], v[58:59], 1.0 op_sel_hi:[1,0]
	v_rcp_f32_e32 v59, v59
	v_rcp_f32_e32 v58, v58
	s_nop 0
	v_pk_mul_f32 v[52:53], v[52:53], v[58:59]
	v_pk_mul_f32 v[48:49], v[52:53], v[48:49]
	v_cvt_pk_bf16_f32 v58, v48, v49
	v_mul_f32_e32 v48, 0xbfb8aa3b, v54
	v_mul_f32_e32 v49, 0xbfb8aa3b, v55
	v_exp_f32_e32 v48, v48
	v_exp_f32_e32 v49, v49
	s_nop 0
	v_pk_add_f32 v[48:49], v[48:49], 1.0 op_sel_hi:[1,0]
	v_rcp_f32_e32 v49, v49
	v_rcp_f32_e32 v48, v48
	s_nop 0
	v_pk_mul_f32 v[48:49], v[54:55], v[48:49]
	v_pk_mul_f32 v[48:49], v[48:49], v[50:51]
	v_mul_f32_e32 v50, 0xbfb8aa3b, v44
	v_mul_f32_e32 v51, 0xbfb8aa3b, v45
	v_exp_f32_e32 v50, v50
	v_exp_f32_e32 v51, v51
	v_cvt_pk_bf16_f32 v59, v48, v49
	global_store_dwordx4 v[66:67], v[56:59], off
	v_add_u32_e32 v48, 0x90, v150
	v_pk_add_f32 v[50:51], v[50:51], 1.0 op_sel_hi:[1,0]
	v_mad_i64_i32 v[48:49], s[16:17], v48, s9, v[140:141]
	v_lshl_add_u64 v[48:49], v[48:49], 0, v[142:143]
	v_rcp_f32_e32 v51, v51
	v_rcp_f32_e32 v50, v50
	s_nop 0
	v_pk_mul_f32 v[44:45], v[44:45], v[50:51]
	v_pk_mul_f32 v[40:41], v[44:45], v[40:41]
	v_cvt_pk_bf16_f32 v40, v40, v41
	v_mul_f32_e32 v41, 0xbfb8aa3b, v46
	v_exp_f32_e32 v44, v41
	v_mul_f32_e32 v41, 0xbfb8aa3b, v47
	v_exp_f32_e32 v45, v41
	s_nop 0
	v_pk_add_f32 v[44:45], v[44:45], 1.0 op_sel_hi:[1,0]
	v_rcp_f32_e32 v45, v45
	v_rcp_f32_e32 v44, v44
	s_nop 0
	v_pk_mul_f32 v[44:45], v[46:47], v[44:45]
	v_pk_mul_f32 v[42:43], v[44:45], v[42:43]
	v_cvt_pk_bf16_f32 v41, v42, v43
	v_mul_f32_e32 v42, 0xbfb8aa3b, v36
	v_mul_f32_e32 v43, 0xbfb8aa3b, v37
	v_exp_f32_e32 v42, v42
	v_exp_f32_e32 v43, v43
	s_nop 0
	v_pk_add_f32 v[42:43], v[42:43], 1.0 op_sel_hi:[1,0]
	v_rcp_f32_e32 v43, v43
; __device__ __forceinline__ unsigned cvt_pk_bf16(float lo, float hi) { f32x2_t v = {lo, hi}; bf2_t r = __builtin_convertvector(v, bf2_t); return __builtin_bit_cast(unsigned, r); }
; __device__ __forceinline__ float siluf_(float x) { return x * sigmoidf_(x); }
; #define PG8_BAR __builtin_amdgcn_s_barrier()
; template <class Epi, class Sched, bool ALIGN_EPI = false, bool SP2 = false>
; __device__ __forceinline__ void gemm_phase(LAS unsigned char* lds, const Gemm g, const Sched& S, const Epi& E) {
;     ...
;         if constexpr (ALIGN_EPI) { if (wr == 0) PG8_BAR; }
;         E(acc, cur, wr, wc, fr, fq);
;         if (!has_next) break;
; #pragma unroll
;         for (int a = 0; a < 2; ++a)
; #pragma unroll
;             for (int b = 0; b < 2; ++b)
; #pragma unroll
;                 for (int m = 0; m < 4; ++m)
; #pragma unroll
;                     for (int n = 0; n < 2; ++n) acc[a][b][m][n] = (f32x4){0.f, 0.f, 0.f, 0.f};
;         cur = nxt; cA = nA; cB = nB; ++ui;
;         if constexpr (ALIGN_EPI) { if (wr == 1) PG8_BAR; }
;     __device__ __forceinline__ void operator()(const f32x4 (&acc)[2][2][4][2], const Unit& u, int wr, int wc, int fr, int fq) const {
;     ...
;         for (int ai = 0; ai < 2; ++ai)
; #pragma unroll
;             for (int m = 0; m < 4; ++m) { bf16_t* rowp = U + (size_t)(row0 + ai * HALF + m * 16) * DFF + col0;
;                 const f32x4 g0 = acc[ai][0][m][0], g1 = acc[ai][0][m][1], h0 = acc[ai][1][m][0], h1 = acc[ai][1][m][1];
;                 u32x4 w; w.x = cvt_pk_bf16(siluf_(g0[0]) * h0[0], siluf_(g0[1]) * h0[1]); w.y = cvt_pk_bf16(siluf_(g0[2]) * h0[2], siluf_(g0[3]) * h0[3]);
;                 w.z = cvt_pk_bf16(siluf_(g1[0]) * h1[0], siluf_(g1[1]) * h1[1]); w.w = cvt_pk_bf16(siluf_(g1[2]) * h1[2], siluf_(g1[3]) * h1[3]);
;                 *(u32x4*)rowp = w; }
	v_rcp_f32_e32 v42, v42
	s_nop 0
	v_pk_mul_f32 v[36:37], v[36:37], v[42:43]
	v_pk_mul_f32 v[32:33], v[36:37], v[32:33]
	v_cvt_pk_bf16_f32 v42, v32, v33
	v_mul_f32_e32 v32, 0xbfb8aa3b, v38
	v_mul_f32_e32 v33, 0xbfb8aa3b, v39
	v_exp_f32_e32 v32, v32
	v_exp_f32_e32 v33, v33
	s_nop 0
	v_pk_add_f32 v[32:33], v[32:33], 1.0 op_sel_hi:[1,0]
	v_rcp_f32_e32 v33, v33
	v_rcp_f32_e32 v32, v32
	s_nop 0
	v_pk_mul_f32 v[32:33], v[38:39], v[32:33]
	v_pk_mul_f32 v[32:33], v[32:33], v[34:35]
	v_mul_f32_e32 v34, 0xbfb8aa3b, v28
	v_mul_f32_e32 v35, 0xbfb8aa3b, v29
	v_exp_f32_e32 v34, v34
	v_exp_f32_e32 v35, v35
	v_cvt_pk_bf16_f32 v43, v32, v33
	global_store_dwordx4 v[48:49], v[40:43], off
	v_add_u32_e32 v32, 0xa0, v150
	v_pk_add_f32 v[34:35], v[34:35], 1.0 op_sel_hi:[1,0]
	v_mad_i64_i32 v[32:33], s[16:17], v32, s9, v[140:141]
	v_lshl_add_u64 v[32:33], v[32:33], 0, v[142:143]
	v_rcp_f32_e32 v35, v35
	v_rcp_f32_e32 v34, v34
	s_nop 0
	v_pk_mul_f32 v[28:29], v[28:29], v[34:35]
	v_pk_mul_f32 v[24:25], v[28:29], v[24:25]
	v_cvt_pk_bf16_f32 v24, v24, v25
	v_mul_f32_e32 v25, 0xbfb8aa3b, v30
	v_exp_f32_e32 v28, v25
	v_mul_f32_e32 v25, 0xbfb8aa3b, v31
	v_exp_f32_e32 v29, v25
	s_nop 0
	v_pk_add_f32 v[28:29], v[28:29], 1.0 op_sel_hi:[1,0]
	v_rcp_f32_e32 v29, v29
	v_rcp_f32_e32 v28, v28
	s_nop 0
	v_pk_mul_f32 v[28:29], v[30:31], v[28:29]
	v_pk_mul_f32 v[26:27], v[28:29], v[26:27]
	v_cvt_pk_bf16_f32 v25, v26, v27
	v_mul_f32_e32 v26, 0xbfb8aa3b, v20
	v_mul_f32_e32 v27, 0xbfb8aa3b, v21
	v_exp_f32_e32 v26, v26
	v_exp_f32_e32 v27, v27
	s_nop 0
	v_pk_add_f32 v[26:27], v[26:27], 1.0 op_sel_hi:[1,0]
	v_rcp_f32_e32 v27, v27
	v_rcp_f32_e32 v26, v26
	s_nop 0
	v_pk_mul_f32 v[20:21], v[20:21], v[26:27]
	v_pk_mul_f32 v[16:17], v[20:21], v[16:17]
	v_cvt_pk_bf16_f32 v26, v16, v17
	v_mul_f32_e32 v16, 0xbfb8aa3b, v22
	v_mul_f32_e32 v17, 0xbfb8aa3b, v23
	v_exp_f32_e32 v16, v16
	v_exp_f32_e32 v17, v17
	s_nop 0
	v_pk_add_f32 v[16:17], v[16:17], 1.0 op_sel_hi:[1,0]
	v_rcp_f32_e32 v17, v17
	v_rcp_f32_e32 v16, v16
	s_nop 0
	v_pk_mul_f32 v[16:17], v[22:23], v[16:17]
	v_pk_mul_f32 v[16:17], v[16:17], v[18:19]
	v_mul_f32_e32 v18, 0xbfb8aa3b, v12
	v_mul_f32_e32 v19, 0xbfb8aa3b, v13
	v_exp_f32_e32 v18, v18
	v_exp_f32_e32 v19, v19
	v_cvt_pk_bf16_f32 v27, v16, v17
	global_store_dwordx4 v[32:33], v[24:27], off
	v_add_u32_e32 v16, 0xb0, v150
	v_pk_add_f32 v[18:19], v[18:19], 1.0 op_sel_hi:[1,0]
	v_mad_i64_i32 v[16:17], s[16:17], v16, s9, v[140:141]
	v_lshl_add_u64 v[16:17], v[16:17], 0, v[142:143]
	v_rcp_f32_e32 v19, v19
	v_rcp_f32_e32 v18, v18
	s_nop 0
	v_pk_mul_f32 v[12:13], v[12:13], v[18:19]
	v_pk_mul_f32 v[8:9], v[12:13], v[8:9]
	v_cvt_pk_bf16_f32 v8, v8, v9
	v_mul_f32_e32 v9, 0xbfb8aa3b, v14
	v_exp_f32_e32 v12, v9
	v_mul_f32_e32 v9, 0xbfb8aa3b, v15
	v_exp_f32_e32 v13, v9
	s_nop 0
	v_pk_add_f32 v[12:13], v[12:13], 1.0 op_sel_hi:[1,0]
	v_rcp_f32_e32 v13, v13
	v_rcp_f32_e32 v12, v12
	s_nop 0
	v_pk_mul_f32 v[12:13], v[14:15], v[12:13]
	v_pk_mul_f32 v[10:11], v[12:13], v[10:11]
	v_cvt_pk_bf16_f32 v9, v10, v11
	v_mul_f32_e32 v10, 0xbfb8aa3b, v4
	v_mul_f32_e32 v11, 0xbfb8aa3b, v5
	v_exp_f32_e32 v10, v10
	v_exp_f32_e32 v11, v11
	s_nop 0
	v_pk_add_f32 v[10:11], v[10:11], 1.0 op_sel_hi:[1,0]
	v_rcp_f32_e32 v11, v11
	v_rcp_f32_e32 v10, v10
	s_nop 0
	v_pk_mul_f32 v[4:5], v[4:5], v[10:11]
	v_pk_mul_f32 v[0:1], v[4:5], v[0:1]
	v_cvt_pk_bf16_f32 v10, v0, v1
	v_mul_f32_e32 v0, 0xbfb8aa3b, v6
	v_mul_f32_e32 v1, 0xbfb8aa3b, v7
	v_exp_f32_e32 v0, v0
	v_exp_f32_e32 v1, v1
	s_nop 0
	v_pk_add_f32 v[0:1], v[0:1], 1.0 op_sel_hi:[1,0]
	v_rcp_f32_e32 v1, v1
	s_mov_b64 s[16:17], -1
	v_rcp_f32_e32 v0, v0
	s_nop 0
	v_pk_mul_f32 v[0:1], v[6:7], v[0:1]
	s_andn2_b64 vcc, exec, s[42:43]
	v_pk_mul_f32 v[0:1], v[0:1], v[2:3]
	v_cvt_pk_bf16_f32 v11, v0, v1
	global_store_dwordx4 v[16:17], v[8:11], off
	s_cbranch_vccnz .LBB0_1122
	s_andn2_b64 vcc, exec, s[0:1]
	s_cbranch_vccnz .LBB0_1121
	s_barrier
	s_branch .LBB0_1121
